# E19: MFMA order per 32-segment: 2x2-blocked snake over (weight fragment x activation fragment) per k half, fewer distinct operand registers per MFMA; bitwise same math; on N5 base
# speedup vs baseline: 1.0143x; 1.0143x over previous
.LBB0_303:
	s_lshl_b32 s18, s91, 20
	s_and_b64 s[8:9], s[34:35], exec
	s_cselect_b32 s8, s18, s94
	s_lshl_b32 s19, s90, 20
	s_and_b64 s[42:43], s[34:35], exec
	s_cselect_b32 s9, s19, s95
	s_add_i32 s94, s94, 0x80080
	s_addk_i32 s95, 0x100
	s_mov_b32 vcc_lo, -2
	ds_read_b128 v[142:145], v136
	ds_read_b128 v[170:173], v136 offset:1024
	ds_read_b128 v[174:177], v136 offset:2048
	ds_read_b128 v[178:181], v136 offset:3072
	ds_read_b128 v[182:185], v137
	ds_read_b128 v[186:189], v137 offset:1024
	ds_read_b128 v[190:193], v137 offset:2048
	ds_read_b128 v[194:197], v137 offset:3072
	s_add_i32 s42, s94, 0xfff80080
	s_cmp_eq_u32 vcc_lo, 28
	s_cselect_b32 s97, s8, s42
	s_cselect_b32 s52, s9, s95
	s_or_b32 vcc_hi, s97, 0x80
	s_mov_b32 m0, s72
	ds_read_b128 v[198:201], v138
	ds_read_b128 v[202:205], v138 offset:1024
	ds_read_b128 v[228:231], v138 offset:2048
	ds_read_b128 v[232:235], v138 offset:3072
	ds_read_b128 v[236:239], v138 offset:4096
	ds_read_b128 v[240:243], v138 offset:5120
	ds_read_b128 v[244:247], v138 offset:6144
	ds_read_b128 v[248:251], v138 offset:7168
	buffer_load_dwordx4 v132, s[60:63], s94 offen lds
	s_mov_b32 m0, s47
	s_nop 0
	buffer_load_dwordx4 v134, s[60:63], s94 offen lds
	s_waitcnt vmcnt(8)
	s_waitcnt lgkmcnt(0)
	s_setprio 1
	s_barrier
	v_mfma_f32_16x16x32_bf16 v[114:117], v[142:145], v[198:201], 0
	v_mfma_f32_16x16x32_bf16 v[110:113], v[174:177], v[198:201], 0
	v_mfma_f32_16x16x32_bf16 v[102:105], v[174:177], v[228:231], 0
	v_mfma_f32_16x16x32_bf16 v[106:109], v[142:145], v[228:231], 0
	v_mfma_f32_16x16x32_bf16 v[94:97], v[142:145], v[236:239], 0
	v_mfma_f32_16x16x32_bf16 v[86:89], v[174:177], v[236:239], 0
	v_mfma_f32_16x16x32_bf16 v[70:73], v[174:177], v[244:247], 0
	v_mfma_f32_16x16x32_bf16 v[78:81], v[142:145], v[244:247], 0
	v_mfma_f32_16x16x32_bf16 v[74:77], v[182:185], v[244:247], 0
	v_mfma_f32_16x16x32_bf16 v[66:69], v[190:193], v[244:247], 0
	v_mfma_f32_16x16x32_bf16 v[82:85], v[190:193], v[236:239], 0
	v_mfma_f32_16x16x32_bf16 v[90:93], v[182:185], v[236:239], 0
	v_mfma_f32_16x16x32_bf16 v[118:121], v[182:185], v[228:231], 0
	v_mfma_f32_16x16x32_bf16 v[98:101], v[190:193], v[228:231], 0
	v_mfma_f32_16x16x32_bf16 v[122:125], v[190:193], v[198:201], 0
	v_mfma_f32_16x16x32_bf16 v[126:129], v[182:185], v[198:201], 0
	v_mfma_f32_16x16x32_bf16 v[114:117], v[170:173], v[202:205], v[114:117]
	v_mfma_f32_16x16x32_bf16 v[110:113], v[178:181], v[202:205], v[110:113]
	v_mfma_f32_16x16x32_bf16 v[102:105], v[178:181], v[232:235], v[102:105]
	v_mfma_f32_16x16x32_bf16 v[106:109], v[170:173], v[232:235], v[106:109]
	v_mfma_f32_16x16x32_bf16 v[94:97], v[170:173], v[240:243], v[94:97]
	v_mfma_f32_16x16x32_bf16 v[86:89], v[178:181], v[240:243], v[86:89]
	v_mfma_f32_16x16x32_bf16 v[70:73], v[178:181], v[248:251], v[70:73]
	v_mfma_f32_16x16x32_bf16 v[78:81], v[170:173], v[248:251], v[78:81]
	v_mfma_f32_16x16x32_bf16 v[74:77], v[186:189], v[248:251], v[74:77]
	v_mfma_f32_16x16x32_bf16 v[66:69], v[194:197], v[248:251], v[66:69]
	v_mfma_f32_16x16x32_bf16 v[82:85], v[194:197], v[240:243], v[82:85]
	v_mfma_f32_16x16x32_bf16 v[90:93], v[186:189], v[240:243], v[90:93]
	v_mfma_f32_16x16x32_bf16 v[118:121], v[186:189], v[232:235], v[118:121]
	v_mfma_f32_16x16x32_bf16 v[98:101], v[194:197], v[232:235], v[98:101]
	v_mfma_f32_16x16x32_bf16 v[122:125], v[194:197], v[202:205], v[122:125]
	v_mfma_f32_16x16x32_bf16 v[126:129], v[186:189], v[202:205], v[126:129]
	s_barrier
	s_setprio 0
	s_mov_b32 m0, s13
	s_mov_b32 s42, s62
	s_mov_b32 s43, s63
	ds_read_b128 v[198:201], v138 offset:16384
	ds_read_b128 v[202:205], v138 offset:17408
	ds_read_b128 v[228:231], v138 offset:18432
	ds_read_b128 v[232:235], v138 offset:19456
	ds_read_b128 v[236:239], v138 offset:20480
	ds_read_b128 v[240:243], v138 offset:21504
	ds_read_b128 v[244:247], v138 offset:22528
	ds_read_b128 v[248:251], v138 offset:23552
	buffer_load_dwordx4 v133, s[40:43], s52 offen lds
	s_mov_b32 m0, s14
	s_add_i32 s96, s52, 0x80000
	buffer_load_dwordx4 v135, s[40:43], s52 offen lds
	s_mov_b32 m0, s15
	s_nop 0
	buffer_load_dwordx4 v133, s[40:43], s96 offen lds
	s_mov_b32 m0, s16
	s_nop 0
	buffer_load_dwordx4 v135, s[40:43], s96 offen lds
	s_mov_b32 m0, s2
	s_nop 0
	buffer_load_dwordx4 v132, s[60:63], s97 offen lds
	s_mov_b32 m0, s21
	s_nop 0
	buffer_load_dwordx4 v134, s[60:63], s97 offen lds
	s_waitcnt vmcnt(8)
	s_waitcnt lgkmcnt(0)
	s_setprio 1
	s_barrier
	v_mfma_f32_16x16x32_bf16 v[62:65], v[142:145], v[198:201], 0
	v_mfma_f32_16x16x32_bf16 v[54:57], v[174:177], v[198:201], 0
	v_mfma_f32_16x16x32_bf16 v[38:41], v[174:177], v[228:231], 0
	v_mfma_f32_16x16x32_bf16 v[46:49], v[142:145], v[228:231], 0
	v_mfma_f32_16x16x32_bf16 v[30:33], v[142:145], v[236:239], 0
	v_mfma_f32_16x16x32_bf16 v[22:25], v[174:177], v[236:239], 0
	v_mfma_f32_16x16x32_bf16 v[6:9], v[174:177], v[244:247], 0
	v_mfma_f32_16x16x32_bf16 v[14:17], v[142:145], v[244:247], 0
	v_mfma_f32_16x16x32_bf16 v[10:13], v[182:185], v[244:247], 0
	v_mfma_f32_16x16x32_bf16 v[2:5], v[190:193], v[244:247], 0
	v_mfma_f32_16x16x32_bf16 v[18:21], v[190:193], v[236:239], 0
	v_mfma_f32_16x16x32_bf16 v[26:29], v[182:185], v[236:239], 0
	v_mfma_f32_16x16x32_bf16 v[42:45], v[182:185], v[228:231], 0
	v_mfma_f32_16x16x32_bf16 v[34:37], v[190:193], v[228:231], 0
	v_mfma_f32_16x16x32_bf16 v[50:53], v[190:193], v[198:201], 0
	v_mfma_f32_16x16x32_bf16 v[58:61], v[182:185], v[198:201], 0
	v_mfma_f32_16x16x32_bf16 v[62:65], v[170:173], v[202:205], v[62:65]
	v_mfma_f32_16x16x32_bf16 v[54:57], v[178:181], v[202:205], v[54:57]
	v_mfma_f32_16x16x32_bf16 v[38:41], v[178:181], v[232:235], v[38:41]
	v_mfma_f32_16x16x32_bf16 v[46:49], v[170:173], v[232:235], v[46:49]
	v_mfma_f32_16x16x32_bf16 v[30:33], v[170:173], v[240:243], v[30:33]
	v_mfma_f32_16x16x32_bf16 v[22:25], v[178:181], v[240:243], v[22:25]
	v_mfma_f32_16x16x32_bf16 v[6:9], v[178:181], v[248:251], v[6:9]
	v_mfma_f32_16x16x32_bf16 v[14:17], v[170:173], v[248:251], v[14:17]
	v_mfma_f32_16x16x32_bf16 v[10:13], v[186:189], v[248:251], v[10:13]
	v_mfma_f32_16x16x32_bf16 v[2:5], v[194:197], v[248:251], v[2:5]
	v_mfma_f32_16x16x32_bf16 v[18:21], v[194:197], v[240:243], v[18:21]
	v_mfma_f32_16x16x32_bf16 v[26:29], v[186:189], v[240:243], v[26:29]
	v_mfma_f32_16x16x32_bf16 v[42:45], v[186:189], v[232:235], v[42:45]
	v_mfma_f32_16x16x32_bf16 v[34:37], v[194:197], v[232:235], v[34:37]
	v_mfma_f32_16x16x32_bf16 v[50:53], v[194:197], v[202:205], v[50:53]
	v_mfma_f32_16x16x32_bf16 v[58:61], v[186:189], v[202:205], v[58:61]
	s_barrier
	s_setprio 0
	ds_read_b128 v[142:145], v139
	ds_read_b128 v[170:173], v139 offset:1024
	ds_read_b128 v[174:177], v139 offset:2048
	ds_read_b128 v[178:181], v139 offset:3072
	ds_read_b128 v[182:185], v140
	ds_read_b128 v[186:189], v140 offset:1024
	ds_read_b128 v[190:193], v140 offset:2048
	ds_read_b128 v[194:197], v140 offset:3072
	s_add_i32 s97, s97, 0x80000
	s_mov_b32 m0, s23
	ds_read_b128 v[198:201], v138 offset:32768
	ds_read_b128 v[202:205], v138 offset:33792
	ds_read_b128 v[228:231], v138 offset:34816
	ds_read_b128 v[232:235], v138 offset:35840
	ds_read_b128 v[236:239], v138 offset:36864
	ds_read_b128 v[240:243], v138 offset:37888
	ds_read_b128 v[244:247], v138 offset:38912
	ds_read_b128 v[248:251], v138 offset:39936
	buffer_load_dwordx4 v132, s[60:63], s97 offen lds
	s_mov_b32 m0, s24
	s_nop 0
	buffer_load_dwordx4 v134, s[60:63], s97 offen lds
	s_waitcnt vmcnt(8)
	s_waitcnt lgkmcnt(0)
	s_setprio 1
	s_barrier
	v_mfma_f32_16x16x32_bf16 v[114:117], v[142:145], v[198:201], v[114:117]
	v_mfma_f32_16x16x32_bf16 v[110:113], v[174:177], v[198:201], v[110:113]
	v_mfma_f32_16x16x32_bf16 v[102:105], v[174:177], v[228:231], v[102:105]
	v_mfma_f32_16x16x32_bf16 v[106:109], v[142:145], v[228:231], v[106:109]
	v_mfma_f32_16x16x32_bf16 v[94:97], v[142:145], v[236:239], v[94:97]
	v_mfma_f32_16x16x32_bf16 v[86:89], v[174:177], v[236:239], v[86:89]
	v_mfma_f32_16x16x32_bf16 v[70:73], v[174:177], v[244:247], v[70:73]
	v_mfma_f32_16x16x32_bf16 v[78:81], v[142:145], v[244:247], v[78:81]
	v_mfma_f32_16x16x32_bf16 v[74:77], v[182:185], v[244:247], v[74:77]
	v_mfma_f32_16x16x32_bf16 v[66:69], v[190:193], v[244:247], v[66:69]
	v_mfma_f32_16x16x32_bf16 v[82:85], v[190:193], v[236:239], v[82:85]
	v_mfma_f32_16x16x32_bf16 v[90:93], v[182:185], v[236:239], v[90:93]
	v_mfma_f32_16x16x32_bf16 v[118:121], v[182:185], v[228:231], v[118:121]
	v_mfma_f32_16x16x32_bf16 v[98:101], v[190:193], v[228:231], v[98:101]
	v_mfma_f32_16x16x32_bf16 v[122:125], v[190:193], v[198:201], v[122:125]
	v_mfma_f32_16x16x32_bf16 v[126:129], v[182:185], v[198:201], v[126:129]
	v_mfma_f32_16x16x32_bf16 v[114:117], v[170:173], v[202:205], v[114:117]
	v_mfma_f32_16x16x32_bf16 v[110:113], v[178:181], v[202:205], v[110:113]
	v_mfma_f32_16x16x32_bf16 v[102:105], v[178:181], v[232:235], v[102:105]
	v_mfma_f32_16x16x32_bf16 v[106:109], v[170:173], v[232:235], v[106:109]
	v_mfma_f32_16x16x32_bf16 v[94:97], v[170:173], v[240:243], v[94:97]
	v_mfma_f32_16x16x32_bf16 v[86:89], v[178:181], v[240:243], v[86:89]
	v_mfma_f32_16x16x32_bf16 v[70:73], v[178:181], v[248:251], v[70:73]
	v_mfma_f32_16x16x32_bf16 v[78:81], v[170:173], v[248:251], v[78:81]
	v_mfma_f32_16x16x32_bf16 v[74:77], v[186:189], v[248:251], v[74:77]
	v_mfma_f32_16x16x32_bf16 v[66:69], v[194:197], v[248:251], v[66:69]
	v_mfma_f32_16x16x32_bf16 v[82:85], v[194:197], v[240:243], v[82:85]
	v_mfma_f32_16x16x32_bf16 v[90:93], v[186:189], v[240:243], v[90:93]
	v_mfma_f32_16x16x32_bf16 v[118:121], v[186:189], v[232:235], v[118:121]
	v_mfma_f32_16x16x32_bf16 v[98:101], v[194:197], v[232:235], v[98:101]
	v_mfma_f32_16x16x32_bf16 v[122:125], v[194:197], v[202:205], v[122:125]
	v_mfma_f32_16x16x32_bf16 v[126:129], v[186:189], v[202:205], v[126:129]
	s_barrier
	s_setprio 0
	s_mov_b32 m0, s31
	s_or_b32 s53, s52, 0x80
	ds_read_b128 v[198:201], v138 offset:49152
	ds_read_b128 v[202:205], v138 offset:50176
	ds_read_b128 v[228:231], v138 offset:51200
	ds_read_b128 v[232:235], v138 offset:52224
	ds_read_b128 v[236:239], v138 offset:53248
	ds_read_b128 v[240:243], v138 offset:54272
	ds_read_b128 v[244:247], v138 offset:55296
	ds_read_b128 v[248:251], v138 offset:56320
	buffer_load_dwordx4 v133, s[40:43], s53 offen lds
	s_mov_b32 m0, s33
	s_add_i32 s52, s52, 0x80080
	buffer_load_dwordx4 v135, s[40:43], s53 offen lds
	s_mov_b32 m0, s68
	s_nop 0
	buffer_load_dwordx4 v133, s[40:43], s52 offen lds
	s_mov_b32 m0, s69
	s_nop 0
	buffer_load_dwordx4 v135, s[40:43], s52 offen lds
	s_mov_b32 m0, s36
	s_nop 0
	buffer_load_dwordx4 v132, s[60:63], vcc_hi offen lds
	s_mov_b32 m0, s37
	s_nop 0
	buffer_load_dwordx4 v134, s[60:63], vcc_hi offen lds
	s_waitcnt vmcnt(8)
	s_waitcnt lgkmcnt(0)
	s_setprio 1
	s_barrier
	v_mfma_f32_16x16x32_bf16 v[62:65], v[142:145], v[198:201], v[62:65]
	v_mfma_f32_16x16x32_bf16 v[54:57], v[174:177], v[198:201], v[54:57]
	v_mfma_f32_16x16x32_bf16 v[38:41], v[174:177], v[228:231], v[38:41]
	v_mfma_f32_16x16x32_bf16 v[46:49], v[142:145], v[228:231], v[46:49]
	v_mfma_f32_16x16x32_bf16 v[30:33], v[142:145], v[236:239], v[30:33]
	v_mfma_f32_16x16x32_bf16 v[22:25], v[174:177], v[236:239], v[22:25]
	v_mfma_f32_16x16x32_bf16 v[6:9], v[174:177], v[244:247], v[6:9]
	v_mfma_f32_16x16x32_bf16 v[14:17], v[142:145], v[244:247], v[14:17]
	v_mfma_f32_16x16x32_bf16 v[10:13], v[182:185], v[244:247], v[10:13]
	v_mfma_f32_16x16x32_bf16 v[2:5], v[190:193], v[244:247], v[2:5]
	v_mfma_f32_16x16x32_bf16 v[18:21], v[190:193], v[236:239], v[18:21]
	v_mfma_f32_16x16x32_bf16 v[26:29], v[182:185], v[236:239], v[26:29]
	v_mfma_f32_16x16x32_bf16 v[42:45], v[182:185], v[228:231], v[42:45]
	v_mfma_f32_16x16x32_bf16 v[34:37], v[190:193], v[228:231], v[34:37]
	v_mfma_f32_16x16x32_bf16 v[50:53], v[190:193], v[198:201], v[50:53]
	v_mfma_f32_16x16x32_bf16 v[58:61], v[182:185], v[198:201], v[58:61]
	v_mfma_f32_16x16x32_bf16 v[62:65], v[170:173], v[202:205], v[62:65]
	v_mfma_f32_16x16x32_bf16 v[54:57], v[178:181], v[202:205], v[54:57]
	v_mfma_f32_16x16x32_bf16 v[38:41], v[178:181], v[232:235], v[38:41]
	v_mfma_f32_16x16x32_bf16 v[46:49], v[170:173], v[232:235], v[46:49]
	v_mfma_f32_16x16x32_bf16 v[30:33], v[170:173], v[240:243], v[30:33]
	v_mfma_f32_16x16x32_bf16 v[22:25], v[178:181], v[240:243], v[22:25]
	v_mfma_f32_16x16x32_bf16 v[6:9], v[178:181], v[248:251], v[6:9]
	v_mfma_f32_16x16x32_bf16 v[14:17], v[170:173], v[248:251], v[14:17]
	v_mfma_f32_16x16x32_bf16 v[10:13], v[186:189], v[248:251], v[10:13]
	v_mfma_f32_16x16x32_bf16 v[2:5], v[194:197], v[248:251], v[2:5]
	v_mfma_f32_16x16x32_bf16 v[18:21], v[194:197], v[240:243], v[18:21]
	v_mfma_f32_16x16x32_bf16 v[26:29], v[186:189], v[240:243], v[26:29]
	v_mfma_f32_16x16x32_bf16 v[42:45], v[186:189], v[232:235], v[42:45]
	v_mfma_f32_16x16x32_bf16 v[34:37], v[194:197], v[232:235], v[34:37]
	v_mfma_f32_16x16x32_bf16 v[50:53], v[194:197], v[202:205], v[50:53]
	v_mfma_f32_16x16x32_bf16 v[58:61], v[186:189], v[202:205], v[58:61]
	s_barrier
	s_setprio 0
	s_add_i32 vcc_lo, vcc_lo, 2
	s_addk_i32 s94, 0x100
	s_addk_i32 s95, 0x100
	s_cmp_gt_u32 vcc_lo, 29
.LBB0_304:
	ds_read_b128 v[142:145], v136
	ds_read_b128 v[170:173], v136 offset:1024
	ds_read_b128 v[174:177], v136 offset:2048
	ds_read_b128 v[178:181], v136 offset:3072
	ds_read_b128 v[182:185], v137
	ds_read_b128 v[186:189], v137 offset:1024
	ds_read_b128 v[190:193], v137 offset:2048
	ds_read_b128 v[194:197], v137 offset:3072
	s_add_i32 s42, s94, 0xfff80080
	s_cmp_eq_u32 vcc_lo, 28
	s_cselect_b32 s97, s8, s42
	s_cselect_b32 s52, s9, s95
	s_or_b32 vcc_hi, s97, 0x80
	s_mov_b32 m0, s72
	ds_read_b128 v[198:201], v138
	ds_read_b128 v[202:205], v138 offset:1024
	ds_read_b128 v[228:231], v138 offset:2048
	ds_read_b128 v[232:235], v138 offset:3072
	ds_read_b128 v[236:239], v138 offset:4096
	ds_read_b128 v[240:243], v138 offset:5120
	ds_read_b128 v[244:247], v138 offset:6144
	ds_read_b128 v[248:251], v138 offset:7168
	buffer_load_dwordx4 v132, s[60:63], s94 offen lds
	s_mov_b32 m0, s47
	s_nop 0
	buffer_load_dwordx4 v134, s[60:63], s94 offen lds
	s_waitcnt vmcnt(8)
	s_waitcnt lgkmcnt(0)
	s_setprio 1
	s_barrier
	v_mfma_f32_16x16x32_bf16 v[114:117], v[142:145], v[198:201], v[114:117]
	v_mfma_f32_16x16x32_bf16 v[110:113], v[174:177], v[198:201], v[110:113]
	v_mfma_f32_16x16x32_bf16 v[102:105], v[174:177], v[228:231], v[102:105]
	v_mfma_f32_16x16x32_bf16 v[106:109], v[142:145], v[228:231], v[106:109]
	v_mfma_f32_16x16x32_bf16 v[94:97], v[142:145], v[236:239], v[94:97]
	v_mfma_f32_16x16x32_bf16 v[86:89], v[174:177], v[236:239], v[86:89]
	v_mfma_f32_16x16x32_bf16 v[70:73], v[174:177], v[244:247], v[70:73]
	v_mfma_f32_16x16x32_bf16 v[78:81], v[142:145], v[244:247], v[78:81]
	v_mfma_f32_16x16x32_bf16 v[74:77], v[182:185], v[244:247], v[74:77]
	v_mfma_f32_16x16x32_bf16 v[66:69], v[190:193], v[244:247], v[66:69]
	v_mfma_f32_16x16x32_bf16 v[82:85], v[190:193], v[236:239], v[82:85]
	v_mfma_f32_16x16x32_bf16 v[90:93], v[182:185], v[236:239], v[90:93]
	v_mfma_f32_16x16x32_bf16 v[118:121], v[182:185], v[228:231], v[118:121]
	v_mfma_f32_16x16x32_bf16 v[98:101], v[190:193], v[228:231], v[98:101]
	v_mfma_f32_16x16x32_bf16 v[122:125], v[190:193], v[198:201], v[122:125]
	v_mfma_f32_16x16x32_bf16 v[126:129], v[182:185], v[198:201], v[126:129]
	v_mfma_f32_16x16x32_bf16 v[114:117], v[170:173], v[202:205], v[114:117]
	v_mfma_f32_16x16x32_bf16 v[110:113], v[178:181], v[202:205], v[110:113]
	v_mfma_f32_16x16x32_bf16 v[102:105], v[178:181], v[232:235], v[102:105]
	v_mfma_f32_16x16x32_bf16 v[106:109], v[170:173], v[232:235], v[106:109]
	v_mfma_f32_16x16x32_bf16 v[94:97], v[170:173], v[240:243], v[94:97]
	v_mfma_f32_16x16x32_bf16 v[86:89], v[178:181], v[240:243], v[86:89]
	v_mfma_f32_16x16x32_bf16 v[70:73], v[178:181], v[248:251], v[70:73]
	v_mfma_f32_16x16x32_bf16 v[78:81], v[170:173], v[248:251], v[78:81]
	v_mfma_f32_16x16x32_bf16 v[74:77], v[186:189], v[248:251], v[74:77]
	v_mfma_f32_16x16x32_bf16 v[66:69], v[194:197], v[248:251], v[66:69]
	v_mfma_f32_16x16x32_bf16 v[82:85], v[194:197], v[240:243], v[82:85]
	v_mfma_f32_16x16x32_bf16 v[90:93], v[186:189], v[240:243], v[90:93]
	v_mfma_f32_16x16x32_bf16 v[118:121], v[186:189], v[232:235], v[118:121]
	v_mfma_f32_16x16x32_bf16 v[98:101], v[194:197], v[232:235], v[98:101]
	v_mfma_f32_16x16x32_bf16 v[122:125], v[194:197], v[202:205], v[122:125]
	v_mfma_f32_16x16x32_bf16 v[126:129], v[186:189], v[202:205], v[126:129]
	s_barrier
	s_setprio 0
	s_mov_b32 m0, s13
	s_mov_b32 s42, s62
	s_mov_b32 s43, s63
	ds_read_b128 v[198:201], v138 offset:16384
	ds_read_b128 v[202:205], v138 offset:17408
	ds_read_b128 v[228:231], v138 offset:18432
	ds_read_b128 v[232:235], v138 offset:19456
	ds_read_b128 v[236:239], v138 offset:20480
	ds_read_b128 v[240:243], v138 offset:21504
	ds_read_b128 v[244:247], v138 offset:22528
	ds_read_b128 v[248:251], v138 offset:23552
	buffer_load_dwordx4 v133, s[40:43], s52 offen lds
	s_mov_b32 m0, s14
	s_add_i32 s96, s52, 0x80000
	buffer_load_dwordx4 v135, s[40:43], s52 offen lds
	s_mov_b32 m0, s15
	s_nop 0
	buffer_load_dwordx4 v133, s[40:43], s96 offen lds
	s_mov_b32 m0, s16
	s_nop 0
	buffer_load_dwordx4 v135, s[40:43], s96 offen lds
	s_mov_b32 m0, s2
	s_nop 0
	buffer_load_dwordx4 v132, s[60:63], s97 offen lds
	s_mov_b32 m0, s21
	s_nop 0
	buffer_load_dwordx4 v134, s[60:63], s97 offen lds
	s_waitcnt vmcnt(8)
	s_waitcnt lgkmcnt(0)
	s_setprio 1
	s_barrier
	v_mfma_f32_16x16x32_bf16 v[62:65], v[142:145], v[198:201], v[62:65]
	v_mfma_f32_16x16x32_bf16 v[54:57], v[174:177], v[198:201], v[54:57]
	v_mfma_f32_16x16x32_bf16 v[38:41], v[174:177], v[228:231], v[38:41]
	v_mfma_f32_16x16x32_bf16 v[46:49], v[142:145], v[228:231], v[46:49]
	v_mfma_f32_16x16x32_bf16 v[30:33], v[142:145], v[236:239], v[30:33]
	v_mfma_f32_16x16x32_bf16 v[22:25], v[174:177], v[236:239], v[22:25]
	v_mfma_f32_16x16x32_bf16 v[6:9], v[174:177], v[244:247], v[6:9]
	v_mfma_f32_16x16x32_bf16 v[14:17], v[142:145], v[244:247], v[14:17]
	v_mfma_f32_16x16x32_bf16 v[10:13], v[182:185], v[244:247], v[10:13]
	v_mfma_f32_16x16x32_bf16 v[2:5], v[190:193], v[244:247], v[2:5]
	v_mfma_f32_16x16x32_bf16 v[18:21], v[190:193], v[236:239], v[18:21]
	v_mfma_f32_16x16x32_bf16 v[26:29], v[182:185], v[236:239], v[26:29]
	v_mfma_f32_16x16x32_bf16 v[42:45], v[182:185], v[228:231], v[42:45]
	v_mfma_f32_16x16x32_bf16 v[34:37], v[190:193], v[228:231], v[34:37]
	v_mfma_f32_16x16x32_bf16 v[50:53], v[190:193], v[198:201], v[50:53]
	v_mfma_f32_16x16x32_bf16 v[58:61], v[182:185], v[198:201], v[58:61]
	v_mfma_f32_16x16x32_bf16 v[62:65], v[170:173], v[202:205], v[62:65]
	v_mfma_f32_16x16x32_bf16 v[54:57], v[178:181], v[202:205], v[54:57]
	v_mfma_f32_16x16x32_bf16 v[38:41], v[178:181], v[232:235], v[38:41]
	v_mfma_f32_16x16x32_bf16 v[46:49], v[170:173], v[232:235], v[46:49]
	v_mfma_f32_16x16x32_bf16 v[30:33], v[170:173], v[240:243], v[30:33]
	v_mfma_f32_16x16x32_bf16 v[22:25], v[178:181], v[240:243], v[22:25]
	v_mfma_f32_16x16x32_bf16 v[6:9], v[178:181], v[248:251], v[6:9]
	v_mfma_f32_16x16x32_bf16 v[14:17], v[170:173], v[248:251], v[14:17]
	v_mfma_f32_16x16x32_bf16 v[10:13], v[186:189], v[248:251], v[10:13]
	v_mfma_f32_16x16x32_bf16 v[2:5], v[194:197], v[248:251], v[2:5]
	v_mfma_f32_16x16x32_bf16 v[18:21], v[194:197], v[240:243], v[18:21]
	v_mfma_f32_16x16x32_bf16 v[26:29], v[186:189], v[240:243], v[26:29]
	v_mfma_f32_16x16x32_bf16 v[42:45], v[186:189], v[232:235], v[42:45]
	v_mfma_f32_16x16x32_bf16 v[34:37], v[194:197], v[232:235], v[34:37]
	v_mfma_f32_16x16x32_bf16 v[50:53], v[194:197], v[202:205], v[50:53]
	v_mfma_f32_16x16x32_bf16 v[58:61], v[186:189], v[202:205], v[58:61]
	s_barrier
	s_setprio 0
	ds_read_b128 v[142:145], v139
	ds_read_b128 v[170:173], v139 offset:1024
	ds_read_b128 v[174:177], v139 offset:2048
	ds_read_b128 v[178:181], v139 offset:3072
	ds_read_b128 v[182:185], v140
	ds_read_b128 v[186:189], v140 offset:1024
	ds_read_b128 v[190:193], v140 offset:2048
	ds_read_b128 v[194:197], v140 offset:3072
	s_add_i32 s97, s97, 0x80000
	s_mov_b32 m0, s23
	ds_read_b128 v[198:201], v138 offset:32768
	ds_read_b128 v[202:205], v138 offset:33792
	ds_read_b128 v[228:231], v138 offset:34816
	ds_read_b128 v[232:235], v138 offset:35840
	ds_read_b128 v[236:239], v138 offset:36864
	ds_read_b128 v[240:243], v138 offset:37888
	ds_read_b128 v[244:247], v138 offset:38912
	ds_read_b128 v[248:251], v138 offset:39936
	buffer_load_dwordx4 v132, s[60:63], s97 offen lds
	s_mov_b32 m0, s24
	s_nop 0
	buffer_load_dwordx4 v134, s[60:63], s97 offen lds
	s_waitcnt vmcnt(8)
	s_waitcnt lgkmcnt(0)
	s_setprio 1
	s_barrier
	v_mfma_f32_16x16x32_bf16 v[114:117], v[142:145], v[198:201], v[114:117]
	v_mfma_f32_16x16x32_bf16 v[110:113], v[174:177], v[198:201], v[110:113]
	v_mfma_f32_16x16x32_bf16 v[102:105], v[174:177], v[228:231], v[102:105]
	v_mfma_f32_16x16x32_bf16 v[106:109], v[142:145], v[228:231], v[106:109]
	v_mfma_f32_16x16x32_bf16 v[94:97], v[142:145], v[236:239], v[94:97]
	v_mfma_f32_16x16x32_bf16 v[86:89], v[174:177], v[236:239], v[86:89]
	v_mfma_f32_16x16x32_bf16 v[70:73], v[174:177], v[244:247], v[70:73]
	v_mfma_f32_16x16x32_bf16 v[78:81], v[142:145], v[244:247], v[78:81]
	v_mfma_f32_16x16x32_bf16 v[74:77], v[182:185], v[244:247], v[74:77]
	v_mfma_f32_16x16x32_bf16 v[66:69], v[190:193], v[244:247], v[66:69]
	v_mfma_f32_16x16x32_bf16 v[82:85], v[190:193], v[236:239], v[82:85]
	v_mfma_f32_16x16x32_bf16 v[90:93], v[182:185], v[236:239], v[90:93]
	v_mfma_f32_16x16x32_bf16 v[118:121], v[182:185], v[228:231], v[118:121]
	v_mfma_f32_16x16x32_bf16 v[98:101], v[190:193], v[228:231], v[98:101]
	v_mfma_f32_16x16x32_bf16 v[122:125], v[190:193], v[198:201], v[122:125]
	v_mfma_f32_16x16x32_bf16 v[126:129], v[182:185], v[198:201], v[126:129]
	v_mfma_f32_16x16x32_bf16 v[114:117], v[170:173], v[202:205], v[114:117]
	v_mfma_f32_16x16x32_bf16 v[110:113], v[178:181], v[202:205], v[110:113]
	v_mfma_f32_16x16x32_bf16 v[102:105], v[178:181], v[232:235], v[102:105]
	v_mfma_f32_16x16x32_bf16 v[106:109], v[170:173], v[232:235], v[106:109]
	v_mfma_f32_16x16x32_bf16 v[94:97], v[170:173], v[240:243], v[94:97]
	v_mfma_f32_16x16x32_bf16 v[86:89], v[178:181], v[240:243], v[86:89]
	v_mfma_f32_16x16x32_bf16 v[70:73], v[178:181], v[248:251], v[70:73]
	v_mfma_f32_16x16x32_bf16 v[78:81], v[170:173], v[248:251], v[78:81]
	v_mfma_f32_16x16x32_bf16 v[74:77], v[186:189], v[248:251], v[74:77]
	v_mfma_f32_16x16x32_bf16 v[66:69], v[194:197], v[248:251], v[66:69]
	v_mfma_f32_16x16x32_bf16 v[82:85], v[194:197], v[240:243], v[82:85]
	v_mfma_f32_16x16x32_bf16 v[90:93], v[186:189], v[240:243], v[90:93]
	v_mfma_f32_16x16x32_bf16 v[118:121], v[186:189], v[232:235], v[118:121]
	v_mfma_f32_16x16x32_bf16 v[98:101], v[194:197], v[232:235], v[98:101]
	v_mfma_f32_16x16x32_bf16 v[122:125], v[194:197], v[202:205], v[122:125]
	v_mfma_f32_16x16x32_bf16 v[126:129], v[186:189], v[202:205], v[126:129]
	s_barrier
	s_setprio 0
	s_mov_b32 m0, s31
	s_or_b32 s53, s52, 0x80
	ds_read_b128 v[198:201], v138 offset:49152
	ds_read_b128 v[202:205], v138 offset:50176
	ds_read_b128 v[228:231], v138 offset:51200
	ds_read_b128 v[232:235], v138 offset:52224
	ds_read_b128 v[236:239], v138 offset:53248
	ds_read_b128 v[240:243], v138 offset:54272
	ds_read_b128 v[244:247], v138 offset:55296
	ds_read_b128 v[248:251], v138 offset:56320
	buffer_load_dwordx4 v133, s[40:43], s53 offen lds
	s_mov_b32 m0, s33
	s_add_i32 s52, s52, 0x80080
	buffer_load_dwordx4 v135, s[40:43], s53 offen lds
	s_mov_b32 m0, s68
	s_nop 0
	buffer_load_dwordx4 v133, s[40:43], s52 offen lds
	s_mov_b32 m0, s69
	s_nop 0
	buffer_load_dwordx4 v135, s[40:43], s52 offen lds
	s_mov_b32 m0, s36
	s_nop 0
	buffer_load_dwordx4 v132, s[60:63], vcc_hi offen lds
	s_mov_b32 m0, s37
	s_nop 0
	buffer_load_dwordx4 v134, s[60:63], vcc_hi offen lds
	s_waitcnt vmcnt(8)
	s_waitcnt lgkmcnt(0)
	s_setprio 1
	s_barrier
	v_mfma_f32_16x16x32_bf16 v[62:65], v[142:145], v[198:201], v[62:65]
	v_mfma_f32_16x16x32_bf16 v[54:57], v[174:177], v[198:201], v[54:57]
	v_mfma_f32_16x16x32_bf16 v[38:41], v[174:177], v[228:231], v[38:41]
	v_mfma_f32_16x16x32_bf16 v[46:49], v[142:145], v[228:231], v[46:49]
	v_mfma_f32_16x16x32_bf16 v[30:33], v[142:145], v[236:239], v[30:33]
	v_mfma_f32_16x16x32_bf16 v[22:25], v[174:177], v[236:239], v[22:25]
	v_mfma_f32_16x16x32_bf16 v[6:9], v[174:177], v[244:247], v[6:9]
	v_mfma_f32_16x16x32_bf16 v[14:17], v[142:145], v[244:247], v[14:17]
	v_mfma_f32_16x16x32_bf16 v[10:13], v[182:185], v[244:247], v[10:13]
	v_mfma_f32_16x16x32_bf16 v[2:5], v[190:193], v[244:247], v[2:5]
	v_mfma_f32_16x16x32_bf16 v[18:21], v[190:193], v[236:239], v[18:21]
	v_mfma_f32_16x16x32_bf16 v[26:29], v[182:185], v[236:239], v[26:29]
	v_mfma_f32_16x16x32_bf16 v[42:45], v[182:185], v[228:231], v[42:45]
	v_mfma_f32_16x16x32_bf16 v[34:37], v[190:193], v[228:231], v[34:37]
	v_mfma_f32_16x16x32_bf16 v[50:53], v[190:193], v[198:201], v[50:53]
	v_mfma_f32_16x16x32_bf16 v[58:61], v[182:185], v[198:201], v[58:61]
	v_mfma_f32_16x16x32_bf16 v[62:65], v[170:173], v[202:205], v[62:65]
	v_mfma_f32_16x16x32_bf16 v[54:57], v[178:181], v[202:205], v[54:57]
	v_mfma_f32_16x16x32_bf16 v[38:41], v[178:181], v[232:235], v[38:41]
	v_mfma_f32_16x16x32_bf16 v[46:49], v[170:173], v[232:235], v[46:49]
	v_mfma_f32_16x16x32_bf16 v[30:33], v[170:173], v[240:243], v[30:33]
	v_mfma_f32_16x16x32_bf16 v[22:25], v[178:181], v[240:243], v[22:25]
	v_mfma_f32_16x16x32_bf16 v[6:9], v[178:181], v[248:251], v[6:9]
	v_mfma_f32_16x16x32_bf16 v[14:17], v[170:173], v[248:251], v[14:17]
	v_mfma_f32_16x16x32_bf16 v[10:13], v[186:189], v[248:251], v[10:13]
	v_mfma_f32_16x16x32_bf16 v[2:5], v[194:197], v[248:251], v[2:5]
	v_mfma_f32_16x16x32_bf16 v[18:21], v[194:197], v[240:243], v[18:21]
	v_mfma_f32_16x16x32_bf16 v[26:29], v[186:189], v[240:243], v[26:29]
	v_mfma_f32_16x16x32_bf16 v[42:45], v[186:189], v[232:235], v[42:45]
	v_mfma_f32_16x16x32_bf16 v[34:37], v[194:197], v[232:235], v[34:37]
	v_mfma_f32_16x16x32_bf16 v[50:53], v[194:197], v[202:205], v[50:53]
	v_mfma_f32_16x16x32_bf16 v[58:61], v[186:189], v[202:205], v[58:61]
	s_barrier
	s_setprio 0
	s_add_i32 vcc_lo, vcc_lo, 2
	s_addk_i32 s94, 0x100
	s_addk_i32 s95, 0x100
	s_cmp_gt_u32 vcc_lo, 29
	s_cbranch_scc0 .LBB0_304
	s_and_b64 vcc, exec, s[48:49]
	s_cbranch_vccz .LBB0_307
	s_barrier

.LBB0_579:
	s_mul_i32 s73, s72, 0x2c0000
	s_and_b64 s[8:9], s[42:43], exec
	s_mul_i32 s84, s71, 0x2c0000
	s_cselect_b32 s8, s73, s21
	s_cselect_b32 s9, s84, s13
	s_addk_i32 s13, 0x100
	s_add_i32 s21, s21, 0xc000
	s_mov_b32 s22, -2
	s_waitcnt lgkmcnt(0)
	v_add_u32_e32 v154, 0x10000, v140
	ds_read_b128 v[132:135], v154
	ds_read_b128 v[142:145], v154 offset:1024
	ds_read_b128 v[170:173], v154 offset:2048
	ds_read_b128 v[174:177], v154 offset:3072
	v_add_u32_e32 v154, 0x14000, v140
	ds_read_b128 v[178:181], v154
	ds_read_b128 v[182:185], v154 offset:1024
	ds_read_b128 v[186:189], v154 offset:2048
	ds_read_b128 v[190:193], v154 offset:3072
	s_add_i32 s23, s21, 0x4000
	s_cmpk_eq_i32 s22, 0x54
	s_cselect_b32 s27, s8, s23
	s_cselect_b32 s26, s9, s13
	s_or_b32 s23, s27, 0x8000
	s_mov_b32 m0, s68
	ds_read_b128 v[194:197], v141
	ds_read_b128 v[198:201], v141 offset:1024
	ds_read_b128 v[202:205], v141 offset:2048
	ds_read_b128 v[228:231], v141 offset:3072
	ds_read_b128 v[232:235], v141 offset:4096
	ds_read_b128 v[236:239], v141 offset:5120
	ds_read_b128 v[240:243], v141 offset:6144
	ds_read_b128 v[244:247], v141 offset:7168
	buffer_load_dwordx4 v136, s[60:63], s21 offen lds
	s_mov_b32 m0, s70
	s_nop 0
	buffer_load_dwordx4 v138, s[60:63], s21 offen lds
	s_waitcnt vmcnt(8)
	s_waitcnt lgkmcnt(0)
	s_setprio 1
	s_barrier
	v_mfma_f32_16x16x32_bf16 v[126:129], v[132:135], v[194:197], 0
	v_mfma_f32_16x16x32_bf16 v[106:109], v[170:173], v[194:197], 0
	v_mfma_f32_16x16x32_bf16 v[114:117], v[170:173], v[202:205], 0
	v_mfma_f32_16x16x32_bf16 v[118:121], v[132:135], v[202:205], 0
	v_mfma_f32_16x16x32_bf16 v[94:97], v[132:135], v[232:235], 0
	v_mfma_f32_16x16x32_bf16 v[90:93], v[170:173], v[232:235], 0
	v_mfma_f32_16x16x32_bf16 v[74:77], v[170:173], v[240:243], 0
	v_mfma_f32_16x16x32_bf16 v[78:81], v[132:135], v[240:243], 0
	v_mfma_f32_16x16x32_bf16 v[70:73], v[178:181], v[240:243], 0
	v_mfma_f32_16x16x32_bf16 v[66:69], v[186:189], v[240:243], 0
	v_mfma_f32_16x16x32_bf16 v[82:85], v[186:189], v[232:235], 0
	v_mfma_f32_16x16x32_bf16 v[86:89], v[178:181], v[232:235], 0
	v_mfma_f32_16x16x32_bf16 v[102:105], v[178:181], v[202:205], 0
	v_mfma_f32_16x16x32_bf16 v[98:101], v[186:189], v[202:205], 0
	v_mfma_f32_16x16x32_bf16 v[110:113], v[186:189], v[194:197], 0
	v_mfma_f32_16x16x32_bf16 v[122:125], v[178:181], v[194:197], 0
	v_mfma_f32_16x16x32_bf16 v[126:129], v[142:145], v[198:201], v[126:129]
	v_mfma_f32_16x16x32_bf16 v[106:109], v[174:177], v[198:201], v[106:109]
	v_mfma_f32_16x16x32_bf16 v[114:117], v[174:177], v[228:231], v[114:117]
	v_mfma_f32_16x16x32_bf16 v[118:121], v[142:145], v[228:231], v[118:121]
	v_mfma_f32_16x16x32_bf16 v[94:97], v[142:145], v[236:239], v[94:97]
	v_mfma_f32_16x16x32_bf16 v[90:93], v[174:177], v[236:239], v[90:93]
	v_mfma_f32_16x16x32_bf16 v[74:77], v[174:177], v[244:247], v[74:77]
	v_mfma_f32_16x16x32_bf16 v[78:81], v[142:145], v[244:247], v[78:81]
	v_mfma_f32_16x16x32_bf16 v[70:73], v[182:185], v[244:247], v[70:73]
	v_mfma_f32_16x16x32_bf16 v[66:69], v[190:193], v[244:247], v[66:69]
	v_mfma_f32_16x16x32_bf16 v[82:85], v[190:193], v[236:239], v[82:85]
	v_mfma_f32_16x16x32_bf16 v[86:89], v[182:185], v[236:239], v[86:89]
	v_mfma_f32_16x16x32_bf16 v[102:105], v[182:185], v[228:231], v[102:105]
	v_mfma_f32_16x16x32_bf16 v[98:101], v[190:193], v[228:231], v[98:101]
	v_mfma_f32_16x16x32_bf16 v[110:113], v[190:193], v[198:201], v[110:113]
	v_mfma_f32_16x16x32_bf16 v[122:125], v[182:185], v[198:201], v[122:125]
	s_barrier
	s_setprio 0
	s_mov_b32 m0, s15
	s_mov_b32 s46, s62
	s_mov_b32 s47, s63
	ds_read_b128 v[194:197], v141 offset:16384
	ds_read_b128 v[198:201], v141 offset:17408
	ds_read_b128 v[202:205], v141 offset:18432
	ds_read_b128 v[228:231], v141 offset:19456
	ds_read_b128 v[232:235], v141 offset:20480
	ds_read_b128 v[236:239], v141 offset:21504
	ds_read_b128 v[240:243], v141 offset:22528
	ds_read_b128 v[244:247], v141 offset:23552
	buffer_load_dwordx4 v137, s[44:47], s26 offen lds
	s_mov_b32 m0, s16
	s_add_i32 s52, s26, 0x160000
	buffer_load_dwordx4 v139, s[44:47], s26 offen lds
	s_mov_b32 m0, s18
	s_nop 0
	buffer_load_dwordx4 v137, s[44:47], s52 offen lds
	s_mov_b32 m0, s19
	s_nop 0
	buffer_load_dwordx4 v139, s[44:47], s52 offen lds
	s_mov_b32 m0, s14
	s_nop 0
	buffer_load_dwordx4 v136, s[60:63], s27 offen lds
	s_mov_b32 m0, s24
	s_nop 0
	buffer_load_dwordx4 v138, s[60:63], s27 offen lds
	s_waitcnt vmcnt(8)
	s_waitcnt lgkmcnt(0)
	s_setprio 1
	s_barrier
	v_mfma_f32_16x16x32_bf16 v[62:65], v[132:135], v[194:197], 0
	v_mfma_f32_16x16x32_bf16 v[58:61], v[170:173], v[194:197], 0
	v_mfma_f32_16x16x32_bf16 v[42:45], v[170:173], v[202:205], 0
	v_mfma_f32_16x16x32_bf16 v[46:49], v[132:135], v[202:205], 0
	v_mfma_f32_16x16x32_bf16 v[30:33], v[132:135], v[232:235], 0
	v_mfma_f32_16x16x32_bf16 v[26:29], v[170:173], v[232:235], 0
	v_mfma_f32_16x16x32_bf16 v[10:13], v[170:173], v[240:243], 0
	v_mfma_f32_16x16x32_bf16 v[14:17], v[132:135], v[240:243], 0
	v_mfma_f32_16x16x32_bf16 v[6:9], v[178:181], v[240:243], 0
	v_mfma_f32_16x16x32_bf16 v[2:5], v[186:189], v[240:243], 0
	v_mfma_f32_16x16x32_bf16 v[18:21], v[186:189], v[232:235], 0
	v_mfma_f32_16x16x32_bf16 v[22:25], v[178:181], v[232:235], 0
	v_mfma_f32_16x16x32_bf16 v[38:41], v[178:181], v[202:205], 0
	v_mfma_f32_16x16x32_bf16 v[34:37], v[186:189], v[202:205], 0
	v_mfma_f32_16x16x32_bf16 v[50:53], v[186:189], v[194:197], 0
	v_mfma_f32_16x16x32_bf16 v[54:57], v[178:181], v[194:197], 0
	v_mfma_f32_16x16x32_bf16 v[62:65], v[142:145], v[198:201], v[62:65]
	v_mfma_f32_16x16x32_bf16 v[58:61], v[174:177], v[198:201], v[58:61]
	v_mfma_f32_16x16x32_bf16 v[42:45], v[174:177], v[228:231], v[42:45]
	v_mfma_f32_16x16x32_bf16 v[46:49], v[142:145], v[228:231], v[46:49]
	v_mfma_f32_16x16x32_bf16 v[30:33], v[142:145], v[236:239], v[30:33]
	v_mfma_f32_16x16x32_bf16 v[26:29], v[174:177], v[236:239], v[26:29]
	v_mfma_f32_16x16x32_bf16 v[10:13], v[174:177], v[244:247], v[10:13]
	v_mfma_f32_16x16x32_bf16 v[14:17], v[142:145], v[244:247], v[14:17]
	v_mfma_f32_16x16x32_bf16 v[6:9], v[182:185], v[244:247], v[6:9]
	v_mfma_f32_16x16x32_bf16 v[2:5], v[190:193], v[244:247], v[2:5]
	v_mfma_f32_16x16x32_bf16 v[18:21], v[190:193], v[236:239], v[18:21]
	v_mfma_f32_16x16x32_bf16 v[22:25], v[182:185], v[236:239], v[22:25]
	v_mfma_f32_16x16x32_bf16 v[38:41], v[182:185], v[228:231], v[38:41]
	v_mfma_f32_16x16x32_bf16 v[34:37], v[190:193], v[228:231], v[34:37]
	v_mfma_f32_16x16x32_bf16 v[50:53], v[190:193], v[198:201], v[50:53]
	v_mfma_f32_16x16x32_bf16 v[54:57], v[182:185], v[198:201], v[54:57]
	s_barrier
	s_setprio 0
	v_add_u32_e32 v154, 0x18000, v140
	ds_read_b128 v[132:135], v154
	ds_read_b128 v[142:145], v154 offset:1024
	ds_read_b128 v[170:173], v154 offset:2048
	ds_read_b128 v[174:177], v154 offset:3072
	v_add_u32_e32 v154, 0x1c000, v140
	ds_read_b128 v[178:181], v154
	ds_read_b128 v[182:185], v154 offset:1024
	ds_read_b128 v[186:189], v154 offset:2048
	ds_read_b128 v[190:193], v154 offset:3072
	s_bitset1_b32 s27, 14
	s_mov_b32 m0, s25
	ds_read_b128 v[194:197], v141 offset:32768
	ds_read_b128 v[198:201], v141 offset:33792
	ds_read_b128 v[202:205], v141 offset:34816
	ds_read_b128 v[228:231], v141 offset:35840
	ds_read_b128 v[232:235], v141 offset:36864
	ds_read_b128 v[236:239], v141 offset:37888
	ds_read_b128 v[240:243], v141 offset:38912
	ds_read_b128 v[244:247], v141 offset:39936
	buffer_load_dwordx4 v136, s[60:63], s27 offen lds
	s_mov_b32 m0, s30
	s_nop 0
	buffer_load_dwordx4 v138, s[60:63], s27 offen lds
	s_waitcnt vmcnt(8)
	s_waitcnt lgkmcnt(0)
	s_setprio 1
	s_barrier
	v_mfma_f32_16x16x32_bf16 v[126:129], v[132:135], v[194:197], v[126:129]
	v_mfma_f32_16x16x32_bf16 v[106:109], v[170:173], v[194:197], v[106:109]
	v_mfma_f32_16x16x32_bf16 v[114:117], v[170:173], v[202:205], v[114:117]
	v_mfma_f32_16x16x32_bf16 v[118:121], v[132:135], v[202:205], v[118:121]
	v_mfma_f32_16x16x32_bf16 v[94:97], v[132:135], v[232:235], v[94:97]
	v_mfma_f32_16x16x32_bf16 v[90:93], v[170:173], v[232:235], v[90:93]
	v_mfma_f32_16x16x32_bf16 v[74:77], v[170:173], v[240:243], v[74:77]
	v_mfma_f32_16x16x32_bf16 v[78:81], v[132:135], v[240:243], v[78:81]
	v_mfma_f32_16x16x32_bf16 v[70:73], v[178:181], v[240:243], v[70:73]
	v_mfma_f32_16x16x32_bf16 v[66:69], v[186:189], v[240:243], v[66:69]
	v_mfma_f32_16x16x32_bf16 v[82:85], v[186:189], v[232:235], v[82:85]
	v_mfma_f32_16x16x32_bf16 v[86:89], v[178:181], v[232:235], v[86:89]
	v_mfma_f32_16x16x32_bf16 v[102:105], v[178:181], v[202:205], v[102:105]
	v_mfma_f32_16x16x32_bf16 v[98:101], v[186:189], v[202:205], v[98:101]
	v_mfma_f32_16x16x32_bf16 v[110:113], v[186:189], v[194:197], v[110:113]
	v_mfma_f32_16x16x32_bf16 v[122:125], v[178:181], v[194:197], v[122:125]
	v_mfma_f32_16x16x32_bf16 v[126:129], v[142:145], v[198:201], v[126:129]
	v_mfma_f32_16x16x32_bf16 v[106:109], v[174:177], v[198:201], v[106:109]
	v_mfma_f32_16x16x32_bf16 v[114:117], v[174:177], v[228:231], v[114:117]
	v_mfma_f32_16x16x32_bf16 v[118:121], v[142:145], v[228:231], v[118:121]
	v_mfma_f32_16x16x32_bf16 v[94:97], v[142:145], v[236:239], v[94:97]
	v_mfma_f32_16x16x32_bf16 v[90:93], v[174:177], v[236:239], v[90:93]
	v_mfma_f32_16x16x32_bf16 v[74:77], v[174:177], v[244:247], v[74:77]
	v_mfma_f32_16x16x32_bf16 v[78:81], v[142:145], v[244:247], v[78:81]
	v_mfma_f32_16x16x32_bf16 v[70:73], v[182:185], v[244:247], v[70:73]
	v_mfma_f32_16x16x32_bf16 v[66:69], v[190:193], v[244:247], v[66:69]
	v_mfma_f32_16x16x32_bf16 v[82:85], v[190:193], v[236:239], v[82:85]
	v_mfma_f32_16x16x32_bf16 v[86:89], v[182:185], v[236:239], v[86:89]
	v_mfma_f32_16x16x32_bf16 v[102:105], v[182:185], v[228:231], v[102:105]
	v_mfma_f32_16x16x32_bf16 v[98:101], v[190:193], v[228:231], v[98:101]
	v_mfma_f32_16x16x32_bf16 v[110:113], v[190:193], v[198:201], v[110:113]
	v_mfma_f32_16x16x32_bf16 v[122:125], v[182:185], v[198:201], v[122:125]
	s_barrier
	s_setprio 0
	s_mov_b32 m0, s36
	s_or_b32 s27, s26, 0x80
	ds_read_b128 v[194:197], v141 offset:49152
	ds_read_b128 v[198:201], v141 offset:50176
	ds_read_b128 v[202:205], v141 offset:51200
	ds_read_b128 v[228:231], v141 offset:52224
	ds_read_b128 v[232:235], v141 offset:53248
	ds_read_b128 v[236:239], v141 offset:54272
	ds_read_b128 v[240:243], v141 offset:55296
	ds_read_b128 v[244:247], v141 offset:56320
	buffer_load_dwordx4 v137, s[44:47], s27 offen lds
	s_mov_b32 m0, s37
	s_add_i32 s26, s26, 0x160080
	buffer_load_dwordx4 v139, s[44:47], s27 offen lds
	s_mov_b32 m0, s66
	s_nop 0
	buffer_load_dwordx4 v137, s[44:47], s26 offen lds
	s_mov_b32 m0, s67
	s_nop 0
	buffer_load_dwordx4 v139, s[44:47], s26 offen lds
	s_mov_b32 m0, s48
	s_nop 0
	buffer_load_dwordx4 v136, s[60:63], s23 offen lds
	s_mov_b32 m0, s49
	s_nop 0
	buffer_load_dwordx4 v138, s[60:63], s23 offen lds
	s_waitcnt vmcnt(8)
	s_waitcnt lgkmcnt(0)
	s_setprio 1
	s_barrier
	v_mfma_f32_16x16x32_bf16 v[62:65], v[132:135], v[194:197], v[62:65]
	v_mfma_f32_16x16x32_bf16 v[58:61], v[170:173], v[194:197], v[58:61]
	v_mfma_f32_16x16x32_bf16 v[42:45], v[170:173], v[202:205], v[42:45]
	v_mfma_f32_16x16x32_bf16 v[46:49], v[132:135], v[202:205], v[46:49]
	v_mfma_f32_16x16x32_bf16 v[30:33], v[132:135], v[232:235], v[30:33]
	v_mfma_f32_16x16x32_bf16 v[26:29], v[170:173], v[232:235], v[26:29]
	v_mfma_f32_16x16x32_bf16 v[10:13], v[170:173], v[240:243], v[10:13]
	v_mfma_f32_16x16x32_bf16 v[14:17], v[132:135], v[240:243], v[14:17]
	v_mfma_f32_16x16x32_bf16 v[6:9], v[178:181], v[240:243], v[6:9]
	v_mfma_f32_16x16x32_bf16 v[2:5], v[186:189], v[240:243], v[2:5]
	v_mfma_f32_16x16x32_bf16 v[18:21], v[186:189], v[232:235], v[18:21]
	v_mfma_f32_16x16x32_bf16 v[22:25], v[178:181], v[232:235], v[22:25]
	v_mfma_f32_16x16x32_bf16 v[38:41], v[178:181], v[202:205], v[38:41]
	v_mfma_f32_16x16x32_bf16 v[34:37], v[186:189], v[202:205], v[34:37]
	v_mfma_f32_16x16x32_bf16 v[50:53], v[186:189], v[194:197], v[50:53]
	v_mfma_f32_16x16x32_bf16 v[54:57], v[178:181], v[194:197], v[54:57]
	v_mfma_f32_16x16x32_bf16 v[62:65], v[142:145], v[198:201], v[62:65]
	v_mfma_f32_16x16x32_bf16 v[58:61], v[174:177], v[198:201], v[58:61]
	v_mfma_f32_16x16x32_bf16 v[42:45], v[174:177], v[228:231], v[42:45]
	v_mfma_f32_16x16x32_bf16 v[46:49], v[142:145], v[228:231], v[46:49]
	v_mfma_f32_16x16x32_bf16 v[30:33], v[142:145], v[236:239], v[30:33]
	v_mfma_f32_16x16x32_bf16 v[26:29], v[174:177], v[236:239], v[26:29]
	v_mfma_f32_16x16x32_bf16 v[10:13], v[174:177], v[244:247], v[10:13]
	v_mfma_f32_16x16x32_bf16 v[14:17], v[142:145], v[244:247], v[14:17]
	v_mfma_f32_16x16x32_bf16 v[6:9], v[182:185], v[244:247], v[6:9]
	v_mfma_f32_16x16x32_bf16 v[2:5], v[190:193], v[244:247], v[2:5]
	v_mfma_f32_16x16x32_bf16 v[18:21], v[190:193], v[236:239], v[18:21]
	v_mfma_f32_16x16x32_bf16 v[22:25], v[182:185], v[236:239], v[22:25]
	v_mfma_f32_16x16x32_bf16 v[38:41], v[182:185], v[228:231], v[38:41]
	v_mfma_f32_16x16x32_bf16 v[34:37], v[190:193], v[228:231], v[34:37]
	v_mfma_f32_16x16x32_bf16 v[50:53], v[190:193], v[198:201], v[50:53]
	v_mfma_f32_16x16x32_bf16 v[54:57], v[182:185], v[198:201], v[54:57]
	s_barrier
	s_setprio 0
	s_addk_i32 s13, 0x100
	s_add_i32 s22, s22, 2
	s_add_i32 s21, s21, 0x10000
	s_cmpk_gt_u32 s22, 0x55
.LBB0_580:
	v_add_u32_e32 v154, 0x10000, v140
	ds_read_b128 v[132:135], v154
	ds_read_b128 v[142:145], v154 offset:1024
	ds_read_b128 v[170:173], v154 offset:2048
	ds_read_b128 v[174:177], v154 offset:3072
	v_add_u32_e32 v154, 0x14000, v140
	ds_read_b128 v[178:181], v154
	ds_read_b128 v[182:185], v154 offset:1024
	ds_read_b128 v[186:189], v154 offset:2048
	ds_read_b128 v[190:193], v154 offset:3072
	s_add_i32 s23, s21, 0x4000
	s_cmpk_eq_i32 s22, 0x54
	s_cselect_b32 s27, s8, s23
	s_cselect_b32 s26, s9, s13
	s_or_b32 s23, s27, 0x8000
	s_mov_b32 m0, s68
	ds_read_b128 v[194:197], v141
	ds_read_b128 v[198:201], v141 offset:1024
	ds_read_b128 v[202:205], v141 offset:2048
	ds_read_b128 v[228:231], v141 offset:3072
	ds_read_b128 v[232:235], v141 offset:4096
	ds_read_b128 v[236:239], v141 offset:5120
	ds_read_b128 v[240:243], v141 offset:6144
	ds_read_b128 v[244:247], v141 offset:7168
	buffer_load_dwordx4 v136, s[60:63], s21 offen lds
	s_mov_b32 m0, s70
	s_nop 0
	buffer_load_dwordx4 v138, s[60:63], s21 offen lds
	s_waitcnt vmcnt(8)
	s_waitcnt lgkmcnt(0)
	s_setprio 1
	s_barrier
	v_mfma_f32_16x16x32_bf16 v[126:129], v[132:135], v[194:197], v[126:129]
	v_mfma_f32_16x16x32_bf16 v[106:109], v[170:173], v[194:197], v[106:109]
	v_mfma_f32_16x16x32_bf16 v[114:117], v[170:173], v[202:205], v[114:117]
	v_mfma_f32_16x16x32_bf16 v[118:121], v[132:135], v[202:205], v[118:121]
	v_mfma_f32_16x16x32_bf16 v[94:97], v[132:135], v[232:235], v[94:97]
	v_mfma_f32_16x16x32_bf16 v[90:93], v[170:173], v[232:235], v[90:93]
	v_mfma_f32_16x16x32_bf16 v[74:77], v[170:173], v[240:243], v[74:77]
	v_mfma_f32_16x16x32_bf16 v[78:81], v[132:135], v[240:243], v[78:81]
	v_mfma_f32_16x16x32_bf16 v[70:73], v[178:181], v[240:243], v[70:73]
	v_mfma_f32_16x16x32_bf16 v[66:69], v[186:189], v[240:243], v[66:69]
	v_mfma_f32_16x16x32_bf16 v[82:85], v[186:189], v[232:235], v[82:85]
	v_mfma_f32_16x16x32_bf16 v[86:89], v[178:181], v[232:235], v[86:89]
	v_mfma_f32_16x16x32_bf16 v[102:105], v[178:181], v[202:205], v[102:105]
	v_mfma_f32_16x16x32_bf16 v[98:101], v[186:189], v[202:205], v[98:101]
	v_mfma_f32_16x16x32_bf16 v[110:113], v[186:189], v[194:197], v[110:113]
	v_mfma_f32_16x16x32_bf16 v[122:125], v[178:181], v[194:197], v[122:125]
	v_mfma_f32_16x16x32_bf16 v[126:129], v[142:145], v[198:201], v[126:129]
	v_mfma_f32_16x16x32_bf16 v[106:109], v[174:177], v[198:201], v[106:109]
	v_mfma_f32_16x16x32_bf16 v[114:117], v[174:177], v[228:231], v[114:117]
	v_mfma_f32_16x16x32_bf16 v[118:121], v[142:145], v[228:231], v[118:121]
	v_mfma_f32_16x16x32_bf16 v[94:97], v[142:145], v[236:239], v[94:97]
	v_mfma_f32_16x16x32_bf16 v[90:93], v[174:177], v[236:239], v[90:93]
	v_mfma_f32_16x16x32_bf16 v[74:77], v[174:177], v[244:247], v[74:77]
	v_mfma_f32_16x16x32_bf16 v[78:81], v[142:145], v[244:247], v[78:81]
	v_mfma_f32_16x16x32_bf16 v[70:73], v[182:185], v[244:247], v[70:73]
	v_mfma_f32_16x16x32_bf16 v[66:69], v[190:193], v[244:247], v[66:69]
	v_mfma_f32_16x16x32_bf16 v[82:85], v[190:193], v[236:239], v[82:85]
	v_mfma_f32_16x16x32_bf16 v[86:89], v[182:185], v[236:239], v[86:89]
	v_mfma_f32_16x16x32_bf16 v[102:105], v[182:185], v[228:231], v[102:105]
	v_mfma_f32_16x16x32_bf16 v[98:101], v[190:193], v[228:231], v[98:101]
	v_mfma_f32_16x16x32_bf16 v[110:113], v[190:193], v[198:201], v[110:113]
	v_mfma_f32_16x16x32_bf16 v[122:125], v[182:185], v[198:201], v[122:125]
	s_barrier
	s_setprio 0
	s_mov_b32 m0, s15
	s_mov_b32 s46, s62
	s_mov_b32 s47, s63
	ds_read_b128 v[194:197], v141 offset:16384
	ds_read_b128 v[198:201], v141 offset:17408
	ds_read_b128 v[202:205], v141 offset:18432
	ds_read_b128 v[228:231], v141 offset:19456
	ds_read_b128 v[232:235], v141 offset:20480
	ds_read_b128 v[236:239], v141 offset:21504
	ds_read_b128 v[240:243], v141 offset:22528
	ds_read_b128 v[244:247], v141 offset:23552
	buffer_load_dwordx4 v137, s[44:47], s26 offen lds
	s_mov_b32 m0, s16
	s_add_i32 s52, s26, 0x160000
	buffer_load_dwordx4 v139, s[44:47], s26 offen lds
	s_mov_b32 m0, s18
	s_nop 0
	buffer_load_dwordx4 v137, s[44:47], s52 offen lds
	s_mov_b32 m0, s19
	s_nop 0
	buffer_load_dwordx4 v139, s[44:47], s52 offen lds
	s_mov_b32 m0, s14
	s_nop 0
	buffer_load_dwordx4 v136, s[60:63], s27 offen lds
	s_mov_b32 m0, s24
	s_nop 0
	buffer_load_dwordx4 v138, s[60:63], s27 offen lds
	s_waitcnt vmcnt(8)
	s_waitcnt lgkmcnt(0)
	s_setprio 1
	s_barrier
	v_mfma_f32_16x16x32_bf16 v[62:65], v[132:135], v[194:197], v[62:65]
	v_mfma_f32_16x16x32_bf16 v[58:61], v[170:173], v[194:197], v[58:61]
	v_mfma_f32_16x16x32_bf16 v[42:45], v[170:173], v[202:205], v[42:45]
	v_mfma_f32_16x16x32_bf16 v[46:49], v[132:135], v[202:205], v[46:49]
	v_mfma_f32_16x16x32_bf16 v[30:33], v[132:135], v[232:235], v[30:33]
	v_mfma_f32_16x16x32_bf16 v[26:29], v[170:173], v[232:235], v[26:29]
	v_mfma_f32_16x16x32_bf16 v[10:13], v[170:173], v[240:243], v[10:13]
	v_mfma_f32_16x16x32_bf16 v[14:17], v[132:135], v[240:243], v[14:17]
	v_mfma_f32_16x16x32_bf16 v[6:9], v[178:181], v[240:243], v[6:9]
	v_mfma_f32_16x16x32_bf16 v[2:5], v[186:189], v[240:243], v[2:5]
	v_mfma_f32_16x16x32_bf16 v[18:21], v[186:189], v[232:235], v[18:21]
	v_mfma_f32_16x16x32_bf16 v[22:25], v[178:181], v[232:235], v[22:25]
	v_mfma_f32_16x16x32_bf16 v[38:41], v[178:181], v[202:205], v[38:41]
	v_mfma_f32_16x16x32_bf16 v[34:37], v[186:189], v[202:205], v[34:37]
	v_mfma_f32_16x16x32_bf16 v[50:53], v[186:189], v[194:197], v[50:53]
	v_mfma_f32_16x16x32_bf16 v[54:57], v[178:181], v[194:197], v[54:57]
	v_mfma_f32_16x16x32_bf16 v[62:65], v[142:145], v[198:201], v[62:65]
	v_mfma_f32_16x16x32_bf16 v[58:61], v[174:177], v[198:201], v[58:61]
	v_mfma_f32_16x16x32_bf16 v[42:45], v[174:177], v[228:231], v[42:45]
	v_mfma_f32_16x16x32_bf16 v[46:49], v[142:145], v[228:231], v[46:49]
	v_mfma_f32_16x16x32_bf16 v[30:33], v[142:145], v[236:239], v[30:33]
	v_mfma_f32_16x16x32_bf16 v[26:29], v[174:177], v[236:239], v[26:29]
	v_mfma_f32_16x16x32_bf16 v[10:13], v[174:177], v[244:247], v[10:13]
	v_mfma_f32_16x16x32_bf16 v[14:17], v[142:145], v[244:247], v[14:17]
	v_mfma_f32_16x16x32_bf16 v[6:9], v[182:185], v[244:247], v[6:9]
	v_mfma_f32_16x16x32_bf16 v[2:5], v[190:193], v[244:247], v[2:5]
	v_mfma_f32_16x16x32_bf16 v[18:21], v[190:193], v[236:239], v[18:21]
	v_mfma_f32_16x16x32_bf16 v[22:25], v[182:185], v[236:239], v[22:25]
	v_mfma_f32_16x16x32_bf16 v[38:41], v[182:185], v[228:231], v[38:41]
	v_mfma_f32_16x16x32_bf16 v[34:37], v[190:193], v[228:231], v[34:37]
	v_mfma_f32_16x16x32_bf16 v[50:53], v[190:193], v[198:201], v[50:53]
	v_mfma_f32_16x16x32_bf16 v[54:57], v[182:185], v[198:201], v[54:57]
	s_barrier
	s_setprio 0
	v_add_u32_e32 v154, 0x18000, v140
	ds_read_b128 v[132:135], v154
	ds_read_b128 v[142:145], v154 offset:1024
	ds_read_b128 v[170:173], v154 offset:2048
	ds_read_b128 v[174:177], v154 offset:3072
	v_add_u32_e32 v154, 0x1c000, v140
	ds_read_b128 v[178:181], v154
	ds_read_b128 v[182:185], v154 offset:1024
	ds_read_b128 v[186:189], v154 offset:2048
	ds_read_b128 v[190:193], v154 offset:3072
	s_bitset1_b32 s27, 14
	s_mov_b32 m0, s25
	ds_read_b128 v[194:197], v141 offset:32768
	ds_read_b128 v[198:201], v141 offset:33792
	ds_read_b128 v[202:205], v141 offset:34816
	ds_read_b128 v[228:231], v141 offset:35840
	ds_read_b128 v[232:235], v141 offset:36864
	ds_read_b128 v[236:239], v141 offset:37888
	ds_read_b128 v[240:243], v141 offset:38912
	ds_read_b128 v[244:247], v141 offset:39936
	buffer_load_dwordx4 v136, s[60:63], s27 offen lds
	s_mov_b32 m0, s30
	s_nop 0
	buffer_load_dwordx4 v138, s[60:63], s27 offen lds
	s_waitcnt vmcnt(8)
	s_waitcnt lgkmcnt(0)
	s_setprio 1
	s_barrier
	v_mfma_f32_16x16x32_bf16 v[126:129], v[132:135], v[194:197], v[126:129]
	v_mfma_f32_16x16x32_bf16 v[106:109], v[170:173], v[194:197], v[106:109]
	v_mfma_f32_16x16x32_bf16 v[114:117], v[170:173], v[202:205], v[114:117]
	v_mfma_f32_16x16x32_bf16 v[118:121], v[132:135], v[202:205], v[118:121]
	v_mfma_f32_16x16x32_bf16 v[94:97], v[132:135], v[232:235], v[94:97]
	v_mfma_f32_16x16x32_bf16 v[90:93], v[170:173], v[232:235], v[90:93]
	v_mfma_f32_16x16x32_bf16 v[74:77], v[170:173], v[240:243], v[74:77]
	v_mfma_f32_16x16x32_bf16 v[78:81], v[132:135], v[240:243], v[78:81]
	v_mfma_f32_16x16x32_bf16 v[70:73], v[178:181], v[240:243], v[70:73]
	v_mfma_f32_16x16x32_bf16 v[66:69], v[186:189], v[240:243], v[66:69]
	v_mfma_f32_16x16x32_bf16 v[82:85], v[186:189], v[232:235], v[82:85]
	v_mfma_f32_16x16x32_bf16 v[86:89], v[178:181], v[232:235], v[86:89]
	v_mfma_f32_16x16x32_bf16 v[102:105], v[178:181], v[202:205], v[102:105]
	v_mfma_f32_16x16x32_bf16 v[98:101], v[186:189], v[202:205], v[98:101]
	v_mfma_f32_16x16x32_bf16 v[110:113], v[186:189], v[194:197], v[110:113]
	v_mfma_f32_16x16x32_bf16 v[122:125], v[178:181], v[194:197], v[122:125]
	v_mfma_f32_16x16x32_bf16 v[126:129], v[142:145], v[198:201], v[126:129]
	v_mfma_f32_16x16x32_bf16 v[106:109], v[174:177], v[198:201], v[106:109]
	v_mfma_f32_16x16x32_bf16 v[114:117], v[174:177], v[228:231], v[114:117]
	v_mfma_f32_16x16x32_bf16 v[118:121], v[142:145], v[228:231], v[118:121]
	v_mfma_f32_16x16x32_bf16 v[94:97], v[142:145], v[236:239], v[94:97]
	v_mfma_f32_16x16x32_bf16 v[90:93], v[174:177], v[236:239], v[90:93]
	v_mfma_f32_16x16x32_bf16 v[74:77], v[174:177], v[244:247], v[74:77]
	v_mfma_f32_16x16x32_bf16 v[78:81], v[142:145], v[244:247], v[78:81]
	v_mfma_f32_16x16x32_bf16 v[70:73], v[182:185], v[244:247], v[70:73]
	v_mfma_f32_16x16x32_bf16 v[66:69], v[190:193], v[244:247], v[66:69]
	v_mfma_f32_16x16x32_bf16 v[82:85], v[190:193], v[236:239], v[82:85]
	v_mfma_f32_16x16x32_bf16 v[86:89], v[182:185], v[236:239], v[86:89]
	v_mfma_f32_16x16x32_bf16 v[102:105], v[182:185], v[228:231], v[102:105]
	v_mfma_f32_16x16x32_bf16 v[98:101], v[190:193], v[228:231], v[98:101]
	v_mfma_f32_16x16x32_bf16 v[110:113], v[190:193], v[198:201], v[110:113]
	v_mfma_f32_16x16x32_bf16 v[122:125], v[182:185], v[198:201], v[122:125]
	s_barrier
	s_setprio 0
	s_mov_b32 m0, s36
	s_or_b32 s27, s26, 0x80
	ds_read_b128 v[194:197], v141 offset:49152
	ds_read_b128 v[198:201], v141 offset:50176
	ds_read_b128 v[202:205], v141 offset:51200
	ds_read_b128 v[228:231], v141 offset:52224
	ds_read_b128 v[232:235], v141 offset:53248
	ds_read_b128 v[236:239], v141 offset:54272
	ds_read_b128 v[240:243], v141 offset:55296
	ds_read_b128 v[244:247], v141 offset:56320
	buffer_load_dwordx4 v137, s[44:47], s27 offen lds
	s_mov_b32 m0, s37
	s_add_i32 s26, s26, 0x160080
	buffer_load_dwordx4 v139, s[44:47], s27 offen lds
	s_mov_b32 m0, s66
	s_nop 0
	buffer_load_dwordx4 v137, s[44:47], s26 offen lds
	s_mov_b32 m0, s67
	s_nop 0
	buffer_load_dwordx4 v139, s[44:47], s26 offen lds
	s_mov_b32 m0, s48
	s_nop 0
	buffer_load_dwordx4 v136, s[60:63], s23 offen lds
	s_mov_b32 m0, s49
	s_nop 0
	buffer_load_dwordx4 v138, s[60:63], s23 offen lds
	s_waitcnt vmcnt(8)
	s_waitcnt lgkmcnt(0)
	s_setprio 1
	s_barrier
	v_mfma_f32_16x16x32_bf16 v[62:65], v[132:135], v[194:197], v[62:65]
	v_mfma_f32_16x16x32_bf16 v[58:61], v[170:173], v[194:197], v[58:61]
	v_mfma_f32_16x16x32_bf16 v[42:45], v[170:173], v[202:205], v[42:45]
	v_mfma_f32_16x16x32_bf16 v[46:49], v[132:135], v[202:205], v[46:49]
	v_mfma_f32_16x16x32_bf16 v[30:33], v[132:135], v[232:235], v[30:33]
	v_mfma_f32_16x16x32_bf16 v[26:29], v[170:173], v[232:235], v[26:29]
	v_mfma_f32_16x16x32_bf16 v[10:13], v[170:173], v[240:243], v[10:13]
	v_mfma_f32_16x16x32_bf16 v[14:17], v[132:135], v[240:243], v[14:17]
	v_mfma_f32_16x16x32_bf16 v[6:9], v[178:181], v[240:243], v[6:9]
	v_mfma_f32_16x16x32_bf16 v[2:5], v[186:189], v[240:243], v[2:5]
	v_mfma_f32_16x16x32_bf16 v[18:21], v[186:189], v[232:235], v[18:21]
	v_mfma_f32_16x16x32_bf16 v[22:25], v[178:181], v[232:235], v[22:25]
	v_mfma_f32_16x16x32_bf16 v[38:41], v[178:181], v[202:205], v[38:41]
	v_mfma_f32_16x16x32_bf16 v[34:37], v[186:189], v[202:205], v[34:37]
	v_mfma_f32_16x16x32_bf16 v[50:53], v[186:189], v[194:197], v[50:53]
	v_mfma_f32_16x16x32_bf16 v[54:57], v[178:181], v[194:197], v[54:57]
	v_mfma_f32_16x16x32_bf16 v[62:65], v[142:145], v[198:201], v[62:65]
	v_mfma_f32_16x16x32_bf16 v[58:61], v[174:177], v[198:201], v[58:61]
	v_mfma_f32_16x16x32_bf16 v[42:45], v[174:177], v[228:231], v[42:45]
	v_mfma_f32_16x16x32_bf16 v[46:49], v[142:145], v[228:231], v[46:49]
	v_mfma_f32_16x16x32_bf16 v[30:33], v[142:145], v[236:239], v[30:33]
	v_mfma_f32_16x16x32_bf16 v[26:29], v[174:177], v[236:239], v[26:29]
	v_mfma_f32_16x16x32_bf16 v[10:13], v[174:177], v[244:247], v[10:13]
	v_mfma_f32_16x16x32_bf16 v[14:17], v[142:145], v[244:247], v[14:17]
	v_mfma_f32_16x16x32_bf16 v[6:9], v[182:185], v[244:247], v[6:9]
	v_mfma_f32_16x16x32_bf16 v[2:5], v[190:193], v[244:247], v[2:5]
	v_mfma_f32_16x16x32_bf16 v[18:21], v[190:193], v[236:239], v[18:21]
	v_mfma_f32_16x16x32_bf16 v[22:25], v[182:185], v[236:239], v[22:25]
	v_mfma_f32_16x16x32_bf16 v[38:41], v[182:185], v[228:231], v[38:41]
	v_mfma_f32_16x16x32_bf16 v[34:37], v[190:193], v[228:231], v[34:37]
	v_mfma_f32_16x16x32_bf16 v[50:53], v[190:193], v[198:201], v[50:53]
	v_mfma_f32_16x16x32_bf16 v[54:57], v[182:185], v[198:201], v[54:57]
	s_barrier
	s_setprio 0
	s_addk_i32 s13, 0x100
	s_add_i32 s22, s22, 2
	s_add_i32 s21, s21, 0x10000
	s_cmpk_gt_u32 s22, 0x55
	s_cbranch_scc0 .LBB0_580
	s_and_b64 vcc, exec, s[64:65]
	s_cbranch_vccz .LBB0_583
	s_barrier

.LBB0_858:
	s_lshl_b32 s2, s21, 20
	s_and_b64 s[8:9], s[42:43], exec
	s_cselect_b32 s8, s2, s18
	s_lshl_b32 s82, s71, 20
	s_and_b64 s[26:27], s[42:43], exec
	s_cselect_b32 s9, s82, s19
	s_add_i32 s18, s18, 0x80080
	s_addk_i32 s19, 0x100
	s_mov_b32 s22, -2
	v_add_u32_e32 v146, 0x10000, v195
	ds_read_b128 v[130:133], v146
	ds_read_b128 v[138:141], v146 offset:1024
	ds_read_b128 v[142:145], v146 offset:2048
	ds_read_b128 v[154:157], v146 offset:3072
	v_add_u32_e32 v146, 0x14000, v195
	ds_read_b128 v[170:173], v146
	ds_read_b128 v[174:177], v146 offset:1024
	ds_read_b128 v[178:181], v146 offset:2048
	ds_read_b128 v[182:185], v146 offset:3072
	s_add_i32 s26, s18, 0xfff80080
	s_cmp_eq_u32 s22, 28
	s_cselect_b32 s52, s8, s26
	s_cselect_b32 s27, s9, s19
	s_or_b32 s26, s52, 0x80
	s_mov_b32 m0, s85
	ds_read_b128 v[186:189], v196
	ds_read_b128 v[198:201], v196 offset:1024
	ds_read_b128 v[202:205], v196 offset:2048
	ds_read_b128 v[228:231], v196 offset:3072
	ds_read_b128 v[232:235], v196 offset:4096
	ds_read_b128 v[236:239], v196 offset:5120
	ds_read_b128 v[240:243], v196 offset:6144
	ds_read_b128 v[244:247], v196 offset:7168
	buffer_load_dwordx4 v135, s[44:47], s18 offen lds
	s_mov_b32 m0, s15
	s_nop 0
	buffer_load_dwordx4 v193, s[44:47], s18 offen lds
	s_waitcnt vmcnt(8)
	s_waitcnt lgkmcnt(0)
	s_setprio 1
	s_barrier
	v_mfma_f32_16x16x32_bf16 v[126:129], v[130:133], v[186:189], 0
	v_mfma_f32_16x16x32_bf16 v[122:125], v[142:145], v[186:189], 0
	v_mfma_f32_16x16x32_bf16 v[106:109], v[142:145], v[202:205], 0
	v_mfma_f32_16x16x32_bf16 v[110:113], v[130:133], v[202:205], 0
	v_mfma_f32_16x16x32_bf16 v[94:97], v[130:133], v[232:235], 0
	v_mfma_f32_16x16x32_bf16 v[90:93], v[142:145], v[232:235], 0
	v_mfma_f32_16x16x32_bf16 v[74:77], v[142:145], v[240:243], 0
	v_mfma_f32_16x16x32_bf16 v[78:81], v[130:133], v[240:243], 0
	v_mfma_f32_16x16x32_bf16 v[70:73], v[170:173], v[240:243], 0
	v_mfma_f32_16x16x32_bf16 v[66:69], v[178:181], v[240:243], 0
	v_mfma_f32_16x16x32_bf16 v[82:85], v[178:181], v[232:235], 0
	v_mfma_f32_16x16x32_bf16 v[86:89], v[170:173], v[232:235], 0
	v_mfma_f32_16x16x32_bf16 v[102:105], v[170:173], v[202:205], 0
	v_mfma_f32_16x16x32_bf16 v[98:101], v[178:181], v[202:205], 0
	v_mfma_f32_16x16x32_bf16 v[114:117], v[178:181], v[186:189], 0
	v_mfma_f32_16x16x32_bf16 v[118:121], v[170:173], v[186:189], 0
	v_mfma_f32_16x16x32_bf16 v[126:129], v[138:141], v[198:201], v[126:129]
	v_mfma_f32_16x16x32_bf16 v[122:125], v[154:157], v[198:201], v[122:125]
	v_mfma_f32_16x16x32_bf16 v[106:109], v[154:157], v[228:231], v[106:109]
	v_mfma_f32_16x16x32_bf16 v[110:113], v[138:141], v[228:231], v[110:113]
	v_mfma_f32_16x16x32_bf16 v[94:97], v[138:141], v[236:239], v[94:97]
	v_mfma_f32_16x16x32_bf16 v[90:93], v[154:157], v[236:239], v[90:93]
	v_mfma_f32_16x16x32_bf16 v[74:77], v[154:157], v[244:247], v[74:77]
	v_mfma_f32_16x16x32_bf16 v[78:81], v[138:141], v[244:247], v[78:81]
	v_mfma_f32_16x16x32_bf16 v[70:73], v[174:177], v[244:247], v[70:73]
	v_mfma_f32_16x16x32_bf16 v[66:69], v[182:185], v[244:247], v[66:69]
	v_mfma_f32_16x16x32_bf16 v[82:85], v[182:185], v[236:239], v[82:85]
	v_mfma_f32_16x16x32_bf16 v[86:89], v[174:177], v[236:239], v[86:89]
	v_mfma_f32_16x16x32_bf16 v[102:105], v[174:177], v[228:231], v[102:105]
	v_mfma_f32_16x16x32_bf16 v[98:101], v[182:185], v[228:231], v[98:101]
	v_mfma_f32_16x16x32_bf16 v[114:117], v[182:185], v[198:201], v[114:117]
	v_mfma_f32_16x16x32_bf16 v[118:121], v[174:177], v[198:201], v[118:121]
	s_barrier
	s_setprio 0
	s_mov_b32 m0, s23
	s_mov_b32 s66, s46
	s_mov_b32 s67, s47
	ds_read_b128 v[186:189], v196 offset:16384
	ds_read_b128 v[198:201], v196 offset:17408
	ds_read_b128 v[202:205], v196 offset:18432
	ds_read_b128 v[228:231], v196 offset:19456
	ds_read_b128 v[232:235], v196 offset:20480
	ds_read_b128 v[236:239], v196 offset:21504
	ds_read_b128 v[240:243], v196 offset:22528
	ds_read_b128 v[244:247], v196 offset:23552
	buffer_load_dwordx4 v192, s[64:67], s27 offen lds
	s_mov_b32 m0, s24
	s_add_i32 s53, s27, 0x80000
	buffer_load_dwordx4 v194, s[64:67], s27 offen lds
	s_mov_b32 m0, s25
	s_nop 0
	buffer_load_dwordx4 v192, s[64:67], s53 offen lds
	s_mov_b32 m0, s33
	s_nop 0
	buffer_load_dwordx4 v194, s[64:67], s53 offen lds
	s_mov_b32 m0, s13
	s_nop 0
	buffer_load_dwordx4 v135, s[44:47], s52 offen lds
	s_mov_b32 m0, s34
	s_nop 0
	buffer_load_dwordx4 v193, s[44:47], s52 offen lds
	s_waitcnt vmcnt(8)
	s_waitcnt lgkmcnt(0)
	s_setprio 1
	s_barrier
	v_mfma_f32_16x16x32_bf16 v[62:65], v[130:133], v[186:189], 0
	v_mfma_f32_16x16x32_bf16 v[58:61], v[142:145], v[186:189], 0
	v_mfma_f32_16x16x32_bf16 v[42:45], v[142:145], v[202:205], 0
	v_mfma_f32_16x16x32_bf16 v[46:49], v[130:133], v[202:205], 0
	v_mfma_f32_16x16x32_bf16 v[30:33], v[130:133], v[232:235], 0
	v_mfma_f32_16x16x32_bf16 v[26:29], v[142:145], v[232:235], 0
	v_mfma_f32_16x16x32_bf16 v[10:13], v[142:145], v[240:243], 0
	v_mfma_f32_16x16x32_bf16 v[14:17], v[130:133], v[240:243], 0
	v_mfma_f32_16x16x32_bf16 v[6:9], v[170:173], v[240:243], 0
	v_mfma_f32_16x16x32_bf16 v[2:5], v[178:181], v[240:243], 0
	v_mfma_f32_16x16x32_bf16 v[18:21], v[178:181], v[232:235], 0
	v_mfma_f32_16x16x32_bf16 v[22:25], v[170:173], v[232:235], 0
	v_mfma_f32_16x16x32_bf16 v[38:41], v[170:173], v[202:205], 0
	v_mfma_f32_16x16x32_bf16 v[34:37], v[178:181], v[202:205], 0
	v_mfma_f32_16x16x32_bf16 v[50:53], v[178:181], v[186:189], 0
	v_mfma_f32_16x16x32_bf16 v[54:57], v[170:173], v[186:189], 0
	v_mfma_f32_16x16x32_bf16 v[62:65], v[138:141], v[198:201], v[62:65]
	v_mfma_f32_16x16x32_bf16 v[58:61], v[154:157], v[198:201], v[58:61]
	v_mfma_f32_16x16x32_bf16 v[42:45], v[154:157], v[228:231], v[42:45]
	v_mfma_f32_16x16x32_bf16 v[46:49], v[138:141], v[228:231], v[46:49]
	v_mfma_f32_16x16x32_bf16 v[30:33], v[138:141], v[236:239], v[30:33]
	v_mfma_f32_16x16x32_bf16 v[26:29], v[154:157], v[236:239], v[26:29]
	v_mfma_f32_16x16x32_bf16 v[10:13], v[154:157], v[244:247], v[10:13]
	v_mfma_f32_16x16x32_bf16 v[14:17], v[138:141], v[244:247], v[14:17]
	v_mfma_f32_16x16x32_bf16 v[6:9], v[174:177], v[244:247], v[6:9]
	v_mfma_f32_16x16x32_bf16 v[2:5], v[182:185], v[244:247], v[2:5]
	v_mfma_f32_16x16x32_bf16 v[18:21], v[182:185], v[236:239], v[18:21]
	v_mfma_f32_16x16x32_bf16 v[22:25], v[174:177], v[236:239], v[22:25]
	v_mfma_f32_16x16x32_bf16 v[38:41], v[174:177], v[228:231], v[38:41]
	v_mfma_f32_16x16x32_bf16 v[34:37], v[182:185], v[228:231], v[34:37]
	v_mfma_f32_16x16x32_bf16 v[50:53], v[182:185], v[198:201], v[50:53]
	v_mfma_f32_16x16x32_bf16 v[54:57], v[174:177], v[198:201], v[54:57]
	s_barrier
	s_setprio 0
	v_add_u32_e32 v146, 0x18000, v195
	ds_read_b128 v[130:133], v146
	ds_read_b128 v[138:141], v146 offset:1024
	ds_read_b128 v[142:145], v146 offset:2048
	ds_read_b128 v[154:157], v146 offset:3072
	v_add_u32_e32 v146, 0x1c000, v195
	ds_read_b128 v[170:173], v146
	ds_read_b128 v[174:177], v146 offset:1024
	ds_read_b128 v[178:181], v146 offset:2048
	ds_read_b128 v[182:185], v146 offset:3072
	s_add_i32 s52, s52, 0x80000
	s_mov_b32 m0, s35
	ds_read_b128 v[186:189], v196 offset:32768
	ds_read_b128 v[198:201], v196 offset:33792
	ds_read_b128 v[202:205], v196 offset:34816
	ds_read_b128 v[228:231], v196 offset:35840
	ds_read_b128 v[232:235], v196 offset:36864
	ds_read_b128 v[236:239], v196 offset:37888
	ds_read_b128 v[240:243], v196 offset:38912
	ds_read_b128 v[244:247], v196 offset:39936
	buffer_load_dwordx4 v135, s[44:47], s52 offen lds
	s_mov_b32 m0, s36
	s_nop 0
	buffer_load_dwordx4 v193, s[44:47], s52 offen lds
	s_waitcnt vmcnt(8)
	s_waitcnt lgkmcnt(0)
	s_setprio 1
	s_barrier
	v_mfma_f32_16x16x32_bf16 v[126:129], v[130:133], v[186:189], v[126:129]
	v_mfma_f32_16x16x32_bf16 v[122:125], v[142:145], v[186:189], v[122:125]
	v_mfma_f32_16x16x32_bf16 v[106:109], v[142:145], v[202:205], v[106:109]
	v_mfma_f32_16x16x32_bf16 v[110:113], v[130:133], v[202:205], v[110:113]
	v_mfma_f32_16x16x32_bf16 v[94:97], v[130:133], v[232:235], v[94:97]
	v_mfma_f32_16x16x32_bf16 v[90:93], v[142:145], v[232:235], v[90:93]
	v_mfma_f32_16x16x32_bf16 v[74:77], v[142:145], v[240:243], v[74:77]
	v_mfma_f32_16x16x32_bf16 v[78:81], v[130:133], v[240:243], v[78:81]
	v_mfma_f32_16x16x32_bf16 v[70:73], v[170:173], v[240:243], v[70:73]
	v_mfma_f32_16x16x32_bf16 v[66:69], v[178:181], v[240:243], v[66:69]
	v_mfma_f32_16x16x32_bf16 v[82:85], v[178:181], v[232:235], v[82:85]
	v_mfma_f32_16x16x32_bf16 v[86:89], v[170:173], v[232:235], v[86:89]
	v_mfma_f32_16x16x32_bf16 v[102:105], v[170:173], v[202:205], v[102:105]
	v_mfma_f32_16x16x32_bf16 v[98:101], v[178:181], v[202:205], v[98:101]
	v_mfma_f32_16x16x32_bf16 v[114:117], v[178:181], v[186:189], v[114:117]
	v_mfma_f32_16x16x32_bf16 v[118:121], v[170:173], v[186:189], v[118:121]
	v_mfma_f32_16x16x32_bf16 v[126:129], v[138:141], v[198:201], v[126:129]
	v_mfma_f32_16x16x32_bf16 v[122:125], v[154:157], v[198:201], v[122:125]
	v_mfma_f32_16x16x32_bf16 v[106:109], v[154:157], v[228:231], v[106:109]
	v_mfma_f32_16x16x32_bf16 v[110:113], v[138:141], v[228:231], v[110:113]
	v_mfma_f32_16x16x32_bf16 v[94:97], v[138:141], v[236:239], v[94:97]
	v_mfma_f32_16x16x32_bf16 v[90:93], v[154:157], v[236:239], v[90:93]
	v_mfma_f32_16x16x32_bf16 v[74:77], v[154:157], v[244:247], v[74:77]
	v_mfma_f32_16x16x32_bf16 v[78:81], v[138:141], v[244:247], v[78:81]
	v_mfma_f32_16x16x32_bf16 v[70:73], v[174:177], v[244:247], v[70:73]
	v_mfma_f32_16x16x32_bf16 v[66:69], v[182:185], v[244:247], v[66:69]
	v_mfma_f32_16x16x32_bf16 v[82:85], v[182:185], v[236:239], v[82:85]
	v_mfma_f32_16x16x32_bf16 v[86:89], v[174:177], v[236:239], v[86:89]
	v_mfma_f32_16x16x32_bf16 v[102:105], v[174:177], v[228:231], v[102:105]
	v_mfma_f32_16x16x32_bf16 v[98:101], v[182:185], v[228:231], v[98:101]
	v_mfma_f32_16x16x32_bf16 v[114:117], v[182:185], v[198:201], v[114:117]
	v_mfma_f32_16x16x32_bf16 v[118:121], v[174:177], v[198:201], v[118:121]
	s_barrier
	s_setprio 0
	s_mov_b32 m0, s41
	s_or_b32 s52, s27, 0x80
	ds_read_b128 v[186:189], v196 offset:49152
	ds_read_b128 v[198:201], v196 offset:50176
	ds_read_b128 v[202:205], v196 offset:51200
	ds_read_b128 v[228:231], v196 offset:52224
	ds_read_b128 v[232:235], v196 offset:53248
	ds_read_b128 v[236:239], v196 offset:54272
	ds_read_b128 v[240:243], v196 offset:55296
	ds_read_b128 v[244:247], v196 offset:56320
	buffer_load_dwordx4 v192, s[64:67], s52 offen lds
	s_mov_b32 m0, s48
	s_add_i32 s27, s27, 0x80080
	buffer_load_dwordx4 v194, s[64:67], s52 offen lds
	s_mov_b32 m0, s69
	s_nop 0
	buffer_load_dwordx4 v192, s[64:67], s27 offen lds
	s_mov_b32 m0, s72
	s_nop 0
	buffer_load_dwordx4 v194, s[64:67], s27 offen lds
	s_mov_b32 m0, s49
	s_nop 0
	buffer_load_dwordx4 v135, s[44:47], s26 offen lds
	s_mov_b32 m0, s68
	s_nop 0
	buffer_load_dwordx4 v193, s[44:47], s26 offen lds
	s_waitcnt vmcnt(8)
	s_waitcnt lgkmcnt(0)
	s_setprio 1
	s_barrier
	v_mfma_f32_16x16x32_bf16 v[62:65], v[130:133], v[186:189], v[62:65]
	v_mfma_f32_16x16x32_bf16 v[58:61], v[142:145], v[186:189], v[58:61]
	v_mfma_f32_16x16x32_bf16 v[42:45], v[142:145], v[202:205], v[42:45]
	v_mfma_f32_16x16x32_bf16 v[46:49], v[130:133], v[202:205], v[46:49]
	v_mfma_f32_16x16x32_bf16 v[30:33], v[130:133], v[232:235], v[30:33]
	v_mfma_f32_16x16x32_bf16 v[26:29], v[142:145], v[232:235], v[26:29]
	v_mfma_f32_16x16x32_bf16 v[10:13], v[142:145], v[240:243], v[10:13]
	v_mfma_f32_16x16x32_bf16 v[14:17], v[130:133], v[240:243], v[14:17]
	v_mfma_f32_16x16x32_bf16 v[6:9], v[170:173], v[240:243], v[6:9]
	v_mfma_f32_16x16x32_bf16 v[2:5], v[178:181], v[240:243], v[2:5]
	v_mfma_f32_16x16x32_bf16 v[18:21], v[178:181], v[232:235], v[18:21]
	v_mfma_f32_16x16x32_bf16 v[22:25], v[170:173], v[232:235], v[22:25]
	v_mfma_f32_16x16x32_bf16 v[38:41], v[170:173], v[202:205], v[38:41]
	v_mfma_f32_16x16x32_bf16 v[34:37], v[178:181], v[202:205], v[34:37]
	v_mfma_f32_16x16x32_bf16 v[50:53], v[178:181], v[186:189], v[50:53]
	v_mfma_f32_16x16x32_bf16 v[54:57], v[170:173], v[186:189], v[54:57]
	v_mfma_f32_16x16x32_bf16 v[62:65], v[138:141], v[198:201], v[62:65]
	v_mfma_f32_16x16x32_bf16 v[58:61], v[154:157], v[198:201], v[58:61]
	v_mfma_f32_16x16x32_bf16 v[42:45], v[154:157], v[228:231], v[42:45]
	v_mfma_f32_16x16x32_bf16 v[46:49], v[138:141], v[228:231], v[46:49]
	v_mfma_f32_16x16x32_bf16 v[30:33], v[138:141], v[236:239], v[30:33]
	v_mfma_f32_16x16x32_bf16 v[26:29], v[154:157], v[236:239], v[26:29]
	v_mfma_f32_16x16x32_bf16 v[10:13], v[154:157], v[244:247], v[10:13]
	v_mfma_f32_16x16x32_bf16 v[14:17], v[138:141], v[244:247], v[14:17]
	v_mfma_f32_16x16x32_bf16 v[6:9], v[174:177], v[244:247], v[6:9]
	v_mfma_f32_16x16x32_bf16 v[2:5], v[182:185], v[244:247], v[2:5]
	v_mfma_f32_16x16x32_bf16 v[18:21], v[182:185], v[236:239], v[18:21]
	v_mfma_f32_16x16x32_bf16 v[22:25], v[174:177], v[236:239], v[22:25]
	v_mfma_f32_16x16x32_bf16 v[38:41], v[174:177], v[228:231], v[38:41]
	v_mfma_f32_16x16x32_bf16 v[34:37], v[182:185], v[228:231], v[34:37]
	v_mfma_f32_16x16x32_bf16 v[50:53], v[182:185], v[198:201], v[50:53]
	v_mfma_f32_16x16x32_bf16 v[54:57], v[174:177], v[198:201], v[54:57]
	s_barrier
	s_setprio 0
	s_add_i32 s22, s22, 2
	s_addk_i32 s18, 0x100
	s_addk_i32 s19, 0x100
	s_cmp_gt_u32 s22, 29
.LBB0_859:
	v_add_u32_e32 v146, 0x10000, v195
	ds_read_b128 v[130:133], v146
	ds_read_b128 v[138:141], v146 offset:1024
	ds_read_b128 v[142:145], v146 offset:2048
	ds_read_b128 v[154:157], v146 offset:3072
	v_add_u32_e32 v146, 0x14000, v195
	ds_read_b128 v[170:173], v146
	ds_read_b128 v[174:177], v146 offset:1024
	ds_read_b128 v[178:181], v146 offset:2048
	ds_read_b128 v[182:185], v146 offset:3072
	s_add_i32 s26, s18, 0xfff80080
	s_cmp_eq_u32 s22, 28
	s_cselect_b32 s52, s8, s26
	s_cselect_b32 s27, s9, s19
	s_or_b32 s26, s52, 0x80
	s_mov_b32 m0, s85
	ds_read_b128 v[186:189], v196
	ds_read_b128 v[198:201], v196 offset:1024
	ds_read_b128 v[202:205], v196 offset:2048
	ds_read_b128 v[228:231], v196 offset:3072
	ds_read_b128 v[232:235], v196 offset:4096
	ds_read_b128 v[236:239], v196 offset:5120
	ds_read_b128 v[240:243], v196 offset:6144
	ds_read_b128 v[244:247], v196 offset:7168
	buffer_load_dwordx4 v135, s[44:47], s18 offen lds
	s_mov_b32 m0, s15
	s_nop 0
	buffer_load_dwordx4 v193, s[44:47], s18 offen lds
	s_waitcnt vmcnt(8)
	s_waitcnt lgkmcnt(0)
	s_setprio 1
	s_barrier
	v_mfma_f32_16x16x32_bf16 v[126:129], v[130:133], v[186:189], v[126:129]
	v_mfma_f32_16x16x32_bf16 v[122:125], v[142:145], v[186:189], v[122:125]
	v_mfma_f32_16x16x32_bf16 v[106:109], v[142:145], v[202:205], v[106:109]
	v_mfma_f32_16x16x32_bf16 v[110:113], v[130:133], v[202:205], v[110:113]
	v_mfma_f32_16x16x32_bf16 v[94:97], v[130:133], v[232:235], v[94:97]
	v_mfma_f32_16x16x32_bf16 v[90:93], v[142:145], v[232:235], v[90:93]
	v_mfma_f32_16x16x32_bf16 v[74:77], v[142:145], v[240:243], v[74:77]
	v_mfma_f32_16x16x32_bf16 v[78:81], v[130:133], v[240:243], v[78:81]
	v_mfma_f32_16x16x32_bf16 v[70:73], v[170:173], v[240:243], v[70:73]
	v_mfma_f32_16x16x32_bf16 v[66:69], v[178:181], v[240:243], v[66:69]
	v_mfma_f32_16x16x32_bf16 v[82:85], v[178:181], v[232:235], v[82:85]
	v_mfma_f32_16x16x32_bf16 v[86:89], v[170:173], v[232:235], v[86:89]
	v_mfma_f32_16x16x32_bf16 v[102:105], v[170:173], v[202:205], v[102:105]
	v_mfma_f32_16x16x32_bf16 v[98:101], v[178:181], v[202:205], v[98:101]
	v_mfma_f32_16x16x32_bf16 v[114:117], v[178:181], v[186:189], v[114:117]
	v_mfma_f32_16x16x32_bf16 v[118:121], v[170:173], v[186:189], v[118:121]
	v_mfma_f32_16x16x32_bf16 v[126:129], v[138:141], v[198:201], v[126:129]
	v_mfma_f32_16x16x32_bf16 v[122:125], v[154:157], v[198:201], v[122:125]
	v_mfma_f32_16x16x32_bf16 v[106:109], v[154:157], v[228:231], v[106:109]
	v_mfma_f32_16x16x32_bf16 v[110:113], v[138:141], v[228:231], v[110:113]
	v_mfma_f32_16x16x32_bf16 v[94:97], v[138:141], v[236:239], v[94:97]
	v_mfma_f32_16x16x32_bf16 v[90:93], v[154:157], v[236:239], v[90:93]
	v_mfma_f32_16x16x32_bf16 v[74:77], v[154:157], v[244:247], v[74:77]
	v_mfma_f32_16x16x32_bf16 v[78:81], v[138:141], v[244:247], v[78:81]
	v_mfma_f32_16x16x32_bf16 v[70:73], v[174:177], v[244:247], v[70:73]
	v_mfma_f32_16x16x32_bf16 v[66:69], v[182:185], v[244:247], v[66:69]
	v_mfma_f32_16x16x32_bf16 v[82:85], v[182:185], v[236:239], v[82:85]
	v_mfma_f32_16x16x32_bf16 v[86:89], v[174:177], v[236:239], v[86:89]
	v_mfma_f32_16x16x32_bf16 v[102:105], v[174:177], v[228:231], v[102:105]
	v_mfma_f32_16x16x32_bf16 v[98:101], v[182:185], v[228:231], v[98:101]
	v_mfma_f32_16x16x32_bf16 v[114:117], v[182:185], v[198:201], v[114:117]
	v_mfma_f32_16x16x32_bf16 v[118:121], v[174:177], v[198:201], v[118:121]
	s_barrier
	s_setprio 0
	s_mov_b32 m0, s23
	s_mov_b32 s66, s46
	s_mov_b32 s67, s47
	ds_read_b128 v[186:189], v196 offset:16384
	ds_read_b128 v[198:201], v196 offset:17408
	ds_read_b128 v[202:205], v196 offset:18432
	ds_read_b128 v[228:231], v196 offset:19456
	ds_read_b128 v[232:235], v196 offset:20480
	ds_read_b128 v[236:239], v196 offset:21504
	ds_read_b128 v[240:243], v196 offset:22528
	ds_read_b128 v[244:247], v196 offset:23552
	buffer_load_dwordx4 v192, s[64:67], s27 offen lds
	s_mov_b32 m0, s24
	s_add_i32 s53, s27, 0x80000
	buffer_load_dwordx4 v194, s[64:67], s27 offen lds
	s_mov_b32 m0, s25
	s_nop 0
	buffer_load_dwordx4 v192, s[64:67], s53 offen lds
	s_mov_b32 m0, s33
	s_nop 0
	buffer_load_dwordx4 v194, s[64:67], s53 offen lds
	s_mov_b32 m0, s13
	s_nop 0
	buffer_load_dwordx4 v135, s[44:47], s52 offen lds
	s_mov_b32 m0, s34
	s_nop 0
	buffer_load_dwordx4 v193, s[44:47], s52 offen lds
	s_waitcnt vmcnt(8)
	s_waitcnt lgkmcnt(0)
	s_setprio 1
	s_barrier
	v_mfma_f32_16x16x32_bf16 v[62:65], v[130:133], v[186:189], v[62:65]
	v_mfma_f32_16x16x32_bf16 v[58:61], v[142:145], v[186:189], v[58:61]
	v_mfma_f32_16x16x32_bf16 v[42:45], v[142:145], v[202:205], v[42:45]
	v_mfma_f32_16x16x32_bf16 v[46:49], v[130:133], v[202:205], v[46:49]
	v_mfma_f32_16x16x32_bf16 v[30:33], v[130:133], v[232:235], v[30:33]
	v_mfma_f32_16x16x32_bf16 v[26:29], v[142:145], v[232:235], v[26:29]
	v_mfma_f32_16x16x32_bf16 v[10:13], v[142:145], v[240:243], v[10:13]
	v_mfma_f32_16x16x32_bf16 v[14:17], v[130:133], v[240:243], v[14:17]
	v_mfma_f32_16x16x32_bf16 v[6:9], v[170:173], v[240:243], v[6:9]
	v_mfma_f32_16x16x32_bf16 v[2:5], v[178:181], v[240:243], v[2:5]
	v_mfma_f32_16x16x32_bf16 v[18:21], v[178:181], v[232:235], v[18:21]
	v_mfma_f32_16x16x32_bf16 v[22:25], v[170:173], v[232:235], v[22:25]
	v_mfma_f32_16x16x32_bf16 v[38:41], v[170:173], v[202:205], v[38:41]
	v_mfma_f32_16x16x32_bf16 v[34:37], v[178:181], v[202:205], v[34:37]
	v_mfma_f32_16x16x32_bf16 v[50:53], v[178:181], v[186:189], v[50:53]
	v_mfma_f32_16x16x32_bf16 v[54:57], v[170:173], v[186:189], v[54:57]
	v_mfma_f32_16x16x32_bf16 v[62:65], v[138:141], v[198:201], v[62:65]
	v_mfma_f32_16x16x32_bf16 v[58:61], v[154:157], v[198:201], v[58:61]
	v_mfma_f32_16x16x32_bf16 v[42:45], v[154:157], v[228:231], v[42:45]
	v_mfma_f32_16x16x32_bf16 v[46:49], v[138:141], v[228:231], v[46:49]
	v_mfma_f32_16x16x32_bf16 v[30:33], v[138:141], v[236:239], v[30:33]
	v_mfma_f32_16x16x32_bf16 v[26:29], v[154:157], v[236:239], v[26:29]
	v_mfma_f32_16x16x32_bf16 v[10:13], v[154:157], v[244:247], v[10:13]
	v_mfma_f32_16x16x32_bf16 v[14:17], v[138:141], v[244:247], v[14:17]
	v_mfma_f32_16x16x32_bf16 v[6:9], v[174:177], v[244:247], v[6:9]
	v_mfma_f32_16x16x32_bf16 v[2:5], v[182:185], v[244:247], v[2:5]
	v_mfma_f32_16x16x32_bf16 v[18:21], v[182:185], v[236:239], v[18:21]
	v_mfma_f32_16x16x32_bf16 v[22:25], v[174:177], v[236:239], v[22:25]
	v_mfma_f32_16x16x32_bf16 v[38:41], v[174:177], v[228:231], v[38:41]
	v_mfma_f32_16x16x32_bf16 v[34:37], v[182:185], v[228:231], v[34:37]
	v_mfma_f32_16x16x32_bf16 v[50:53], v[182:185], v[198:201], v[50:53]
	v_mfma_f32_16x16x32_bf16 v[54:57], v[174:177], v[198:201], v[54:57]
	s_barrier
	s_setprio 0
	v_add_u32_e32 v146, 0x18000, v195
	ds_read_b128 v[130:133], v146
	ds_read_b128 v[138:141], v146 offset:1024
	ds_read_b128 v[142:145], v146 offset:2048
	ds_read_b128 v[154:157], v146 offset:3072
	v_add_u32_e32 v146, 0x1c000, v195
	ds_read_b128 v[170:173], v146
	ds_read_b128 v[174:177], v146 offset:1024
	ds_read_b128 v[178:181], v146 offset:2048
	ds_read_b128 v[182:185], v146 offset:3072
	s_add_i32 s52, s52, 0x80000
	s_mov_b32 m0, s35
	ds_read_b128 v[186:189], v196 offset:32768
	ds_read_b128 v[198:201], v196 offset:33792
	ds_read_b128 v[202:205], v196 offset:34816
	ds_read_b128 v[228:231], v196 offset:35840
	ds_read_b128 v[232:235], v196 offset:36864
	ds_read_b128 v[236:239], v196 offset:37888
	ds_read_b128 v[240:243], v196 offset:38912
	ds_read_b128 v[244:247], v196 offset:39936
	buffer_load_dwordx4 v135, s[44:47], s52 offen lds
	s_mov_b32 m0, s36
	s_nop 0
	buffer_load_dwordx4 v193, s[44:47], s52 offen lds
	s_waitcnt vmcnt(8)
	s_waitcnt lgkmcnt(0)
	s_setprio 1
	s_barrier
	v_mfma_f32_16x16x32_bf16 v[126:129], v[130:133], v[186:189], v[126:129]
	v_mfma_f32_16x16x32_bf16 v[122:125], v[142:145], v[186:189], v[122:125]
	v_mfma_f32_16x16x32_bf16 v[106:109], v[142:145], v[202:205], v[106:109]
	v_mfma_f32_16x16x32_bf16 v[110:113], v[130:133], v[202:205], v[110:113]
	v_mfma_f32_16x16x32_bf16 v[94:97], v[130:133], v[232:235], v[94:97]
	v_mfma_f32_16x16x32_bf16 v[90:93], v[142:145], v[232:235], v[90:93]
	v_mfma_f32_16x16x32_bf16 v[74:77], v[142:145], v[240:243], v[74:77]
	v_mfma_f32_16x16x32_bf16 v[78:81], v[130:133], v[240:243], v[78:81]
	v_mfma_f32_16x16x32_bf16 v[70:73], v[170:173], v[240:243], v[70:73]
	v_mfma_f32_16x16x32_bf16 v[66:69], v[178:181], v[240:243], v[66:69]
	v_mfma_f32_16x16x32_bf16 v[82:85], v[178:181], v[232:235], v[82:85]
	v_mfma_f32_16x16x32_bf16 v[86:89], v[170:173], v[232:235], v[86:89]
	v_mfma_f32_16x16x32_bf16 v[102:105], v[170:173], v[202:205], v[102:105]
	v_mfma_f32_16x16x32_bf16 v[98:101], v[178:181], v[202:205], v[98:101]
	v_mfma_f32_16x16x32_bf16 v[114:117], v[178:181], v[186:189], v[114:117]
	v_mfma_f32_16x16x32_bf16 v[118:121], v[170:173], v[186:189], v[118:121]
	v_mfma_f32_16x16x32_bf16 v[126:129], v[138:141], v[198:201], v[126:129]
	v_mfma_f32_16x16x32_bf16 v[122:125], v[154:157], v[198:201], v[122:125]
	v_mfma_f32_16x16x32_bf16 v[106:109], v[154:157], v[228:231], v[106:109]
	v_mfma_f32_16x16x32_bf16 v[110:113], v[138:141], v[228:231], v[110:113]
	v_mfma_f32_16x16x32_bf16 v[94:97], v[138:141], v[236:239], v[94:97]
	v_mfma_f32_16x16x32_bf16 v[90:93], v[154:157], v[236:239], v[90:93]
	v_mfma_f32_16x16x32_bf16 v[74:77], v[154:157], v[244:247], v[74:77]
	v_mfma_f32_16x16x32_bf16 v[78:81], v[138:141], v[244:247], v[78:81]
	v_mfma_f32_16x16x32_bf16 v[70:73], v[174:177], v[244:247], v[70:73]
	v_mfma_f32_16x16x32_bf16 v[66:69], v[182:185], v[244:247], v[66:69]
	v_mfma_f32_16x16x32_bf16 v[82:85], v[182:185], v[236:239], v[82:85]
	v_mfma_f32_16x16x32_bf16 v[86:89], v[174:177], v[236:239], v[86:89]
	v_mfma_f32_16x16x32_bf16 v[102:105], v[174:177], v[228:231], v[102:105]
	v_mfma_f32_16x16x32_bf16 v[98:101], v[182:185], v[228:231], v[98:101]
	v_mfma_f32_16x16x32_bf16 v[114:117], v[182:185], v[198:201], v[114:117]
	v_mfma_f32_16x16x32_bf16 v[118:121], v[174:177], v[198:201], v[118:121]
	s_barrier
	s_setprio 0
	s_mov_b32 m0, s41
	s_or_b32 s52, s27, 0x80
	ds_read_b128 v[186:189], v196 offset:49152
	ds_read_b128 v[198:201], v196 offset:50176
	ds_read_b128 v[202:205], v196 offset:51200
	ds_read_b128 v[228:231], v196 offset:52224
	ds_read_b128 v[232:235], v196 offset:53248
	ds_read_b128 v[236:239], v196 offset:54272
	ds_read_b128 v[240:243], v196 offset:55296
	ds_read_b128 v[244:247], v196 offset:56320
	buffer_load_dwordx4 v192, s[64:67], s52 offen lds
	s_mov_b32 m0, s48
	s_add_i32 s27, s27, 0x80080
	buffer_load_dwordx4 v194, s[64:67], s52 offen lds
	s_mov_b32 m0, s69
	s_nop 0
	buffer_load_dwordx4 v192, s[64:67], s27 offen lds
	s_mov_b32 m0, s72
	s_nop 0
	buffer_load_dwordx4 v194, s[64:67], s27 offen lds
	s_mov_b32 m0, s49
	s_nop 0
	buffer_load_dwordx4 v135, s[44:47], s26 offen lds
	s_mov_b32 m0, s68
	s_nop 0
	buffer_load_dwordx4 v193, s[44:47], s26 offen lds
	s_waitcnt vmcnt(8)
	s_waitcnt lgkmcnt(0)
	s_setprio 1
	s_barrier
	v_mfma_f32_16x16x32_bf16 v[62:65], v[130:133], v[186:189], v[62:65]
	v_mfma_f32_16x16x32_bf16 v[58:61], v[142:145], v[186:189], v[58:61]
	v_mfma_f32_16x16x32_bf16 v[42:45], v[142:145], v[202:205], v[42:45]
	v_mfma_f32_16x16x32_bf16 v[46:49], v[130:133], v[202:205], v[46:49]
	v_mfma_f32_16x16x32_bf16 v[30:33], v[130:133], v[232:235], v[30:33]
	v_mfma_f32_16x16x32_bf16 v[26:29], v[142:145], v[232:235], v[26:29]
	v_mfma_f32_16x16x32_bf16 v[10:13], v[142:145], v[240:243], v[10:13]
	v_mfma_f32_16x16x32_bf16 v[14:17], v[130:133], v[240:243], v[14:17]
	v_mfma_f32_16x16x32_bf16 v[6:9], v[170:173], v[240:243], v[6:9]
	v_mfma_f32_16x16x32_bf16 v[2:5], v[178:181], v[240:243], v[2:5]
	v_mfma_f32_16x16x32_bf16 v[18:21], v[178:181], v[232:235], v[18:21]
	v_mfma_f32_16x16x32_bf16 v[22:25], v[170:173], v[232:235], v[22:25]
	v_mfma_f32_16x16x32_bf16 v[38:41], v[170:173], v[202:205], v[38:41]
	v_mfma_f32_16x16x32_bf16 v[34:37], v[178:181], v[202:205], v[34:37]
	v_mfma_f32_16x16x32_bf16 v[50:53], v[178:181], v[186:189], v[50:53]
	v_mfma_f32_16x16x32_bf16 v[54:57], v[170:173], v[186:189], v[54:57]
	v_mfma_f32_16x16x32_bf16 v[62:65], v[138:141], v[198:201], v[62:65]
	v_mfma_f32_16x16x32_bf16 v[58:61], v[154:157], v[198:201], v[58:61]
	v_mfma_f32_16x16x32_bf16 v[42:45], v[154:157], v[228:231], v[42:45]
	v_mfma_f32_16x16x32_bf16 v[46:49], v[138:141], v[228:231], v[46:49]
	v_mfma_f32_16x16x32_bf16 v[30:33], v[138:141], v[236:239], v[30:33]
	v_mfma_f32_16x16x32_bf16 v[26:29], v[154:157], v[236:239], v[26:29]
	v_mfma_f32_16x16x32_bf16 v[10:13], v[154:157], v[244:247], v[10:13]
	v_mfma_f32_16x16x32_bf16 v[14:17], v[138:141], v[244:247], v[14:17]
	v_mfma_f32_16x16x32_bf16 v[6:9], v[174:177], v[244:247], v[6:9]
	v_mfma_f32_16x16x32_bf16 v[2:5], v[182:185], v[244:247], v[2:5]
	v_mfma_f32_16x16x32_bf16 v[18:21], v[182:185], v[236:239], v[18:21]
	v_mfma_f32_16x16x32_bf16 v[22:25], v[174:177], v[236:239], v[22:25]
	v_mfma_f32_16x16x32_bf16 v[38:41], v[174:177], v[228:231], v[38:41]
	v_mfma_f32_16x16x32_bf16 v[34:37], v[182:185], v[228:231], v[34:37]
	v_mfma_f32_16x16x32_bf16 v[50:53], v[182:185], v[198:201], v[50:53]
	v_mfma_f32_16x16x32_bf16 v[54:57], v[174:177], v[198:201], v[54:57]
	s_barrier
	s_setprio 0
	s_add_i32 s22, s22, 2
	s_addk_i32 s18, 0x100
	s_addk_i32 s19, 0x100
	s_cmp_gt_u32 s22, 29
	s_cbranch_scc0 .LBB0_859
	s_and_b64 vcc, exec, s[60:61]
	s_cbranch_vccz .LBB0_862
	s_barrier

.LBB0_880:
	s_lshl_b32 s14, s85, 20
	s_and_b64 s[8:9], s[42:43], exec
	s_cselect_b32 s8, s14, s12
	s_lshl_b32 s15, s66, 20
	s_and_b64 s[22:23], s[42:43], exec
	s_cselect_b32 s9, s15, s13
	s_add_i32 s12, s12, 0x80080
	s_addk_i32 s13, 0x100
	s_mov_b32 s16, -2
	v_add_u32_e32 v139, 0x10000, v234
	ds_read_b128 v[130:133], v139
	ds_read_b128 v[140:143], v139 offset:1024
	ds_read_b128 v[170:173], v139 offset:2048
	ds_read_b128 v[174:177], v139 offset:3072
	v_add_u32_e32 v139, 0x14000, v234
	ds_read_b128 v[178:181], v139
	ds_read_b128 v[182:185], v139 offset:1024
	ds_read_b128 v[186:189], v139 offset:2048
	ds_read_b128 v[190:193], v139 offset:3072
	s_add_i32 s21, s12, 0xfff80080
	s_cmp_eq_u32 s16, 28
	s_cselect_b32 s23, s8, s21
	s_cselect_b32 s22, s9, s13
	s_or_b32 s21, s23, 0x80
	s_mov_b32 m0, s72
	ds_read_b128 v[194:197], v235
	ds_read_b128 v[198:201], v235 offset:1024
	ds_read_b128 v[202:205], v235 offset:2048
	ds_read_b128 v[236:239], v235 offset:3072
	ds_read_b128 v[240:243], v235 offset:4096
	ds_read_b128 v[244:247], v235 offset:5120
	ds_read_b128 v[248:251], v235 offset:6144
	ds_read_b128 v[154:157], v235 offset:7168
	buffer_load_dwordx4 v228, s[60:63], s12 offen lds
	s_mov_b32 m0, s73
	s_nop 0
	buffer_load_dwordx4 v230, s[60:63], s12 offen lds
	s_waitcnt vmcnt(8)
	s_waitcnt lgkmcnt(0)
	s_setprio 1
	s_barrier
	v_mfma_f32_16x16x32_bf16 v[126:129], v[130:133], v[194:197], 0
	v_mfma_f32_16x16x32_bf16 v[122:125], v[170:173], v[194:197], 0
	v_mfma_f32_16x16x32_bf16 v[106:109], v[170:173], v[202:205], 0
	v_mfma_f32_16x16x32_bf16 v[114:117], v[130:133], v[202:205], 0
	v_mfma_f32_16x16x32_bf16 v[98:101], v[130:133], v[240:243], 0
	v_mfma_f32_16x16x32_bf16 v[90:93], v[170:173], v[240:243], 0
	v_mfma_f32_16x16x32_bf16 v[74:77], v[170:173], v[248:251], 0
	v_mfma_f32_16x16x32_bf16 v[82:85], v[130:133], v[248:251], 0
	v_mfma_f32_16x16x32_bf16 v[70:73], v[178:181], v[248:251], 0
	v_mfma_f32_16x16x32_bf16 v[66:69], v[186:189], v[248:251], 0
	v_mfma_f32_16x16x32_bf16 v[78:81], v[186:189], v[240:243], 0
	v_mfma_f32_16x16x32_bf16 v[86:89], v[178:181], v[240:243], 0
	v_mfma_f32_16x16x32_bf16 v[102:105], v[178:181], v[202:205], 0
	v_mfma_f32_16x16x32_bf16 v[94:97], v[186:189], v[202:205], 0
	v_mfma_f32_16x16x32_bf16 v[110:113], v[186:189], v[194:197], 0
	v_mfma_f32_16x16x32_bf16 v[118:121], v[178:181], v[194:197], 0
	v_mfma_f32_16x16x32_bf16 v[126:129], v[140:143], v[198:201], v[126:129]
	v_mfma_f32_16x16x32_bf16 v[122:125], v[174:177], v[198:201], v[122:125]
	v_mfma_f32_16x16x32_bf16 v[106:109], v[174:177], v[236:239], v[106:109]
	v_mfma_f32_16x16x32_bf16 v[114:117], v[140:143], v[236:239], v[114:117]
	v_mfma_f32_16x16x32_bf16 v[98:101], v[140:143], v[244:247], v[98:101]
	v_mfma_f32_16x16x32_bf16 v[90:93], v[174:177], v[244:247], v[90:93]
	v_mfma_f32_16x16x32_bf16 v[74:77], v[174:177], v[154:157], v[74:77]
	v_mfma_f32_16x16x32_bf16 v[82:85], v[140:143], v[154:157], v[82:85]
	v_mfma_f32_16x16x32_bf16 v[70:73], v[182:185], v[154:157], v[70:73]
	v_mfma_f32_16x16x32_bf16 v[66:69], v[190:193], v[154:157], v[66:69]
	v_mfma_f32_16x16x32_bf16 v[78:81], v[190:193], v[244:247], v[78:81]
	v_mfma_f32_16x16x32_bf16 v[86:89], v[182:185], v[244:247], v[86:89]
	v_mfma_f32_16x16x32_bf16 v[102:105], v[182:185], v[236:239], v[102:105]
	v_mfma_f32_16x16x32_bf16 v[94:97], v[190:193], v[236:239], v[94:97]
	v_mfma_f32_16x16x32_bf16 v[110:113], v[190:193], v[198:201], v[110:113]
	v_mfma_f32_16x16x32_bf16 v[118:121], v[182:185], v[198:201], v[118:121]
	s_barrier
	s_setprio 0
	s_mov_b32 m0, s26
	s_mov_b32 s46, s62
	s_mov_b32 s47, s63
	ds_read_b128 v[154:157], v235 offset:16384
	ds_read_b128 v[194:197], v235 offset:17408
	ds_read_b128 v[198:201], v235 offset:18432
	ds_read_b128 v[202:205], v235 offset:19456
	ds_read_b128 v[236:239], v235 offset:20480
	ds_read_b128 v[240:243], v235 offset:21504
	ds_read_b128 v[244:247], v235 offset:22528
	ds_read_b128 v[248:251], v235 offset:23552
	buffer_load_dwordx4 v229, s[44:47], s22 offen lds
	s_mov_b32 m0, s27
	s_add_i32 s38, s22, 0x80000
	buffer_load_dwordx4 v231, s[44:47], s22 offen lds
	s_mov_b32 m0, s34
	s_nop 0
	buffer_load_dwordx4 v229, s[44:47], s38 offen lds
	s_mov_b32 m0, s35
	s_nop 0
	buffer_load_dwordx4 v231, s[44:47], s38 offen lds
	s_mov_b32 m0, s19
	s_nop 0
	buffer_load_dwordx4 v228, s[60:63], s23 offen lds
	s_mov_b32 m0, s36
	s_nop 0
	buffer_load_dwordx4 v230, s[60:63], s23 offen lds
	s_waitcnt vmcnt(8)
	s_waitcnt lgkmcnt(0)
	s_setprio 1
	s_barrier
	v_mfma_f32_16x16x32_bf16 v[62:65], v[130:133], v[154:157], 0
	v_mfma_f32_16x16x32_bf16 v[58:61], v[170:173], v[154:157], 0
	v_mfma_f32_16x16x32_bf16 v[42:45], v[170:173], v[198:201], 0
	v_mfma_f32_16x16x32_bf16 v[50:53], v[130:133], v[198:201], 0
	v_mfma_f32_16x16x32_bf16 v[34:37], v[130:133], v[236:239], 0
	v_mfma_f32_16x16x32_bf16 v[26:29], v[170:173], v[236:239], 0
	v_mfma_f32_16x16x32_bf16 v[10:13], v[170:173], v[244:247], 0
	v_mfma_f32_16x16x32_bf16 v[18:21], v[130:133], v[244:247], 0
	v_mfma_f32_16x16x32_bf16 v[6:9], v[178:181], v[244:247], 0
	v_mfma_f32_16x16x32_bf16 v[2:5], v[186:189], v[244:247], 0
	v_mfma_f32_16x16x32_bf16 v[14:17], v[186:189], v[236:239], 0
	v_mfma_f32_16x16x32_bf16 v[22:25], v[178:181], v[236:239], 0
	v_mfma_f32_16x16x32_bf16 v[38:41], v[178:181], v[198:201], 0
	v_mfma_f32_16x16x32_bf16 v[30:33], v[186:189], v[198:201], 0
	v_mfma_f32_16x16x32_bf16 v[46:49], v[186:189], v[154:157], 0
	v_mfma_f32_16x16x32_bf16 v[54:57], v[178:181], v[154:157], 0
	v_mfma_f32_16x16x32_bf16 v[62:65], v[140:143], v[194:197], v[62:65]
	v_mfma_f32_16x16x32_bf16 v[58:61], v[174:177], v[194:197], v[58:61]
	v_mfma_f32_16x16x32_bf16 v[42:45], v[174:177], v[202:205], v[42:45]
	v_mfma_f32_16x16x32_bf16 v[50:53], v[140:143], v[202:205], v[50:53]
	v_mfma_f32_16x16x32_bf16 v[34:37], v[140:143], v[240:243], v[34:37]
	v_mfma_f32_16x16x32_bf16 v[26:29], v[174:177], v[240:243], v[26:29]
	v_mfma_f32_16x16x32_bf16 v[10:13], v[174:177], v[248:251], v[10:13]
	v_mfma_f32_16x16x32_bf16 v[18:21], v[140:143], v[248:251], v[18:21]
	v_mfma_f32_16x16x32_bf16 v[6:9], v[182:185], v[248:251], v[6:9]
	v_mfma_f32_16x16x32_bf16 v[2:5], v[190:193], v[248:251], v[2:5]
	v_mfma_f32_16x16x32_bf16 v[14:17], v[190:193], v[240:243], v[14:17]
	v_mfma_f32_16x16x32_bf16 v[22:25], v[182:185], v[240:243], v[22:25]
	v_mfma_f32_16x16x32_bf16 v[38:41], v[182:185], v[202:205], v[38:41]
	v_mfma_f32_16x16x32_bf16 v[30:33], v[190:193], v[202:205], v[30:33]
	v_mfma_f32_16x16x32_bf16 v[46:49], v[190:193], v[194:197], v[46:49]
	v_mfma_f32_16x16x32_bf16 v[54:57], v[182:185], v[194:197], v[54:57]
	s_barrier
	s_setprio 0
	v_add_u32_e32 v139, 0x18000, v234
	ds_read_b128 v[130:133], v139
	ds_read_b128 v[140:143], v139 offset:1024
	ds_read_b128 v[154:157], v139 offset:2048
	ds_read_b128 v[170:173], v139 offset:3072
	v_add_u32_e32 v139, 0x1c000, v234
	ds_read_b128 v[174:177], v139
	ds_read_b128 v[178:181], v139 offset:1024
	ds_read_b128 v[182:185], v139 offset:2048
	ds_read_b128 v[186:189], v139 offset:3072
	s_add_i32 s23, s23, 0x80000
	s_mov_b32 m0, s37
	ds_read_b128 v[190:193], v235 offset:32768
	ds_read_b128 v[194:197], v235 offset:33792
	ds_read_b128 v[198:201], v235 offset:34816
	ds_read_b128 v[202:205], v235 offset:35840
	ds_read_b128 v[236:239], v235 offset:36864
	ds_read_b128 v[240:243], v235 offset:37888
	ds_read_b128 v[244:247], v235 offset:38912
	ds_read_b128 v[248:251], v235 offset:39936
	buffer_load_dwordx4 v228, s[60:63], s23 offen lds
	s_mov_b32 m0, s18
	s_nop 0
	buffer_load_dwordx4 v230, s[60:63], s23 offen lds
	s_waitcnt vmcnt(8)
	s_waitcnt lgkmcnt(0)
	s_setprio 1
	s_barrier
	v_mfma_f32_16x16x32_bf16 v[126:129], v[130:133], v[190:193], v[126:129]
	v_mfma_f32_16x16x32_bf16 v[122:125], v[154:157], v[190:193], v[122:125]
	v_mfma_f32_16x16x32_bf16 v[106:109], v[154:157], v[198:201], v[106:109]
	v_mfma_f32_16x16x32_bf16 v[114:117], v[130:133], v[198:201], v[114:117]
	v_mfma_f32_16x16x32_bf16 v[98:101], v[130:133], v[236:239], v[98:101]
	v_mfma_f32_16x16x32_bf16 v[90:93], v[154:157], v[236:239], v[90:93]
	v_mfma_f32_16x16x32_bf16 v[74:77], v[154:157], v[244:247], v[74:77]
	v_mfma_f32_16x16x32_bf16 v[82:85], v[130:133], v[244:247], v[82:85]
	v_mfma_f32_16x16x32_bf16 v[70:73], v[174:177], v[244:247], v[70:73]
	v_mfma_f32_16x16x32_bf16 v[66:69], v[182:185], v[244:247], v[66:69]
	v_mfma_f32_16x16x32_bf16 v[78:81], v[182:185], v[236:239], v[78:81]
	v_mfma_f32_16x16x32_bf16 v[86:89], v[174:177], v[236:239], v[86:89]
	v_mfma_f32_16x16x32_bf16 v[102:105], v[174:177], v[198:201], v[102:105]
	v_mfma_f32_16x16x32_bf16 v[94:97], v[182:185], v[198:201], v[94:97]
	v_mfma_f32_16x16x32_bf16 v[110:113], v[182:185], v[190:193], v[110:113]
	v_mfma_f32_16x16x32_bf16 v[118:121], v[174:177], v[190:193], v[118:121]
	v_mfma_f32_16x16x32_bf16 v[126:129], v[140:143], v[194:197], v[126:129]
	v_mfma_f32_16x16x32_bf16 v[122:125], v[170:173], v[194:197], v[122:125]
	v_mfma_f32_16x16x32_bf16 v[106:109], v[170:173], v[202:205], v[106:109]
	v_mfma_f32_16x16x32_bf16 v[114:117], v[140:143], v[202:205], v[114:117]
	v_mfma_f32_16x16x32_bf16 v[98:101], v[140:143], v[240:243], v[98:101]
	v_mfma_f32_16x16x32_bf16 v[90:93], v[170:173], v[240:243], v[90:93]
	v_mfma_f32_16x16x32_bf16 v[74:77], v[170:173], v[248:251], v[74:77]
	v_mfma_f32_16x16x32_bf16 v[82:85], v[140:143], v[248:251], v[82:85]
	v_mfma_f32_16x16x32_bf16 v[70:73], v[178:181], v[248:251], v[70:73]
	v_mfma_f32_16x16x32_bf16 v[66:69], v[186:189], v[248:251], v[66:69]
	v_mfma_f32_16x16x32_bf16 v[78:81], v[186:189], v[240:243], v[78:81]
	v_mfma_f32_16x16x32_bf16 v[86:89], v[178:181], v[240:243], v[86:89]
	v_mfma_f32_16x16x32_bf16 v[102:105], v[178:181], v[202:205], v[102:105]
	v_mfma_f32_16x16x32_bf16 v[94:97], v[186:189], v[202:205], v[94:97]
	v_mfma_f32_16x16x32_bf16 v[110:113], v[186:189], v[194:197], v[110:113]
	v_mfma_f32_16x16x32_bf16 v[118:121], v[178:181], v[194:197], v[118:121]
	s_barrier
	s_setprio 0
	s_mov_b32 m0, s24
	s_or_b32 s23, s22, 0x80
	ds_read_b128 v[190:193], v235 offset:49152
	ds_read_b128 v[194:197], v235 offset:50176
	ds_read_b128 v[198:201], v235 offset:51200
	ds_read_b128 v[202:205], v235 offset:52224
	ds_read_b128 v[236:239], v235 offset:53248
	ds_read_b128 v[240:243], v235 offset:54272
	ds_read_b128 v[244:247], v235 offset:55296
	ds_read_b128 v[248:251], v235 offset:56320
	buffer_load_dwordx4 v229, s[44:47], s23 offen lds
	s_mov_b32 m0, s25
	s_add_i32 s22, s22, 0x80080
	buffer_load_dwordx4 v231, s[44:47], s23 offen lds
	s_mov_b32 m0, s64
	s_nop 0
	buffer_load_dwordx4 v229, s[44:47], s22 offen lds
	s_mov_b32 m0, s65
	s_nop 0
	buffer_load_dwordx4 v231, s[44:47], s22 offen lds
	s_mov_b32 m0, s48
	s_nop 0
	buffer_load_dwordx4 v228, s[60:63], s21 offen lds
	s_mov_b32 m0, s49
	s_nop 0
	buffer_load_dwordx4 v230, s[60:63], s21 offen lds
	s_waitcnt vmcnt(8)
	s_waitcnt lgkmcnt(0)
	s_setprio 1
	s_barrier
	v_mfma_f32_16x16x32_bf16 v[62:65], v[130:133], v[190:193], v[62:65]
	v_mfma_f32_16x16x32_bf16 v[58:61], v[154:157], v[190:193], v[58:61]
	v_mfma_f32_16x16x32_bf16 v[42:45], v[154:157], v[198:201], v[42:45]
	v_mfma_f32_16x16x32_bf16 v[50:53], v[130:133], v[198:201], v[50:53]
	v_mfma_f32_16x16x32_bf16 v[34:37], v[130:133], v[236:239], v[34:37]
	v_mfma_f32_16x16x32_bf16 v[26:29], v[154:157], v[236:239], v[26:29]
	v_mfma_f32_16x16x32_bf16 v[10:13], v[154:157], v[244:247], v[10:13]
	v_mfma_f32_16x16x32_bf16 v[18:21], v[130:133], v[244:247], v[18:21]
	v_mfma_f32_16x16x32_bf16 v[6:9], v[174:177], v[244:247], v[6:9]
	v_mfma_f32_16x16x32_bf16 v[2:5], v[182:185], v[244:247], v[2:5]
	v_mfma_f32_16x16x32_bf16 v[14:17], v[182:185], v[236:239], v[14:17]
	v_mfma_f32_16x16x32_bf16 v[22:25], v[174:177], v[236:239], v[22:25]
	v_mfma_f32_16x16x32_bf16 v[38:41], v[174:177], v[198:201], v[38:41]
	v_mfma_f32_16x16x32_bf16 v[30:33], v[182:185], v[198:201], v[30:33]
	v_mfma_f32_16x16x32_bf16 v[46:49], v[182:185], v[190:193], v[46:49]
	v_mfma_f32_16x16x32_bf16 v[54:57], v[174:177], v[190:193], v[54:57]
	v_mfma_f32_16x16x32_bf16 v[62:65], v[140:143], v[194:197], v[62:65]
	v_mfma_f32_16x16x32_bf16 v[58:61], v[170:173], v[194:197], v[58:61]
	v_mfma_f32_16x16x32_bf16 v[42:45], v[170:173], v[202:205], v[42:45]
	v_mfma_f32_16x16x32_bf16 v[50:53], v[140:143], v[202:205], v[50:53]
	v_mfma_f32_16x16x32_bf16 v[34:37], v[140:143], v[240:243], v[34:37]
	v_mfma_f32_16x16x32_bf16 v[26:29], v[170:173], v[240:243], v[26:29]
	v_mfma_f32_16x16x32_bf16 v[10:13], v[170:173], v[248:251], v[10:13]
	v_mfma_f32_16x16x32_bf16 v[18:21], v[140:143], v[248:251], v[18:21]
	v_mfma_f32_16x16x32_bf16 v[6:9], v[178:181], v[248:251], v[6:9]
	v_mfma_f32_16x16x32_bf16 v[2:5], v[186:189], v[248:251], v[2:5]
	v_mfma_f32_16x16x32_bf16 v[14:17], v[186:189], v[240:243], v[14:17]
	v_mfma_f32_16x16x32_bf16 v[22:25], v[178:181], v[240:243], v[22:25]
	v_mfma_f32_16x16x32_bf16 v[38:41], v[178:181], v[202:205], v[38:41]
	v_mfma_f32_16x16x32_bf16 v[30:33], v[186:189], v[202:205], v[30:33]
	v_mfma_f32_16x16x32_bf16 v[46:49], v[186:189], v[194:197], v[46:49]
	v_mfma_f32_16x16x32_bf16 v[54:57], v[178:181], v[194:197], v[54:57]
	s_barrier
	s_setprio 0
	s_add_i32 s16, s16, 2
	s_addk_i32 s12, 0x100
	s_addk_i32 s13, 0x100
	s_cmp_gt_u32 s16, 29
.LBB0_881:
	v_add_u32_e32 v139, 0x10000, v234
	ds_read_b128 v[130:133], v139
	ds_read_b128 v[140:143], v139 offset:1024
	ds_read_b128 v[170:173], v139 offset:2048
	ds_read_b128 v[174:177], v139 offset:3072
	v_add_u32_e32 v139, 0x14000, v234
	ds_read_b128 v[178:181], v139
	ds_read_b128 v[182:185], v139 offset:1024
	ds_read_b128 v[186:189], v139 offset:2048
	ds_read_b128 v[190:193], v139 offset:3072
	s_add_i32 s21, s12, 0xfff80080
	s_cmp_eq_u32 s16, 28
	s_cselect_b32 s23, s8, s21
	s_cselect_b32 s22, s9, s13
	s_or_b32 s21, s23, 0x80
	s_mov_b32 m0, s72
	ds_read_b128 v[194:197], v235
	ds_read_b128 v[198:201], v235 offset:1024
	ds_read_b128 v[202:205], v235 offset:2048
	ds_read_b128 v[236:239], v235 offset:3072
	ds_read_b128 v[240:243], v235 offset:4096
	ds_read_b128 v[244:247], v235 offset:5120
	ds_read_b128 v[248:251], v235 offset:6144
	ds_read_b128 v[154:157], v235 offset:7168
	buffer_load_dwordx4 v228, s[60:63], s12 offen lds
	s_mov_b32 m0, s73
	s_nop 0
	buffer_load_dwordx4 v230, s[60:63], s12 offen lds
	s_waitcnt vmcnt(8)
	s_waitcnt lgkmcnt(0)
	s_setprio 1
	s_barrier
	v_mfma_f32_16x16x32_bf16 v[126:129], v[130:133], v[194:197], v[126:129]
	v_mfma_f32_16x16x32_bf16 v[122:125], v[170:173], v[194:197], v[122:125]
	v_mfma_f32_16x16x32_bf16 v[106:109], v[170:173], v[202:205], v[106:109]
	v_mfma_f32_16x16x32_bf16 v[114:117], v[130:133], v[202:205], v[114:117]
	v_mfma_f32_16x16x32_bf16 v[98:101], v[130:133], v[240:243], v[98:101]
	v_mfma_f32_16x16x32_bf16 v[90:93], v[170:173], v[240:243], v[90:93]
	v_mfma_f32_16x16x32_bf16 v[74:77], v[170:173], v[248:251], v[74:77]
	v_mfma_f32_16x16x32_bf16 v[82:85], v[130:133], v[248:251], v[82:85]
	v_mfma_f32_16x16x32_bf16 v[70:73], v[178:181], v[248:251], v[70:73]
	v_mfma_f32_16x16x32_bf16 v[66:69], v[186:189], v[248:251], v[66:69]
	v_mfma_f32_16x16x32_bf16 v[78:81], v[186:189], v[240:243], v[78:81]
	v_mfma_f32_16x16x32_bf16 v[86:89], v[178:181], v[240:243], v[86:89]
	v_mfma_f32_16x16x32_bf16 v[102:105], v[178:181], v[202:205], v[102:105]
	v_mfma_f32_16x16x32_bf16 v[94:97], v[186:189], v[202:205], v[94:97]
	v_mfma_f32_16x16x32_bf16 v[110:113], v[186:189], v[194:197], v[110:113]
	v_mfma_f32_16x16x32_bf16 v[118:121], v[178:181], v[194:197], v[118:121]
	v_mfma_f32_16x16x32_bf16 v[126:129], v[140:143], v[198:201], v[126:129]
	v_mfma_f32_16x16x32_bf16 v[122:125], v[174:177], v[198:201], v[122:125]
	v_mfma_f32_16x16x32_bf16 v[106:109], v[174:177], v[236:239], v[106:109]
	v_mfma_f32_16x16x32_bf16 v[114:117], v[140:143], v[236:239], v[114:117]
	v_mfma_f32_16x16x32_bf16 v[98:101], v[140:143], v[244:247], v[98:101]
	v_mfma_f32_16x16x32_bf16 v[90:93], v[174:177], v[244:247], v[90:93]
	v_mfma_f32_16x16x32_bf16 v[74:77], v[174:177], v[154:157], v[74:77]
	v_mfma_f32_16x16x32_bf16 v[82:85], v[140:143], v[154:157], v[82:85]
	v_mfma_f32_16x16x32_bf16 v[70:73], v[182:185], v[154:157], v[70:73]
	v_mfma_f32_16x16x32_bf16 v[66:69], v[190:193], v[154:157], v[66:69]
	v_mfma_f32_16x16x32_bf16 v[78:81], v[190:193], v[244:247], v[78:81]
	v_mfma_f32_16x16x32_bf16 v[86:89], v[182:185], v[244:247], v[86:89]
	v_mfma_f32_16x16x32_bf16 v[102:105], v[182:185], v[236:239], v[102:105]
	v_mfma_f32_16x16x32_bf16 v[94:97], v[190:193], v[236:239], v[94:97]
	v_mfma_f32_16x16x32_bf16 v[110:113], v[190:193], v[198:201], v[110:113]
	v_mfma_f32_16x16x32_bf16 v[118:121], v[182:185], v[198:201], v[118:121]
	s_barrier
	s_setprio 0
	s_mov_b32 m0, s26
	s_mov_b32 s46, s62
	s_mov_b32 s47, s63
	ds_read_b128 v[154:157], v235 offset:16384
	ds_read_b128 v[194:197], v235 offset:17408
	ds_read_b128 v[198:201], v235 offset:18432
	ds_read_b128 v[202:205], v235 offset:19456
	ds_read_b128 v[236:239], v235 offset:20480
	ds_read_b128 v[240:243], v235 offset:21504
	ds_read_b128 v[244:247], v235 offset:22528
	ds_read_b128 v[248:251], v235 offset:23552
	buffer_load_dwordx4 v229, s[44:47], s22 offen lds
	s_mov_b32 m0, s27
	s_add_i32 s38, s22, 0x80000
	buffer_load_dwordx4 v231, s[44:47], s22 offen lds
	s_mov_b32 m0, s34
	s_nop 0
	buffer_load_dwordx4 v229, s[44:47], s38 offen lds
	s_mov_b32 m0, s35
	s_nop 0
	buffer_load_dwordx4 v231, s[44:47], s38 offen lds
	s_mov_b32 m0, s19
	s_nop 0
	buffer_load_dwordx4 v228, s[60:63], s23 offen lds
	s_mov_b32 m0, s36
	s_nop 0
	buffer_load_dwordx4 v230, s[60:63], s23 offen lds
	s_waitcnt vmcnt(8)
	s_waitcnt lgkmcnt(0)
	s_setprio 1
	s_barrier
	v_mfma_f32_16x16x32_bf16 v[62:65], v[130:133], v[154:157], v[62:65]
	v_mfma_f32_16x16x32_bf16 v[58:61], v[170:173], v[154:157], v[58:61]
	v_mfma_f32_16x16x32_bf16 v[42:45], v[170:173], v[198:201], v[42:45]
	v_mfma_f32_16x16x32_bf16 v[50:53], v[130:133], v[198:201], v[50:53]
	v_mfma_f32_16x16x32_bf16 v[34:37], v[130:133], v[236:239], v[34:37]
	v_mfma_f32_16x16x32_bf16 v[26:29], v[170:173], v[236:239], v[26:29]
	v_mfma_f32_16x16x32_bf16 v[10:13], v[170:173], v[244:247], v[10:13]
	v_mfma_f32_16x16x32_bf16 v[18:21], v[130:133], v[244:247], v[18:21]
	v_mfma_f32_16x16x32_bf16 v[6:9], v[178:181], v[244:247], v[6:9]
	v_mfma_f32_16x16x32_bf16 v[2:5], v[186:189], v[244:247], v[2:5]
	v_mfma_f32_16x16x32_bf16 v[14:17], v[186:189], v[236:239], v[14:17]
	v_mfma_f32_16x16x32_bf16 v[22:25], v[178:181], v[236:239], v[22:25]
	v_mfma_f32_16x16x32_bf16 v[38:41], v[178:181], v[198:201], v[38:41]
	v_mfma_f32_16x16x32_bf16 v[30:33], v[186:189], v[198:201], v[30:33]
	v_mfma_f32_16x16x32_bf16 v[46:49], v[186:189], v[154:157], v[46:49]
	v_mfma_f32_16x16x32_bf16 v[54:57], v[178:181], v[154:157], v[54:57]
	v_mfma_f32_16x16x32_bf16 v[62:65], v[140:143], v[194:197], v[62:65]
	v_mfma_f32_16x16x32_bf16 v[58:61], v[174:177], v[194:197], v[58:61]
	v_mfma_f32_16x16x32_bf16 v[42:45], v[174:177], v[202:205], v[42:45]
	v_mfma_f32_16x16x32_bf16 v[50:53], v[140:143], v[202:205], v[50:53]
	v_mfma_f32_16x16x32_bf16 v[34:37], v[140:143], v[240:243], v[34:37]
	v_mfma_f32_16x16x32_bf16 v[26:29], v[174:177], v[240:243], v[26:29]
	v_mfma_f32_16x16x32_bf16 v[10:13], v[174:177], v[248:251], v[10:13]
	v_mfma_f32_16x16x32_bf16 v[18:21], v[140:143], v[248:251], v[18:21]
	v_mfma_f32_16x16x32_bf16 v[6:9], v[182:185], v[248:251], v[6:9]
	v_mfma_f32_16x16x32_bf16 v[2:5], v[190:193], v[248:251], v[2:5]
	v_mfma_f32_16x16x32_bf16 v[14:17], v[190:193], v[240:243], v[14:17]
	v_mfma_f32_16x16x32_bf16 v[22:25], v[182:185], v[240:243], v[22:25]
	v_mfma_f32_16x16x32_bf16 v[38:41], v[182:185], v[202:205], v[38:41]
	v_mfma_f32_16x16x32_bf16 v[30:33], v[190:193], v[202:205], v[30:33]
	v_mfma_f32_16x16x32_bf16 v[46:49], v[190:193], v[194:197], v[46:49]
	v_mfma_f32_16x16x32_bf16 v[54:57], v[182:185], v[194:197], v[54:57]
	s_barrier
	s_setprio 0
	v_add_u32_e32 v139, 0x18000, v234
	ds_read_b128 v[130:133], v139
	ds_read_b128 v[140:143], v139 offset:1024
	ds_read_b128 v[154:157], v139 offset:2048
	ds_read_b128 v[170:173], v139 offset:3072
	v_add_u32_e32 v139, 0x1c000, v234
	ds_read_b128 v[174:177], v139
	ds_read_b128 v[178:181], v139 offset:1024
	ds_read_b128 v[182:185], v139 offset:2048
	ds_read_b128 v[186:189], v139 offset:3072
	s_add_i32 s23, s23, 0x80000
	s_mov_b32 m0, s37
	ds_read_b128 v[190:193], v235 offset:32768
	ds_read_b128 v[194:197], v235 offset:33792
	ds_read_b128 v[198:201], v235 offset:34816
	ds_read_b128 v[202:205], v235 offset:35840
	ds_read_b128 v[236:239], v235 offset:36864
	ds_read_b128 v[240:243], v235 offset:37888
	ds_read_b128 v[244:247], v235 offset:38912
	ds_read_b128 v[248:251], v235 offset:39936
	buffer_load_dwordx4 v228, s[60:63], s23 offen lds
	s_mov_b32 m0, s18
	s_nop 0
	buffer_load_dwordx4 v230, s[60:63], s23 offen lds
	s_waitcnt vmcnt(8)
	s_waitcnt lgkmcnt(0)
	s_setprio 1
	s_barrier
	v_mfma_f32_16x16x32_bf16 v[126:129], v[130:133], v[190:193], v[126:129]
	v_mfma_f32_16x16x32_bf16 v[122:125], v[154:157], v[190:193], v[122:125]
	v_mfma_f32_16x16x32_bf16 v[106:109], v[154:157], v[198:201], v[106:109]
	v_mfma_f32_16x16x32_bf16 v[114:117], v[130:133], v[198:201], v[114:117]
	v_mfma_f32_16x16x32_bf16 v[98:101], v[130:133], v[236:239], v[98:101]
	v_mfma_f32_16x16x32_bf16 v[90:93], v[154:157], v[236:239], v[90:93]
	v_mfma_f32_16x16x32_bf16 v[74:77], v[154:157], v[244:247], v[74:77]
	v_mfma_f32_16x16x32_bf16 v[82:85], v[130:133], v[244:247], v[82:85]
	v_mfma_f32_16x16x32_bf16 v[70:73], v[174:177], v[244:247], v[70:73]
	v_mfma_f32_16x16x32_bf16 v[66:69], v[182:185], v[244:247], v[66:69]
	v_mfma_f32_16x16x32_bf16 v[78:81], v[182:185], v[236:239], v[78:81]
	v_mfma_f32_16x16x32_bf16 v[86:89], v[174:177], v[236:239], v[86:89]
	v_mfma_f32_16x16x32_bf16 v[102:105], v[174:177], v[198:201], v[102:105]
	v_mfma_f32_16x16x32_bf16 v[94:97], v[182:185], v[198:201], v[94:97]
	v_mfma_f32_16x16x32_bf16 v[110:113], v[182:185], v[190:193], v[110:113]
	v_mfma_f32_16x16x32_bf16 v[118:121], v[174:177], v[190:193], v[118:121]
	v_mfma_f32_16x16x32_bf16 v[126:129], v[140:143], v[194:197], v[126:129]
	v_mfma_f32_16x16x32_bf16 v[122:125], v[170:173], v[194:197], v[122:125]
	v_mfma_f32_16x16x32_bf16 v[106:109], v[170:173], v[202:205], v[106:109]
	v_mfma_f32_16x16x32_bf16 v[114:117], v[140:143], v[202:205], v[114:117]
	v_mfma_f32_16x16x32_bf16 v[98:101], v[140:143], v[240:243], v[98:101]
	v_mfma_f32_16x16x32_bf16 v[90:93], v[170:173], v[240:243], v[90:93]
	v_mfma_f32_16x16x32_bf16 v[74:77], v[170:173], v[248:251], v[74:77]
	v_mfma_f32_16x16x32_bf16 v[82:85], v[140:143], v[248:251], v[82:85]
	v_mfma_f32_16x16x32_bf16 v[70:73], v[178:181], v[248:251], v[70:73]
	v_mfma_f32_16x16x32_bf16 v[66:69], v[186:189], v[248:251], v[66:69]
	v_mfma_f32_16x16x32_bf16 v[78:81], v[186:189], v[240:243], v[78:81]
	v_mfma_f32_16x16x32_bf16 v[86:89], v[178:181], v[240:243], v[86:89]
	v_mfma_f32_16x16x32_bf16 v[102:105], v[178:181], v[202:205], v[102:105]
	v_mfma_f32_16x16x32_bf16 v[94:97], v[186:189], v[202:205], v[94:97]
	v_mfma_f32_16x16x32_bf16 v[110:113], v[186:189], v[194:197], v[110:113]
	v_mfma_f32_16x16x32_bf16 v[118:121], v[178:181], v[194:197], v[118:121]
	s_barrier
	s_setprio 0
	s_mov_b32 m0, s24
	s_or_b32 s23, s22, 0x80
	ds_read_b128 v[190:193], v235 offset:49152
	ds_read_b128 v[194:197], v235 offset:50176
	ds_read_b128 v[198:201], v235 offset:51200
	ds_read_b128 v[202:205], v235 offset:52224
	ds_read_b128 v[236:239], v235 offset:53248
	ds_read_b128 v[240:243], v235 offset:54272
	ds_read_b128 v[244:247], v235 offset:55296
	ds_read_b128 v[248:251], v235 offset:56320
	buffer_load_dwordx4 v229, s[44:47], s23 offen lds
	s_mov_b32 m0, s25
	s_add_i32 s22, s22, 0x80080
	buffer_load_dwordx4 v231, s[44:47], s23 offen lds
	s_mov_b32 m0, s64
	s_nop 0
	buffer_load_dwordx4 v229, s[44:47], s22 offen lds
	s_mov_b32 m0, s65
	s_nop 0
	buffer_load_dwordx4 v231, s[44:47], s22 offen lds
	s_mov_b32 m0, s48
	s_nop 0
	buffer_load_dwordx4 v228, s[60:63], s21 offen lds
	s_mov_b32 m0, s49
	s_nop 0
	buffer_load_dwordx4 v230, s[60:63], s21 offen lds
	s_waitcnt vmcnt(8)
	s_waitcnt lgkmcnt(0)
	s_setprio 1
	s_barrier
	v_mfma_f32_16x16x32_bf16 v[62:65], v[130:133], v[190:193], v[62:65]
	v_mfma_f32_16x16x32_bf16 v[58:61], v[154:157], v[190:193], v[58:61]
	v_mfma_f32_16x16x32_bf16 v[42:45], v[154:157], v[198:201], v[42:45]
	v_mfma_f32_16x16x32_bf16 v[50:53], v[130:133], v[198:201], v[50:53]
	v_mfma_f32_16x16x32_bf16 v[34:37], v[130:133], v[236:239], v[34:37]
	v_mfma_f32_16x16x32_bf16 v[26:29], v[154:157], v[236:239], v[26:29]
	v_mfma_f32_16x16x32_bf16 v[10:13], v[154:157], v[244:247], v[10:13]
	v_mfma_f32_16x16x32_bf16 v[18:21], v[130:133], v[244:247], v[18:21]
	v_mfma_f32_16x16x32_bf16 v[6:9], v[174:177], v[244:247], v[6:9]
	v_mfma_f32_16x16x32_bf16 v[2:5], v[182:185], v[244:247], v[2:5]
	v_mfma_f32_16x16x32_bf16 v[14:17], v[182:185], v[236:239], v[14:17]
	v_mfma_f32_16x16x32_bf16 v[22:25], v[174:177], v[236:239], v[22:25]
	v_mfma_f32_16x16x32_bf16 v[38:41], v[174:177], v[198:201], v[38:41]
	v_mfma_f32_16x16x32_bf16 v[30:33], v[182:185], v[198:201], v[30:33]
	v_mfma_f32_16x16x32_bf16 v[46:49], v[182:185], v[190:193], v[46:49]
	v_mfma_f32_16x16x32_bf16 v[54:57], v[174:177], v[190:193], v[54:57]
	v_mfma_f32_16x16x32_bf16 v[62:65], v[140:143], v[194:197], v[62:65]
	v_mfma_f32_16x16x32_bf16 v[58:61], v[170:173], v[194:197], v[58:61]
	v_mfma_f32_16x16x32_bf16 v[42:45], v[170:173], v[202:205], v[42:45]
	v_mfma_f32_16x16x32_bf16 v[50:53], v[140:143], v[202:205], v[50:53]
	v_mfma_f32_16x16x32_bf16 v[34:37], v[140:143], v[240:243], v[34:37]
	v_mfma_f32_16x16x32_bf16 v[26:29], v[170:173], v[240:243], v[26:29]
	v_mfma_f32_16x16x32_bf16 v[10:13], v[170:173], v[248:251], v[10:13]
	v_mfma_f32_16x16x32_bf16 v[18:21], v[140:143], v[248:251], v[18:21]
	v_mfma_f32_16x16x32_bf16 v[6:9], v[178:181], v[248:251], v[6:9]
	v_mfma_f32_16x16x32_bf16 v[2:5], v[186:189], v[248:251], v[2:5]
	v_mfma_f32_16x16x32_bf16 v[14:17], v[186:189], v[240:243], v[14:17]
	v_mfma_f32_16x16x32_bf16 v[22:25], v[178:181], v[240:243], v[22:25]
	v_mfma_f32_16x16x32_bf16 v[38:41], v[178:181], v[202:205], v[38:41]
	v_mfma_f32_16x16x32_bf16 v[30:33], v[186:189], v[202:205], v[30:33]
	v_mfma_f32_16x16x32_bf16 v[46:49], v[186:189], v[194:197], v[46:49]
	v_mfma_f32_16x16x32_bf16 v[54:57], v[178:181], v[194:197], v[54:57]
	s_barrier
	s_setprio 0
	s_add_i32 s16, s16, 2
	s_addk_i32 s12, 0x100
	s_addk_i32 s13, 0x100
	s_cmp_gt_u32 s16, 29
	s_cbranch_scc0 .LBB0_881
	v_readlane_b32 s8, v255, 44
	v_readlane_b32 s9, v255, 45
	s_and_b64 vcc, exec, s[8:9]
	s_cbranch_vccz .LBB0_884
	s_barrier

.LBB0_904:
	s_lshl_b32 s73, s72, 20
	s_and_b64 s[8:9], s[42:43], exec
	s_cselect_b32 s8, s73, s13
	s_lshl_b32 s84, s71, 20
	s_and_b64 s[22:23], s[42:43], exec
	s_cselect_b32 s9, s84, s21
	s_add_i32 s13, s13, 0x80080
	s_addk_i32 s21, 0x100
	s_mov_b32 s22, -2
	v_add_u32_e32 v133, 0x10000, v178
	ds_read_b128 v[134:137], v133
	ds_read_b128 v[138:141], v133 offset:1024
	ds_read_b128 v[142:145], v133 offset:2048
	ds_read_b128 v[154:157], v133 offset:3072
	v_add_u32_e32 v133, 0x14000, v178
	ds_read_b128 v[170:173], v133
	ds_read_b128 v[180:183], v133 offset:1024
	ds_read_b128 v[184:187], v133 offset:2048
	ds_read_b128 v[188:191], v133 offset:3072
	s_add_i32 s23, s13, 0xfff80080
	s_cmp_eq_u32 s22, 28
	s_cselect_b32 s27, s8, s23
	s_cselect_b32 s26, s9, s21
	s_or_b32 s23, s27, 0x80
	s_mov_b32 s46, s62
	s_mov_b32 s47, s63
	s_mov_b32 m0, s68
	ds_read_b128 v[192:195], v179
	ds_read_b128 v[196:199], v179 offset:1024
	ds_read_b128 v[200:203], v179 offset:2048
	ds_read_b128 v[204:207], v179 offset:3072
	ds_read_b128 v[228:231], v179 offset:4096
	ds_read_b128 v[232:235], v179 offset:5120
	ds_read_b128 v[236:239], v179 offset:6144
	ds_read_b128 v[240:243], v179 offset:7168
	buffer_load_dwordx4 v174, s[44:47], s13 offen lds
	s_mov_b32 m0, s69
	s_nop 0
	buffer_load_dwordx4 v176, s[44:47], s13 offen lds
	s_waitcnt vmcnt(8)
	s_waitcnt lgkmcnt(0)
	s_setprio 1
	s_barrier
	v_mfma_f32_16x16x32_bf16 v[126:129], v[134:137], v[192:195], 0
	v_mfma_f32_16x16x32_bf16 v[122:125], v[142:145], v[192:195], 0
	v_mfma_f32_16x16x32_bf16 v[106:109], v[142:145], v[200:203], 0
	v_mfma_f32_16x16x32_bf16 v[110:113], v[134:137], v[200:203], 0
	v_mfma_f32_16x16x32_bf16 v[94:97], v[134:137], v[228:231], 0
	v_mfma_f32_16x16x32_bf16 v[90:93], v[142:145], v[228:231], 0
	v_mfma_f32_16x16x32_bf16 v[74:77], v[142:145], v[236:239], 0
	v_mfma_f32_16x16x32_bf16 v[78:81], v[134:137], v[236:239], 0
	v_mfma_f32_16x16x32_bf16 v[70:73], v[170:173], v[236:239], 0
	v_mfma_f32_16x16x32_bf16 v[66:69], v[184:187], v[236:239], 0
	v_mfma_f32_16x16x32_bf16 v[82:85], v[184:187], v[228:231], 0
	v_mfma_f32_16x16x32_bf16 v[86:89], v[170:173], v[228:231], 0
	v_mfma_f32_16x16x32_bf16 v[102:105], v[170:173], v[200:203], 0
	v_mfma_f32_16x16x32_bf16 v[98:101], v[184:187], v[200:203], 0
	v_mfma_f32_16x16x32_bf16 v[114:117], v[184:187], v[192:195], 0
	v_mfma_f32_16x16x32_bf16 v[118:121], v[170:173], v[192:195], 0
	v_mfma_f32_16x16x32_bf16 v[126:129], v[138:141], v[196:199], v[126:129]
	v_mfma_f32_16x16x32_bf16 v[122:125], v[154:157], v[196:199], v[122:125]
	v_mfma_f32_16x16x32_bf16 v[106:109], v[154:157], v[204:207], v[106:109]
	v_mfma_f32_16x16x32_bf16 v[110:113], v[138:141], v[204:207], v[110:113]
	v_mfma_f32_16x16x32_bf16 v[94:97], v[138:141], v[232:235], v[94:97]
	v_mfma_f32_16x16x32_bf16 v[90:93], v[154:157], v[232:235], v[90:93]
	v_mfma_f32_16x16x32_bf16 v[74:77], v[154:157], v[240:243], v[74:77]
	v_mfma_f32_16x16x32_bf16 v[78:81], v[138:141], v[240:243], v[78:81]
	v_mfma_f32_16x16x32_bf16 v[70:73], v[180:183], v[240:243], v[70:73]
	v_mfma_f32_16x16x32_bf16 v[66:69], v[188:191], v[240:243], v[66:69]
	v_mfma_f32_16x16x32_bf16 v[82:85], v[188:191], v[232:235], v[82:85]
	v_mfma_f32_16x16x32_bf16 v[86:89], v[180:183], v[232:235], v[86:89]
	v_mfma_f32_16x16x32_bf16 v[102:105], v[180:183], v[204:207], v[102:105]
	v_mfma_f32_16x16x32_bf16 v[98:101], v[188:191], v[204:207], v[98:101]
	v_mfma_f32_16x16x32_bf16 v[114:117], v[188:191], v[196:199], v[114:117]
	v_mfma_f32_16x16x32_bf16 v[118:121], v[180:183], v[196:199], v[118:121]
	s_barrier
	s_setprio 0
	s_mov_b32 m0, s15
	ds_read_b128 v[192:195], v179 offset:16384
	ds_read_b128 v[196:199], v179 offset:17408
	ds_read_b128 v[200:203], v179 offset:18432
	ds_read_b128 v[204:207], v179 offset:19456
	ds_read_b128 v[228:231], v179 offset:20480
	ds_read_b128 v[232:235], v179 offset:21504
	ds_read_b128 v[236:239], v179 offset:22528
	ds_read_b128 v[240:243], v179 offset:23552
	buffer_load_dwordx4 v175, s[60:63], s26 offen lds
	s_mov_b32 m0, s16
	s_add_i32 s34, s26, 0x80000
	buffer_load_dwordx4 v177, s[60:63], s26 offen lds
	s_mov_b32 m0, s18
	s_nop 0
	buffer_load_dwordx4 v175, s[60:63], s34 offen lds
	s_mov_b32 m0, s19
	s_nop 0
	buffer_load_dwordx4 v177, s[60:63], s34 offen lds
	s_mov_b32 m0, s14
	s_nop 0
	buffer_load_dwordx4 v174, s[44:47], s27 offen lds
	s_mov_b32 m0, s24
	s_nop 0
	buffer_load_dwordx4 v176, s[44:47], s27 offen lds
	s_waitcnt vmcnt(8)
	s_waitcnt lgkmcnt(0)
	s_setprio 1
	s_barrier
	v_mfma_f32_16x16x32_bf16 v[62:65], v[134:137], v[192:195], 0
	v_mfma_f32_16x16x32_bf16 v[58:61], v[142:145], v[192:195], 0
	v_mfma_f32_16x16x32_bf16 v[42:45], v[142:145], v[200:203], 0
	v_mfma_f32_16x16x32_bf16 v[46:49], v[134:137], v[200:203], 0
	v_mfma_f32_16x16x32_bf16 v[30:33], v[134:137], v[228:231], 0
	v_mfma_f32_16x16x32_bf16 v[26:29], v[142:145], v[228:231], 0
	v_mfma_f32_16x16x32_bf16 v[10:13], v[142:145], v[236:239], 0
	v_mfma_f32_16x16x32_bf16 v[14:17], v[134:137], v[236:239], 0
	v_mfma_f32_16x16x32_bf16 v[6:9], v[170:173], v[236:239], 0
	v_mfma_f32_16x16x32_bf16 v[2:5], v[184:187], v[236:239], 0
	v_mfma_f32_16x16x32_bf16 v[18:21], v[184:187], v[228:231], 0
	v_mfma_f32_16x16x32_bf16 v[22:25], v[170:173], v[228:231], 0
	v_mfma_f32_16x16x32_bf16 v[38:41], v[170:173], v[200:203], 0
	v_mfma_f32_16x16x32_bf16 v[34:37], v[184:187], v[200:203], 0
	v_mfma_f32_16x16x32_bf16 v[50:53], v[184:187], v[192:195], 0
	v_mfma_f32_16x16x32_bf16 v[54:57], v[170:173], v[192:195], 0
	v_mfma_f32_16x16x32_bf16 v[62:65], v[138:141], v[196:199], v[62:65]
	v_mfma_f32_16x16x32_bf16 v[58:61], v[154:157], v[196:199], v[58:61]
	v_mfma_f32_16x16x32_bf16 v[42:45], v[154:157], v[204:207], v[42:45]
	v_mfma_f32_16x16x32_bf16 v[46:49], v[138:141], v[204:207], v[46:49]
	v_mfma_f32_16x16x32_bf16 v[30:33], v[138:141], v[232:235], v[30:33]
	v_mfma_f32_16x16x32_bf16 v[26:29], v[154:157], v[232:235], v[26:29]
	v_mfma_f32_16x16x32_bf16 v[10:13], v[154:157], v[240:243], v[10:13]
	v_mfma_f32_16x16x32_bf16 v[14:17], v[138:141], v[240:243], v[14:17]
	v_mfma_f32_16x16x32_bf16 v[6:9], v[180:183], v[240:243], v[6:9]
	v_mfma_f32_16x16x32_bf16 v[2:5], v[188:191], v[240:243], v[2:5]
	v_mfma_f32_16x16x32_bf16 v[18:21], v[188:191], v[232:235], v[18:21]
	v_mfma_f32_16x16x32_bf16 v[22:25], v[180:183], v[232:235], v[22:25]
	v_mfma_f32_16x16x32_bf16 v[38:41], v[180:183], v[204:207], v[38:41]
	v_mfma_f32_16x16x32_bf16 v[34:37], v[188:191], v[204:207], v[34:37]
	v_mfma_f32_16x16x32_bf16 v[50:53], v[188:191], v[196:199], v[50:53]
	v_mfma_f32_16x16x32_bf16 v[54:57], v[180:183], v[196:199], v[54:57]
	s_barrier
	s_setprio 0
	v_add_u32_e32 v133, 0x18000, v178
	ds_read_b128 v[134:137], v133
	ds_read_b128 v[138:141], v133 offset:1024
	ds_read_b128 v[142:145], v133 offset:2048
	ds_read_b128 v[154:157], v133 offset:3072
	v_add_u32_e32 v133, 0x1c000, v178
	ds_read_b128 v[170:173], v133
	ds_read_b128 v[180:183], v133 offset:1024
	ds_read_b128 v[184:187], v133 offset:2048
	ds_read_b128 v[188:191], v133 offset:3072
	s_add_i32 s27, s27, 0x80000
	s_mov_b32 m0, s25
	ds_read_b128 v[192:195], v179 offset:32768
	ds_read_b128 v[196:199], v179 offset:33792
	ds_read_b128 v[200:203], v179 offset:34816
	ds_read_b128 v[204:207], v179 offset:35840
	ds_read_b128 v[228:231], v179 offset:36864
	ds_read_b128 v[232:235], v179 offset:37888
	ds_read_b128 v[236:239], v179 offset:38912
	ds_read_b128 v[240:243], v179 offset:39936
	buffer_load_dwordx4 v174, s[44:47], s27 offen lds
	s_mov_b32 m0, s30
	s_nop 0
	buffer_load_dwordx4 v176, s[44:47], s27 offen lds
	s_waitcnt vmcnt(8)
	s_waitcnt lgkmcnt(0)
	s_setprio 1
	s_barrier
	v_mfma_f32_16x16x32_bf16 v[126:129], v[134:137], v[192:195], v[126:129]
	v_mfma_f32_16x16x32_bf16 v[122:125], v[142:145], v[192:195], v[122:125]
	v_mfma_f32_16x16x32_bf16 v[106:109], v[142:145], v[200:203], v[106:109]
	v_mfma_f32_16x16x32_bf16 v[110:113], v[134:137], v[200:203], v[110:113]
	v_mfma_f32_16x16x32_bf16 v[94:97], v[134:137], v[228:231], v[94:97]
	v_mfma_f32_16x16x32_bf16 v[90:93], v[142:145], v[228:231], v[90:93]
	v_mfma_f32_16x16x32_bf16 v[74:77], v[142:145], v[236:239], v[74:77]
	v_mfma_f32_16x16x32_bf16 v[78:81], v[134:137], v[236:239], v[78:81]
	v_mfma_f32_16x16x32_bf16 v[70:73], v[170:173], v[236:239], v[70:73]
	v_mfma_f32_16x16x32_bf16 v[66:69], v[184:187], v[236:239], v[66:69]
	v_mfma_f32_16x16x32_bf16 v[82:85], v[184:187], v[228:231], v[82:85]
	v_mfma_f32_16x16x32_bf16 v[86:89], v[170:173], v[228:231], v[86:89]
	v_mfma_f32_16x16x32_bf16 v[102:105], v[170:173], v[200:203], v[102:105]
	v_mfma_f32_16x16x32_bf16 v[98:101], v[184:187], v[200:203], v[98:101]
	v_mfma_f32_16x16x32_bf16 v[114:117], v[184:187], v[192:195], v[114:117]
	v_mfma_f32_16x16x32_bf16 v[118:121], v[170:173], v[192:195], v[118:121]
	v_mfma_f32_16x16x32_bf16 v[126:129], v[138:141], v[196:199], v[126:129]
	v_mfma_f32_16x16x32_bf16 v[122:125], v[154:157], v[196:199], v[122:125]
	v_mfma_f32_16x16x32_bf16 v[106:109], v[154:157], v[204:207], v[106:109]
	v_mfma_f32_16x16x32_bf16 v[110:113], v[138:141], v[204:207], v[110:113]
	v_mfma_f32_16x16x32_bf16 v[94:97], v[138:141], v[232:235], v[94:97]
	v_mfma_f32_16x16x32_bf16 v[90:93], v[154:157], v[232:235], v[90:93]
	v_mfma_f32_16x16x32_bf16 v[74:77], v[154:157], v[240:243], v[74:77]
	v_mfma_f32_16x16x32_bf16 v[78:81], v[138:141], v[240:243], v[78:81]
	v_mfma_f32_16x16x32_bf16 v[70:73], v[180:183], v[240:243], v[70:73]
	v_mfma_f32_16x16x32_bf16 v[66:69], v[188:191], v[240:243], v[66:69]
	v_mfma_f32_16x16x32_bf16 v[82:85], v[188:191], v[232:235], v[82:85]
	v_mfma_f32_16x16x32_bf16 v[86:89], v[180:183], v[232:235], v[86:89]
	v_mfma_f32_16x16x32_bf16 v[102:105], v[180:183], v[204:207], v[102:105]
	v_mfma_f32_16x16x32_bf16 v[98:101], v[188:191], v[204:207], v[98:101]
	v_mfma_f32_16x16x32_bf16 v[114:117], v[188:191], v[196:199], v[114:117]
	v_mfma_f32_16x16x32_bf16 v[118:121], v[180:183], v[196:199], v[118:121]
	s_barrier
	s_setprio 0
	s_mov_b32 m0, s36
	s_or_b32 s27, s26, 0x80
	ds_read_b128 v[192:195], v179 offset:49152
	ds_read_b128 v[196:199], v179 offset:50176
	ds_read_b128 v[200:203], v179 offset:51200
	ds_read_b128 v[204:207], v179 offset:52224
	ds_read_b128 v[228:231], v179 offset:53248
	ds_read_b128 v[232:235], v179 offset:54272
	ds_read_b128 v[236:239], v179 offset:55296
	ds_read_b128 v[240:243], v179 offset:56320
	buffer_load_dwordx4 v175, s[60:63], s27 offen lds
	s_mov_b32 m0, s37
	s_add_i32 s26, s26, 0x80080
	buffer_load_dwordx4 v177, s[60:63], s27 offen lds
	s_mov_b32 m0, s48
	s_nop 0
	buffer_load_dwordx4 v175, s[60:63], s26 offen lds
	s_mov_b32 m0, s49
	s_nop 0
	buffer_load_dwordx4 v177, s[60:63], s26 offen lds
	s_mov_b32 m0, s40
	s_nop 0
	buffer_load_dwordx4 v174, s[44:47], s23 offen lds
	s_mov_b32 m0, s41
	s_nop 0
	buffer_load_dwordx4 v176, s[44:47], s23 offen lds
	s_waitcnt vmcnt(8)
	s_waitcnt lgkmcnt(0)
	s_setprio 1
	s_barrier
	v_mfma_f32_16x16x32_bf16 v[62:65], v[134:137], v[192:195], v[62:65]
	v_mfma_f32_16x16x32_bf16 v[58:61], v[142:145], v[192:195], v[58:61]
	v_mfma_f32_16x16x32_bf16 v[42:45], v[142:145], v[200:203], v[42:45]
	v_mfma_f32_16x16x32_bf16 v[46:49], v[134:137], v[200:203], v[46:49]
	v_mfma_f32_16x16x32_bf16 v[30:33], v[134:137], v[228:231], v[30:33]
	v_mfma_f32_16x16x32_bf16 v[26:29], v[142:145], v[228:231], v[26:29]
	v_mfma_f32_16x16x32_bf16 v[10:13], v[142:145], v[236:239], v[10:13]
	v_mfma_f32_16x16x32_bf16 v[14:17], v[134:137], v[236:239], v[14:17]
	v_mfma_f32_16x16x32_bf16 v[6:9], v[170:173], v[236:239], v[6:9]
	v_mfma_f32_16x16x32_bf16 v[2:5], v[184:187], v[236:239], v[2:5]
	v_mfma_f32_16x16x32_bf16 v[18:21], v[184:187], v[228:231], v[18:21]
	v_mfma_f32_16x16x32_bf16 v[22:25], v[170:173], v[228:231], v[22:25]
	v_mfma_f32_16x16x32_bf16 v[38:41], v[170:173], v[200:203], v[38:41]
	v_mfma_f32_16x16x32_bf16 v[34:37], v[184:187], v[200:203], v[34:37]
	v_mfma_f32_16x16x32_bf16 v[50:53], v[184:187], v[192:195], v[50:53]
	v_mfma_f32_16x16x32_bf16 v[54:57], v[170:173], v[192:195], v[54:57]
	v_mfma_f32_16x16x32_bf16 v[62:65], v[138:141], v[196:199], v[62:65]
	v_mfma_f32_16x16x32_bf16 v[58:61], v[154:157], v[196:199], v[58:61]
	v_mfma_f32_16x16x32_bf16 v[42:45], v[154:157], v[204:207], v[42:45]
	v_mfma_f32_16x16x32_bf16 v[46:49], v[138:141], v[204:207], v[46:49]
	v_mfma_f32_16x16x32_bf16 v[30:33], v[138:141], v[232:235], v[30:33]
	v_mfma_f32_16x16x32_bf16 v[26:29], v[154:157], v[232:235], v[26:29]
	v_mfma_f32_16x16x32_bf16 v[10:13], v[154:157], v[240:243], v[10:13]
	v_mfma_f32_16x16x32_bf16 v[14:17], v[138:141], v[240:243], v[14:17]
	v_mfma_f32_16x16x32_bf16 v[6:9], v[180:183], v[240:243], v[6:9]
	v_mfma_f32_16x16x32_bf16 v[2:5], v[188:191], v[240:243], v[2:5]
	v_mfma_f32_16x16x32_bf16 v[18:21], v[188:191], v[232:235], v[18:21]
	v_mfma_f32_16x16x32_bf16 v[22:25], v[180:183], v[232:235], v[22:25]
	v_mfma_f32_16x16x32_bf16 v[38:41], v[180:183], v[204:207], v[38:41]
	v_mfma_f32_16x16x32_bf16 v[34:37], v[188:191], v[204:207], v[34:37]
	v_mfma_f32_16x16x32_bf16 v[50:53], v[188:191], v[196:199], v[50:53]
	v_mfma_f32_16x16x32_bf16 v[54:57], v[180:183], v[196:199], v[54:57]
	s_barrier
	s_setprio 0
	s_add_i32 s22, s22, 2
	s_addk_i32 s13, 0x100
	s_addk_i32 s21, 0x100
	s_cmp_gt_u32 s22, 29
.LBB0_905:
	v_add_u32_e32 v133, 0x10000, v178
	ds_read_b128 v[134:137], v133
	ds_read_b128 v[138:141], v133 offset:1024
	ds_read_b128 v[142:145], v133 offset:2048
	ds_read_b128 v[154:157], v133 offset:3072
	v_add_u32_e32 v133, 0x14000, v178
	ds_read_b128 v[170:173], v133
	ds_read_b128 v[180:183], v133 offset:1024
	ds_read_b128 v[184:187], v133 offset:2048
	ds_read_b128 v[188:191], v133 offset:3072
	s_add_i32 s23, s13, 0xfff80080
	s_cmp_eq_u32 s22, 28
	s_cselect_b32 s27, s8, s23
	s_cselect_b32 s26, s9, s21
	s_or_b32 s23, s27, 0x80
	s_mov_b32 s46, s62
	s_mov_b32 s47, s63
	s_mov_b32 m0, s68
	ds_read_b128 v[192:195], v179
	ds_read_b128 v[196:199], v179 offset:1024
	ds_read_b128 v[200:203], v179 offset:2048
	ds_read_b128 v[204:207], v179 offset:3072
	ds_read_b128 v[228:231], v179 offset:4096
	ds_read_b128 v[232:235], v179 offset:5120
	ds_read_b128 v[236:239], v179 offset:6144
	ds_read_b128 v[240:243], v179 offset:7168
	buffer_load_dwordx4 v174, s[44:47], s13 offen lds
	s_mov_b32 m0, s69
	s_nop 0
	buffer_load_dwordx4 v176, s[44:47], s13 offen lds
	s_waitcnt vmcnt(8)
	s_waitcnt lgkmcnt(0)
	s_setprio 1
	s_barrier
	v_mfma_f32_16x16x32_bf16 v[126:129], v[134:137], v[192:195], v[126:129]
	v_mfma_f32_16x16x32_bf16 v[122:125], v[142:145], v[192:195], v[122:125]
	v_mfma_f32_16x16x32_bf16 v[106:109], v[142:145], v[200:203], v[106:109]
	v_mfma_f32_16x16x32_bf16 v[110:113], v[134:137], v[200:203], v[110:113]
	v_mfma_f32_16x16x32_bf16 v[94:97], v[134:137], v[228:231], v[94:97]
	v_mfma_f32_16x16x32_bf16 v[90:93], v[142:145], v[228:231], v[90:93]
	v_mfma_f32_16x16x32_bf16 v[74:77], v[142:145], v[236:239], v[74:77]
	v_mfma_f32_16x16x32_bf16 v[78:81], v[134:137], v[236:239], v[78:81]
	v_mfma_f32_16x16x32_bf16 v[70:73], v[170:173], v[236:239], v[70:73]
	v_mfma_f32_16x16x32_bf16 v[66:69], v[184:187], v[236:239], v[66:69]
	v_mfma_f32_16x16x32_bf16 v[82:85], v[184:187], v[228:231], v[82:85]
	v_mfma_f32_16x16x32_bf16 v[86:89], v[170:173], v[228:231], v[86:89]
	v_mfma_f32_16x16x32_bf16 v[102:105], v[170:173], v[200:203], v[102:105]
	v_mfma_f32_16x16x32_bf16 v[98:101], v[184:187], v[200:203], v[98:101]
	v_mfma_f32_16x16x32_bf16 v[114:117], v[184:187], v[192:195], v[114:117]
	v_mfma_f32_16x16x32_bf16 v[118:121], v[170:173], v[192:195], v[118:121]
	v_mfma_f32_16x16x32_bf16 v[126:129], v[138:141], v[196:199], v[126:129]
	v_mfma_f32_16x16x32_bf16 v[122:125], v[154:157], v[196:199], v[122:125]
	v_mfma_f32_16x16x32_bf16 v[106:109], v[154:157], v[204:207], v[106:109]
	v_mfma_f32_16x16x32_bf16 v[110:113], v[138:141], v[204:207], v[110:113]
	v_mfma_f32_16x16x32_bf16 v[94:97], v[138:141], v[232:235], v[94:97]
	v_mfma_f32_16x16x32_bf16 v[90:93], v[154:157], v[232:235], v[90:93]
	v_mfma_f32_16x16x32_bf16 v[74:77], v[154:157], v[240:243], v[74:77]
	v_mfma_f32_16x16x32_bf16 v[78:81], v[138:141], v[240:243], v[78:81]
	v_mfma_f32_16x16x32_bf16 v[70:73], v[180:183], v[240:243], v[70:73]
	v_mfma_f32_16x16x32_bf16 v[66:69], v[188:191], v[240:243], v[66:69]
	v_mfma_f32_16x16x32_bf16 v[82:85], v[188:191], v[232:235], v[82:85]
	v_mfma_f32_16x16x32_bf16 v[86:89], v[180:183], v[232:235], v[86:89]
	v_mfma_f32_16x16x32_bf16 v[102:105], v[180:183], v[204:207], v[102:105]
	v_mfma_f32_16x16x32_bf16 v[98:101], v[188:191], v[204:207], v[98:101]
	v_mfma_f32_16x16x32_bf16 v[114:117], v[188:191], v[196:199], v[114:117]
	v_mfma_f32_16x16x32_bf16 v[118:121], v[180:183], v[196:199], v[118:121]
	s_barrier
	s_setprio 0
	s_mov_b32 m0, s15
	ds_read_b128 v[192:195], v179 offset:16384
	ds_read_b128 v[196:199], v179 offset:17408
	ds_read_b128 v[200:203], v179 offset:18432
	ds_read_b128 v[204:207], v179 offset:19456
	ds_read_b128 v[228:231], v179 offset:20480
	ds_read_b128 v[232:235], v179 offset:21504
	ds_read_b128 v[236:239], v179 offset:22528
	ds_read_b128 v[240:243], v179 offset:23552
	buffer_load_dwordx4 v175, s[60:63], s26 offen lds
	s_mov_b32 m0, s16
	s_add_i32 s34, s26, 0x80000
	buffer_load_dwordx4 v177, s[60:63], s26 offen lds
	s_mov_b32 m0, s18
	s_nop 0
	buffer_load_dwordx4 v175, s[60:63], s34 offen lds
	s_mov_b32 m0, s19
	s_nop 0
	buffer_load_dwordx4 v177, s[60:63], s34 offen lds
	s_mov_b32 m0, s14
	s_nop 0
	buffer_load_dwordx4 v174, s[44:47], s27 offen lds
	s_mov_b32 m0, s24
	s_nop 0
	buffer_load_dwordx4 v176, s[44:47], s27 offen lds
	s_waitcnt vmcnt(8)
	s_waitcnt lgkmcnt(0)
	s_setprio 1
	s_barrier
	v_mfma_f32_16x16x32_bf16 v[62:65], v[134:137], v[192:195], v[62:65]
	v_mfma_f32_16x16x32_bf16 v[58:61], v[142:145], v[192:195], v[58:61]
	v_mfma_f32_16x16x32_bf16 v[42:45], v[142:145], v[200:203], v[42:45]
	v_mfma_f32_16x16x32_bf16 v[46:49], v[134:137], v[200:203], v[46:49]
	v_mfma_f32_16x16x32_bf16 v[30:33], v[134:137], v[228:231], v[30:33]
	v_mfma_f32_16x16x32_bf16 v[26:29], v[142:145], v[228:231], v[26:29]
	v_mfma_f32_16x16x32_bf16 v[10:13], v[142:145], v[236:239], v[10:13]
	v_mfma_f32_16x16x32_bf16 v[14:17], v[134:137], v[236:239], v[14:17]
	v_mfma_f32_16x16x32_bf16 v[6:9], v[170:173], v[236:239], v[6:9]
	v_mfma_f32_16x16x32_bf16 v[2:5], v[184:187], v[236:239], v[2:5]
	v_mfma_f32_16x16x32_bf16 v[18:21], v[184:187], v[228:231], v[18:21]
	v_mfma_f32_16x16x32_bf16 v[22:25], v[170:173], v[228:231], v[22:25]
	v_mfma_f32_16x16x32_bf16 v[38:41], v[170:173], v[200:203], v[38:41]
	v_mfma_f32_16x16x32_bf16 v[34:37], v[184:187], v[200:203], v[34:37]
	v_mfma_f32_16x16x32_bf16 v[50:53], v[184:187], v[192:195], v[50:53]
	v_mfma_f32_16x16x32_bf16 v[54:57], v[170:173], v[192:195], v[54:57]
	v_mfma_f32_16x16x32_bf16 v[62:65], v[138:141], v[196:199], v[62:65]
	v_mfma_f32_16x16x32_bf16 v[58:61], v[154:157], v[196:199], v[58:61]
	v_mfma_f32_16x16x32_bf16 v[42:45], v[154:157], v[204:207], v[42:45]
	v_mfma_f32_16x16x32_bf16 v[46:49], v[138:141], v[204:207], v[46:49]
	v_mfma_f32_16x16x32_bf16 v[30:33], v[138:141], v[232:235], v[30:33]
	v_mfma_f32_16x16x32_bf16 v[26:29], v[154:157], v[232:235], v[26:29]
	v_mfma_f32_16x16x32_bf16 v[10:13], v[154:157], v[240:243], v[10:13]
	v_mfma_f32_16x16x32_bf16 v[14:17], v[138:141], v[240:243], v[14:17]
	v_mfma_f32_16x16x32_bf16 v[6:9], v[180:183], v[240:243], v[6:9]
	v_mfma_f32_16x16x32_bf16 v[2:5], v[188:191], v[240:243], v[2:5]
	v_mfma_f32_16x16x32_bf16 v[18:21], v[188:191], v[232:235], v[18:21]
	v_mfma_f32_16x16x32_bf16 v[22:25], v[180:183], v[232:235], v[22:25]
	v_mfma_f32_16x16x32_bf16 v[38:41], v[180:183], v[204:207], v[38:41]
	v_mfma_f32_16x16x32_bf16 v[34:37], v[188:191], v[204:207], v[34:37]
	v_mfma_f32_16x16x32_bf16 v[50:53], v[188:191], v[196:199], v[50:53]
	v_mfma_f32_16x16x32_bf16 v[54:57], v[180:183], v[196:199], v[54:57]
	s_barrier
	s_setprio 0
	v_add_u32_e32 v133, 0x18000, v178
	ds_read_b128 v[134:137], v133
	ds_read_b128 v[138:141], v133 offset:1024
	ds_read_b128 v[142:145], v133 offset:2048
	ds_read_b128 v[154:157], v133 offset:3072
	v_add_u32_e32 v133, 0x1c000, v178
	ds_read_b128 v[170:173], v133
	ds_read_b128 v[180:183], v133 offset:1024
	ds_read_b128 v[184:187], v133 offset:2048
	ds_read_b128 v[188:191], v133 offset:3072
	s_add_i32 s27, s27, 0x80000
	s_mov_b32 m0, s25
	ds_read_b128 v[192:195], v179 offset:32768
	ds_read_b128 v[196:199], v179 offset:33792
	ds_read_b128 v[200:203], v179 offset:34816
	ds_read_b128 v[204:207], v179 offset:35840
	ds_read_b128 v[228:231], v179 offset:36864
	ds_read_b128 v[232:235], v179 offset:37888
	ds_read_b128 v[236:239], v179 offset:38912
	ds_read_b128 v[240:243], v179 offset:39936
	buffer_load_dwordx4 v174, s[44:47], s27 offen lds
	s_mov_b32 m0, s30
	s_nop 0
	buffer_load_dwordx4 v176, s[44:47], s27 offen lds
	s_waitcnt vmcnt(8)
	s_waitcnt lgkmcnt(0)
	s_setprio 1
	s_barrier
	v_mfma_f32_16x16x32_bf16 v[126:129], v[134:137], v[192:195], v[126:129]
	v_mfma_f32_16x16x32_bf16 v[122:125], v[142:145], v[192:195], v[122:125]
	v_mfma_f32_16x16x32_bf16 v[106:109], v[142:145], v[200:203], v[106:109]
	v_mfma_f32_16x16x32_bf16 v[110:113], v[134:137], v[200:203], v[110:113]
	v_mfma_f32_16x16x32_bf16 v[94:97], v[134:137], v[228:231], v[94:97]
	v_mfma_f32_16x16x32_bf16 v[90:93], v[142:145], v[228:231], v[90:93]
	v_mfma_f32_16x16x32_bf16 v[74:77], v[142:145], v[236:239], v[74:77]
	v_mfma_f32_16x16x32_bf16 v[78:81], v[134:137], v[236:239], v[78:81]
	v_mfma_f32_16x16x32_bf16 v[70:73], v[170:173], v[236:239], v[70:73]
	v_mfma_f32_16x16x32_bf16 v[66:69], v[184:187], v[236:239], v[66:69]
	v_mfma_f32_16x16x32_bf16 v[82:85], v[184:187], v[228:231], v[82:85]
	v_mfma_f32_16x16x32_bf16 v[86:89], v[170:173], v[228:231], v[86:89]
	v_mfma_f32_16x16x32_bf16 v[102:105], v[170:173], v[200:203], v[102:105]
	v_mfma_f32_16x16x32_bf16 v[98:101], v[184:187], v[200:203], v[98:101]
	v_mfma_f32_16x16x32_bf16 v[114:117], v[184:187], v[192:195], v[114:117]
	v_mfma_f32_16x16x32_bf16 v[118:121], v[170:173], v[192:195], v[118:121]
	v_mfma_f32_16x16x32_bf16 v[126:129], v[138:141], v[196:199], v[126:129]
	v_mfma_f32_16x16x32_bf16 v[122:125], v[154:157], v[196:199], v[122:125]
	v_mfma_f32_16x16x32_bf16 v[106:109], v[154:157], v[204:207], v[106:109]
	v_mfma_f32_16x16x32_bf16 v[110:113], v[138:141], v[204:207], v[110:113]
	v_mfma_f32_16x16x32_bf16 v[94:97], v[138:141], v[232:235], v[94:97]
	v_mfma_f32_16x16x32_bf16 v[90:93], v[154:157], v[232:235], v[90:93]
	v_mfma_f32_16x16x32_bf16 v[74:77], v[154:157], v[240:243], v[74:77]
	v_mfma_f32_16x16x32_bf16 v[78:81], v[138:141], v[240:243], v[78:81]
	v_mfma_f32_16x16x32_bf16 v[70:73], v[180:183], v[240:243], v[70:73]
	v_mfma_f32_16x16x32_bf16 v[66:69], v[188:191], v[240:243], v[66:69]
	v_mfma_f32_16x16x32_bf16 v[82:85], v[188:191], v[232:235], v[82:85]
	v_mfma_f32_16x16x32_bf16 v[86:89], v[180:183], v[232:235], v[86:89]
	v_mfma_f32_16x16x32_bf16 v[102:105], v[180:183], v[204:207], v[102:105]
	v_mfma_f32_16x16x32_bf16 v[98:101], v[188:191], v[204:207], v[98:101]
	v_mfma_f32_16x16x32_bf16 v[114:117], v[188:191], v[196:199], v[114:117]
	v_mfma_f32_16x16x32_bf16 v[118:121], v[180:183], v[196:199], v[118:121]
	s_barrier
	s_setprio 0
	s_mov_b32 m0, s36
	s_or_b32 s27, s26, 0x80
	ds_read_b128 v[192:195], v179 offset:49152
	ds_read_b128 v[196:199], v179 offset:50176
	ds_read_b128 v[200:203], v179 offset:51200
	ds_read_b128 v[204:207], v179 offset:52224
	ds_read_b128 v[228:231], v179 offset:53248
	ds_read_b128 v[232:235], v179 offset:54272
	ds_read_b128 v[236:239], v179 offset:55296
	ds_read_b128 v[240:243], v179 offset:56320
	buffer_load_dwordx4 v175, s[60:63], s27 offen lds
	s_mov_b32 m0, s37
	s_add_i32 s26, s26, 0x80080
	buffer_load_dwordx4 v177, s[60:63], s27 offen lds
	s_mov_b32 m0, s48
	s_nop 0
	buffer_load_dwordx4 v175, s[60:63], s26 offen lds
	s_mov_b32 m0, s49
	s_nop 0
	buffer_load_dwordx4 v177, s[60:63], s26 offen lds
	s_mov_b32 m0, s40
	s_nop 0
	buffer_load_dwordx4 v174, s[44:47], s23 offen lds
	s_mov_b32 m0, s41
	s_nop 0
	buffer_load_dwordx4 v176, s[44:47], s23 offen lds
	s_waitcnt vmcnt(8)
	s_waitcnt lgkmcnt(0)
	s_setprio 1
	s_barrier
	v_mfma_f32_16x16x32_bf16 v[62:65], v[134:137], v[192:195], v[62:65]
	v_mfma_f32_16x16x32_bf16 v[58:61], v[142:145], v[192:195], v[58:61]
	v_mfma_f32_16x16x32_bf16 v[42:45], v[142:145], v[200:203], v[42:45]
	v_mfma_f32_16x16x32_bf16 v[46:49], v[134:137], v[200:203], v[46:49]
	v_mfma_f32_16x16x32_bf16 v[30:33], v[134:137], v[228:231], v[30:33]
	v_mfma_f32_16x16x32_bf16 v[26:29], v[142:145], v[228:231], v[26:29]
	v_mfma_f32_16x16x32_bf16 v[10:13], v[142:145], v[236:239], v[10:13]
	v_mfma_f32_16x16x32_bf16 v[14:17], v[134:137], v[236:239], v[14:17]
	v_mfma_f32_16x16x32_bf16 v[6:9], v[170:173], v[236:239], v[6:9]
	v_mfma_f32_16x16x32_bf16 v[2:5], v[184:187], v[236:239], v[2:5]
	v_mfma_f32_16x16x32_bf16 v[18:21], v[184:187], v[228:231], v[18:21]
	v_mfma_f32_16x16x32_bf16 v[22:25], v[170:173], v[228:231], v[22:25]
	v_mfma_f32_16x16x32_bf16 v[38:41], v[170:173], v[200:203], v[38:41]
	v_mfma_f32_16x16x32_bf16 v[34:37], v[184:187], v[200:203], v[34:37]
	v_mfma_f32_16x16x32_bf16 v[50:53], v[184:187], v[192:195], v[50:53]
	v_mfma_f32_16x16x32_bf16 v[54:57], v[170:173], v[192:195], v[54:57]
	v_mfma_f32_16x16x32_bf16 v[62:65], v[138:141], v[196:199], v[62:65]
	v_mfma_f32_16x16x32_bf16 v[58:61], v[154:157], v[196:199], v[58:61]
	v_mfma_f32_16x16x32_bf16 v[42:45], v[154:157], v[204:207], v[42:45]
	v_mfma_f32_16x16x32_bf16 v[46:49], v[138:141], v[204:207], v[46:49]
	v_mfma_f32_16x16x32_bf16 v[30:33], v[138:141], v[232:235], v[30:33]
	v_mfma_f32_16x16x32_bf16 v[26:29], v[154:157], v[232:235], v[26:29]
	v_mfma_f32_16x16x32_bf16 v[10:13], v[154:157], v[240:243], v[10:13]
	v_mfma_f32_16x16x32_bf16 v[14:17], v[138:141], v[240:243], v[14:17]
	v_mfma_f32_16x16x32_bf16 v[6:9], v[180:183], v[240:243], v[6:9]
	v_mfma_f32_16x16x32_bf16 v[2:5], v[188:191], v[240:243], v[2:5]
	v_mfma_f32_16x16x32_bf16 v[18:21], v[188:191], v[232:235], v[18:21]
	v_mfma_f32_16x16x32_bf16 v[22:25], v[180:183], v[232:235], v[22:25]
	v_mfma_f32_16x16x32_bf16 v[38:41], v[180:183], v[204:207], v[38:41]
	v_mfma_f32_16x16x32_bf16 v[34:37], v[188:191], v[204:207], v[34:37]
	v_mfma_f32_16x16x32_bf16 v[50:53], v[188:191], v[196:199], v[50:53]
	v_mfma_f32_16x16x32_bf16 v[54:57], v[180:183], v[196:199], v[54:57]
	s_barrier
	s_setprio 0
	s_add_i32 s22, s22, 2
	s_addk_i32 s13, 0x100
	s_addk_i32 s21, 0x100
	s_cmp_gt_u32 s22, 29
	s_cbranch_scc0 .LBB0_905
	s_and_b64 vcc, exec, s[64:65]
	s_cbranch_vccz .LBB0_908
	s_barrier

.LBB0_1192:
	s_lshl_b32 s12, s70, 22
	s_and_b64 s[8:9], s[26:27], exec
	s_cselect_b32 s8, s12, s30
	s_lshl_b32 s22, s71, 22
	s_and_b64 s[66:67], s[26:27], exec
	s_cselect_b32 s9, s22, s31
	s_add_i32 s30, s30, 0x200080
	s_addk_i32 s31, 0x100
	s_mov_b32 s72, -2
	v_add_u32_e32 v141, 0x10000, v139
	ds_read_b128 v[142:145], v141
	ds_read_b128 v[154:157], v141 offset:1024
	ds_read_b128 v[170:173], v141 offset:2048
	ds_read_b128 v[174:177], v141 offset:3072
	v_add_u32_e32 v141, 0x14000, v139
	ds_read_b128 v[178:181], v141
	ds_read_b128 v[182:185], v141 offset:1024
	ds_read_b128 v[186:189], v141 offset:2048
	ds_read_b128 v[190:193], v141 offset:3072
	s_add_i32 s52, s30, 0xffe00080
	s_cmpk_eq_i32 s72, 0x7c
	s_cselect_b32 s52, s8, s52
	s_cselect_b32 s82, s9, s31
	s_or_b32 s73, s52, 0x80
	s_mov_b32 m0, s69
	ds_read_b128 v[194:197], v140
	ds_read_b128 v[198:201], v140 offset:1024
	ds_read_b128 v[202:205], v140 offset:2048
	ds_read_b128 v[228:231], v140 offset:3072
	ds_read_b128 v[232:235], v140 offset:4096
	ds_read_b128 v[236:239], v140 offset:5120
	ds_read_b128 v[240:243], v140 offset:6144
	ds_read_b128 v[244:247], v140 offset:7168
	buffer_load_dwordx4 v131, s[60:63], s30 offen lds
	s_mov_b32 m0, s46
	s_nop 0
	buffer_load_dwordx4 v135, s[60:63], s30 offen lds
	s_waitcnt vmcnt(8)
	s_waitcnt lgkmcnt(0)
	s_setprio 1
	s_barrier
	v_mfma_f32_16x16x32_bf16 v[126:129], v[142:145], v[194:197], 0
	v_mfma_f32_16x16x32_bf16 v[122:125], v[170:173], v[194:197], 0
	v_mfma_f32_16x16x32_bf16 v[114:117], v[170:173], v[202:205], 0
	v_mfma_f32_16x16x32_bf16 v[118:121], v[142:145], v[202:205], 0
	v_mfma_f32_16x16x32_bf16 v[110:113], v[142:145], v[232:235], 0
	v_mfma_f32_16x16x32_bf16 v[106:109], v[170:173], v[232:235], 0
	v_mfma_f32_16x16x32_bf16 v[98:101], v[170:173], v[240:243], 0
	v_mfma_f32_16x16x32_bf16 v[102:105], v[142:145], v[240:243], 0
	v_mfma_f32_16x16x32_bf16 v[38:41], v[178:181], v[240:243], 0
	v_mfma_f32_16x16x32_bf16 v[34:37], v[186:189], v[240:243], 0
	v_mfma_f32_16x16x32_bf16 v[42:45], v[186:189], v[232:235], 0
	v_mfma_f32_16x16x32_bf16 v[46:49], v[178:181], v[232:235], 0
	v_mfma_f32_16x16x32_bf16 v[54:57], v[178:181], v[202:205], 0
	v_mfma_f32_16x16x32_bf16 v[50:53], v[186:189], v[202:205], 0
	v_mfma_f32_16x16x32_bf16 v[58:61], v[186:189], v[194:197], 0
	v_mfma_f32_16x16x32_bf16 v[62:65], v[178:181], v[194:197], 0
	v_mfma_f32_16x16x32_bf16 v[126:129], v[154:157], v[198:201], v[126:129]
	v_mfma_f32_16x16x32_bf16 v[122:125], v[174:177], v[198:201], v[122:125]
	v_mfma_f32_16x16x32_bf16 v[114:117], v[174:177], v[228:231], v[114:117]
	v_mfma_f32_16x16x32_bf16 v[118:121], v[154:157], v[228:231], v[118:121]
	v_mfma_f32_16x16x32_bf16 v[110:113], v[154:157], v[236:239], v[110:113]
	v_mfma_f32_16x16x32_bf16 v[106:109], v[174:177], v[236:239], v[106:109]
	v_mfma_f32_16x16x32_bf16 v[98:101], v[174:177], v[244:247], v[98:101]
	v_mfma_f32_16x16x32_bf16 v[102:105], v[154:157], v[244:247], v[102:105]
	v_mfma_f32_16x16x32_bf16 v[38:41], v[182:185], v[244:247], v[38:41]
	v_mfma_f32_16x16x32_bf16 v[34:37], v[190:193], v[244:247], v[34:37]
	v_mfma_f32_16x16x32_bf16 v[42:45], v[190:193], v[236:239], v[42:45]
	v_mfma_f32_16x16x32_bf16 v[46:49], v[182:185], v[236:239], v[46:49]
	v_mfma_f32_16x16x32_bf16 v[54:57], v[182:185], v[228:231], v[54:57]
	v_mfma_f32_16x16x32_bf16 v[50:53], v[190:193], v[228:231], v[50:53]
	v_mfma_f32_16x16x32_bf16 v[58:61], v[190:193], v[198:201], v[58:61]
	v_mfma_f32_16x16x32_bf16 v[62:65], v[182:185], v[198:201], v[62:65]
	s_barrier
	s_setprio 0
	s_mov_b32 m0, s15
	s_mov_b32 s66, s62
	s_mov_b32 s67, s63
	ds_read_b128 v[194:197], v140 offset:16384
	ds_read_b128 v[198:201], v140 offset:17408
	ds_read_b128 v[202:205], v140 offset:18432
	ds_read_b128 v[228:231], v140 offset:19456
	ds_read_b128 v[232:235], v140 offset:20480
	ds_read_b128 v[236:239], v140 offset:21504
	ds_read_b128 v[240:243], v140 offset:22528
	ds_read_b128 v[244:247], v140 offset:23552
	buffer_load_dwordx4 v134, s[64:67], s82 offen lds
	s_mov_b32 m0, s16
	s_add_i32 s53, s82, 0x200000
	buffer_load_dwordx4 v136, s[64:67], s82 offen lds
	s_mov_b32 m0, s21
	s_nop 0
	buffer_load_dwordx4 v134, s[64:67], s53 offen lds
	s_mov_b32 m0, s23
	s_nop 0
	buffer_load_dwordx4 v136, s[64:67], s53 offen lds
	s_mov_b32 m0, s2
	s_nop 0
	buffer_load_dwordx4 v131, s[60:63], s52 offen lds
	s_mov_b32 m0, s24
	s_nop 0
	buffer_load_dwordx4 v135, s[60:63], s52 offen lds
	s_waitcnt vmcnt(8)
	s_waitcnt lgkmcnt(0)
	s_setprio 1
	s_barrier
	v_mfma_f32_16x16x32_bf16 v[94:97], v[142:145], v[194:197], 0
	v_mfma_f32_16x16x32_bf16 v[90:93], v[170:173], v[194:197], 0
	v_mfma_f32_16x16x32_bf16 v[82:85], v[170:173], v[202:205], 0
	v_mfma_f32_16x16x32_bf16 v[86:89], v[142:145], v[202:205], 0
	v_mfma_f32_16x16x32_bf16 v[78:81], v[142:145], v[232:235], 0
	v_mfma_f32_16x16x32_bf16 v[74:77], v[170:173], v[232:235], 0
	v_mfma_f32_16x16x32_bf16 v[66:69], v[170:173], v[240:243], 0
	v_mfma_f32_16x16x32_bf16 v[70:73], v[142:145], v[240:243], 0
	v_mfma_f32_16x16x32_bf16 v[6:9], v[178:181], v[240:243], 0
	v_mfma_f32_16x16x32_bf16 v[2:5], v[186:189], v[240:243], 0
	v_mfma_f32_16x16x32_bf16 v[10:13], v[186:189], v[232:235], 0
	v_mfma_f32_16x16x32_bf16 v[14:17], v[178:181], v[232:235], 0
	v_mfma_f32_16x16x32_bf16 v[22:25], v[178:181], v[202:205], 0
	v_mfma_f32_16x16x32_bf16 v[18:21], v[186:189], v[202:205], 0
	v_mfma_f32_16x16x32_bf16 v[26:29], v[186:189], v[194:197], 0
	v_mfma_f32_16x16x32_bf16 v[30:33], v[178:181], v[194:197], 0
	v_mfma_f32_16x16x32_bf16 v[94:97], v[154:157], v[198:201], v[94:97]
	v_mfma_f32_16x16x32_bf16 v[90:93], v[174:177], v[198:201], v[90:93]
	v_mfma_f32_16x16x32_bf16 v[82:85], v[174:177], v[228:231], v[82:85]
	v_mfma_f32_16x16x32_bf16 v[86:89], v[154:157], v[228:231], v[86:89]
	v_mfma_f32_16x16x32_bf16 v[78:81], v[154:157], v[236:239], v[78:81]
	v_mfma_f32_16x16x32_bf16 v[74:77], v[174:177], v[236:239], v[74:77]
	v_mfma_f32_16x16x32_bf16 v[66:69], v[174:177], v[244:247], v[66:69]
	v_mfma_f32_16x16x32_bf16 v[70:73], v[154:157], v[244:247], v[70:73]
	v_mfma_f32_16x16x32_bf16 v[6:9], v[182:185], v[244:247], v[6:9]
	v_mfma_f32_16x16x32_bf16 v[2:5], v[190:193], v[244:247], v[2:5]
	v_mfma_f32_16x16x32_bf16 v[10:13], v[190:193], v[236:239], v[10:13]
	v_mfma_f32_16x16x32_bf16 v[14:17], v[182:185], v[236:239], v[14:17]
	v_mfma_f32_16x16x32_bf16 v[22:25], v[182:185], v[228:231], v[22:25]
	v_mfma_f32_16x16x32_bf16 v[18:21], v[190:193], v[228:231], v[18:21]
	v_mfma_f32_16x16x32_bf16 v[26:29], v[190:193], v[198:201], v[26:29]
	v_mfma_f32_16x16x32_bf16 v[30:33], v[182:185], v[198:201], v[30:33]
	s_barrier
	s_setprio 0
	v_add_u32_e32 v141, 0x18000, v139
	ds_read_b128 v[142:145], v141
	ds_read_b128 v[154:157], v141 offset:1024
	ds_read_b128 v[170:173], v141 offset:2048
	ds_read_b128 v[174:177], v141 offset:3072
	v_add_u32_e32 v141, 0x1c000, v139
	ds_read_b128 v[178:181], v141
	ds_read_b128 v[182:185], v141 offset:1024
	ds_read_b128 v[186:189], v141 offset:2048
	ds_read_b128 v[190:193], v141 offset:3072
	s_add_i32 s52, s52, 0x200000
	s_mov_b32 m0, s25
	ds_read_b128 v[194:197], v140 offset:32768
	ds_read_b128 v[198:201], v140 offset:33792
	ds_read_b128 v[202:205], v140 offset:34816
	ds_read_b128 v[228:231], v140 offset:35840
	ds_read_b128 v[232:235], v140 offset:36864
	ds_read_b128 v[236:239], v140 offset:37888
	ds_read_b128 v[240:243], v140 offset:38912
	ds_read_b128 v[244:247], v140 offset:39936
	buffer_load_dwordx4 v131, s[60:63], s52 offen lds
	s_mov_b32 m0, s33
	s_nop 0
	buffer_load_dwordx4 v135, s[60:63], s52 offen lds
	s_waitcnt vmcnt(8)
	s_waitcnt lgkmcnt(0)
	s_setprio 1
	s_barrier
	v_mfma_f32_16x16x32_bf16 v[126:129], v[142:145], v[194:197], v[126:129]
	v_mfma_f32_16x16x32_bf16 v[122:125], v[170:173], v[194:197], v[122:125]
	v_mfma_f32_16x16x32_bf16 v[114:117], v[170:173], v[202:205], v[114:117]
	v_mfma_f32_16x16x32_bf16 v[118:121], v[142:145], v[202:205], v[118:121]
	v_mfma_f32_16x16x32_bf16 v[110:113], v[142:145], v[232:235], v[110:113]
	v_mfma_f32_16x16x32_bf16 v[106:109], v[170:173], v[232:235], v[106:109]
	v_mfma_f32_16x16x32_bf16 v[98:101], v[170:173], v[240:243], v[98:101]
	v_mfma_f32_16x16x32_bf16 v[102:105], v[142:145], v[240:243], v[102:105]
	v_mfma_f32_16x16x32_bf16 v[38:41], v[178:181], v[240:243], v[38:41]
	v_mfma_f32_16x16x32_bf16 v[34:37], v[186:189], v[240:243], v[34:37]
	v_mfma_f32_16x16x32_bf16 v[42:45], v[186:189], v[232:235], v[42:45]
	v_mfma_f32_16x16x32_bf16 v[46:49], v[178:181], v[232:235], v[46:49]
	v_mfma_f32_16x16x32_bf16 v[54:57], v[178:181], v[202:205], v[54:57]
	v_mfma_f32_16x16x32_bf16 v[50:53], v[186:189], v[202:205], v[50:53]
	v_mfma_f32_16x16x32_bf16 v[58:61], v[186:189], v[194:197], v[58:61]
	v_mfma_f32_16x16x32_bf16 v[62:65], v[178:181], v[194:197], v[62:65]
	v_mfma_f32_16x16x32_bf16 v[126:129], v[154:157], v[198:201], v[126:129]
	v_mfma_f32_16x16x32_bf16 v[122:125], v[174:177], v[198:201], v[122:125]
	v_mfma_f32_16x16x32_bf16 v[114:117], v[174:177], v[228:231], v[114:117]
	v_mfma_f32_16x16x32_bf16 v[118:121], v[154:157], v[228:231], v[118:121]
	v_mfma_f32_16x16x32_bf16 v[110:113], v[154:157], v[236:239], v[110:113]
	v_mfma_f32_16x16x32_bf16 v[106:109], v[174:177], v[236:239], v[106:109]
	v_mfma_f32_16x16x32_bf16 v[98:101], v[174:177], v[244:247], v[98:101]
	v_mfma_f32_16x16x32_bf16 v[102:105], v[154:157], v[244:247], v[102:105]
	v_mfma_f32_16x16x32_bf16 v[38:41], v[182:185], v[244:247], v[38:41]
	v_mfma_f32_16x16x32_bf16 v[34:37], v[190:193], v[244:247], v[34:37]
	v_mfma_f32_16x16x32_bf16 v[42:45], v[190:193], v[236:239], v[42:45]
	v_mfma_f32_16x16x32_bf16 v[46:49], v[182:185], v[236:239], v[46:49]
	v_mfma_f32_16x16x32_bf16 v[54:57], v[182:185], v[228:231], v[54:57]
	v_mfma_f32_16x16x32_bf16 v[50:53], v[190:193], v[228:231], v[50:53]
	v_mfma_f32_16x16x32_bf16 v[58:61], v[190:193], v[198:201], v[58:61]
	v_mfma_f32_16x16x32_bf16 v[62:65], v[182:185], v[198:201], v[62:65]
	s_barrier
	s_setprio 0
	s_mov_b32 m0, s34
	s_or_b32 s52, s82, 0x80
	ds_read_b128 v[194:197], v140 offset:49152
	ds_read_b128 v[198:201], v140 offset:50176
	ds_read_b128 v[202:205], v140 offset:51200
	ds_read_b128 v[228:231], v140 offset:52224
	ds_read_b128 v[232:235], v140 offset:53248
	ds_read_b128 v[236:239], v140 offset:54272
	ds_read_b128 v[240:243], v140 offset:55296
	ds_read_b128 v[244:247], v140 offset:56320
	buffer_load_dwordx4 v134, s[64:67], s52 offen lds
	s_mov_b32 m0, s35
	s_add_i32 s82, s82, 0x200080
	buffer_load_dwordx4 v136, s[64:67], s52 offen lds
	s_mov_b32 m0, s37
	s_nop 0
	buffer_load_dwordx4 v134, s[64:67], s82 offen lds
	s_mov_b32 m0, s44
	s_nop 0
	buffer_load_dwordx4 v136, s[64:67], s82 offen lds
	s_mov_b32 m0, s14
	s_nop 0
	buffer_load_dwordx4 v131, s[60:63], s73 offen lds
	s_mov_b32 m0, s36
	s_nop 0
	buffer_load_dwordx4 v135, s[60:63], s73 offen lds
	s_waitcnt vmcnt(8)
	s_waitcnt lgkmcnt(0)
	s_setprio 1
	s_barrier
	v_mfma_f32_16x16x32_bf16 v[94:97], v[142:145], v[194:197], v[94:97]
	v_mfma_f32_16x16x32_bf16 v[90:93], v[170:173], v[194:197], v[90:93]
	v_mfma_f32_16x16x32_bf16 v[82:85], v[170:173], v[202:205], v[82:85]
	v_mfma_f32_16x16x32_bf16 v[86:89], v[142:145], v[202:205], v[86:89]
	v_mfma_f32_16x16x32_bf16 v[78:81], v[142:145], v[232:235], v[78:81]
	v_mfma_f32_16x16x32_bf16 v[74:77], v[170:173], v[232:235], v[74:77]
	v_mfma_f32_16x16x32_bf16 v[66:69], v[170:173], v[240:243], v[66:69]
	v_mfma_f32_16x16x32_bf16 v[70:73], v[142:145], v[240:243], v[70:73]
	v_mfma_f32_16x16x32_bf16 v[6:9], v[178:181], v[240:243], v[6:9]
	v_mfma_f32_16x16x32_bf16 v[2:5], v[186:189], v[240:243], v[2:5]
	v_mfma_f32_16x16x32_bf16 v[10:13], v[186:189], v[232:235], v[10:13]
	v_mfma_f32_16x16x32_bf16 v[14:17], v[178:181], v[232:235], v[14:17]
	v_mfma_f32_16x16x32_bf16 v[22:25], v[178:181], v[202:205], v[22:25]
	v_mfma_f32_16x16x32_bf16 v[18:21], v[186:189], v[202:205], v[18:21]
	v_mfma_f32_16x16x32_bf16 v[26:29], v[186:189], v[194:197], v[26:29]
	v_mfma_f32_16x16x32_bf16 v[30:33], v[178:181], v[194:197], v[30:33]
	v_mfma_f32_16x16x32_bf16 v[94:97], v[154:157], v[198:201], v[94:97]
	v_mfma_f32_16x16x32_bf16 v[90:93], v[174:177], v[198:201], v[90:93]
	v_mfma_f32_16x16x32_bf16 v[82:85], v[174:177], v[228:231], v[82:85]
	v_mfma_f32_16x16x32_bf16 v[86:89], v[154:157], v[228:231], v[86:89]
	v_mfma_f32_16x16x32_bf16 v[78:81], v[154:157], v[236:239], v[78:81]
	v_mfma_f32_16x16x32_bf16 v[74:77], v[174:177], v[236:239], v[74:77]
	v_mfma_f32_16x16x32_bf16 v[66:69], v[174:177], v[244:247], v[66:69]
	v_mfma_f32_16x16x32_bf16 v[70:73], v[154:157], v[244:247], v[70:73]
	v_mfma_f32_16x16x32_bf16 v[6:9], v[182:185], v[244:247], v[6:9]
	v_mfma_f32_16x16x32_bf16 v[2:5], v[190:193], v[244:247], v[2:5]
	v_mfma_f32_16x16x32_bf16 v[10:13], v[190:193], v[236:239], v[10:13]
	v_mfma_f32_16x16x32_bf16 v[14:17], v[182:185], v[236:239], v[14:17]
	v_mfma_f32_16x16x32_bf16 v[22:25], v[182:185], v[228:231], v[22:25]
	v_mfma_f32_16x16x32_bf16 v[18:21], v[190:193], v[228:231], v[18:21]
	v_mfma_f32_16x16x32_bf16 v[26:29], v[190:193], v[198:201], v[26:29]
	v_mfma_f32_16x16x32_bf16 v[30:33], v[182:185], v[198:201], v[30:33]
	s_barrier
	s_setprio 0
	s_add_i32 s72, s72, 2
	s_addk_i32 s30, 0x100
	s_addk_i32 s31, 0x100
	s_cmpk_gt_u32 s72, 0x7d
.LBB0_1193:
	v_add_u32_e32 v141, 0x10000, v139
	ds_read_b128 v[142:145], v141
	ds_read_b128 v[154:157], v141 offset:1024
	ds_read_b128 v[170:173], v141 offset:2048
	ds_read_b128 v[174:177], v141 offset:3072
	v_add_u32_e32 v141, 0x14000, v139
	ds_read_b128 v[178:181], v141
	ds_read_b128 v[182:185], v141 offset:1024
	ds_read_b128 v[186:189], v141 offset:2048
	ds_read_b128 v[190:193], v141 offset:3072
	s_add_i32 s52, s30, 0xffe00080
	s_cmpk_eq_i32 s72, 0x7c
	s_cselect_b32 s52, s8, s52
	s_cselect_b32 s82, s9, s31
	s_or_b32 s73, s52, 0x80
	s_mov_b32 m0, s69
	ds_read_b128 v[194:197], v140
	ds_read_b128 v[198:201], v140 offset:1024
	ds_read_b128 v[202:205], v140 offset:2048
	ds_read_b128 v[228:231], v140 offset:3072
	ds_read_b128 v[232:235], v140 offset:4096
	ds_read_b128 v[236:239], v140 offset:5120
	ds_read_b128 v[240:243], v140 offset:6144
	ds_read_b128 v[244:247], v140 offset:7168
	buffer_load_dwordx4 v131, s[60:63], s30 offen lds
	s_mov_b32 m0, s46
	s_nop 0
	buffer_load_dwordx4 v135, s[60:63], s30 offen lds
	s_waitcnt vmcnt(8)
	s_waitcnt lgkmcnt(0)
	s_setprio 1
	s_barrier
	v_mfma_f32_16x16x32_bf16 v[126:129], v[142:145], v[194:197], v[126:129]
	v_mfma_f32_16x16x32_bf16 v[122:125], v[170:173], v[194:197], v[122:125]
	v_mfma_f32_16x16x32_bf16 v[114:117], v[170:173], v[202:205], v[114:117]
	v_mfma_f32_16x16x32_bf16 v[118:121], v[142:145], v[202:205], v[118:121]
	v_mfma_f32_16x16x32_bf16 v[110:113], v[142:145], v[232:235], v[110:113]
	v_mfma_f32_16x16x32_bf16 v[106:109], v[170:173], v[232:235], v[106:109]
	v_mfma_f32_16x16x32_bf16 v[98:101], v[170:173], v[240:243], v[98:101]
	v_mfma_f32_16x16x32_bf16 v[102:105], v[142:145], v[240:243], v[102:105]
	v_mfma_f32_16x16x32_bf16 v[38:41], v[178:181], v[240:243], v[38:41]
	v_mfma_f32_16x16x32_bf16 v[34:37], v[186:189], v[240:243], v[34:37]
	v_mfma_f32_16x16x32_bf16 v[42:45], v[186:189], v[232:235], v[42:45]
	v_mfma_f32_16x16x32_bf16 v[46:49], v[178:181], v[232:235], v[46:49]
	v_mfma_f32_16x16x32_bf16 v[54:57], v[178:181], v[202:205], v[54:57]
	v_mfma_f32_16x16x32_bf16 v[50:53], v[186:189], v[202:205], v[50:53]
	v_mfma_f32_16x16x32_bf16 v[58:61], v[186:189], v[194:197], v[58:61]
	v_mfma_f32_16x16x32_bf16 v[62:65], v[178:181], v[194:197], v[62:65]
	v_mfma_f32_16x16x32_bf16 v[126:129], v[154:157], v[198:201], v[126:129]
	v_mfma_f32_16x16x32_bf16 v[122:125], v[174:177], v[198:201], v[122:125]
	v_mfma_f32_16x16x32_bf16 v[114:117], v[174:177], v[228:231], v[114:117]
	v_mfma_f32_16x16x32_bf16 v[118:121], v[154:157], v[228:231], v[118:121]
	v_mfma_f32_16x16x32_bf16 v[110:113], v[154:157], v[236:239], v[110:113]
	v_mfma_f32_16x16x32_bf16 v[106:109], v[174:177], v[236:239], v[106:109]
	v_mfma_f32_16x16x32_bf16 v[98:101], v[174:177], v[244:247], v[98:101]
	v_mfma_f32_16x16x32_bf16 v[102:105], v[154:157], v[244:247], v[102:105]
	v_mfma_f32_16x16x32_bf16 v[38:41], v[182:185], v[244:247], v[38:41]
	v_mfma_f32_16x16x32_bf16 v[34:37], v[190:193], v[244:247], v[34:37]
	v_mfma_f32_16x16x32_bf16 v[42:45], v[190:193], v[236:239], v[42:45]
	v_mfma_f32_16x16x32_bf16 v[46:49], v[182:185], v[236:239], v[46:49]
	v_mfma_f32_16x16x32_bf16 v[54:57], v[182:185], v[228:231], v[54:57]
	v_mfma_f32_16x16x32_bf16 v[50:53], v[190:193], v[228:231], v[50:53]
	v_mfma_f32_16x16x32_bf16 v[58:61], v[190:193], v[198:201], v[58:61]
	v_mfma_f32_16x16x32_bf16 v[62:65], v[182:185], v[198:201], v[62:65]
	s_barrier
	s_setprio 0
	s_mov_b32 m0, s15
	s_mov_b32 s66, s62
	s_mov_b32 s67, s63
	ds_read_b128 v[194:197], v140 offset:16384
	ds_read_b128 v[198:201], v140 offset:17408
	ds_read_b128 v[202:205], v140 offset:18432
	ds_read_b128 v[228:231], v140 offset:19456
	ds_read_b128 v[232:235], v140 offset:20480
	ds_read_b128 v[236:239], v140 offset:21504
	ds_read_b128 v[240:243], v140 offset:22528
	ds_read_b128 v[244:247], v140 offset:23552
	buffer_load_dwordx4 v134, s[64:67], s82 offen lds
	s_mov_b32 m0, s16
	s_add_i32 s53, s82, 0x200000
	buffer_load_dwordx4 v136, s[64:67], s82 offen lds
	s_mov_b32 m0, s21
	s_nop 0
	buffer_load_dwordx4 v134, s[64:67], s53 offen lds
	s_mov_b32 m0, s23
	s_nop 0
	buffer_load_dwordx4 v136, s[64:67], s53 offen lds
	s_mov_b32 m0, s2
	s_nop 0
	buffer_load_dwordx4 v131, s[60:63], s52 offen lds
	s_mov_b32 m0, s24
	s_nop 0
	buffer_load_dwordx4 v135, s[60:63], s52 offen lds
	s_waitcnt vmcnt(8)
	s_waitcnt lgkmcnt(0)
	s_setprio 1
	s_barrier
	v_mfma_f32_16x16x32_bf16 v[94:97], v[142:145], v[194:197], v[94:97]
	v_mfma_f32_16x16x32_bf16 v[90:93], v[170:173], v[194:197], v[90:93]
	v_mfma_f32_16x16x32_bf16 v[82:85], v[170:173], v[202:205], v[82:85]
	v_mfma_f32_16x16x32_bf16 v[86:89], v[142:145], v[202:205], v[86:89]
	v_mfma_f32_16x16x32_bf16 v[78:81], v[142:145], v[232:235], v[78:81]
	v_mfma_f32_16x16x32_bf16 v[74:77], v[170:173], v[232:235], v[74:77]
	v_mfma_f32_16x16x32_bf16 v[66:69], v[170:173], v[240:243], v[66:69]
	v_mfma_f32_16x16x32_bf16 v[70:73], v[142:145], v[240:243], v[70:73]
	v_mfma_f32_16x16x32_bf16 v[6:9], v[178:181], v[240:243], v[6:9]
	v_mfma_f32_16x16x32_bf16 v[2:5], v[186:189], v[240:243], v[2:5]
	v_mfma_f32_16x16x32_bf16 v[10:13], v[186:189], v[232:235], v[10:13]
	v_mfma_f32_16x16x32_bf16 v[14:17], v[178:181], v[232:235], v[14:17]
	v_mfma_f32_16x16x32_bf16 v[22:25], v[178:181], v[202:205], v[22:25]
	v_mfma_f32_16x16x32_bf16 v[18:21], v[186:189], v[202:205], v[18:21]
	v_mfma_f32_16x16x32_bf16 v[26:29], v[186:189], v[194:197], v[26:29]
	v_mfma_f32_16x16x32_bf16 v[30:33], v[178:181], v[194:197], v[30:33]
	v_mfma_f32_16x16x32_bf16 v[94:97], v[154:157], v[198:201], v[94:97]
	v_mfma_f32_16x16x32_bf16 v[90:93], v[174:177], v[198:201], v[90:93]
	v_mfma_f32_16x16x32_bf16 v[82:85], v[174:177], v[228:231], v[82:85]
	v_mfma_f32_16x16x32_bf16 v[86:89], v[154:157], v[228:231], v[86:89]
	v_mfma_f32_16x16x32_bf16 v[78:81], v[154:157], v[236:239], v[78:81]
	v_mfma_f32_16x16x32_bf16 v[74:77], v[174:177], v[236:239], v[74:77]
	v_mfma_f32_16x16x32_bf16 v[66:69], v[174:177], v[244:247], v[66:69]
	v_mfma_f32_16x16x32_bf16 v[70:73], v[154:157], v[244:247], v[70:73]
	v_mfma_f32_16x16x32_bf16 v[6:9], v[182:185], v[244:247], v[6:9]
	v_mfma_f32_16x16x32_bf16 v[2:5], v[190:193], v[244:247], v[2:5]
	v_mfma_f32_16x16x32_bf16 v[10:13], v[190:193], v[236:239], v[10:13]
	v_mfma_f32_16x16x32_bf16 v[14:17], v[182:185], v[236:239], v[14:17]
	v_mfma_f32_16x16x32_bf16 v[22:25], v[182:185], v[228:231], v[22:25]
	v_mfma_f32_16x16x32_bf16 v[18:21], v[190:193], v[228:231], v[18:21]
	v_mfma_f32_16x16x32_bf16 v[26:29], v[190:193], v[198:201], v[26:29]
	v_mfma_f32_16x16x32_bf16 v[30:33], v[182:185], v[198:201], v[30:33]
	s_barrier
	s_setprio 0
	v_add_u32_e32 v141, 0x18000, v139
	ds_read_b128 v[142:145], v141
	ds_read_b128 v[154:157], v141 offset:1024
	ds_read_b128 v[170:173], v141 offset:2048
	ds_read_b128 v[174:177], v141 offset:3072
	v_add_u32_e32 v141, 0x1c000, v139
	ds_read_b128 v[178:181], v141
	ds_read_b128 v[182:185], v141 offset:1024
	ds_read_b128 v[186:189], v141 offset:2048
	ds_read_b128 v[190:193], v141 offset:3072
	s_add_i32 s52, s52, 0x200000
	s_mov_b32 m0, s25
	ds_read_b128 v[194:197], v140 offset:32768
	ds_read_b128 v[198:201], v140 offset:33792
	ds_read_b128 v[202:205], v140 offset:34816
	ds_read_b128 v[228:231], v140 offset:35840
	ds_read_b128 v[232:235], v140 offset:36864
	ds_read_b128 v[236:239], v140 offset:37888
	ds_read_b128 v[240:243], v140 offset:38912
	ds_read_b128 v[244:247], v140 offset:39936
	buffer_load_dwordx4 v131, s[60:63], s52 offen lds
	s_mov_b32 m0, s33
	s_nop 0
	buffer_load_dwordx4 v135, s[60:63], s52 offen lds
	s_waitcnt vmcnt(8)
	s_waitcnt lgkmcnt(0)
	s_setprio 1
	s_barrier
	v_mfma_f32_16x16x32_bf16 v[126:129], v[142:145], v[194:197], v[126:129]
	v_mfma_f32_16x16x32_bf16 v[122:125], v[170:173], v[194:197], v[122:125]
	v_mfma_f32_16x16x32_bf16 v[114:117], v[170:173], v[202:205], v[114:117]
	v_mfma_f32_16x16x32_bf16 v[118:121], v[142:145], v[202:205], v[118:121]
	v_mfma_f32_16x16x32_bf16 v[110:113], v[142:145], v[232:235], v[110:113]
	v_mfma_f32_16x16x32_bf16 v[106:109], v[170:173], v[232:235], v[106:109]
	v_mfma_f32_16x16x32_bf16 v[98:101], v[170:173], v[240:243], v[98:101]
	v_mfma_f32_16x16x32_bf16 v[102:105], v[142:145], v[240:243], v[102:105]
	v_mfma_f32_16x16x32_bf16 v[38:41], v[178:181], v[240:243], v[38:41]
	v_mfma_f32_16x16x32_bf16 v[34:37], v[186:189], v[240:243], v[34:37]
	v_mfma_f32_16x16x32_bf16 v[42:45], v[186:189], v[232:235], v[42:45]
	v_mfma_f32_16x16x32_bf16 v[46:49], v[178:181], v[232:235], v[46:49]
	v_mfma_f32_16x16x32_bf16 v[54:57], v[178:181], v[202:205], v[54:57]
	v_mfma_f32_16x16x32_bf16 v[50:53], v[186:189], v[202:205], v[50:53]
	v_mfma_f32_16x16x32_bf16 v[58:61], v[186:189], v[194:197], v[58:61]
	v_mfma_f32_16x16x32_bf16 v[62:65], v[178:181], v[194:197], v[62:65]
	v_mfma_f32_16x16x32_bf16 v[126:129], v[154:157], v[198:201], v[126:129]
	v_mfma_f32_16x16x32_bf16 v[122:125], v[174:177], v[198:201], v[122:125]
	v_mfma_f32_16x16x32_bf16 v[114:117], v[174:177], v[228:231], v[114:117]
	v_mfma_f32_16x16x32_bf16 v[118:121], v[154:157], v[228:231], v[118:121]
	v_mfma_f32_16x16x32_bf16 v[110:113], v[154:157], v[236:239], v[110:113]
	v_mfma_f32_16x16x32_bf16 v[106:109], v[174:177], v[236:239], v[106:109]
	v_mfma_f32_16x16x32_bf16 v[98:101], v[174:177], v[244:247], v[98:101]
	v_mfma_f32_16x16x32_bf16 v[102:105], v[154:157], v[244:247], v[102:105]
	v_mfma_f32_16x16x32_bf16 v[38:41], v[182:185], v[244:247], v[38:41]
	v_mfma_f32_16x16x32_bf16 v[34:37], v[190:193], v[244:247], v[34:37]
	v_mfma_f32_16x16x32_bf16 v[42:45], v[190:193], v[236:239], v[42:45]
	v_mfma_f32_16x16x32_bf16 v[46:49], v[182:185], v[236:239], v[46:49]
	v_mfma_f32_16x16x32_bf16 v[54:57], v[182:185], v[228:231], v[54:57]
	v_mfma_f32_16x16x32_bf16 v[50:53], v[190:193], v[228:231], v[50:53]
	v_mfma_f32_16x16x32_bf16 v[58:61], v[190:193], v[198:201], v[58:61]
	v_mfma_f32_16x16x32_bf16 v[62:65], v[182:185], v[198:201], v[62:65]
	s_barrier
	s_setprio 0
	s_mov_b32 m0, s34
	s_or_b32 s52, s82, 0x80
	ds_read_b128 v[194:197], v140 offset:49152
	ds_read_b128 v[198:201], v140 offset:50176
	ds_read_b128 v[202:205], v140 offset:51200
	ds_read_b128 v[228:231], v140 offset:52224
	ds_read_b128 v[232:235], v140 offset:53248
	ds_read_b128 v[236:239], v140 offset:54272
	ds_read_b128 v[240:243], v140 offset:55296
	ds_read_b128 v[244:247], v140 offset:56320
	buffer_load_dwordx4 v134, s[64:67], s52 offen lds
	s_mov_b32 m0, s35
	s_add_i32 s82, s82, 0x200080
	buffer_load_dwordx4 v136, s[64:67], s52 offen lds
	s_mov_b32 m0, s37
	s_nop 0
	buffer_load_dwordx4 v134, s[64:67], s82 offen lds
	s_mov_b32 m0, s44
	s_nop 0
	buffer_load_dwordx4 v136, s[64:67], s82 offen lds
	s_mov_b32 m0, s14
	s_nop 0
	buffer_load_dwordx4 v131, s[60:63], s73 offen lds
	s_mov_b32 m0, s36
	s_nop 0
	buffer_load_dwordx4 v135, s[60:63], s73 offen lds
	s_waitcnt vmcnt(8)
	s_waitcnt lgkmcnt(0)
	s_setprio 1
	s_barrier
	v_mfma_f32_16x16x32_bf16 v[94:97], v[142:145], v[194:197], v[94:97]
	v_mfma_f32_16x16x32_bf16 v[90:93], v[170:173], v[194:197], v[90:93]
	v_mfma_f32_16x16x32_bf16 v[82:85], v[170:173], v[202:205], v[82:85]
	v_mfma_f32_16x16x32_bf16 v[86:89], v[142:145], v[202:205], v[86:89]
	v_mfma_f32_16x16x32_bf16 v[78:81], v[142:145], v[232:235], v[78:81]
	v_mfma_f32_16x16x32_bf16 v[74:77], v[170:173], v[232:235], v[74:77]
	v_mfma_f32_16x16x32_bf16 v[66:69], v[170:173], v[240:243], v[66:69]
	v_mfma_f32_16x16x32_bf16 v[70:73], v[142:145], v[240:243], v[70:73]
	v_mfma_f32_16x16x32_bf16 v[6:9], v[178:181], v[240:243], v[6:9]
	v_mfma_f32_16x16x32_bf16 v[2:5], v[186:189], v[240:243], v[2:5]
	v_mfma_f32_16x16x32_bf16 v[10:13], v[186:189], v[232:235], v[10:13]
	v_mfma_f32_16x16x32_bf16 v[14:17], v[178:181], v[232:235], v[14:17]
	v_mfma_f32_16x16x32_bf16 v[22:25], v[178:181], v[202:205], v[22:25]
	v_mfma_f32_16x16x32_bf16 v[18:21], v[186:189], v[202:205], v[18:21]
	v_mfma_f32_16x16x32_bf16 v[26:29], v[186:189], v[194:197], v[26:29]
	v_mfma_f32_16x16x32_bf16 v[30:33], v[178:181], v[194:197], v[30:33]
	v_mfma_f32_16x16x32_bf16 v[94:97], v[154:157], v[198:201], v[94:97]
	v_mfma_f32_16x16x32_bf16 v[90:93], v[174:177], v[198:201], v[90:93]
	v_mfma_f32_16x16x32_bf16 v[82:85], v[174:177], v[228:231], v[82:85]
	v_mfma_f32_16x16x32_bf16 v[86:89], v[154:157], v[228:231], v[86:89]
	v_mfma_f32_16x16x32_bf16 v[78:81], v[154:157], v[236:239], v[78:81]
	v_mfma_f32_16x16x32_bf16 v[74:77], v[174:177], v[236:239], v[74:77]
	v_mfma_f32_16x16x32_bf16 v[66:69], v[174:177], v[244:247], v[66:69]
	v_mfma_f32_16x16x32_bf16 v[70:73], v[154:157], v[244:247], v[70:73]
	v_mfma_f32_16x16x32_bf16 v[6:9], v[182:185], v[244:247], v[6:9]
	v_mfma_f32_16x16x32_bf16 v[2:5], v[190:193], v[244:247], v[2:5]
	v_mfma_f32_16x16x32_bf16 v[10:13], v[190:193], v[236:239], v[10:13]
	v_mfma_f32_16x16x32_bf16 v[14:17], v[182:185], v[236:239], v[14:17]
	v_mfma_f32_16x16x32_bf16 v[22:25], v[182:185], v[228:231], v[22:25]
	v_mfma_f32_16x16x32_bf16 v[18:21], v[190:193], v[228:231], v[18:21]
	v_mfma_f32_16x16x32_bf16 v[26:29], v[190:193], v[198:201], v[26:29]
	v_mfma_f32_16x16x32_bf16 v[30:33], v[182:185], v[198:201], v[30:33]
	s_barrier
	s_setprio 0
	s_add_i32 s72, s72, 2
	s_addk_i32 s30, 0x100
	s_addk_i32 s31, 0x100
	s_cmpk_gt_u32 s72, 0x7d
	s_cbranch_scc0 .LBB0_1193
	s_and_b64 vcc, exec, s[42:43]
	s_cbranch_vccz .LBB0_1196
	s_barrier

.LBB0_1222:
	s_lshl_b32 s14, s82, 22
	s_and_b64 s[8:9], s[44:45], exec
	s_cselect_b32 s8, s14, s19
	s_lshl_b32 s46, s84, 22
	s_and_b64 s[26:27], s[44:45], exec
	s_cselect_b32 s9, s46, s22
	s_add_i32 s19, s19, 0x200080
	s_addk_i32 s22, 0x100
	s_mov_b32 s26, -2
	v_add_u32_e32 v141, 0x10000, v139
	ds_read_b128 v[142:145], v141
	ds_read_b128 v[154:157], v141 offset:1024
	ds_read_b128 v[170:173], v141 offset:2048
	ds_read_b128 v[174:177], v141 offset:3072
	v_add_u32_e32 v141, 0x14000, v139
	ds_read_b128 v[178:181], v141
	ds_read_b128 v[182:185], v141 offset:1024
	ds_read_b128 v[186:189], v141 offset:2048
	ds_read_b128 v[190:193], v141 offset:3072
	s_add_i32 s27, s19, 0xffe00080
	s_cmpk_eq_i32 s26, 0x7c
	s_cselect_b32 s52, s8, s27
	s_cselect_b32 s47, s9, s22
	s_or_b32 s27, s52, 0x80
	s_mov_b32 m0, s71
	ds_read_b128 v[194:197], v140
	ds_read_b128 v[198:201], v140 offset:1024
	ds_read_b128 v[202:205], v140 offset:2048
	ds_read_b128 v[228:231], v140 offset:3072
	ds_read_b128 v[232:235], v140 offset:4096
	ds_read_b128 v[236:239], v140 offset:5120
	ds_read_b128 v[240:243], v140 offset:6144
	ds_read_b128 v[244:247], v140 offset:7168
	buffer_load_dwordx4 v131, s[60:63], s19 offen lds
	s_mov_b32 m0, s72
	s_nop 0
	buffer_load_dwordx4 v135, s[60:63], s19 offen lds
	s_waitcnt vmcnt(8)
	s_waitcnt lgkmcnt(0)
	s_setprio 1
	s_barrier
	v_mfma_f32_16x16x32_bf16 v[126:129], v[142:145], v[194:197], 0
	v_mfma_f32_16x16x32_bf16 v[122:125], v[170:173], v[194:197], 0
	v_mfma_f32_16x16x32_bf16 v[114:117], v[170:173], v[202:205], 0
	v_mfma_f32_16x16x32_bf16 v[118:121], v[142:145], v[202:205], 0
	v_mfma_f32_16x16x32_bf16 v[110:113], v[142:145], v[232:235], 0
	v_mfma_f32_16x16x32_bf16 v[106:109], v[170:173], v[232:235], 0
	v_mfma_f32_16x16x32_bf16 v[98:101], v[170:173], v[240:243], 0
	v_mfma_f32_16x16x32_bf16 v[102:105], v[142:145], v[240:243], 0
	v_mfma_f32_16x16x32_bf16 v[38:41], v[178:181], v[240:243], 0
	v_mfma_f32_16x16x32_bf16 v[34:37], v[186:189], v[240:243], 0
	v_mfma_f32_16x16x32_bf16 v[42:45], v[186:189], v[232:235], 0
	v_mfma_f32_16x16x32_bf16 v[46:49], v[178:181], v[232:235], 0
	v_mfma_f32_16x16x32_bf16 v[54:57], v[178:181], v[202:205], 0
	v_mfma_f32_16x16x32_bf16 v[50:53], v[186:189], v[202:205], 0
	v_mfma_f32_16x16x32_bf16 v[58:61], v[186:189], v[194:197], 0
	v_mfma_f32_16x16x32_bf16 v[62:65], v[178:181], v[194:197], 0
	v_mfma_f32_16x16x32_bf16 v[126:129], v[154:157], v[198:201], v[126:129]
	v_mfma_f32_16x16x32_bf16 v[122:125], v[174:177], v[198:201], v[122:125]
	v_mfma_f32_16x16x32_bf16 v[114:117], v[174:177], v[228:231], v[114:117]
	v_mfma_f32_16x16x32_bf16 v[118:121], v[154:157], v[228:231], v[118:121]
	v_mfma_f32_16x16x32_bf16 v[110:113], v[154:157], v[236:239], v[110:113]
	v_mfma_f32_16x16x32_bf16 v[106:109], v[174:177], v[236:239], v[106:109]
	v_mfma_f32_16x16x32_bf16 v[98:101], v[174:177], v[244:247], v[98:101]
	v_mfma_f32_16x16x32_bf16 v[102:105], v[154:157], v[244:247], v[102:105]
	v_mfma_f32_16x16x32_bf16 v[38:41], v[182:185], v[244:247], v[38:41]
	v_mfma_f32_16x16x32_bf16 v[34:37], v[190:193], v[244:247], v[34:37]
	v_mfma_f32_16x16x32_bf16 v[42:45], v[190:193], v[236:239], v[42:45]
	v_mfma_f32_16x16x32_bf16 v[46:49], v[182:185], v[236:239], v[46:49]
	v_mfma_f32_16x16x32_bf16 v[54:57], v[182:185], v[228:231], v[54:57]
	v_mfma_f32_16x16x32_bf16 v[50:53], v[190:193], v[228:231], v[50:53]
	v_mfma_f32_16x16x32_bf16 v[58:61], v[190:193], v[198:201], v[58:61]
	v_mfma_f32_16x16x32_bf16 v[62:65], v[182:185], v[198:201], v[62:65]
	s_barrier
	s_setprio 0
	s_mov_b32 m0, s2
	s_mov_b32 s66, s62
	s_mov_b32 s67, s63
	ds_read_b128 v[194:197], v140 offset:16384
	ds_read_b128 v[198:201], v140 offset:17408
	ds_read_b128 v[202:205], v140 offset:18432
	ds_read_b128 v[228:231], v140 offset:19456
	ds_read_b128 v[232:235], v140 offset:20480
	ds_read_b128 v[236:239], v140 offset:21504
	ds_read_b128 v[240:243], v140 offset:22528
	ds_read_b128 v[244:247], v140 offset:23552
	buffer_load_dwordx4 v134, s[64:67], s47 offen lds
	s_mov_b32 m0, s21
	s_add_i32 s53, s47, 0x200000
	buffer_load_dwordx4 v136, s[64:67], s47 offen lds
	s_mov_b32 m0, s23
	s_nop 0
	buffer_load_dwordx4 v134, s[64:67], s53 offen lds
	s_mov_b32 m0, s24
	s_nop 0
	buffer_load_dwordx4 v136, s[64:67], s53 offen lds
	s_mov_b32 m0, s16
	s_nop 0
	buffer_load_dwordx4 v131, s[60:63], s52 offen lds
	s_mov_b32 m0, s25
	s_nop 0
	buffer_load_dwordx4 v135, s[60:63], s52 offen lds
	s_waitcnt vmcnt(8)
	s_waitcnt lgkmcnt(0)
	s_setprio 1
	s_barrier
	v_mfma_f32_16x16x32_bf16 v[94:97], v[142:145], v[194:197], 0
	v_mfma_f32_16x16x32_bf16 v[90:93], v[170:173], v[194:197], 0
	v_mfma_f32_16x16x32_bf16 v[82:85], v[170:173], v[202:205], 0
	v_mfma_f32_16x16x32_bf16 v[86:89], v[142:145], v[202:205], 0
	v_mfma_f32_16x16x32_bf16 v[78:81], v[142:145], v[232:235], 0
	v_mfma_f32_16x16x32_bf16 v[74:77], v[170:173], v[232:235], 0
	v_mfma_f32_16x16x32_bf16 v[66:69], v[170:173], v[240:243], 0
	v_mfma_f32_16x16x32_bf16 v[70:73], v[142:145], v[240:243], 0
	v_mfma_f32_16x16x32_bf16 v[6:9], v[178:181], v[240:243], 0
	v_mfma_f32_16x16x32_bf16 v[2:5], v[186:189], v[240:243], 0
	v_mfma_f32_16x16x32_bf16 v[10:13], v[186:189], v[232:235], 0
	v_mfma_f32_16x16x32_bf16 v[14:17], v[178:181], v[232:235], 0
	v_mfma_f32_16x16x32_bf16 v[22:25], v[178:181], v[202:205], 0
	v_mfma_f32_16x16x32_bf16 v[18:21], v[186:189], v[202:205], 0
	v_mfma_f32_16x16x32_bf16 v[26:29], v[186:189], v[194:197], 0
	v_mfma_f32_16x16x32_bf16 v[30:33], v[178:181], v[194:197], 0
	v_mfma_f32_16x16x32_bf16 v[94:97], v[154:157], v[198:201], v[94:97]
	v_mfma_f32_16x16x32_bf16 v[90:93], v[174:177], v[198:201], v[90:93]
	v_mfma_f32_16x16x32_bf16 v[82:85], v[174:177], v[228:231], v[82:85]
	v_mfma_f32_16x16x32_bf16 v[86:89], v[154:157], v[228:231], v[86:89]
	v_mfma_f32_16x16x32_bf16 v[78:81], v[154:157], v[236:239], v[78:81]
	v_mfma_f32_16x16x32_bf16 v[74:77], v[174:177], v[236:239], v[74:77]
	v_mfma_f32_16x16x32_bf16 v[66:69], v[174:177], v[244:247], v[66:69]
	v_mfma_f32_16x16x32_bf16 v[70:73], v[154:157], v[244:247], v[70:73]
	v_mfma_f32_16x16x32_bf16 v[6:9], v[182:185], v[244:247], v[6:9]
	v_mfma_f32_16x16x32_bf16 v[2:5], v[190:193], v[244:247], v[2:5]
	v_mfma_f32_16x16x32_bf16 v[10:13], v[190:193], v[236:239], v[10:13]
	v_mfma_f32_16x16x32_bf16 v[14:17], v[182:185], v[236:239], v[14:17]
	v_mfma_f32_16x16x32_bf16 v[22:25], v[182:185], v[228:231], v[22:25]
	v_mfma_f32_16x16x32_bf16 v[18:21], v[190:193], v[228:231], v[18:21]
	v_mfma_f32_16x16x32_bf16 v[26:29], v[190:193], v[198:201], v[26:29]
	v_mfma_f32_16x16x32_bf16 v[30:33], v[182:185], v[198:201], v[30:33]
	s_barrier
	s_setprio 0
	v_add_u32_e32 v141, 0x18000, v139
	ds_read_b128 v[142:145], v141
	ds_read_b128 v[154:157], v141 offset:1024
	ds_read_b128 v[170:173], v141 offset:2048
	ds_read_b128 v[174:177], v141 offset:3072
	v_add_u32_e32 v141, 0x1c000, v139
	ds_read_b128 v[178:181], v141
	ds_read_b128 v[182:185], v141 offset:1024
	ds_read_b128 v[186:189], v141 offset:2048
	ds_read_b128 v[190:193], v141 offset:3072
	s_add_i32 s52, s52, 0x200000
	s_mov_b32 m0, s30
	ds_read_b128 v[194:197], v140 offset:32768
	ds_read_b128 v[198:201], v140 offset:33792
	ds_read_b128 v[202:205], v140 offset:34816
	ds_read_b128 v[228:231], v140 offset:35840
	ds_read_b128 v[232:235], v140 offset:36864
	ds_read_b128 v[236:239], v140 offset:37888
	ds_read_b128 v[240:243], v140 offset:38912
	ds_read_b128 v[244:247], v140 offset:39936
	buffer_load_dwordx4 v131, s[60:63], s52 offen lds
	s_mov_b32 m0, s31
	s_nop 0
	buffer_load_dwordx4 v135, s[60:63], s52 offen lds
	s_waitcnt vmcnt(8)
	s_waitcnt lgkmcnt(0)
	s_setprio 1
	s_barrier
	v_mfma_f32_16x16x32_bf16 v[126:129], v[142:145], v[194:197], v[126:129]
	v_mfma_f32_16x16x32_bf16 v[122:125], v[170:173], v[194:197], v[122:125]
	v_mfma_f32_16x16x32_bf16 v[114:117], v[170:173], v[202:205], v[114:117]
	v_mfma_f32_16x16x32_bf16 v[118:121], v[142:145], v[202:205], v[118:121]
	v_mfma_f32_16x16x32_bf16 v[110:113], v[142:145], v[232:235], v[110:113]
	v_mfma_f32_16x16x32_bf16 v[106:109], v[170:173], v[232:235], v[106:109]
	v_mfma_f32_16x16x32_bf16 v[98:101], v[170:173], v[240:243], v[98:101]
	v_mfma_f32_16x16x32_bf16 v[102:105], v[142:145], v[240:243], v[102:105]
	v_mfma_f32_16x16x32_bf16 v[38:41], v[178:181], v[240:243], v[38:41]
	v_mfma_f32_16x16x32_bf16 v[34:37], v[186:189], v[240:243], v[34:37]
	v_mfma_f32_16x16x32_bf16 v[42:45], v[186:189], v[232:235], v[42:45]
	v_mfma_f32_16x16x32_bf16 v[46:49], v[178:181], v[232:235], v[46:49]
	v_mfma_f32_16x16x32_bf16 v[54:57], v[178:181], v[202:205], v[54:57]
	v_mfma_f32_16x16x32_bf16 v[50:53], v[186:189], v[202:205], v[50:53]
	v_mfma_f32_16x16x32_bf16 v[58:61], v[186:189], v[194:197], v[58:61]
	v_mfma_f32_16x16x32_bf16 v[62:65], v[178:181], v[194:197], v[62:65]
	v_mfma_f32_16x16x32_bf16 v[126:129], v[154:157], v[198:201], v[126:129]
	v_mfma_f32_16x16x32_bf16 v[122:125], v[174:177], v[198:201], v[122:125]
	v_mfma_f32_16x16x32_bf16 v[114:117], v[174:177], v[228:231], v[114:117]
	v_mfma_f32_16x16x32_bf16 v[118:121], v[154:157], v[228:231], v[118:121]
	v_mfma_f32_16x16x32_bf16 v[110:113], v[154:157], v[236:239], v[110:113]
	v_mfma_f32_16x16x32_bf16 v[106:109], v[174:177], v[236:239], v[106:109]
	v_mfma_f32_16x16x32_bf16 v[98:101], v[174:177], v[244:247], v[98:101]
	v_mfma_f32_16x16x32_bf16 v[102:105], v[154:157], v[244:247], v[102:105]
	v_mfma_f32_16x16x32_bf16 v[38:41], v[182:185], v[244:247], v[38:41]
	v_mfma_f32_16x16x32_bf16 v[34:37], v[190:193], v[244:247], v[34:37]
	v_mfma_f32_16x16x32_bf16 v[42:45], v[190:193], v[236:239], v[42:45]
	v_mfma_f32_16x16x32_bf16 v[46:49], v[182:185], v[236:239], v[46:49]
	v_mfma_f32_16x16x32_bf16 v[54:57], v[182:185], v[228:231], v[54:57]
	v_mfma_f32_16x16x32_bf16 v[50:53], v[190:193], v[228:231], v[50:53]
	v_mfma_f32_16x16x32_bf16 v[58:61], v[190:193], v[198:201], v[58:61]
	v_mfma_f32_16x16x32_bf16 v[62:65], v[182:185], v[198:201], v[62:65]
	s_barrier
	s_setprio 0
	s_mov_b32 m0, s33
	s_or_b32 s52, s47, 0x80
	ds_read_b128 v[194:197], v140 offset:49152
	ds_read_b128 v[198:201], v140 offset:50176
	ds_read_b128 v[202:205], v140 offset:51200
	ds_read_b128 v[228:231], v140 offset:52224
	ds_read_b128 v[232:235], v140 offset:53248
	ds_read_b128 v[236:239], v140 offset:54272
	ds_read_b128 v[240:243], v140 offset:55296
	ds_read_b128 v[244:247], v140 offset:56320
	buffer_load_dwordx4 v134, s[64:67], s52 offen lds
	s_mov_b32 m0, s34
	s_add_i32 s47, s47, 0x200080
	buffer_load_dwordx4 v136, s[64:67], s52 offen lds
	s_mov_b32 m0, s37
	s_nop 0
	buffer_load_dwordx4 v134, s[64:67], s47 offen lds
	s_mov_b32 m0, s68
	s_nop 0
	buffer_load_dwordx4 v136, s[64:67], s47 offen lds
	s_mov_b32 m0, s35
	s_nop 0
	buffer_load_dwordx4 v131, s[60:63], s27 offen lds
	s_mov_b32 m0, s36
	s_nop 0
	buffer_load_dwordx4 v135, s[60:63], s27 offen lds
	s_waitcnt vmcnt(8)
	s_waitcnt lgkmcnt(0)
	s_setprio 1
	s_barrier
	v_mfma_f32_16x16x32_bf16 v[94:97], v[142:145], v[194:197], v[94:97]
	v_mfma_f32_16x16x32_bf16 v[90:93], v[170:173], v[194:197], v[90:93]
	v_mfma_f32_16x16x32_bf16 v[82:85], v[170:173], v[202:205], v[82:85]
	v_mfma_f32_16x16x32_bf16 v[86:89], v[142:145], v[202:205], v[86:89]
	v_mfma_f32_16x16x32_bf16 v[78:81], v[142:145], v[232:235], v[78:81]
	v_mfma_f32_16x16x32_bf16 v[74:77], v[170:173], v[232:235], v[74:77]
	v_mfma_f32_16x16x32_bf16 v[66:69], v[170:173], v[240:243], v[66:69]
	v_mfma_f32_16x16x32_bf16 v[70:73], v[142:145], v[240:243], v[70:73]
	v_mfma_f32_16x16x32_bf16 v[6:9], v[178:181], v[240:243], v[6:9]
	v_mfma_f32_16x16x32_bf16 v[2:5], v[186:189], v[240:243], v[2:5]
	v_mfma_f32_16x16x32_bf16 v[10:13], v[186:189], v[232:235], v[10:13]
	v_mfma_f32_16x16x32_bf16 v[14:17], v[178:181], v[232:235], v[14:17]
	v_mfma_f32_16x16x32_bf16 v[22:25], v[178:181], v[202:205], v[22:25]
	v_mfma_f32_16x16x32_bf16 v[18:21], v[186:189], v[202:205], v[18:21]
	v_mfma_f32_16x16x32_bf16 v[26:29], v[186:189], v[194:197], v[26:29]
	v_mfma_f32_16x16x32_bf16 v[30:33], v[178:181], v[194:197], v[30:33]
	v_mfma_f32_16x16x32_bf16 v[94:97], v[154:157], v[198:201], v[94:97]
	v_mfma_f32_16x16x32_bf16 v[90:93], v[174:177], v[198:201], v[90:93]
	v_mfma_f32_16x16x32_bf16 v[82:85], v[174:177], v[228:231], v[82:85]
	v_mfma_f32_16x16x32_bf16 v[86:89], v[154:157], v[228:231], v[86:89]
	v_mfma_f32_16x16x32_bf16 v[78:81], v[154:157], v[236:239], v[78:81]
	v_mfma_f32_16x16x32_bf16 v[74:77], v[174:177], v[236:239], v[74:77]
	v_mfma_f32_16x16x32_bf16 v[66:69], v[174:177], v[244:247], v[66:69]
	v_mfma_f32_16x16x32_bf16 v[70:73], v[154:157], v[244:247], v[70:73]
	v_mfma_f32_16x16x32_bf16 v[6:9], v[182:185], v[244:247], v[6:9]
	v_mfma_f32_16x16x32_bf16 v[2:5], v[190:193], v[244:247], v[2:5]
	v_mfma_f32_16x16x32_bf16 v[10:13], v[190:193], v[236:239], v[10:13]
	v_mfma_f32_16x16x32_bf16 v[14:17], v[182:185], v[236:239], v[14:17]
	v_mfma_f32_16x16x32_bf16 v[22:25], v[182:185], v[228:231], v[22:25]
	v_mfma_f32_16x16x32_bf16 v[18:21], v[190:193], v[228:231], v[18:21]
	v_mfma_f32_16x16x32_bf16 v[26:29], v[190:193], v[198:201], v[26:29]
	v_mfma_f32_16x16x32_bf16 v[30:33], v[182:185], v[198:201], v[30:33]
	s_barrier
	s_setprio 0
	s_add_i32 s26, s26, 2
	s_addk_i32 s19, 0x100
	s_addk_i32 s22, 0x100
	s_cmpk_gt_u32 s26, 0x7d
.LBB0_1223:
	v_add_u32_e32 v141, 0x10000, v139
	ds_read_b128 v[142:145], v141
	ds_read_b128 v[154:157], v141 offset:1024
	ds_read_b128 v[170:173], v141 offset:2048
	ds_read_b128 v[174:177], v141 offset:3072
	v_add_u32_e32 v141, 0x14000, v139
	ds_read_b128 v[178:181], v141
	ds_read_b128 v[182:185], v141 offset:1024
	ds_read_b128 v[186:189], v141 offset:2048
	ds_read_b128 v[190:193], v141 offset:3072
	s_add_i32 s27, s19, 0xffe00080
	s_cmpk_eq_i32 s26, 0x7c
	s_cselect_b32 s52, s8, s27
	s_cselect_b32 s47, s9, s22
	s_or_b32 s27, s52, 0x80
	s_mov_b32 m0, s71
	ds_read_b128 v[194:197], v140
	ds_read_b128 v[198:201], v140 offset:1024
	ds_read_b128 v[202:205], v140 offset:2048
	ds_read_b128 v[228:231], v140 offset:3072
	ds_read_b128 v[232:235], v140 offset:4096
	ds_read_b128 v[236:239], v140 offset:5120
	ds_read_b128 v[240:243], v140 offset:6144
	ds_read_b128 v[244:247], v140 offset:7168
	buffer_load_dwordx4 v131, s[60:63], s19 offen lds
	s_mov_b32 m0, s72
	s_nop 0
	buffer_load_dwordx4 v135, s[60:63], s19 offen lds
	s_waitcnt vmcnt(8)
	s_waitcnt lgkmcnt(0)
	s_setprio 1
	s_barrier
	v_mfma_f32_16x16x32_bf16 v[126:129], v[142:145], v[194:197], v[126:129]
	v_mfma_f32_16x16x32_bf16 v[122:125], v[170:173], v[194:197], v[122:125]
	v_mfma_f32_16x16x32_bf16 v[114:117], v[170:173], v[202:205], v[114:117]
	v_mfma_f32_16x16x32_bf16 v[118:121], v[142:145], v[202:205], v[118:121]
	v_mfma_f32_16x16x32_bf16 v[110:113], v[142:145], v[232:235], v[110:113]
	v_mfma_f32_16x16x32_bf16 v[106:109], v[170:173], v[232:235], v[106:109]
	v_mfma_f32_16x16x32_bf16 v[98:101], v[170:173], v[240:243], v[98:101]
	v_mfma_f32_16x16x32_bf16 v[102:105], v[142:145], v[240:243], v[102:105]
	v_mfma_f32_16x16x32_bf16 v[38:41], v[178:181], v[240:243], v[38:41]
	v_mfma_f32_16x16x32_bf16 v[34:37], v[186:189], v[240:243], v[34:37]
	v_mfma_f32_16x16x32_bf16 v[42:45], v[186:189], v[232:235], v[42:45]
	v_mfma_f32_16x16x32_bf16 v[46:49], v[178:181], v[232:235], v[46:49]
	v_mfma_f32_16x16x32_bf16 v[54:57], v[178:181], v[202:205], v[54:57]
	v_mfma_f32_16x16x32_bf16 v[50:53], v[186:189], v[202:205], v[50:53]
	v_mfma_f32_16x16x32_bf16 v[58:61], v[186:189], v[194:197], v[58:61]
	v_mfma_f32_16x16x32_bf16 v[62:65], v[178:181], v[194:197], v[62:65]
	v_mfma_f32_16x16x32_bf16 v[126:129], v[154:157], v[198:201], v[126:129]
	v_mfma_f32_16x16x32_bf16 v[122:125], v[174:177], v[198:201], v[122:125]
	v_mfma_f32_16x16x32_bf16 v[114:117], v[174:177], v[228:231], v[114:117]
	v_mfma_f32_16x16x32_bf16 v[118:121], v[154:157], v[228:231], v[118:121]
	v_mfma_f32_16x16x32_bf16 v[110:113], v[154:157], v[236:239], v[110:113]
	v_mfma_f32_16x16x32_bf16 v[106:109], v[174:177], v[236:239], v[106:109]
	v_mfma_f32_16x16x32_bf16 v[98:101], v[174:177], v[244:247], v[98:101]
	v_mfma_f32_16x16x32_bf16 v[102:105], v[154:157], v[244:247], v[102:105]
	v_mfma_f32_16x16x32_bf16 v[38:41], v[182:185], v[244:247], v[38:41]
	v_mfma_f32_16x16x32_bf16 v[34:37], v[190:193], v[244:247], v[34:37]
	v_mfma_f32_16x16x32_bf16 v[42:45], v[190:193], v[236:239], v[42:45]
	v_mfma_f32_16x16x32_bf16 v[46:49], v[182:185], v[236:239], v[46:49]
	v_mfma_f32_16x16x32_bf16 v[54:57], v[182:185], v[228:231], v[54:57]
	v_mfma_f32_16x16x32_bf16 v[50:53], v[190:193], v[228:231], v[50:53]
	v_mfma_f32_16x16x32_bf16 v[58:61], v[190:193], v[198:201], v[58:61]
	v_mfma_f32_16x16x32_bf16 v[62:65], v[182:185], v[198:201], v[62:65]
	s_barrier
	s_setprio 0
	s_mov_b32 m0, s2
	s_mov_b32 s66, s62
	s_mov_b32 s67, s63
	ds_read_b128 v[194:197], v140 offset:16384
	ds_read_b128 v[198:201], v140 offset:17408
	ds_read_b128 v[202:205], v140 offset:18432
	ds_read_b128 v[228:231], v140 offset:19456
	ds_read_b128 v[232:235], v140 offset:20480
	ds_read_b128 v[236:239], v140 offset:21504
	ds_read_b128 v[240:243], v140 offset:22528
	ds_read_b128 v[244:247], v140 offset:23552
	buffer_load_dwordx4 v134, s[64:67], s47 offen lds
	s_mov_b32 m0, s21
	s_add_i32 s53, s47, 0x200000
	buffer_load_dwordx4 v136, s[64:67], s47 offen lds
	s_mov_b32 m0, s23
	s_nop 0
	buffer_load_dwordx4 v134, s[64:67], s53 offen lds
	s_mov_b32 m0, s24
	s_nop 0
	buffer_load_dwordx4 v136, s[64:67], s53 offen lds
	s_mov_b32 m0, s16
	s_nop 0
	buffer_load_dwordx4 v131, s[60:63], s52 offen lds
	s_mov_b32 m0, s25
	s_nop 0
	buffer_load_dwordx4 v135, s[60:63], s52 offen lds
	s_waitcnt vmcnt(8)
	s_waitcnt lgkmcnt(0)
	s_setprio 1
	s_barrier
	v_mfma_f32_16x16x32_bf16 v[94:97], v[142:145], v[194:197], v[94:97]
	v_mfma_f32_16x16x32_bf16 v[90:93], v[170:173], v[194:197], v[90:93]
	v_mfma_f32_16x16x32_bf16 v[82:85], v[170:173], v[202:205], v[82:85]
	v_mfma_f32_16x16x32_bf16 v[86:89], v[142:145], v[202:205], v[86:89]
	v_mfma_f32_16x16x32_bf16 v[78:81], v[142:145], v[232:235], v[78:81]
	v_mfma_f32_16x16x32_bf16 v[74:77], v[170:173], v[232:235], v[74:77]
	v_mfma_f32_16x16x32_bf16 v[66:69], v[170:173], v[240:243], v[66:69]
	v_mfma_f32_16x16x32_bf16 v[70:73], v[142:145], v[240:243], v[70:73]
	v_mfma_f32_16x16x32_bf16 v[6:9], v[178:181], v[240:243], v[6:9]
	v_mfma_f32_16x16x32_bf16 v[2:5], v[186:189], v[240:243], v[2:5]
	v_mfma_f32_16x16x32_bf16 v[10:13], v[186:189], v[232:235], v[10:13]
	v_mfma_f32_16x16x32_bf16 v[14:17], v[178:181], v[232:235], v[14:17]
	v_mfma_f32_16x16x32_bf16 v[22:25], v[178:181], v[202:205], v[22:25]
	v_mfma_f32_16x16x32_bf16 v[18:21], v[186:189], v[202:205], v[18:21]
	v_mfma_f32_16x16x32_bf16 v[26:29], v[186:189], v[194:197], v[26:29]
	v_mfma_f32_16x16x32_bf16 v[30:33], v[178:181], v[194:197], v[30:33]
	v_mfma_f32_16x16x32_bf16 v[94:97], v[154:157], v[198:201], v[94:97]
	v_mfma_f32_16x16x32_bf16 v[90:93], v[174:177], v[198:201], v[90:93]
	v_mfma_f32_16x16x32_bf16 v[82:85], v[174:177], v[228:231], v[82:85]
	v_mfma_f32_16x16x32_bf16 v[86:89], v[154:157], v[228:231], v[86:89]
	v_mfma_f32_16x16x32_bf16 v[78:81], v[154:157], v[236:239], v[78:81]
	v_mfma_f32_16x16x32_bf16 v[74:77], v[174:177], v[236:239], v[74:77]
	v_mfma_f32_16x16x32_bf16 v[66:69], v[174:177], v[244:247], v[66:69]
	v_mfma_f32_16x16x32_bf16 v[70:73], v[154:157], v[244:247], v[70:73]
	v_mfma_f32_16x16x32_bf16 v[6:9], v[182:185], v[244:247], v[6:9]
	v_mfma_f32_16x16x32_bf16 v[2:5], v[190:193], v[244:247], v[2:5]
	v_mfma_f32_16x16x32_bf16 v[10:13], v[190:193], v[236:239], v[10:13]
	v_mfma_f32_16x16x32_bf16 v[14:17], v[182:185], v[236:239], v[14:17]
	v_mfma_f32_16x16x32_bf16 v[22:25], v[182:185], v[228:231], v[22:25]
	v_mfma_f32_16x16x32_bf16 v[18:21], v[190:193], v[228:231], v[18:21]
	v_mfma_f32_16x16x32_bf16 v[26:29], v[190:193], v[198:201], v[26:29]
	v_mfma_f32_16x16x32_bf16 v[30:33], v[182:185], v[198:201], v[30:33]
	s_barrier
	s_setprio 0
	v_add_u32_e32 v141, 0x18000, v139
	ds_read_b128 v[142:145], v141
	ds_read_b128 v[154:157], v141 offset:1024
	ds_read_b128 v[170:173], v141 offset:2048
	ds_read_b128 v[174:177], v141 offset:3072
	v_add_u32_e32 v141, 0x1c000, v139
	ds_read_b128 v[178:181], v141
	ds_read_b128 v[182:185], v141 offset:1024
	ds_read_b128 v[186:189], v141 offset:2048
	ds_read_b128 v[190:193], v141 offset:3072
	s_add_i32 s52, s52, 0x200000
	s_mov_b32 m0, s30
	ds_read_b128 v[194:197], v140 offset:32768
	ds_read_b128 v[198:201], v140 offset:33792
	ds_read_b128 v[202:205], v140 offset:34816
	ds_read_b128 v[228:231], v140 offset:35840
	ds_read_b128 v[232:235], v140 offset:36864
	ds_read_b128 v[236:239], v140 offset:37888
	ds_read_b128 v[240:243], v140 offset:38912
	ds_read_b128 v[244:247], v140 offset:39936
	buffer_load_dwordx4 v131, s[60:63], s52 offen lds
	s_mov_b32 m0, s31
	s_nop 0
	buffer_load_dwordx4 v135, s[60:63], s52 offen lds
	s_waitcnt vmcnt(8)
	s_waitcnt lgkmcnt(0)
	s_setprio 1
	s_barrier
	v_mfma_f32_16x16x32_bf16 v[126:129], v[142:145], v[194:197], v[126:129]
	v_mfma_f32_16x16x32_bf16 v[122:125], v[170:173], v[194:197], v[122:125]
	v_mfma_f32_16x16x32_bf16 v[114:117], v[170:173], v[202:205], v[114:117]
	v_mfma_f32_16x16x32_bf16 v[118:121], v[142:145], v[202:205], v[118:121]
	v_mfma_f32_16x16x32_bf16 v[110:113], v[142:145], v[232:235], v[110:113]
	v_mfma_f32_16x16x32_bf16 v[106:109], v[170:173], v[232:235], v[106:109]
	v_mfma_f32_16x16x32_bf16 v[98:101], v[170:173], v[240:243], v[98:101]
	v_mfma_f32_16x16x32_bf16 v[102:105], v[142:145], v[240:243], v[102:105]
	v_mfma_f32_16x16x32_bf16 v[38:41], v[178:181], v[240:243], v[38:41]
	v_mfma_f32_16x16x32_bf16 v[34:37], v[186:189], v[240:243], v[34:37]
	v_mfma_f32_16x16x32_bf16 v[42:45], v[186:189], v[232:235], v[42:45]
	v_mfma_f32_16x16x32_bf16 v[46:49], v[178:181], v[232:235], v[46:49]
	v_mfma_f32_16x16x32_bf16 v[54:57], v[178:181], v[202:205], v[54:57]
	v_mfma_f32_16x16x32_bf16 v[50:53], v[186:189], v[202:205], v[50:53]
	v_mfma_f32_16x16x32_bf16 v[58:61], v[186:189], v[194:197], v[58:61]
	v_mfma_f32_16x16x32_bf16 v[62:65], v[178:181], v[194:197], v[62:65]
	v_mfma_f32_16x16x32_bf16 v[126:129], v[154:157], v[198:201], v[126:129]
	v_mfma_f32_16x16x32_bf16 v[122:125], v[174:177], v[198:201], v[122:125]
	v_mfma_f32_16x16x32_bf16 v[114:117], v[174:177], v[228:231], v[114:117]
	v_mfma_f32_16x16x32_bf16 v[118:121], v[154:157], v[228:231], v[118:121]
	v_mfma_f32_16x16x32_bf16 v[110:113], v[154:157], v[236:239], v[110:113]
	v_mfma_f32_16x16x32_bf16 v[106:109], v[174:177], v[236:239], v[106:109]
	v_mfma_f32_16x16x32_bf16 v[98:101], v[174:177], v[244:247], v[98:101]
	v_mfma_f32_16x16x32_bf16 v[102:105], v[154:157], v[244:247], v[102:105]
	v_mfma_f32_16x16x32_bf16 v[38:41], v[182:185], v[244:247], v[38:41]
	v_mfma_f32_16x16x32_bf16 v[34:37], v[190:193], v[244:247], v[34:37]
	v_mfma_f32_16x16x32_bf16 v[42:45], v[190:193], v[236:239], v[42:45]
	v_mfma_f32_16x16x32_bf16 v[46:49], v[182:185], v[236:239], v[46:49]
	v_mfma_f32_16x16x32_bf16 v[54:57], v[182:185], v[228:231], v[54:57]
	v_mfma_f32_16x16x32_bf16 v[50:53], v[190:193], v[228:231], v[50:53]
	v_mfma_f32_16x16x32_bf16 v[58:61], v[190:193], v[198:201], v[58:61]
	v_mfma_f32_16x16x32_bf16 v[62:65], v[182:185], v[198:201], v[62:65]
	s_barrier
	s_setprio 0
	s_mov_b32 m0, s33
	s_or_b32 s52, s47, 0x80
	ds_read_b128 v[194:197], v140 offset:49152
	ds_read_b128 v[198:201], v140 offset:50176
	ds_read_b128 v[202:205], v140 offset:51200
	ds_read_b128 v[228:231], v140 offset:52224
	ds_read_b128 v[232:235], v140 offset:53248
	ds_read_b128 v[236:239], v140 offset:54272
	ds_read_b128 v[240:243], v140 offset:55296
	ds_read_b128 v[244:247], v140 offset:56320
	buffer_load_dwordx4 v134, s[64:67], s52 offen lds
	s_mov_b32 m0, s34
	s_add_i32 s47, s47, 0x200080
	buffer_load_dwordx4 v136, s[64:67], s52 offen lds
	s_mov_b32 m0, s37
	s_nop 0
	buffer_load_dwordx4 v134, s[64:67], s47 offen lds
	s_mov_b32 m0, s68
	s_nop 0
	buffer_load_dwordx4 v136, s[64:67], s47 offen lds
	s_mov_b32 m0, s35
	s_nop 0
	buffer_load_dwordx4 v131, s[60:63], s27 offen lds
	s_mov_b32 m0, s36
	s_nop 0
	buffer_load_dwordx4 v135, s[60:63], s27 offen lds
	s_waitcnt vmcnt(8)
	s_waitcnt lgkmcnt(0)
	s_setprio 1
	s_barrier
	v_mfma_f32_16x16x32_bf16 v[94:97], v[142:145], v[194:197], v[94:97]
	v_mfma_f32_16x16x32_bf16 v[90:93], v[170:173], v[194:197], v[90:93]
	v_mfma_f32_16x16x32_bf16 v[82:85], v[170:173], v[202:205], v[82:85]
	v_mfma_f32_16x16x32_bf16 v[86:89], v[142:145], v[202:205], v[86:89]
	v_mfma_f32_16x16x32_bf16 v[78:81], v[142:145], v[232:235], v[78:81]
	v_mfma_f32_16x16x32_bf16 v[74:77], v[170:173], v[232:235], v[74:77]
	v_mfma_f32_16x16x32_bf16 v[66:69], v[170:173], v[240:243], v[66:69]
	v_mfma_f32_16x16x32_bf16 v[70:73], v[142:145], v[240:243], v[70:73]
	v_mfma_f32_16x16x32_bf16 v[6:9], v[178:181], v[240:243], v[6:9]
	v_mfma_f32_16x16x32_bf16 v[2:5], v[186:189], v[240:243], v[2:5]
	v_mfma_f32_16x16x32_bf16 v[10:13], v[186:189], v[232:235], v[10:13]
	v_mfma_f32_16x16x32_bf16 v[14:17], v[178:181], v[232:235], v[14:17]
	v_mfma_f32_16x16x32_bf16 v[22:25], v[178:181], v[202:205], v[22:25]
	v_mfma_f32_16x16x32_bf16 v[18:21], v[186:189], v[202:205], v[18:21]
	v_mfma_f32_16x16x32_bf16 v[26:29], v[186:189], v[194:197], v[26:29]
	v_mfma_f32_16x16x32_bf16 v[30:33], v[178:181], v[194:197], v[30:33]
	v_mfma_f32_16x16x32_bf16 v[94:97], v[154:157], v[198:201], v[94:97]
	v_mfma_f32_16x16x32_bf16 v[90:93], v[174:177], v[198:201], v[90:93]
	v_mfma_f32_16x16x32_bf16 v[82:85], v[174:177], v[228:231], v[82:85]
	v_mfma_f32_16x16x32_bf16 v[86:89], v[154:157], v[228:231], v[86:89]
	v_mfma_f32_16x16x32_bf16 v[78:81], v[154:157], v[236:239], v[78:81]
	v_mfma_f32_16x16x32_bf16 v[74:77], v[174:177], v[236:239], v[74:77]
	v_mfma_f32_16x16x32_bf16 v[66:69], v[174:177], v[244:247], v[66:69]
	v_mfma_f32_16x16x32_bf16 v[70:73], v[154:157], v[244:247], v[70:73]
	v_mfma_f32_16x16x32_bf16 v[6:9], v[182:185], v[244:247], v[6:9]
	v_mfma_f32_16x16x32_bf16 v[2:5], v[190:193], v[244:247], v[2:5]
	v_mfma_f32_16x16x32_bf16 v[10:13], v[190:193], v[236:239], v[10:13]
	v_mfma_f32_16x16x32_bf16 v[14:17], v[182:185], v[236:239], v[14:17]
	v_mfma_f32_16x16x32_bf16 v[22:25], v[182:185], v[228:231], v[22:25]
	v_mfma_f32_16x16x32_bf16 v[18:21], v[190:193], v[228:231], v[18:21]
	v_mfma_f32_16x16x32_bf16 v[26:29], v[190:193], v[198:201], v[26:29]
	v_mfma_f32_16x16x32_bf16 v[30:33], v[182:185], v[198:201], v[30:33]
	s_barrier
	s_setprio 0
	s_add_i32 s26, s26, 2
	s_addk_i32 s19, 0x100
	s_addk_i32 s22, 0x100
	s_cmpk_gt_u32 s26, 0x7d
	s_cbranch_scc0 .LBB0_1223
	s_and_b64 vcc, exec, s[42:43]
	s_cbranch_vccz .LBB0_1226
	s_barrier

.LBB0_1252:
	s_lshl_b32 s12, s73, 20
	s_and_b64 s[8:9], s[40:41], exec
	s_cselect_b32 s8, s12, s26
	s_lshl_b32 s22, s82, 20
	s_and_b64 s[70:71], s[40:41], exec
	s_cselect_b32 s9, s22, s27
	s_add_i32 s26, s26, 0x80080
	s_addk_i32 s27, 0x100
	s_mov_b32 s83, -2
	v_add_u32_e32 v141, 0x10000, v139
	ds_read_b128 v[142:145], v141
	ds_read_b128 v[154:157], v141 offset:1024
	ds_read_b128 v[170:173], v141 offset:2048
	ds_read_b128 v[174:177], v141 offset:3072
	v_add_u32_e32 v141, 0x14000, v139
	ds_read_b128 v[178:181], v141
	ds_read_b128 v[182:185], v141 offset:1024
	ds_read_b128 v[186:189], v141 offset:2048
	ds_read_b128 v[190:193], v141 offset:3072
	s_add_i32 s52, s26, 0xfff80080
	s_cmp_eq_u32 s83, 28
	s_cselect_b32 s52, s8, s52
	s_cselect_b32 s85, s9, s27
	s_or_b32 s84, s52, 0x80
	s_mov_b32 m0, s72
	ds_read_b128 v[194:197], v140
	ds_read_b128 v[198:201], v140 offset:1024
	ds_read_b128 v[202:205], v140 offset:2048
	ds_read_b128 v[228:231], v140 offset:3072
	ds_read_b128 v[232:235], v140 offset:4096
	ds_read_b128 v[236:239], v140 offset:5120
	ds_read_b128 v[240:243], v140 offset:6144
	ds_read_b128 v[244:247], v140 offset:7168
	buffer_load_dwordx4 v131, s[60:63], s26 offen lds
	s_mov_b32 m0, s46
	s_nop 0
	buffer_load_dwordx4 v135, s[60:63], s26 offen lds
	s_waitcnt vmcnt(8)
	s_waitcnt lgkmcnt(0)
	s_setprio 1
	s_barrier
	v_mfma_f32_16x16x32_bf16 v[126:129], v[142:145], v[194:197], 0
	v_mfma_f32_16x16x32_bf16 v[122:125], v[170:173], v[194:197], 0
	v_mfma_f32_16x16x32_bf16 v[114:117], v[170:173], v[202:205], 0
	v_mfma_f32_16x16x32_bf16 v[118:121], v[142:145], v[202:205], 0
	v_mfma_f32_16x16x32_bf16 v[110:113], v[142:145], v[232:235], 0
	v_mfma_f32_16x16x32_bf16 v[106:109], v[170:173], v[232:235], 0
	v_mfma_f32_16x16x32_bf16 v[98:101], v[170:173], v[240:243], 0
	v_mfma_f32_16x16x32_bf16 v[102:105], v[142:145], v[240:243], 0
	v_mfma_f32_16x16x32_bf16 v[38:41], v[178:181], v[240:243], 0
	v_mfma_f32_16x16x32_bf16 v[34:37], v[186:189], v[240:243], 0
	v_mfma_f32_16x16x32_bf16 v[42:45], v[186:189], v[232:235], 0
	v_mfma_f32_16x16x32_bf16 v[46:49], v[178:181], v[232:235], 0
	v_mfma_f32_16x16x32_bf16 v[54:57], v[178:181], v[202:205], 0
	v_mfma_f32_16x16x32_bf16 v[50:53], v[186:189], v[202:205], 0
	v_mfma_f32_16x16x32_bf16 v[58:61], v[186:189], v[194:197], 0
	v_mfma_f32_16x16x32_bf16 v[62:65], v[178:181], v[194:197], 0
	v_mfma_f32_16x16x32_bf16 v[126:129], v[154:157], v[198:201], v[126:129]
	v_mfma_f32_16x16x32_bf16 v[122:125], v[174:177], v[198:201], v[122:125]
	v_mfma_f32_16x16x32_bf16 v[114:117], v[174:177], v[228:231], v[114:117]
	v_mfma_f32_16x16x32_bf16 v[118:121], v[154:157], v[228:231], v[118:121]
	v_mfma_f32_16x16x32_bf16 v[110:113], v[154:157], v[236:239], v[110:113]
	v_mfma_f32_16x16x32_bf16 v[106:109], v[174:177], v[236:239], v[106:109]
	v_mfma_f32_16x16x32_bf16 v[98:101], v[174:177], v[244:247], v[98:101]
	v_mfma_f32_16x16x32_bf16 v[102:105], v[154:157], v[244:247], v[102:105]
	v_mfma_f32_16x16x32_bf16 v[38:41], v[182:185], v[244:247], v[38:41]
	v_mfma_f32_16x16x32_bf16 v[34:37], v[190:193], v[244:247], v[34:37]
	v_mfma_f32_16x16x32_bf16 v[42:45], v[190:193], v[236:239], v[42:45]
	v_mfma_f32_16x16x32_bf16 v[46:49], v[182:185], v[236:239], v[46:49]
	v_mfma_f32_16x16x32_bf16 v[54:57], v[182:185], v[228:231], v[54:57]
	v_mfma_f32_16x16x32_bf16 v[50:53], v[190:193], v[228:231], v[50:53]
	v_mfma_f32_16x16x32_bf16 v[58:61], v[190:193], v[198:201], v[58:61]
	v_mfma_f32_16x16x32_bf16 v[62:65], v[182:185], v[198:201], v[62:65]
	s_barrier
	s_setprio 0
	s_mov_b32 m0, s21
	s_mov_b32 s70, s62
	s_mov_b32 s71, s63
	ds_read_b128 v[194:197], v140 offset:16384
	ds_read_b128 v[198:201], v140 offset:17408
	ds_read_b128 v[202:205], v140 offset:18432
	ds_read_b128 v[228:231], v140 offset:19456
	ds_read_b128 v[232:235], v140 offset:20480
	ds_read_b128 v[236:239], v140 offset:21504
	ds_read_b128 v[240:243], v140 offset:22528
	ds_read_b128 v[244:247], v140 offset:23552
	buffer_load_dwordx4 v134, s[68:71], s85 offen lds
	s_mov_b32 m0, s23
	s_add_i32 s53, s85, 0x80000
	buffer_load_dwordx4 v136, s[68:71], s85 offen lds
	s_mov_b32 m0, s24
	s_nop 0
	buffer_load_dwordx4 v134, s[68:71], s53 offen lds
	s_mov_b32 m0, s25
	s_nop 0
	buffer_load_dwordx4 v136, s[68:71], s53 offen lds
	s_mov_b32 m0, s16
	s_nop 0
	buffer_load_dwordx4 v131, s[60:63], s52 offen lds
	s_mov_b32 m0, s30
	s_nop 0
	buffer_load_dwordx4 v135, s[60:63], s52 offen lds
	s_waitcnt vmcnt(8)
	s_waitcnt lgkmcnt(0)
	s_setprio 1
	s_barrier
	v_mfma_f32_16x16x32_bf16 v[94:97], v[142:145], v[194:197], 0
	v_mfma_f32_16x16x32_bf16 v[90:93], v[170:173], v[194:197], 0
	v_mfma_f32_16x16x32_bf16 v[82:85], v[170:173], v[202:205], 0
	v_mfma_f32_16x16x32_bf16 v[86:89], v[142:145], v[202:205], 0
	v_mfma_f32_16x16x32_bf16 v[78:81], v[142:145], v[232:235], 0
	v_mfma_f32_16x16x32_bf16 v[74:77], v[170:173], v[232:235], 0
	v_mfma_f32_16x16x32_bf16 v[66:69], v[170:173], v[240:243], 0
	v_mfma_f32_16x16x32_bf16 v[70:73], v[142:145], v[240:243], 0
	v_mfma_f32_16x16x32_bf16 v[6:9], v[178:181], v[240:243], 0
	v_mfma_f32_16x16x32_bf16 v[2:5], v[186:189], v[240:243], 0
	v_mfma_f32_16x16x32_bf16 v[10:13], v[186:189], v[232:235], 0
	v_mfma_f32_16x16x32_bf16 v[14:17], v[178:181], v[232:235], 0
	v_mfma_f32_16x16x32_bf16 v[22:25], v[178:181], v[202:205], 0
	v_mfma_f32_16x16x32_bf16 v[18:21], v[186:189], v[202:205], 0
	v_mfma_f32_16x16x32_bf16 v[26:29], v[186:189], v[194:197], 0
	v_mfma_f32_16x16x32_bf16 v[30:33], v[178:181], v[194:197], 0
	v_mfma_f32_16x16x32_bf16 v[94:97], v[154:157], v[198:201], v[94:97]
	v_mfma_f32_16x16x32_bf16 v[90:93], v[174:177], v[198:201], v[90:93]
	v_mfma_f32_16x16x32_bf16 v[82:85], v[174:177], v[228:231], v[82:85]
	v_mfma_f32_16x16x32_bf16 v[86:89], v[154:157], v[228:231], v[86:89]
	v_mfma_f32_16x16x32_bf16 v[78:81], v[154:157], v[236:239], v[78:81]
	v_mfma_f32_16x16x32_bf16 v[74:77], v[174:177], v[236:239], v[74:77]
	v_mfma_f32_16x16x32_bf16 v[66:69], v[174:177], v[244:247], v[66:69]
	v_mfma_f32_16x16x32_bf16 v[70:73], v[154:157], v[244:247], v[70:73]
	v_mfma_f32_16x16x32_bf16 v[6:9], v[182:185], v[244:247], v[6:9]
	v_mfma_f32_16x16x32_bf16 v[2:5], v[190:193], v[244:247], v[2:5]
	v_mfma_f32_16x16x32_bf16 v[10:13], v[190:193], v[236:239], v[10:13]
	v_mfma_f32_16x16x32_bf16 v[14:17], v[182:185], v[236:239], v[14:17]
	v_mfma_f32_16x16x32_bf16 v[22:25], v[182:185], v[228:231], v[22:25]
	v_mfma_f32_16x16x32_bf16 v[18:21], v[190:193], v[228:231], v[18:21]
	v_mfma_f32_16x16x32_bf16 v[26:29], v[190:193], v[198:201], v[26:29]
	v_mfma_f32_16x16x32_bf16 v[30:33], v[182:185], v[198:201], v[30:33]
	s_barrier
	s_setprio 0
	v_add_u32_e32 v141, 0x18000, v139
	ds_read_b128 v[142:145], v141
	ds_read_b128 v[154:157], v141 offset:1024
	ds_read_b128 v[170:173], v141 offset:2048
	ds_read_b128 v[174:177], v141 offset:3072
	v_add_u32_e32 v141, 0x1c000, v139
	ds_read_b128 v[178:181], v141
	ds_read_b128 v[182:185], v141 offset:1024
	ds_read_b128 v[186:189], v141 offset:2048
	ds_read_b128 v[190:193], v141 offset:3072
	s_add_i32 s52, s52, 0x80000
	s_mov_b32 m0, s31
	ds_read_b128 v[194:197], v140 offset:32768
	ds_read_b128 v[198:201], v140 offset:33792
	ds_read_b128 v[202:205], v140 offset:34816
	ds_read_b128 v[228:231], v140 offset:35840
	ds_read_b128 v[232:235], v140 offset:36864
	ds_read_b128 v[236:239], v140 offset:37888
	ds_read_b128 v[240:243], v140 offset:38912
	ds_read_b128 v[244:247], v140 offset:39936
	buffer_load_dwordx4 v131, s[60:63], s52 offen lds
	s_mov_b32 m0, s33
	s_nop 0
	buffer_load_dwordx4 v135, s[60:63], s52 offen lds
	s_waitcnt vmcnt(8)
	s_waitcnt lgkmcnt(0)
	s_setprio 1
	s_barrier
	v_mfma_f32_16x16x32_bf16 v[126:129], v[142:145], v[194:197], v[126:129]
	v_mfma_f32_16x16x32_bf16 v[122:125], v[170:173], v[194:197], v[122:125]
	v_mfma_f32_16x16x32_bf16 v[114:117], v[170:173], v[202:205], v[114:117]
	v_mfma_f32_16x16x32_bf16 v[118:121], v[142:145], v[202:205], v[118:121]
	v_mfma_f32_16x16x32_bf16 v[110:113], v[142:145], v[232:235], v[110:113]
	v_mfma_f32_16x16x32_bf16 v[106:109], v[170:173], v[232:235], v[106:109]
	v_mfma_f32_16x16x32_bf16 v[98:101], v[170:173], v[240:243], v[98:101]
	v_mfma_f32_16x16x32_bf16 v[102:105], v[142:145], v[240:243], v[102:105]
	v_mfma_f32_16x16x32_bf16 v[38:41], v[178:181], v[240:243], v[38:41]
	v_mfma_f32_16x16x32_bf16 v[34:37], v[186:189], v[240:243], v[34:37]
	v_mfma_f32_16x16x32_bf16 v[42:45], v[186:189], v[232:235], v[42:45]
	v_mfma_f32_16x16x32_bf16 v[46:49], v[178:181], v[232:235], v[46:49]
	v_mfma_f32_16x16x32_bf16 v[54:57], v[178:181], v[202:205], v[54:57]
	v_mfma_f32_16x16x32_bf16 v[50:53], v[186:189], v[202:205], v[50:53]
	v_mfma_f32_16x16x32_bf16 v[58:61], v[186:189], v[194:197], v[58:61]
	v_mfma_f32_16x16x32_bf16 v[62:65], v[178:181], v[194:197], v[62:65]
	v_mfma_f32_16x16x32_bf16 v[126:129], v[154:157], v[198:201], v[126:129]
	v_mfma_f32_16x16x32_bf16 v[122:125], v[174:177], v[198:201], v[122:125]
	v_mfma_f32_16x16x32_bf16 v[114:117], v[174:177], v[228:231], v[114:117]
	v_mfma_f32_16x16x32_bf16 v[118:121], v[154:157], v[228:231], v[118:121]
	v_mfma_f32_16x16x32_bf16 v[110:113], v[154:157], v[236:239], v[110:113]
	v_mfma_f32_16x16x32_bf16 v[106:109], v[174:177], v[236:239], v[106:109]
	v_mfma_f32_16x16x32_bf16 v[98:101], v[174:177], v[244:247], v[98:101]
	v_mfma_f32_16x16x32_bf16 v[102:105], v[154:157], v[244:247], v[102:105]
	v_mfma_f32_16x16x32_bf16 v[38:41], v[182:185], v[244:247], v[38:41]
	v_mfma_f32_16x16x32_bf16 v[34:37], v[190:193], v[244:247], v[34:37]
	v_mfma_f32_16x16x32_bf16 v[42:45], v[190:193], v[236:239], v[42:45]
	v_mfma_f32_16x16x32_bf16 v[46:49], v[182:185], v[236:239], v[46:49]
	v_mfma_f32_16x16x32_bf16 v[54:57], v[182:185], v[228:231], v[54:57]
	v_mfma_f32_16x16x32_bf16 v[50:53], v[190:193], v[228:231], v[50:53]
	v_mfma_f32_16x16x32_bf16 v[58:61], v[190:193], v[198:201], v[58:61]
	v_mfma_f32_16x16x32_bf16 v[62:65], v[182:185], v[198:201], v[62:65]
	s_barrier
	s_setprio 0
	s_mov_b32 m0, s34
	s_or_b32 s52, s85, 0x80
	ds_read_b128 v[194:197], v140 offset:49152
	ds_read_b128 v[198:201], v140 offset:50176
	ds_read_b128 v[202:205], v140 offset:51200
	ds_read_b128 v[228:231], v140 offset:52224
	ds_read_b128 v[232:235], v140 offset:53248
	ds_read_b128 v[236:239], v140 offset:54272
	ds_read_b128 v[240:243], v140 offset:55296
	ds_read_b128 v[244:247], v140 offset:56320
	buffer_load_dwordx4 v134, s[68:71], s52 offen lds
	s_mov_b32 m0, s35
	s_add_i32 s85, s85, 0x80080
	buffer_load_dwordx4 v136, s[68:71], s52 offen lds
	s_mov_b32 m0, s37
	s_nop 0
	buffer_load_dwordx4 v134, s[68:71], s85 offen lds
	s_mov_b32 m0, s65
	s_nop 0
	buffer_load_dwordx4 v136, s[68:71], s85 offen lds
	s_mov_b32 m0, s14
	s_nop 0
	buffer_load_dwordx4 v131, s[60:63], s84 offen lds
	s_mov_b32 m0, s36
	s_nop 0
	buffer_load_dwordx4 v135, s[60:63], s84 offen lds
	s_waitcnt vmcnt(8)
	s_waitcnt lgkmcnt(0)
	s_setprio 1
	s_barrier
	v_mfma_f32_16x16x32_bf16 v[94:97], v[142:145], v[194:197], v[94:97]
	v_mfma_f32_16x16x32_bf16 v[90:93], v[170:173], v[194:197], v[90:93]
	v_mfma_f32_16x16x32_bf16 v[82:85], v[170:173], v[202:205], v[82:85]
	v_mfma_f32_16x16x32_bf16 v[86:89], v[142:145], v[202:205], v[86:89]
	v_mfma_f32_16x16x32_bf16 v[78:81], v[142:145], v[232:235], v[78:81]
	v_mfma_f32_16x16x32_bf16 v[74:77], v[170:173], v[232:235], v[74:77]
	v_mfma_f32_16x16x32_bf16 v[66:69], v[170:173], v[240:243], v[66:69]
	v_mfma_f32_16x16x32_bf16 v[70:73], v[142:145], v[240:243], v[70:73]
	v_mfma_f32_16x16x32_bf16 v[6:9], v[178:181], v[240:243], v[6:9]
	v_mfma_f32_16x16x32_bf16 v[2:5], v[186:189], v[240:243], v[2:5]
	v_mfma_f32_16x16x32_bf16 v[10:13], v[186:189], v[232:235], v[10:13]
	v_mfma_f32_16x16x32_bf16 v[14:17], v[178:181], v[232:235], v[14:17]
	v_mfma_f32_16x16x32_bf16 v[22:25], v[178:181], v[202:205], v[22:25]
	v_mfma_f32_16x16x32_bf16 v[18:21], v[186:189], v[202:205], v[18:21]
	v_mfma_f32_16x16x32_bf16 v[26:29], v[186:189], v[194:197], v[26:29]
	v_mfma_f32_16x16x32_bf16 v[30:33], v[178:181], v[194:197], v[30:33]
	v_mfma_f32_16x16x32_bf16 v[94:97], v[154:157], v[198:201], v[94:97]
	v_mfma_f32_16x16x32_bf16 v[90:93], v[174:177], v[198:201], v[90:93]
	v_mfma_f32_16x16x32_bf16 v[82:85], v[174:177], v[228:231], v[82:85]
	v_mfma_f32_16x16x32_bf16 v[86:89], v[154:157], v[228:231], v[86:89]
	v_mfma_f32_16x16x32_bf16 v[78:81], v[154:157], v[236:239], v[78:81]
	v_mfma_f32_16x16x32_bf16 v[74:77], v[174:177], v[236:239], v[74:77]
	v_mfma_f32_16x16x32_bf16 v[66:69], v[174:177], v[244:247], v[66:69]
	v_mfma_f32_16x16x32_bf16 v[70:73], v[154:157], v[244:247], v[70:73]
	v_mfma_f32_16x16x32_bf16 v[6:9], v[182:185], v[244:247], v[6:9]
	v_mfma_f32_16x16x32_bf16 v[2:5], v[190:193], v[244:247], v[2:5]
	v_mfma_f32_16x16x32_bf16 v[10:13], v[190:193], v[236:239], v[10:13]
	v_mfma_f32_16x16x32_bf16 v[14:17], v[182:185], v[236:239], v[14:17]
	v_mfma_f32_16x16x32_bf16 v[22:25], v[182:185], v[228:231], v[22:25]
	v_mfma_f32_16x16x32_bf16 v[18:21], v[190:193], v[228:231], v[18:21]
	v_mfma_f32_16x16x32_bf16 v[26:29], v[190:193], v[198:201], v[26:29]
	v_mfma_f32_16x16x32_bf16 v[30:33], v[182:185], v[198:201], v[30:33]
	s_barrier
	s_setprio 0
	s_add_i32 s83, s83, 2
	s_addk_i32 s26, 0x100
	s_addk_i32 s27, 0x100
	s_cmp_gt_u32 s83, 29
.LBB0_1253:
	v_add_u32_e32 v141, 0x10000, v139
	ds_read_b128 v[142:145], v141
	ds_read_b128 v[154:157], v141 offset:1024
	ds_read_b128 v[170:173], v141 offset:2048
	ds_read_b128 v[174:177], v141 offset:3072
	v_add_u32_e32 v141, 0x14000, v139
	ds_read_b128 v[178:181], v141
	ds_read_b128 v[182:185], v141 offset:1024
	ds_read_b128 v[186:189], v141 offset:2048
	ds_read_b128 v[190:193], v141 offset:3072
	s_add_i32 s52, s26, 0xfff80080
	s_cmp_eq_u32 s83, 28
	s_cselect_b32 s52, s8, s52
	s_cselect_b32 s85, s9, s27
	s_or_b32 s84, s52, 0x80
	s_mov_b32 m0, s72
	ds_read_b128 v[194:197], v140
	ds_read_b128 v[198:201], v140 offset:1024
	ds_read_b128 v[202:205], v140 offset:2048
	ds_read_b128 v[228:231], v140 offset:3072
	ds_read_b128 v[232:235], v140 offset:4096
	ds_read_b128 v[236:239], v140 offset:5120
	ds_read_b128 v[240:243], v140 offset:6144
	ds_read_b128 v[244:247], v140 offset:7168
	buffer_load_dwordx4 v131, s[60:63], s26 offen lds
	s_mov_b32 m0, s46
	s_nop 0
	buffer_load_dwordx4 v135, s[60:63], s26 offen lds
	s_waitcnt vmcnt(8)
	s_waitcnt lgkmcnt(0)
	s_setprio 1
	s_barrier
	v_mfma_f32_16x16x32_bf16 v[126:129], v[142:145], v[194:197], v[126:129]
	v_mfma_f32_16x16x32_bf16 v[122:125], v[170:173], v[194:197], v[122:125]
	v_mfma_f32_16x16x32_bf16 v[114:117], v[170:173], v[202:205], v[114:117]
	v_mfma_f32_16x16x32_bf16 v[118:121], v[142:145], v[202:205], v[118:121]
	v_mfma_f32_16x16x32_bf16 v[110:113], v[142:145], v[232:235], v[110:113]
	v_mfma_f32_16x16x32_bf16 v[106:109], v[170:173], v[232:235], v[106:109]
	v_mfma_f32_16x16x32_bf16 v[98:101], v[170:173], v[240:243], v[98:101]
	v_mfma_f32_16x16x32_bf16 v[102:105], v[142:145], v[240:243], v[102:105]
	v_mfma_f32_16x16x32_bf16 v[38:41], v[178:181], v[240:243], v[38:41]
	v_mfma_f32_16x16x32_bf16 v[34:37], v[186:189], v[240:243], v[34:37]
	v_mfma_f32_16x16x32_bf16 v[42:45], v[186:189], v[232:235], v[42:45]
	v_mfma_f32_16x16x32_bf16 v[46:49], v[178:181], v[232:235], v[46:49]
	v_mfma_f32_16x16x32_bf16 v[54:57], v[178:181], v[202:205], v[54:57]
	v_mfma_f32_16x16x32_bf16 v[50:53], v[186:189], v[202:205], v[50:53]
	v_mfma_f32_16x16x32_bf16 v[58:61], v[186:189], v[194:197], v[58:61]
	v_mfma_f32_16x16x32_bf16 v[62:65], v[178:181], v[194:197], v[62:65]
	v_mfma_f32_16x16x32_bf16 v[126:129], v[154:157], v[198:201], v[126:129]
	v_mfma_f32_16x16x32_bf16 v[122:125], v[174:177], v[198:201], v[122:125]
	v_mfma_f32_16x16x32_bf16 v[114:117], v[174:177], v[228:231], v[114:117]
	v_mfma_f32_16x16x32_bf16 v[118:121], v[154:157], v[228:231], v[118:121]
	v_mfma_f32_16x16x32_bf16 v[110:113], v[154:157], v[236:239], v[110:113]
	v_mfma_f32_16x16x32_bf16 v[106:109], v[174:177], v[236:239], v[106:109]
	v_mfma_f32_16x16x32_bf16 v[98:101], v[174:177], v[244:247], v[98:101]
	v_mfma_f32_16x16x32_bf16 v[102:105], v[154:157], v[244:247], v[102:105]
	v_mfma_f32_16x16x32_bf16 v[38:41], v[182:185], v[244:247], v[38:41]
	v_mfma_f32_16x16x32_bf16 v[34:37], v[190:193], v[244:247], v[34:37]
	v_mfma_f32_16x16x32_bf16 v[42:45], v[190:193], v[236:239], v[42:45]
	v_mfma_f32_16x16x32_bf16 v[46:49], v[182:185], v[236:239], v[46:49]
	v_mfma_f32_16x16x32_bf16 v[54:57], v[182:185], v[228:231], v[54:57]
	v_mfma_f32_16x16x32_bf16 v[50:53], v[190:193], v[228:231], v[50:53]
	v_mfma_f32_16x16x32_bf16 v[58:61], v[190:193], v[198:201], v[58:61]
	v_mfma_f32_16x16x32_bf16 v[62:65], v[182:185], v[198:201], v[62:65]
	s_barrier
	s_setprio 0
	s_mov_b32 m0, s21
	s_mov_b32 s70, s62
	s_mov_b32 s71, s63
	ds_read_b128 v[194:197], v140 offset:16384
	ds_read_b128 v[198:201], v140 offset:17408
	ds_read_b128 v[202:205], v140 offset:18432
	ds_read_b128 v[228:231], v140 offset:19456
	ds_read_b128 v[232:235], v140 offset:20480
	ds_read_b128 v[236:239], v140 offset:21504
	ds_read_b128 v[240:243], v140 offset:22528
	ds_read_b128 v[244:247], v140 offset:23552
	buffer_load_dwordx4 v134, s[68:71], s85 offen lds
	s_mov_b32 m0, s23
	s_add_i32 s53, s85, 0x80000
	buffer_load_dwordx4 v136, s[68:71], s85 offen lds
	s_mov_b32 m0, s24
	s_nop 0
	buffer_load_dwordx4 v134, s[68:71], s53 offen lds
	s_mov_b32 m0, s25
	s_nop 0
	buffer_load_dwordx4 v136, s[68:71], s53 offen lds
	s_mov_b32 m0, s16
	s_nop 0
	buffer_load_dwordx4 v131, s[60:63], s52 offen lds
	s_mov_b32 m0, s30
	s_nop 0
	buffer_load_dwordx4 v135, s[60:63], s52 offen lds
	s_waitcnt vmcnt(8)
	s_waitcnt lgkmcnt(0)
	s_setprio 1
	s_barrier
	v_mfma_f32_16x16x32_bf16 v[94:97], v[142:145], v[194:197], v[94:97]
	v_mfma_f32_16x16x32_bf16 v[90:93], v[170:173], v[194:197], v[90:93]
	v_mfma_f32_16x16x32_bf16 v[82:85], v[170:173], v[202:205], v[82:85]
	v_mfma_f32_16x16x32_bf16 v[86:89], v[142:145], v[202:205], v[86:89]
	v_mfma_f32_16x16x32_bf16 v[78:81], v[142:145], v[232:235], v[78:81]
	v_mfma_f32_16x16x32_bf16 v[74:77], v[170:173], v[232:235], v[74:77]
	v_mfma_f32_16x16x32_bf16 v[66:69], v[170:173], v[240:243], v[66:69]
	v_mfma_f32_16x16x32_bf16 v[70:73], v[142:145], v[240:243], v[70:73]
	v_mfma_f32_16x16x32_bf16 v[6:9], v[178:181], v[240:243], v[6:9]
	v_mfma_f32_16x16x32_bf16 v[2:5], v[186:189], v[240:243], v[2:5]
	v_mfma_f32_16x16x32_bf16 v[10:13], v[186:189], v[232:235], v[10:13]
	v_mfma_f32_16x16x32_bf16 v[14:17], v[178:181], v[232:235], v[14:17]
	v_mfma_f32_16x16x32_bf16 v[22:25], v[178:181], v[202:205], v[22:25]
	v_mfma_f32_16x16x32_bf16 v[18:21], v[186:189], v[202:205], v[18:21]
	v_mfma_f32_16x16x32_bf16 v[26:29], v[186:189], v[194:197], v[26:29]
	v_mfma_f32_16x16x32_bf16 v[30:33], v[178:181], v[194:197], v[30:33]
	v_mfma_f32_16x16x32_bf16 v[94:97], v[154:157], v[198:201], v[94:97]
	v_mfma_f32_16x16x32_bf16 v[90:93], v[174:177], v[198:201], v[90:93]
	v_mfma_f32_16x16x32_bf16 v[82:85], v[174:177], v[228:231], v[82:85]
	v_mfma_f32_16x16x32_bf16 v[86:89], v[154:157], v[228:231], v[86:89]
	v_mfma_f32_16x16x32_bf16 v[78:81], v[154:157], v[236:239], v[78:81]
	v_mfma_f32_16x16x32_bf16 v[74:77], v[174:177], v[236:239], v[74:77]
	v_mfma_f32_16x16x32_bf16 v[66:69], v[174:177], v[244:247], v[66:69]
	v_mfma_f32_16x16x32_bf16 v[70:73], v[154:157], v[244:247], v[70:73]
	v_mfma_f32_16x16x32_bf16 v[6:9], v[182:185], v[244:247], v[6:9]
	v_mfma_f32_16x16x32_bf16 v[2:5], v[190:193], v[244:247], v[2:5]
	v_mfma_f32_16x16x32_bf16 v[10:13], v[190:193], v[236:239], v[10:13]
	v_mfma_f32_16x16x32_bf16 v[14:17], v[182:185], v[236:239], v[14:17]
	v_mfma_f32_16x16x32_bf16 v[22:25], v[182:185], v[228:231], v[22:25]
	v_mfma_f32_16x16x32_bf16 v[18:21], v[190:193], v[228:231], v[18:21]
	v_mfma_f32_16x16x32_bf16 v[26:29], v[190:193], v[198:201], v[26:29]
	v_mfma_f32_16x16x32_bf16 v[30:33], v[182:185], v[198:201], v[30:33]
	s_barrier
	s_setprio 0
	v_add_u32_e32 v141, 0x18000, v139
	ds_read_b128 v[142:145], v141
	ds_read_b128 v[154:157], v141 offset:1024
	ds_read_b128 v[170:173], v141 offset:2048
	ds_read_b128 v[174:177], v141 offset:3072
	v_add_u32_e32 v141, 0x1c000, v139
	ds_read_b128 v[178:181], v141
	ds_read_b128 v[182:185], v141 offset:1024
	ds_read_b128 v[186:189], v141 offset:2048
	ds_read_b128 v[190:193], v141 offset:3072
	s_add_i32 s52, s52, 0x80000
	s_mov_b32 m0, s31
	ds_read_b128 v[194:197], v140 offset:32768
	ds_read_b128 v[198:201], v140 offset:33792
	ds_read_b128 v[202:205], v140 offset:34816
	ds_read_b128 v[228:231], v140 offset:35840
	ds_read_b128 v[232:235], v140 offset:36864
	ds_read_b128 v[236:239], v140 offset:37888
	ds_read_b128 v[240:243], v140 offset:38912
	ds_read_b128 v[244:247], v140 offset:39936
	buffer_load_dwordx4 v131, s[60:63], s52 offen lds
	s_mov_b32 m0, s33
	s_nop 0
	buffer_load_dwordx4 v135, s[60:63], s52 offen lds
	s_waitcnt vmcnt(8)
	s_waitcnt lgkmcnt(0)
	s_setprio 1
	s_barrier
	v_mfma_f32_16x16x32_bf16 v[126:129], v[142:145], v[194:197], v[126:129]
	v_mfma_f32_16x16x32_bf16 v[122:125], v[170:173], v[194:197], v[122:125]
	v_mfma_f32_16x16x32_bf16 v[114:117], v[170:173], v[202:205], v[114:117]
	v_mfma_f32_16x16x32_bf16 v[118:121], v[142:145], v[202:205], v[118:121]
	v_mfma_f32_16x16x32_bf16 v[110:113], v[142:145], v[232:235], v[110:113]
	v_mfma_f32_16x16x32_bf16 v[106:109], v[170:173], v[232:235], v[106:109]
	v_mfma_f32_16x16x32_bf16 v[98:101], v[170:173], v[240:243], v[98:101]
	v_mfma_f32_16x16x32_bf16 v[102:105], v[142:145], v[240:243], v[102:105]
	v_mfma_f32_16x16x32_bf16 v[38:41], v[178:181], v[240:243], v[38:41]
	v_mfma_f32_16x16x32_bf16 v[34:37], v[186:189], v[240:243], v[34:37]
	v_mfma_f32_16x16x32_bf16 v[42:45], v[186:189], v[232:235], v[42:45]
	v_mfma_f32_16x16x32_bf16 v[46:49], v[178:181], v[232:235], v[46:49]
	v_mfma_f32_16x16x32_bf16 v[54:57], v[178:181], v[202:205], v[54:57]
	v_mfma_f32_16x16x32_bf16 v[50:53], v[186:189], v[202:205], v[50:53]
	v_mfma_f32_16x16x32_bf16 v[58:61], v[186:189], v[194:197], v[58:61]
	v_mfma_f32_16x16x32_bf16 v[62:65], v[178:181], v[194:197], v[62:65]
	v_mfma_f32_16x16x32_bf16 v[126:129], v[154:157], v[198:201], v[126:129]
	v_mfma_f32_16x16x32_bf16 v[122:125], v[174:177], v[198:201], v[122:125]
	v_mfma_f32_16x16x32_bf16 v[114:117], v[174:177], v[228:231], v[114:117]
	v_mfma_f32_16x16x32_bf16 v[118:121], v[154:157], v[228:231], v[118:121]
	v_mfma_f32_16x16x32_bf16 v[110:113], v[154:157], v[236:239], v[110:113]
	v_mfma_f32_16x16x32_bf16 v[106:109], v[174:177], v[236:239], v[106:109]
	v_mfma_f32_16x16x32_bf16 v[98:101], v[174:177], v[244:247], v[98:101]
	v_mfma_f32_16x16x32_bf16 v[102:105], v[154:157], v[244:247], v[102:105]
	v_mfma_f32_16x16x32_bf16 v[38:41], v[182:185], v[244:247], v[38:41]
	v_mfma_f32_16x16x32_bf16 v[34:37], v[190:193], v[244:247], v[34:37]
	v_mfma_f32_16x16x32_bf16 v[42:45], v[190:193], v[236:239], v[42:45]
	v_mfma_f32_16x16x32_bf16 v[46:49], v[182:185], v[236:239], v[46:49]
	v_mfma_f32_16x16x32_bf16 v[54:57], v[182:185], v[228:231], v[54:57]
	v_mfma_f32_16x16x32_bf16 v[50:53], v[190:193], v[228:231], v[50:53]
	v_mfma_f32_16x16x32_bf16 v[58:61], v[190:193], v[198:201], v[58:61]
	v_mfma_f32_16x16x32_bf16 v[62:65], v[182:185], v[198:201], v[62:65]
	s_barrier
	s_setprio 0
	s_mov_b32 m0, s34
	s_or_b32 s52, s85, 0x80
	ds_read_b128 v[194:197], v140 offset:49152
	ds_read_b128 v[198:201], v140 offset:50176
	ds_read_b128 v[202:205], v140 offset:51200
	ds_read_b128 v[228:231], v140 offset:52224
	ds_read_b128 v[232:235], v140 offset:53248
	ds_read_b128 v[236:239], v140 offset:54272
	ds_read_b128 v[240:243], v140 offset:55296
	ds_read_b128 v[244:247], v140 offset:56320
	buffer_load_dwordx4 v134, s[68:71], s52 offen lds
	s_mov_b32 m0, s35
	s_add_i32 s85, s85, 0x80080
	buffer_load_dwordx4 v136, s[68:71], s52 offen lds
	s_mov_b32 m0, s37
	s_nop 0
	buffer_load_dwordx4 v134, s[68:71], s85 offen lds
	s_mov_b32 m0, s65
	s_nop 0
	buffer_load_dwordx4 v136, s[68:71], s85 offen lds
	s_mov_b32 m0, s14
	s_nop 0
	buffer_load_dwordx4 v131, s[60:63], s84 offen lds
	s_mov_b32 m0, s36
	s_nop 0
	buffer_load_dwordx4 v135, s[60:63], s84 offen lds
	s_waitcnt vmcnt(8)
	s_waitcnt lgkmcnt(0)
	s_setprio 1
	s_barrier
	v_mfma_f32_16x16x32_bf16 v[94:97], v[142:145], v[194:197], v[94:97]
	v_mfma_f32_16x16x32_bf16 v[90:93], v[170:173], v[194:197], v[90:93]
	v_mfma_f32_16x16x32_bf16 v[82:85], v[170:173], v[202:205], v[82:85]
	v_mfma_f32_16x16x32_bf16 v[86:89], v[142:145], v[202:205], v[86:89]
	v_mfma_f32_16x16x32_bf16 v[78:81], v[142:145], v[232:235], v[78:81]
	v_mfma_f32_16x16x32_bf16 v[74:77], v[170:173], v[232:235], v[74:77]
	v_mfma_f32_16x16x32_bf16 v[66:69], v[170:173], v[240:243], v[66:69]
	v_mfma_f32_16x16x32_bf16 v[70:73], v[142:145], v[240:243], v[70:73]
	v_mfma_f32_16x16x32_bf16 v[6:9], v[178:181], v[240:243], v[6:9]
	v_mfma_f32_16x16x32_bf16 v[2:5], v[186:189], v[240:243], v[2:5]
	v_mfma_f32_16x16x32_bf16 v[10:13], v[186:189], v[232:235], v[10:13]
	v_mfma_f32_16x16x32_bf16 v[14:17], v[178:181], v[232:235], v[14:17]
	v_mfma_f32_16x16x32_bf16 v[22:25], v[178:181], v[202:205], v[22:25]
	v_mfma_f32_16x16x32_bf16 v[18:21], v[186:189], v[202:205], v[18:21]
	v_mfma_f32_16x16x32_bf16 v[26:29], v[186:189], v[194:197], v[26:29]
	v_mfma_f32_16x16x32_bf16 v[30:33], v[178:181], v[194:197], v[30:33]
	v_mfma_f32_16x16x32_bf16 v[94:97], v[154:157], v[198:201], v[94:97]
	v_mfma_f32_16x16x32_bf16 v[90:93], v[174:177], v[198:201], v[90:93]
	v_mfma_f32_16x16x32_bf16 v[82:85], v[174:177], v[228:231], v[82:85]
	v_mfma_f32_16x16x32_bf16 v[86:89], v[154:157], v[228:231], v[86:89]
	v_mfma_f32_16x16x32_bf16 v[78:81], v[154:157], v[236:239], v[78:81]
	v_mfma_f32_16x16x32_bf16 v[74:77], v[174:177], v[236:239], v[74:77]
	v_mfma_f32_16x16x32_bf16 v[66:69], v[174:177], v[244:247], v[66:69]
	v_mfma_f32_16x16x32_bf16 v[70:73], v[154:157], v[244:247], v[70:73]
	v_mfma_f32_16x16x32_bf16 v[6:9], v[182:185], v[244:247], v[6:9]
	v_mfma_f32_16x16x32_bf16 v[2:5], v[190:193], v[244:247], v[2:5]
	v_mfma_f32_16x16x32_bf16 v[10:13], v[190:193], v[236:239], v[10:13]
	v_mfma_f32_16x16x32_bf16 v[14:17], v[182:185], v[236:239], v[14:17]
	v_mfma_f32_16x16x32_bf16 v[22:25], v[182:185], v[228:231], v[22:25]
	v_mfma_f32_16x16x32_bf16 v[18:21], v[190:193], v[228:231], v[18:21]
	v_mfma_f32_16x16x32_bf16 v[26:29], v[190:193], v[198:201], v[26:29]
	v_mfma_f32_16x16x32_bf16 v[30:33], v[182:185], v[198:201], v[30:33]
	s_barrier
	s_setprio 0
	s_add_i32 s83, s83, 2
	s_addk_i32 s26, 0x100
	s_addk_i32 s27, 0x100
	s_cmp_gt_u32 s83, 29
	s_cbranch_scc0 .LBB0_1253
	s_and_b64 vcc, exec, s[44:45]
	s_cbranch_vccz .LBB0_1256
	s_barrier

.LBB0_1282:
	s_lshl_b32 s46, s85, 20
	s_and_b64 s[8:9], s[40:41], exec
	s_cselect_b32 s8, s46, s19
	s_lshl_b32 s47, s14, 20
	s_and_b64 s[26:27], s[40:41], exec
	s_cselect_b32 s9, s47, s22
	s_add_i32 s19, s19, 0x80080
	s_addk_i32 s22, 0x100
	s_mov_b32 s26, -2
	v_add_u32_e32 v141, 0x10000, v139
	ds_read_b128 v[142:145], v141
	ds_read_b128 v[154:157], v141 offset:1024
	ds_read_b128 v[170:173], v141 offset:2048
	ds_read_b128 v[174:177], v141 offset:3072
	v_add_u32_e32 v141, 0x14000, v139
	ds_read_b128 v[178:181], v141
	ds_read_b128 v[182:185], v141 offset:1024
	ds_read_b128 v[186:189], v141 offset:2048
	ds_read_b128 v[190:193], v141 offset:3072
	s_add_i32 s27, s19, 0xfff80080
	s_cmp_eq_u32 s26, 28
	s_cselect_b32 s52, s8, s27
	s_cselect_b32 s83, s9, s22
	s_or_b32 s27, s52, 0x80
	s_mov_b32 m0, s73
	ds_read_b128 v[194:197], v140
	ds_read_b128 v[198:201], v140 offset:1024
	ds_read_b128 v[202:205], v140 offset:2048
	ds_read_b128 v[228:231], v140 offset:3072
	ds_read_b128 v[232:235], v140 offset:4096
	ds_read_b128 v[236:239], v140 offset:5120
	ds_read_b128 v[240:243], v140 offset:6144
	ds_read_b128 v[244:247], v140 offset:7168
	buffer_load_dwordx4 v131, s[60:63], s19 offen lds
	s_mov_b32 m0, s82
	s_nop 0
	buffer_load_dwordx4 v135, s[60:63], s19 offen lds
	s_waitcnt vmcnt(8)
	s_waitcnt lgkmcnt(0)
	s_setprio 1
	s_barrier
	v_mfma_f32_16x16x32_bf16 v[126:129], v[142:145], v[194:197], 0
	v_mfma_f32_16x16x32_bf16 v[122:125], v[170:173], v[194:197], 0
	v_mfma_f32_16x16x32_bf16 v[114:117], v[170:173], v[202:205], 0
	v_mfma_f32_16x16x32_bf16 v[118:121], v[142:145], v[202:205], 0
	v_mfma_f32_16x16x32_bf16 v[110:113], v[142:145], v[232:235], 0
	v_mfma_f32_16x16x32_bf16 v[106:109], v[170:173], v[232:235], 0
	v_mfma_f32_16x16x32_bf16 v[98:101], v[170:173], v[240:243], 0
	v_mfma_f32_16x16x32_bf16 v[102:105], v[142:145], v[240:243], 0
	v_mfma_f32_16x16x32_bf16 v[38:41], v[178:181], v[240:243], 0
	v_mfma_f32_16x16x32_bf16 v[34:37], v[186:189], v[240:243], 0
	v_mfma_f32_16x16x32_bf16 v[42:45], v[186:189], v[232:235], 0
	v_mfma_f32_16x16x32_bf16 v[46:49], v[178:181], v[232:235], 0
	v_mfma_f32_16x16x32_bf16 v[54:57], v[178:181], v[202:205], 0
	v_mfma_f32_16x16x32_bf16 v[50:53], v[186:189], v[202:205], 0
	v_mfma_f32_16x16x32_bf16 v[58:61], v[186:189], v[194:197], 0
	v_mfma_f32_16x16x32_bf16 v[62:65], v[178:181], v[194:197], 0
	v_mfma_f32_16x16x32_bf16 v[126:129], v[154:157], v[198:201], v[126:129]
	v_mfma_f32_16x16x32_bf16 v[122:125], v[174:177], v[198:201], v[122:125]
	v_mfma_f32_16x16x32_bf16 v[114:117], v[174:177], v[228:231], v[114:117]
	v_mfma_f32_16x16x32_bf16 v[118:121], v[154:157], v[228:231], v[118:121]
	v_mfma_f32_16x16x32_bf16 v[110:113], v[154:157], v[236:239], v[110:113]
	v_mfma_f32_16x16x32_bf16 v[106:109], v[174:177], v[236:239], v[106:109]
	v_mfma_f32_16x16x32_bf16 v[98:101], v[174:177], v[244:247], v[98:101]
	v_mfma_f32_16x16x32_bf16 v[102:105], v[154:157], v[244:247], v[102:105]
	v_mfma_f32_16x16x32_bf16 v[38:41], v[182:185], v[244:247], v[38:41]
	v_mfma_f32_16x16x32_bf16 v[34:37], v[190:193], v[244:247], v[34:37]
	v_mfma_f32_16x16x32_bf16 v[42:45], v[190:193], v[236:239], v[42:45]
	v_mfma_f32_16x16x32_bf16 v[46:49], v[182:185], v[236:239], v[46:49]
	v_mfma_f32_16x16x32_bf16 v[54:57], v[182:185], v[228:231], v[54:57]
	v_mfma_f32_16x16x32_bf16 v[50:53], v[190:193], v[228:231], v[50:53]
	v_mfma_f32_16x16x32_bf16 v[58:61], v[190:193], v[198:201], v[58:61]
	v_mfma_f32_16x16x32_bf16 v[62:65], v[182:185], v[198:201], v[62:65]
	s_barrier
	s_setprio 0
	s_mov_b32 m0, s21
	s_mov_b32 s70, s62
	s_mov_b32 s71, s63
	ds_read_b128 v[194:197], v140 offset:16384
	ds_read_b128 v[198:201], v140 offset:17408
	ds_read_b128 v[202:205], v140 offset:18432
	ds_read_b128 v[228:231], v140 offset:19456
	ds_read_b128 v[232:235], v140 offset:20480
	ds_read_b128 v[236:239], v140 offset:21504
	ds_read_b128 v[240:243], v140 offset:22528
	ds_read_b128 v[244:247], v140 offset:23552
	buffer_load_dwordx4 v134, s[68:71], s83 offen lds
	s_mov_b32 m0, s23
	s_add_i32 s53, s83, 0x80000
	buffer_load_dwordx4 v136, s[68:71], s83 offen lds
	s_mov_b32 m0, s24
	s_nop 0
	buffer_load_dwordx4 v134, s[68:71], s53 offen lds
	s_mov_b32 m0, s25
	s_nop 0
	buffer_load_dwordx4 v136, s[68:71], s53 offen lds
	s_mov_b32 m0, s2
	s_nop 0
	buffer_load_dwordx4 v131, s[60:63], s52 offen lds
	s_mov_b32 m0, s30
	s_nop 0
	buffer_load_dwordx4 v135, s[60:63], s52 offen lds
	s_waitcnt vmcnt(8)
	s_waitcnt lgkmcnt(0)
	s_setprio 1
	s_barrier
	v_mfma_f32_16x16x32_bf16 v[94:97], v[142:145], v[194:197], 0
	v_mfma_f32_16x16x32_bf16 v[90:93], v[170:173], v[194:197], 0
	v_mfma_f32_16x16x32_bf16 v[82:85], v[170:173], v[202:205], 0
	v_mfma_f32_16x16x32_bf16 v[86:89], v[142:145], v[202:205], 0
	v_mfma_f32_16x16x32_bf16 v[78:81], v[142:145], v[232:235], 0
	v_mfma_f32_16x16x32_bf16 v[74:77], v[170:173], v[232:235], 0
	v_mfma_f32_16x16x32_bf16 v[66:69], v[170:173], v[240:243], 0
	v_mfma_f32_16x16x32_bf16 v[70:73], v[142:145], v[240:243], 0
	v_mfma_f32_16x16x32_bf16 v[6:9], v[178:181], v[240:243], 0
	v_mfma_f32_16x16x32_bf16 v[2:5], v[186:189], v[240:243], 0
	v_mfma_f32_16x16x32_bf16 v[10:13], v[186:189], v[232:235], 0
	v_mfma_f32_16x16x32_bf16 v[14:17], v[178:181], v[232:235], 0
	v_mfma_f32_16x16x32_bf16 v[22:25], v[178:181], v[202:205], 0
	v_mfma_f32_16x16x32_bf16 v[18:21], v[186:189], v[202:205], 0
	v_mfma_f32_16x16x32_bf16 v[26:29], v[186:189], v[194:197], 0
	v_mfma_f32_16x16x32_bf16 v[30:33], v[178:181], v[194:197], 0
	v_mfma_f32_16x16x32_bf16 v[94:97], v[154:157], v[198:201], v[94:97]
	v_mfma_f32_16x16x32_bf16 v[90:93], v[174:177], v[198:201], v[90:93]
	v_mfma_f32_16x16x32_bf16 v[82:85], v[174:177], v[228:231], v[82:85]
	v_mfma_f32_16x16x32_bf16 v[86:89], v[154:157], v[228:231], v[86:89]
	v_mfma_f32_16x16x32_bf16 v[78:81], v[154:157], v[236:239], v[78:81]
	v_mfma_f32_16x16x32_bf16 v[74:77], v[174:177], v[236:239], v[74:77]
	v_mfma_f32_16x16x32_bf16 v[66:69], v[174:177], v[244:247], v[66:69]
	v_mfma_f32_16x16x32_bf16 v[70:73], v[154:157], v[244:247], v[70:73]
	v_mfma_f32_16x16x32_bf16 v[6:9], v[182:185], v[244:247], v[6:9]
	v_mfma_f32_16x16x32_bf16 v[2:5], v[190:193], v[244:247], v[2:5]
	v_mfma_f32_16x16x32_bf16 v[10:13], v[190:193], v[236:239], v[10:13]
	v_mfma_f32_16x16x32_bf16 v[14:17], v[182:185], v[236:239], v[14:17]
	v_mfma_f32_16x16x32_bf16 v[22:25], v[182:185], v[228:231], v[22:25]
	v_mfma_f32_16x16x32_bf16 v[18:21], v[190:193], v[228:231], v[18:21]
	v_mfma_f32_16x16x32_bf16 v[26:29], v[190:193], v[198:201], v[26:29]
	v_mfma_f32_16x16x32_bf16 v[30:33], v[182:185], v[198:201], v[30:33]
	s_barrier
	s_setprio 0
	v_add_u32_e32 v141, 0x18000, v139
	ds_read_b128 v[142:145], v141
	ds_read_b128 v[154:157], v141 offset:1024
	ds_read_b128 v[170:173], v141 offset:2048
	ds_read_b128 v[174:177], v141 offset:3072
	v_add_u32_e32 v141, 0x1c000, v139
	ds_read_b128 v[178:181], v141
	ds_read_b128 v[182:185], v141 offset:1024
	ds_read_b128 v[186:189], v141 offset:2048
	ds_read_b128 v[190:193], v141 offset:3072
	s_add_i32 s52, s52, 0x80000
	s_mov_b32 m0, s31
	ds_read_b128 v[194:197], v140 offset:32768
	ds_read_b128 v[198:201], v140 offset:33792
	ds_read_b128 v[202:205], v140 offset:34816
	ds_read_b128 v[228:231], v140 offset:35840
	ds_read_b128 v[232:235], v140 offset:36864
	ds_read_b128 v[236:239], v140 offset:37888
	ds_read_b128 v[240:243], v140 offset:38912
	ds_read_b128 v[244:247], v140 offset:39936
	buffer_load_dwordx4 v131, s[60:63], s52 offen lds
	s_mov_b32 m0, s33
	s_nop 0
	buffer_load_dwordx4 v135, s[60:63], s52 offen lds
	s_waitcnt vmcnt(8)
	s_waitcnt lgkmcnt(0)
	s_setprio 1
	s_barrier
	v_mfma_f32_16x16x32_bf16 v[126:129], v[142:145], v[194:197], v[126:129]
	v_mfma_f32_16x16x32_bf16 v[122:125], v[170:173], v[194:197], v[122:125]
	v_mfma_f32_16x16x32_bf16 v[114:117], v[170:173], v[202:205], v[114:117]
	v_mfma_f32_16x16x32_bf16 v[118:121], v[142:145], v[202:205], v[118:121]
	v_mfma_f32_16x16x32_bf16 v[110:113], v[142:145], v[232:235], v[110:113]
	v_mfma_f32_16x16x32_bf16 v[106:109], v[170:173], v[232:235], v[106:109]
	v_mfma_f32_16x16x32_bf16 v[98:101], v[170:173], v[240:243], v[98:101]
	v_mfma_f32_16x16x32_bf16 v[102:105], v[142:145], v[240:243], v[102:105]
	v_mfma_f32_16x16x32_bf16 v[38:41], v[178:181], v[240:243], v[38:41]
	v_mfma_f32_16x16x32_bf16 v[34:37], v[186:189], v[240:243], v[34:37]
	v_mfma_f32_16x16x32_bf16 v[42:45], v[186:189], v[232:235], v[42:45]
	v_mfma_f32_16x16x32_bf16 v[46:49], v[178:181], v[232:235], v[46:49]
	v_mfma_f32_16x16x32_bf16 v[54:57], v[178:181], v[202:205], v[54:57]
	v_mfma_f32_16x16x32_bf16 v[50:53], v[186:189], v[202:205], v[50:53]
	v_mfma_f32_16x16x32_bf16 v[58:61], v[186:189], v[194:197], v[58:61]
	v_mfma_f32_16x16x32_bf16 v[62:65], v[178:181], v[194:197], v[62:65]
	v_mfma_f32_16x16x32_bf16 v[126:129], v[154:157], v[198:201], v[126:129]
	v_mfma_f32_16x16x32_bf16 v[122:125], v[174:177], v[198:201], v[122:125]
	v_mfma_f32_16x16x32_bf16 v[114:117], v[174:177], v[228:231], v[114:117]
	v_mfma_f32_16x16x32_bf16 v[118:121], v[154:157], v[228:231], v[118:121]
	v_mfma_f32_16x16x32_bf16 v[110:113], v[154:157], v[236:239], v[110:113]
	v_mfma_f32_16x16x32_bf16 v[106:109], v[174:177], v[236:239], v[106:109]
	v_mfma_f32_16x16x32_bf16 v[98:101], v[174:177], v[244:247], v[98:101]
	v_mfma_f32_16x16x32_bf16 v[102:105], v[154:157], v[244:247], v[102:105]
	v_mfma_f32_16x16x32_bf16 v[38:41], v[182:185], v[244:247], v[38:41]
	v_mfma_f32_16x16x32_bf16 v[34:37], v[190:193], v[244:247], v[34:37]
	v_mfma_f32_16x16x32_bf16 v[42:45], v[190:193], v[236:239], v[42:45]
	v_mfma_f32_16x16x32_bf16 v[46:49], v[182:185], v[236:239], v[46:49]
	v_mfma_f32_16x16x32_bf16 v[54:57], v[182:185], v[228:231], v[54:57]
	v_mfma_f32_16x16x32_bf16 v[50:53], v[190:193], v[228:231], v[50:53]
	v_mfma_f32_16x16x32_bf16 v[58:61], v[190:193], v[198:201], v[58:61]
	v_mfma_f32_16x16x32_bf16 v[62:65], v[182:185], v[198:201], v[62:65]
	s_barrier
	s_setprio 0
	s_mov_b32 m0, s34
	s_or_b32 s52, s83, 0x80
	ds_read_b128 v[194:197], v140 offset:49152
	ds_read_b128 v[198:201], v140 offset:50176
	ds_read_b128 v[202:205], v140 offset:51200
	ds_read_b128 v[228:231], v140 offset:52224
	ds_read_b128 v[232:235], v140 offset:53248
	ds_read_b128 v[236:239], v140 offset:54272
	ds_read_b128 v[240:243], v140 offset:55296
	ds_read_b128 v[244:247], v140 offset:56320
	buffer_load_dwordx4 v134, s[68:71], s52 offen lds
	s_mov_b32 m0, s35
	s_add_i32 s83, s83, 0x80080
	buffer_load_dwordx4 v136, s[68:71], s52 offen lds
	s_mov_b32 m0, s65
	s_nop 0
	buffer_load_dwordx4 v134, s[68:71], s83 offen lds
	s_mov_b32 m0, s66
	s_nop 0
	buffer_load_dwordx4 v136, s[68:71], s83 offen lds
	s_mov_b32 m0, s36
	s_nop 0
	buffer_load_dwordx4 v131, s[60:63], s27 offen lds
	s_mov_b32 m0, s37
	s_nop 0
	buffer_load_dwordx4 v135, s[60:63], s27 offen lds
	s_waitcnt vmcnt(8)
	s_waitcnt lgkmcnt(0)
	s_setprio 1
	s_barrier
	v_mfma_f32_16x16x32_bf16 v[94:97], v[142:145], v[194:197], v[94:97]
	v_mfma_f32_16x16x32_bf16 v[90:93], v[170:173], v[194:197], v[90:93]
	v_mfma_f32_16x16x32_bf16 v[82:85], v[170:173], v[202:205], v[82:85]
	v_mfma_f32_16x16x32_bf16 v[86:89], v[142:145], v[202:205], v[86:89]
	v_mfma_f32_16x16x32_bf16 v[78:81], v[142:145], v[232:235], v[78:81]
	v_mfma_f32_16x16x32_bf16 v[74:77], v[170:173], v[232:235], v[74:77]
	v_mfma_f32_16x16x32_bf16 v[66:69], v[170:173], v[240:243], v[66:69]
	v_mfma_f32_16x16x32_bf16 v[70:73], v[142:145], v[240:243], v[70:73]
	v_mfma_f32_16x16x32_bf16 v[6:9], v[178:181], v[240:243], v[6:9]
	v_mfma_f32_16x16x32_bf16 v[2:5], v[186:189], v[240:243], v[2:5]
	v_mfma_f32_16x16x32_bf16 v[10:13], v[186:189], v[232:235], v[10:13]
	v_mfma_f32_16x16x32_bf16 v[14:17], v[178:181], v[232:235], v[14:17]
	v_mfma_f32_16x16x32_bf16 v[22:25], v[178:181], v[202:205], v[22:25]
	v_mfma_f32_16x16x32_bf16 v[18:21], v[186:189], v[202:205], v[18:21]
	v_mfma_f32_16x16x32_bf16 v[26:29], v[186:189], v[194:197], v[26:29]
	v_mfma_f32_16x16x32_bf16 v[30:33], v[178:181], v[194:197], v[30:33]
	v_mfma_f32_16x16x32_bf16 v[94:97], v[154:157], v[198:201], v[94:97]
	v_mfma_f32_16x16x32_bf16 v[90:93], v[174:177], v[198:201], v[90:93]
	v_mfma_f32_16x16x32_bf16 v[82:85], v[174:177], v[228:231], v[82:85]
	v_mfma_f32_16x16x32_bf16 v[86:89], v[154:157], v[228:231], v[86:89]
	v_mfma_f32_16x16x32_bf16 v[78:81], v[154:157], v[236:239], v[78:81]
	v_mfma_f32_16x16x32_bf16 v[74:77], v[174:177], v[236:239], v[74:77]
	v_mfma_f32_16x16x32_bf16 v[66:69], v[174:177], v[244:247], v[66:69]
	v_mfma_f32_16x16x32_bf16 v[70:73], v[154:157], v[244:247], v[70:73]
	v_mfma_f32_16x16x32_bf16 v[6:9], v[182:185], v[244:247], v[6:9]
	v_mfma_f32_16x16x32_bf16 v[2:5], v[190:193], v[244:247], v[2:5]
	v_mfma_f32_16x16x32_bf16 v[10:13], v[190:193], v[236:239], v[10:13]
	v_mfma_f32_16x16x32_bf16 v[14:17], v[182:185], v[236:239], v[14:17]
	v_mfma_f32_16x16x32_bf16 v[22:25], v[182:185], v[228:231], v[22:25]
	v_mfma_f32_16x16x32_bf16 v[18:21], v[190:193], v[228:231], v[18:21]
	v_mfma_f32_16x16x32_bf16 v[26:29], v[190:193], v[198:201], v[26:29]
	v_mfma_f32_16x16x32_bf16 v[30:33], v[182:185], v[198:201], v[30:33]
	s_barrier
	s_setprio 0
	s_add_i32 s26, s26, 2
	s_addk_i32 s19, 0x100
	s_addk_i32 s22, 0x100
	s_cmp_gt_u32 s26, 29
.LBB0_1283:
	v_add_u32_e32 v141, 0x10000, v139
	ds_read_b128 v[142:145], v141
	ds_read_b128 v[154:157], v141 offset:1024
	ds_read_b128 v[170:173], v141 offset:2048
	ds_read_b128 v[174:177], v141 offset:3072
	v_add_u32_e32 v141, 0x14000, v139
	ds_read_b128 v[178:181], v141
	ds_read_b128 v[182:185], v141 offset:1024
	ds_read_b128 v[186:189], v141 offset:2048
	ds_read_b128 v[190:193], v141 offset:3072
	s_add_i32 s27, s19, 0xfff80080
	s_cmp_eq_u32 s26, 28
	s_cselect_b32 s52, s8, s27
	s_cselect_b32 s83, s9, s22
	s_or_b32 s27, s52, 0x80
	s_mov_b32 m0, s73
	ds_read_b128 v[194:197], v140
	ds_read_b128 v[198:201], v140 offset:1024
	ds_read_b128 v[202:205], v140 offset:2048
	ds_read_b128 v[228:231], v140 offset:3072
	ds_read_b128 v[232:235], v140 offset:4096
	ds_read_b128 v[236:239], v140 offset:5120
	ds_read_b128 v[240:243], v140 offset:6144
	ds_read_b128 v[244:247], v140 offset:7168
	buffer_load_dwordx4 v131, s[60:63], s19 offen lds
	s_mov_b32 m0, s82
	s_nop 0
	buffer_load_dwordx4 v135, s[60:63], s19 offen lds
	s_waitcnt vmcnt(8)
	s_waitcnt lgkmcnt(0)
	s_setprio 1
	s_barrier
	v_mfma_f32_16x16x32_bf16 v[126:129], v[142:145], v[194:197], v[126:129]
	v_mfma_f32_16x16x32_bf16 v[122:125], v[170:173], v[194:197], v[122:125]
	v_mfma_f32_16x16x32_bf16 v[114:117], v[170:173], v[202:205], v[114:117]
	v_mfma_f32_16x16x32_bf16 v[118:121], v[142:145], v[202:205], v[118:121]
	v_mfma_f32_16x16x32_bf16 v[110:113], v[142:145], v[232:235], v[110:113]
	v_mfma_f32_16x16x32_bf16 v[106:109], v[170:173], v[232:235], v[106:109]
	v_mfma_f32_16x16x32_bf16 v[98:101], v[170:173], v[240:243], v[98:101]
	v_mfma_f32_16x16x32_bf16 v[102:105], v[142:145], v[240:243], v[102:105]
	v_mfma_f32_16x16x32_bf16 v[38:41], v[178:181], v[240:243], v[38:41]
	v_mfma_f32_16x16x32_bf16 v[34:37], v[186:189], v[240:243], v[34:37]
	v_mfma_f32_16x16x32_bf16 v[42:45], v[186:189], v[232:235], v[42:45]
	v_mfma_f32_16x16x32_bf16 v[46:49], v[178:181], v[232:235], v[46:49]
	v_mfma_f32_16x16x32_bf16 v[54:57], v[178:181], v[202:205], v[54:57]
	v_mfma_f32_16x16x32_bf16 v[50:53], v[186:189], v[202:205], v[50:53]
	v_mfma_f32_16x16x32_bf16 v[58:61], v[186:189], v[194:197], v[58:61]
	v_mfma_f32_16x16x32_bf16 v[62:65], v[178:181], v[194:197], v[62:65]
	v_mfma_f32_16x16x32_bf16 v[126:129], v[154:157], v[198:201], v[126:129]
	v_mfma_f32_16x16x32_bf16 v[122:125], v[174:177], v[198:201], v[122:125]
	v_mfma_f32_16x16x32_bf16 v[114:117], v[174:177], v[228:231], v[114:117]
	v_mfma_f32_16x16x32_bf16 v[118:121], v[154:157], v[228:231], v[118:121]
	v_mfma_f32_16x16x32_bf16 v[110:113], v[154:157], v[236:239], v[110:113]
	v_mfma_f32_16x16x32_bf16 v[106:109], v[174:177], v[236:239], v[106:109]
	v_mfma_f32_16x16x32_bf16 v[98:101], v[174:177], v[244:247], v[98:101]
	v_mfma_f32_16x16x32_bf16 v[102:105], v[154:157], v[244:247], v[102:105]
	v_mfma_f32_16x16x32_bf16 v[38:41], v[182:185], v[244:247], v[38:41]
	v_mfma_f32_16x16x32_bf16 v[34:37], v[190:193], v[244:247], v[34:37]
	v_mfma_f32_16x16x32_bf16 v[42:45], v[190:193], v[236:239], v[42:45]
	v_mfma_f32_16x16x32_bf16 v[46:49], v[182:185], v[236:239], v[46:49]
	v_mfma_f32_16x16x32_bf16 v[54:57], v[182:185], v[228:231], v[54:57]
	v_mfma_f32_16x16x32_bf16 v[50:53], v[190:193], v[228:231], v[50:53]
	v_mfma_f32_16x16x32_bf16 v[58:61], v[190:193], v[198:201], v[58:61]
	v_mfma_f32_16x16x32_bf16 v[62:65], v[182:185], v[198:201], v[62:65]
	s_barrier
	s_setprio 0
	s_mov_b32 m0, s21
	s_mov_b32 s70, s62
	s_mov_b32 s71, s63
	ds_read_b128 v[194:197], v140 offset:16384
	ds_read_b128 v[198:201], v140 offset:17408
	ds_read_b128 v[202:205], v140 offset:18432
	ds_read_b128 v[228:231], v140 offset:19456
	ds_read_b128 v[232:235], v140 offset:20480
	ds_read_b128 v[236:239], v140 offset:21504
	ds_read_b128 v[240:243], v140 offset:22528
	ds_read_b128 v[244:247], v140 offset:23552
	buffer_load_dwordx4 v134, s[68:71], s83 offen lds
	s_mov_b32 m0, s23
	s_add_i32 s53, s83, 0x80000
	buffer_load_dwordx4 v136, s[68:71], s83 offen lds
	s_mov_b32 m0, s24
	s_nop 0
	buffer_load_dwordx4 v134, s[68:71], s53 offen lds
	s_mov_b32 m0, s25
	s_nop 0
	buffer_load_dwordx4 v136, s[68:71], s53 offen lds
	s_mov_b32 m0, s2
	s_nop 0
	buffer_load_dwordx4 v131, s[60:63], s52 offen lds
	s_mov_b32 m0, s30
	s_nop 0
	buffer_load_dwordx4 v135, s[60:63], s52 offen lds
	s_waitcnt vmcnt(8)
	s_waitcnt lgkmcnt(0)
	s_setprio 1
	s_barrier
	v_mfma_f32_16x16x32_bf16 v[94:97], v[142:145], v[194:197], v[94:97]
	v_mfma_f32_16x16x32_bf16 v[90:93], v[170:173], v[194:197], v[90:93]
	v_mfma_f32_16x16x32_bf16 v[82:85], v[170:173], v[202:205], v[82:85]
	v_mfma_f32_16x16x32_bf16 v[86:89], v[142:145], v[202:205], v[86:89]
	v_mfma_f32_16x16x32_bf16 v[78:81], v[142:145], v[232:235], v[78:81]
	v_mfma_f32_16x16x32_bf16 v[74:77], v[170:173], v[232:235], v[74:77]
	v_mfma_f32_16x16x32_bf16 v[66:69], v[170:173], v[240:243], v[66:69]
	v_mfma_f32_16x16x32_bf16 v[70:73], v[142:145], v[240:243], v[70:73]
	v_mfma_f32_16x16x32_bf16 v[6:9], v[178:181], v[240:243], v[6:9]
	v_mfma_f32_16x16x32_bf16 v[2:5], v[186:189], v[240:243], v[2:5]
	v_mfma_f32_16x16x32_bf16 v[10:13], v[186:189], v[232:235], v[10:13]
	v_mfma_f32_16x16x32_bf16 v[14:17], v[178:181], v[232:235], v[14:17]
	v_mfma_f32_16x16x32_bf16 v[22:25], v[178:181], v[202:205], v[22:25]
	v_mfma_f32_16x16x32_bf16 v[18:21], v[186:189], v[202:205], v[18:21]
	v_mfma_f32_16x16x32_bf16 v[26:29], v[186:189], v[194:197], v[26:29]
	v_mfma_f32_16x16x32_bf16 v[30:33], v[178:181], v[194:197], v[30:33]
	v_mfma_f32_16x16x32_bf16 v[94:97], v[154:157], v[198:201], v[94:97]
	v_mfma_f32_16x16x32_bf16 v[90:93], v[174:177], v[198:201], v[90:93]
	v_mfma_f32_16x16x32_bf16 v[82:85], v[174:177], v[228:231], v[82:85]
	v_mfma_f32_16x16x32_bf16 v[86:89], v[154:157], v[228:231], v[86:89]
	v_mfma_f32_16x16x32_bf16 v[78:81], v[154:157], v[236:239], v[78:81]
	v_mfma_f32_16x16x32_bf16 v[74:77], v[174:177], v[236:239], v[74:77]
	v_mfma_f32_16x16x32_bf16 v[66:69], v[174:177], v[244:247], v[66:69]
	v_mfma_f32_16x16x32_bf16 v[70:73], v[154:157], v[244:247], v[70:73]
	v_mfma_f32_16x16x32_bf16 v[6:9], v[182:185], v[244:247], v[6:9]
	v_mfma_f32_16x16x32_bf16 v[2:5], v[190:193], v[244:247], v[2:5]
	v_mfma_f32_16x16x32_bf16 v[10:13], v[190:193], v[236:239], v[10:13]
	v_mfma_f32_16x16x32_bf16 v[14:17], v[182:185], v[236:239], v[14:17]
	v_mfma_f32_16x16x32_bf16 v[22:25], v[182:185], v[228:231], v[22:25]
	v_mfma_f32_16x16x32_bf16 v[18:21], v[190:193], v[228:231], v[18:21]
	v_mfma_f32_16x16x32_bf16 v[26:29], v[190:193], v[198:201], v[26:29]
	v_mfma_f32_16x16x32_bf16 v[30:33], v[182:185], v[198:201], v[30:33]
	s_barrier
	s_setprio 0
	v_add_u32_e32 v141, 0x18000, v139
	ds_read_b128 v[142:145], v141
	ds_read_b128 v[154:157], v141 offset:1024
	ds_read_b128 v[170:173], v141 offset:2048
	ds_read_b128 v[174:177], v141 offset:3072
	v_add_u32_e32 v141, 0x1c000, v139
	ds_read_b128 v[178:181], v141
	ds_read_b128 v[182:185], v141 offset:1024
	ds_read_b128 v[186:189], v141 offset:2048
	ds_read_b128 v[190:193], v141 offset:3072
	s_add_i32 s52, s52, 0x80000
	s_mov_b32 m0, s31
	ds_read_b128 v[194:197], v140 offset:32768
	ds_read_b128 v[198:201], v140 offset:33792
	ds_read_b128 v[202:205], v140 offset:34816
	ds_read_b128 v[228:231], v140 offset:35840
	ds_read_b128 v[232:235], v140 offset:36864
	ds_read_b128 v[236:239], v140 offset:37888
	ds_read_b128 v[240:243], v140 offset:38912
	ds_read_b128 v[244:247], v140 offset:39936
	buffer_load_dwordx4 v131, s[60:63], s52 offen lds
	s_mov_b32 m0, s33
	s_nop 0
	buffer_load_dwordx4 v135, s[60:63], s52 offen lds
	s_waitcnt vmcnt(8)
	s_waitcnt lgkmcnt(0)
	s_setprio 1
	s_barrier
	v_mfma_f32_16x16x32_bf16 v[126:129], v[142:145], v[194:197], v[126:129]
	v_mfma_f32_16x16x32_bf16 v[122:125], v[170:173], v[194:197], v[122:125]
	v_mfma_f32_16x16x32_bf16 v[114:117], v[170:173], v[202:205], v[114:117]
	v_mfma_f32_16x16x32_bf16 v[118:121], v[142:145], v[202:205], v[118:121]
	v_mfma_f32_16x16x32_bf16 v[110:113], v[142:145], v[232:235], v[110:113]
	v_mfma_f32_16x16x32_bf16 v[106:109], v[170:173], v[232:235], v[106:109]
	v_mfma_f32_16x16x32_bf16 v[98:101], v[170:173], v[240:243], v[98:101]
	v_mfma_f32_16x16x32_bf16 v[102:105], v[142:145], v[240:243], v[102:105]
	v_mfma_f32_16x16x32_bf16 v[38:41], v[178:181], v[240:243], v[38:41]
	v_mfma_f32_16x16x32_bf16 v[34:37], v[186:189], v[240:243], v[34:37]
	v_mfma_f32_16x16x32_bf16 v[42:45], v[186:189], v[232:235], v[42:45]
	v_mfma_f32_16x16x32_bf16 v[46:49], v[178:181], v[232:235], v[46:49]
	v_mfma_f32_16x16x32_bf16 v[54:57], v[178:181], v[202:205], v[54:57]
	v_mfma_f32_16x16x32_bf16 v[50:53], v[186:189], v[202:205], v[50:53]
	v_mfma_f32_16x16x32_bf16 v[58:61], v[186:189], v[194:197], v[58:61]
	v_mfma_f32_16x16x32_bf16 v[62:65], v[178:181], v[194:197], v[62:65]
	v_mfma_f32_16x16x32_bf16 v[126:129], v[154:157], v[198:201], v[126:129]
	v_mfma_f32_16x16x32_bf16 v[122:125], v[174:177], v[198:201], v[122:125]
	v_mfma_f32_16x16x32_bf16 v[114:117], v[174:177], v[228:231], v[114:117]
	v_mfma_f32_16x16x32_bf16 v[118:121], v[154:157], v[228:231], v[118:121]
	v_mfma_f32_16x16x32_bf16 v[110:113], v[154:157], v[236:239], v[110:113]
	v_mfma_f32_16x16x32_bf16 v[106:109], v[174:177], v[236:239], v[106:109]
	v_mfma_f32_16x16x32_bf16 v[98:101], v[174:177], v[244:247], v[98:101]
	v_mfma_f32_16x16x32_bf16 v[102:105], v[154:157], v[244:247], v[102:105]
	v_mfma_f32_16x16x32_bf16 v[38:41], v[182:185], v[244:247], v[38:41]
	v_mfma_f32_16x16x32_bf16 v[34:37], v[190:193], v[244:247], v[34:37]
	v_mfma_f32_16x16x32_bf16 v[42:45], v[190:193], v[236:239], v[42:45]
	v_mfma_f32_16x16x32_bf16 v[46:49], v[182:185], v[236:239], v[46:49]
	v_mfma_f32_16x16x32_bf16 v[54:57], v[182:185], v[228:231], v[54:57]
	v_mfma_f32_16x16x32_bf16 v[50:53], v[190:193], v[228:231], v[50:53]
	v_mfma_f32_16x16x32_bf16 v[58:61], v[190:193], v[198:201], v[58:61]
	v_mfma_f32_16x16x32_bf16 v[62:65], v[182:185], v[198:201], v[62:65]
	s_barrier
	s_setprio 0
	s_mov_b32 m0, s34
	s_or_b32 s52, s83, 0x80
	ds_read_b128 v[194:197], v140 offset:49152
	ds_read_b128 v[198:201], v140 offset:50176
	ds_read_b128 v[202:205], v140 offset:51200
	ds_read_b128 v[228:231], v140 offset:52224
	ds_read_b128 v[232:235], v140 offset:53248
	ds_read_b128 v[236:239], v140 offset:54272
	ds_read_b128 v[240:243], v140 offset:55296
	ds_read_b128 v[244:247], v140 offset:56320
	buffer_load_dwordx4 v134, s[68:71], s52 offen lds
	s_mov_b32 m0, s35
	s_add_i32 s83, s83, 0x80080
	buffer_load_dwordx4 v136, s[68:71], s52 offen lds
	s_mov_b32 m0, s65
	s_nop 0
	buffer_load_dwordx4 v134, s[68:71], s83 offen lds
	s_mov_b32 m0, s66
	s_nop 0
	buffer_load_dwordx4 v136, s[68:71], s83 offen lds
	s_mov_b32 m0, s36
	s_nop 0
	buffer_load_dwordx4 v131, s[60:63], s27 offen lds
	s_mov_b32 m0, s37
	s_nop 0
	buffer_load_dwordx4 v135, s[60:63], s27 offen lds
	s_waitcnt vmcnt(8)
	s_waitcnt lgkmcnt(0)
	s_setprio 1
	s_barrier
	v_mfma_f32_16x16x32_bf16 v[94:97], v[142:145], v[194:197], v[94:97]
	v_mfma_f32_16x16x32_bf16 v[90:93], v[170:173], v[194:197], v[90:93]
	v_mfma_f32_16x16x32_bf16 v[82:85], v[170:173], v[202:205], v[82:85]
	v_mfma_f32_16x16x32_bf16 v[86:89], v[142:145], v[202:205], v[86:89]
	v_mfma_f32_16x16x32_bf16 v[78:81], v[142:145], v[232:235], v[78:81]
	v_mfma_f32_16x16x32_bf16 v[74:77], v[170:173], v[232:235], v[74:77]
	v_mfma_f32_16x16x32_bf16 v[66:69], v[170:173], v[240:243], v[66:69]
	v_mfma_f32_16x16x32_bf16 v[70:73], v[142:145], v[240:243], v[70:73]
	v_mfma_f32_16x16x32_bf16 v[6:9], v[178:181], v[240:243], v[6:9]
	v_mfma_f32_16x16x32_bf16 v[2:5], v[186:189], v[240:243], v[2:5]
	v_mfma_f32_16x16x32_bf16 v[10:13], v[186:189], v[232:235], v[10:13]
	v_mfma_f32_16x16x32_bf16 v[14:17], v[178:181], v[232:235], v[14:17]
	v_mfma_f32_16x16x32_bf16 v[22:25], v[178:181], v[202:205], v[22:25]
	v_mfma_f32_16x16x32_bf16 v[18:21], v[186:189], v[202:205], v[18:21]
	v_mfma_f32_16x16x32_bf16 v[26:29], v[186:189], v[194:197], v[26:29]
	v_mfma_f32_16x16x32_bf16 v[30:33], v[178:181], v[194:197], v[30:33]
	v_mfma_f32_16x16x32_bf16 v[94:97], v[154:157], v[198:201], v[94:97]
	v_mfma_f32_16x16x32_bf16 v[90:93], v[174:177], v[198:201], v[90:93]
	v_mfma_f32_16x16x32_bf16 v[82:85], v[174:177], v[228:231], v[82:85]
	v_mfma_f32_16x16x32_bf16 v[86:89], v[154:157], v[228:231], v[86:89]
	v_mfma_f32_16x16x32_bf16 v[78:81], v[154:157], v[236:239], v[78:81]
	v_mfma_f32_16x16x32_bf16 v[74:77], v[174:177], v[236:239], v[74:77]
	v_mfma_f32_16x16x32_bf16 v[66:69], v[174:177], v[244:247], v[66:69]
	v_mfma_f32_16x16x32_bf16 v[70:73], v[154:157], v[244:247], v[70:73]
	v_mfma_f32_16x16x32_bf16 v[6:9], v[182:185], v[244:247], v[6:9]
	v_mfma_f32_16x16x32_bf16 v[2:5], v[190:193], v[244:247], v[2:5]
	v_mfma_f32_16x16x32_bf16 v[10:13], v[190:193], v[236:239], v[10:13]
	v_mfma_f32_16x16x32_bf16 v[14:17], v[182:185], v[236:239], v[14:17]
	v_mfma_f32_16x16x32_bf16 v[22:25], v[182:185], v[228:231], v[22:25]
	v_mfma_f32_16x16x32_bf16 v[18:21], v[190:193], v[228:231], v[18:21]
	v_mfma_f32_16x16x32_bf16 v[26:29], v[190:193], v[198:201], v[26:29]
	v_mfma_f32_16x16x32_bf16 v[30:33], v[182:185], v[198:201], v[30:33]
	s_barrier
	s_setprio 0
	s_add_i32 s26, s26, 2
	s_addk_i32 s19, 0x100
	s_addk_i32 s22, 0x100
	s_cmp_gt_u32 s26, 29
	s_cbranch_scc0 .LBB0_1283
	s_and_b64 vcc, exec, s[44:45]
	s_cbranch_vccz .LBB0_1286
	s_barrier

.LBB0_1588:
	s_lshl_b32 s85, s84, 20
	s_and_b64 s[8:9], s[42:43], exec
	s_cselect_b32 s8, s85, s13
	s_lshl_b32 s48, s73, 20
	s_and_b64 s[22:23], s[42:43], exec
	s_cselect_b32 s9, s48, s21
	s_add_i32 s13, s13, 0x80080
	s_addk_i32 s21, 0x100
	s_mov_b32 s22, -2
	s_waitcnt lgkmcnt(0)
	v_add_u32_e32 v170, 0x10000, v140
	v_add_u32_e32 v186, 0x14000, v140
	ds_read_b128 v[132:135], v170
	ds_read_b128 v[142:145], v170 offset:1024
	ds_read_b128 v[154:157], v170 offset:2048
	ds_read_b128 v[170:173], v170 offset:3072
	ds_read_b128 v[174:177], v186
	ds_read_b128 v[178:181], v186 offset:1024
	ds_read_b128 v[182:185], v186 offset:2048
	ds_read_b128 v[186:189], v186 offset:3072
	s_add_i32 s23, s13, 0xfff80080
	s_cmp_eq_u32 s22, 28
	s_cselect_b32 s27, s8, s23
	s_cselect_b32 s26, s9, s21
	s_or_b32 s23, s27, 0x80
	s_mov_b32 m0, s70
	ds_read_b128 v[190:193], v141
	ds_read_b128 v[194:197], v141 offset:1024
	ds_read_b128 v[198:201], v141 offset:2048
	ds_read_b128 v[202:205], v141 offset:3072
	ds_read_b128 v[228:231], v141 offset:4096
	ds_read_b128 v[232:235], v141 offset:5120
	ds_read_b128 v[236:239], v141 offset:6144
	ds_read_b128 v[240:243], v141 offset:7168
	buffer_load_dwordx4 v136, s[60:63], s13 offen lds
	s_mov_b32 m0, s72
	s_nop 0
	buffer_load_dwordx4 v138, s[60:63], s13 offen lds
	s_waitcnt vmcnt(8)
	s_waitcnt lgkmcnt(0)
	s_setprio 1
	s_barrier
	v_mfma_f32_16x16x32_bf16 v[126:129], v[132:135], v[190:193], 0
	v_mfma_f32_16x16x32_bf16 v[106:109], v[154:157], v[190:193], 0
	v_mfma_f32_16x16x32_bf16 v[114:117], v[154:157], v[198:201], 0
	v_mfma_f32_16x16x32_bf16 v[118:121], v[132:135], v[198:201], 0
	v_mfma_f32_16x16x32_bf16 v[94:97], v[132:135], v[228:231], 0
	v_mfma_f32_16x16x32_bf16 v[90:93], v[154:157], v[228:231], 0
	v_mfma_f32_16x16x32_bf16 v[74:77], v[154:157], v[236:239], 0
	v_mfma_f32_16x16x32_bf16 v[78:81], v[132:135], v[236:239], 0
	v_mfma_f32_16x16x32_bf16 v[70:73], v[174:177], v[236:239], 0
	v_mfma_f32_16x16x32_bf16 v[66:69], v[182:185], v[236:239], 0
	v_mfma_f32_16x16x32_bf16 v[82:85], v[182:185], v[228:231], 0
	v_mfma_f32_16x16x32_bf16 v[86:89], v[174:177], v[228:231], 0
	v_mfma_f32_16x16x32_bf16 v[102:105], v[174:177], v[198:201], 0
	v_mfma_f32_16x16x32_bf16 v[98:101], v[182:185], v[198:201], 0
	v_mfma_f32_16x16x32_bf16 v[110:113], v[182:185], v[190:193], 0
	v_mfma_f32_16x16x32_bf16 v[122:125], v[174:177], v[190:193], 0
	v_mfma_f32_16x16x32_bf16 v[126:129], v[142:145], v[194:197], v[126:129]
	v_mfma_f32_16x16x32_bf16 v[106:109], v[170:173], v[194:197], v[106:109]
	v_mfma_f32_16x16x32_bf16 v[114:117], v[170:173], v[202:205], v[114:117]
	v_mfma_f32_16x16x32_bf16 v[118:121], v[142:145], v[202:205], v[118:121]
	v_mfma_f32_16x16x32_bf16 v[94:97], v[142:145], v[232:235], v[94:97]
	v_mfma_f32_16x16x32_bf16 v[90:93], v[170:173], v[232:235], v[90:93]
	v_mfma_f32_16x16x32_bf16 v[74:77], v[170:173], v[240:243], v[74:77]
	v_mfma_f32_16x16x32_bf16 v[78:81], v[142:145], v[240:243], v[78:81]
	v_mfma_f32_16x16x32_bf16 v[70:73], v[178:181], v[240:243], v[70:73]
	v_mfma_f32_16x16x32_bf16 v[66:69], v[186:189], v[240:243], v[66:69]
	v_mfma_f32_16x16x32_bf16 v[82:85], v[186:189], v[232:235], v[82:85]
	v_mfma_f32_16x16x32_bf16 v[86:89], v[178:181], v[232:235], v[86:89]
	v_mfma_f32_16x16x32_bf16 v[102:105], v[178:181], v[202:205], v[102:105]
	v_mfma_f32_16x16x32_bf16 v[98:101], v[186:189], v[202:205], v[98:101]
	v_mfma_f32_16x16x32_bf16 v[110:113], v[186:189], v[194:197], v[110:113]
	v_mfma_f32_16x16x32_bf16 v[122:125], v[178:181], v[194:197], v[122:125]
	s_barrier
	s_setprio 0
	s_mov_b32 m0, s15
	s_mov_b32 s46, s62
	s_mov_b32 s47, s63
	ds_read_b128 v[190:193], v141 offset:16384
	ds_read_b128 v[194:197], v141 offset:17408
	ds_read_b128 v[198:201], v141 offset:18432
	ds_read_b128 v[202:205], v141 offset:19456
	ds_read_b128 v[228:231], v141 offset:20480
	ds_read_b128 v[232:235], v141 offset:21504
	ds_read_b128 v[236:239], v141 offset:22528
	ds_read_b128 v[240:243], v141 offset:23552
	buffer_load_dwordx4 v137, s[44:47], s26 offen lds
	s_mov_b32 m0, s16
	s_add_i32 s49, s26, 0x80000
	buffer_load_dwordx4 v139, s[44:47], s26 offen lds
	s_mov_b32 m0, s18
	s_nop 0
	buffer_load_dwordx4 v137, s[44:47], s49 offen lds
	s_mov_b32 m0, s19
	s_nop 0
	buffer_load_dwordx4 v139, s[44:47], s49 offen lds
	s_mov_b32 m0, s14
	s_nop 0
	buffer_load_dwordx4 v136, s[60:63], s27 offen lds
	s_mov_b32 m0, s24
	s_nop 0
	buffer_load_dwordx4 v138, s[60:63], s27 offen lds
	s_waitcnt vmcnt(8)
	s_waitcnt lgkmcnt(0)
	s_setprio 1
	s_barrier
	v_mfma_f32_16x16x32_bf16 v[62:65], v[132:135], v[190:193], 0
	v_mfma_f32_16x16x32_bf16 v[58:61], v[154:157], v[190:193], 0
	v_mfma_f32_16x16x32_bf16 v[42:45], v[154:157], v[198:201], 0
	v_mfma_f32_16x16x32_bf16 v[46:49], v[132:135], v[198:201], 0
	v_mfma_f32_16x16x32_bf16 v[30:33], v[132:135], v[228:231], 0
	v_mfma_f32_16x16x32_bf16 v[26:29], v[154:157], v[228:231], 0
	v_mfma_f32_16x16x32_bf16 v[10:13], v[154:157], v[236:239], 0
	v_mfma_f32_16x16x32_bf16 v[14:17], v[132:135], v[236:239], 0
	v_mfma_f32_16x16x32_bf16 v[6:9], v[174:177], v[236:239], 0
	v_mfma_f32_16x16x32_bf16 v[2:5], v[182:185], v[236:239], 0
	v_mfma_f32_16x16x32_bf16 v[18:21], v[182:185], v[228:231], 0
	v_mfma_f32_16x16x32_bf16 v[22:25], v[174:177], v[228:231], 0
	v_mfma_f32_16x16x32_bf16 v[38:41], v[174:177], v[198:201], 0
	v_mfma_f32_16x16x32_bf16 v[34:37], v[182:185], v[198:201], 0
	v_mfma_f32_16x16x32_bf16 v[50:53], v[182:185], v[190:193], 0
	v_mfma_f32_16x16x32_bf16 v[54:57], v[174:177], v[190:193], 0
	v_mfma_f32_16x16x32_bf16 v[62:65], v[142:145], v[194:197], v[62:65]
	v_mfma_f32_16x16x32_bf16 v[58:61], v[170:173], v[194:197], v[58:61]
	v_mfma_f32_16x16x32_bf16 v[42:45], v[170:173], v[202:205], v[42:45]
	v_mfma_f32_16x16x32_bf16 v[46:49], v[142:145], v[202:205], v[46:49]
	v_mfma_f32_16x16x32_bf16 v[30:33], v[142:145], v[232:235], v[30:33]
	v_mfma_f32_16x16x32_bf16 v[26:29], v[170:173], v[232:235], v[26:29]
	v_mfma_f32_16x16x32_bf16 v[10:13], v[170:173], v[240:243], v[10:13]
	v_mfma_f32_16x16x32_bf16 v[14:17], v[142:145], v[240:243], v[14:17]
	v_mfma_f32_16x16x32_bf16 v[6:9], v[178:181], v[240:243], v[6:9]
	v_mfma_f32_16x16x32_bf16 v[2:5], v[186:189], v[240:243], v[2:5]
	v_mfma_f32_16x16x32_bf16 v[18:21], v[186:189], v[232:235], v[18:21]
	v_mfma_f32_16x16x32_bf16 v[22:25], v[178:181], v[232:235], v[22:25]
	v_mfma_f32_16x16x32_bf16 v[38:41], v[178:181], v[202:205], v[38:41]
	v_mfma_f32_16x16x32_bf16 v[34:37], v[186:189], v[202:205], v[34:37]
	v_mfma_f32_16x16x32_bf16 v[50:53], v[186:189], v[194:197], v[50:53]
	v_mfma_f32_16x16x32_bf16 v[54:57], v[178:181], v[194:197], v[54:57]
	s_barrier
	s_setprio 0
	v_add_u32_e32 v170, 0x18000, v140
	v_add_u32_e32 v186, 0x1c000, v140
	ds_read_b128 v[132:135], v170
	ds_read_b128 v[142:145], v170 offset:1024
	ds_read_b128 v[154:157], v170 offset:2048
	ds_read_b128 v[170:173], v170 offset:3072
	ds_read_b128 v[174:177], v186
	ds_read_b128 v[178:181], v186 offset:1024
	ds_read_b128 v[182:185], v186 offset:2048
	ds_read_b128 v[186:189], v186 offset:3072
	s_add_i32 s27, s27, 0x80000
	s_mov_b32 m0, s25
	ds_read_b128 v[190:193], v141 offset:32768
	ds_read_b128 v[194:197], v141 offset:33792
	ds_read_b128 v[198:201], v141 offset:34816
	ds_read_b128 v[202:205], v141 offset:35840
	ds_read_b128 v[228:231], v141 offset:36864
	ds_read_b128 v[232:235], v141 offset:37888
	ds_read_b128 v[236:239], v141 offset:38912
	ds_read_b128 v[240:243], v141 offset:39936
	buffer_load_dwordx4 v136, s[60:63], s27 offen lds
	s_mov_b32 m0, s30
	s_nop 0
	buffer_load_dwordx4 v138, s[60:63], s27 offen lds
	s_waitcnt vmcnt(8)
	s_waitcnt lgkmcnt(0)
	s_setprio 1
	s_barrier
	v_mfma_f32_16x16x32_bf16 v[126:129], v[132:135], v[190:193], v[126:129]
	v_mfma_f32_16x16x32_bf16 v[106:109], v[154:157], v[190:193], v[106:109]
	v_mfma_f32_16x16x32_bf16 v[114:117], v[154:157], v[198:201], v[114:117]
	v_mfma_f32_16x16x32_bf16 v[118:121], v[132:135], v[198:201], v[118:121]
	v_mfma_f32_16x16x32_bf16 v[94:97], v[132:135], v[228:231], v[94:97]
	v_mfma_f32_16x16x32_bf16 v[90:93], v[154:157], v[228:231], v[90:93]
	v_mfma_f32_16x16x32_bf16 v[74:77], v[154:157], v[236:239], v[74:77]
	v_mfma_f32_16x16x32_bf16 v[78:81], v[132:135], v[236:239], v[78:81]
	v_mfma_f32_16x16x32_bf16 v[70:73], v[174:177], v[236:239], v[70:73]
	v_mfma_f32_16x16x32_bf16 v[66:69], v[182:185], v[236:239], v[66:69]
	v_mfma_f32_16x16x32_bf16 v[82:85], v[182:185], v[228:231], v[82:85]
	v_mfma_f32_16x16x32_bf16 v[86:89], v[174:177], v[228:231], v[86:89]
	v_mfma_f32_16x16x32_bf16 v[102:105], v[174:177], v[198:201], v[102:105]
	v_mfma_f32_16x16x32_bf16 v[98:101], v[182:185], v[198:201], v[98:101]
	v_mfma_f32_16x16x32_bf16 v[110:113], v[182:185], v[190:193], v[110:113]
	v_mfma_f32_16x16x32_bf16 v[122:125], v[174:177], v[190:193], v[122:125]
	v_mfma_f32_16x16x32_bf16 v[126:129], v[142:145], v[194:197], v[126:129]
	v_mfma_f32_16x16x32_bf16 v[106:109], v[170:173], v[194:197], v[106:109]
	v_mfma_f32_16x16x32_bf16 v[114:117], v[170:173], v[202:205], v[114:117]
	v_mfma_f32_16x16x32_bf16 v[118:121], v[142:145], v[202:205], v[118:121]
	v_mfma_f32_16x16x32_bf16 v[94:97], v[142:145], v[232:235], v[94:97]
	v_mfma_f32_16x16x32_bf16 v[90:93], v[170:173], v[232:235], v[90:93]
	v_mfma_f32_16x16x32_bf16 v[74:77], v[170:173], v[240:243], v[74:77]
	v_mfma_f32_16x16x32_bf16 v[78:81], v[142:145], v[240:243], v[78:81]
	v_mfma_f32_16x16x32_bf16 v[70:73], v[178:181], v[240:243], v[70:73]
	v_mfma_f32_16x16x32_bf16 v[66:69], v[186:189], v[240:243], v[66:69]
	v_mfma_f32_16x16x32_bf16 v[82:85], v[186:189], v[232:235], v[82:85]
	v_mfma_f32_16x16x32_bf16 v[86:89], v[178:181], v[232:235], v[86:89]
	v_mfma_f32_16x16x32_bf16 v[102:105], v[178:181], v[202:205], v[102:105]
	v_mfma_f32_16x16x32_bf16 v[98:101], v[186:189], v[202:205], v[98:101]
	v_mfma_f32_16x16x32_bf16 v[110:113], v[186:189], v[194:197], v[110:113]
	v_mfma_f32_16x16x32_bf16 v[122:125], v[178:181], v[194:197], v[122:125]
	s_barrier
	s_setprio 0
	s_mov_b32 m0, s36
	s_or_b32 s27, s26, 0x80
	ds_read_b128 v[190:193], v141 offset:49152
	ds_read_b128 v[194:197], v141 offset:50176
	ds_read_b128 v[198:201], v141 offset:51200
	ds_read_b128 v[202:205], v141 offset:52224
	ds_read_b128 v[228:231], v141 offset:53248
	ds_read_b128 v[232:235], v141 offset:54272
	ds_read_b128 v[236:239], v141 offset:55296
	ds_read_b128 v[240:243], v141 offset:56320
	buffer_load_dwordx4 v137, s[44:47], s27 offen lds
	s_mov_b32 m0, s37
	s_add_i32 s26, s26, 0x80080
	buffer_load_dwordx4 v139, s[44:47], s27 offen lds
	s_mov_b32 m0, s68
	s_nop 0
	buffer_load_dwordx4 v137, s[44:47], s26 offen lds
	s_mov_b32 m0, s69
	s_nop 0
	buffer_load_dwordx4 v139, s[44:47], s26 offen lds
	s_mov_b32 m0, s66
	s_nop 0
	buffer_load_dwordx4 v136, s[60:63], s23 offen lds
	s_mov_b32 m0, s67
	s_nop 0
	buffer_load_dwordx4 v138, s[60:63], s23 offen lds
	s_waitcnt vmcnt(8)
	s_waitcnt lgkmcnt(0)
	s_setprio 1
	s_barrier
	v_mfma_f32_16x16x32_bf16 v[62:65], v[132:135], v[190:193], v[62:65]
	v_mfma_f32_16x16x32_bf16 v[58:61], v[154:157], v[190:193], v[58:61]
	v_mfma_f32_16x16x32_bf16 v[42:45], v[154:157], v[198:201], v[42:45]
	v_mfma_f32_16x16x32_bf16 v[46:49], v[132:135], v[198:201], v[46:49]
	v_mfma_f32_16x16x32_bf16 v[30:33], v[132:135], v[228:231], v[30:33]
	v_mfma_f32_16x16x32_bf16 v[26:29], v[154:157], v[228:231], v[26:29]
	v_mfma_f32_16x16x32_bf16 v[10:13], v[154:157], v[236:239], v[10:13]
	v_mfma_f32_16x16x32_bf16 v[14:17], v[132:135], v[236:239], v[14:17]
	v_mfma_f32_16x16x32_bf16 v[6:9], v[174:177], v[236:239], v[6:9]
	v_mfma_f32_16x16x32_bf16 v[2:5], v[182:185], v[236:239], v[2:5]
	v_mfma_f32_16x16x32_bf16 v[18:21], v[182:185], v[228:231], v[18:21]
	v_mfma_f32_16x16x32_bf16 v[22:25], v[174:177], v[228:231], v[22:25]
	v_mfma_f32_16x16x32_bf16 v[38:41], v[174:177], v[198:201], v[38:41]
	v_mfma_f32_16x16x32_bf16 v[34:37], v[182:185], v[198:201], v[34:37]
	v_mfma_f32_16x16x32_bf16 v[50:53], v[182:185], v[190:193], v[50:53]
	v_mfma_f32_16x16x32_bf16 v[54:57], v[174:177], v[190:193], v[54:57]
	v_mfma_f32_16x16x32_bf16 v[62:65], v[142:145], v[194:197], v[62:65]
	v_mfma_f32_16x16x32_bf16 v[58:61], v[170:173], v[194:197], v[58:61]
	v_mfma_f32_16x16x32_bf16 v[42:45], v[170:173], v[202:205], v[42:45]
	v_mfma_f32_16x16x32_bf16 v[46:49], v[142:145], v[202:205], v[46:49]
	v_mfma_f32_16x16x32_bf16 v[30:33], v[142:145], v[232:235], v[30:33]
	v_mfma_f32_16x16x32_bf16 v[26:29], v[170:173], v[232:235], v[26:29]
	v_mfma_f32_16x16x32_bf16 v[10:13], v[170:173], v[240:243], v[10:13]
	v_mfma_f32_16x16x32_bf16 v[14:17], v[142:145], v[240:243], v[14:17]
	v_mfma_f32_16x16x32_bf16 v[6:9], v[178:181], v[240:243], v[6:9]
	v_mfma_f32_16x16x32_bf16 v[2:5], v[186:189], v[240:243], v[2:5]
	v_mfma_f32_16x16x32_bf16 v[18:21], v[186:189], v[232:235], v[18:21]
	v_mfma_f32_16x16x32_bf16 v[22:25], v[178:181], v[232:235], v[22:25]
	v_mfma_f32_16x16x32_bf16 v[38:41], v[178:181], v[202:205], v[38:41]
	v_mfma_f32_16x16x32_bf16 v[34:37], v[186:189], v[202:205], v[34:37]
	v_mfma_f32_16x16x32_bf16 v[50:53], v[186:189], v[194:197], v[50:53]
	v_mfma_f32_16x16x32_bf16 v[54:57], v[178:181], v[194:197], v[54:57]
	s_barrier
	s_setprio 0
	s_add_i32 s22, s22, 2
	s_addk_i32 s13, 0x100
	s_addk_i32 s21, 0x100
	s_cmp_gt_u32 s22, 29
.LBB0_1589:
	v_add_u32_e32 v170, 0x10000, v140
	v_add_u32_e32 v186, 0x14000, v140
	ds_read_b128 v[132:135], v170
	ds_read_b128 v[142:145], v170 offset:1024
	ds_read_b128 v[154:157], v170 offset:2048
	ds_read_b128 v[170:173], v170 offset:3072
	ds_read_b128 v[174:177], v186
	ds_read_b128 v[178:181], v186 offset:1024
	ds_read_b128 v[182:185], v186 offset:2048
	ds_read_b128 v[186:189], v186 offset:3072
	s_add_i32 s23, s13, 0xfff80080
	s_cmp_eq_u32 s22, 28
	s_cselect_b32 s27, s8, s23
	s_cselect_b32 s26, s9, s21
	s_or_b32 s23, s27, 0x80
	s_mov_b32 m0, s70
	ds_read_b128 v[190:193], v141
	ds_read_b128 v[194:197], v141 offset:1024
	ds_read_b128 v[198:201], v141 offset:2048
	ds_read_b128 v[202:205], v141 offset:3072
	ds_read_b128 v[228:231], v141 offset:4096
	ds_read_b128 v[232:235], v141 offset:5120
	ds_read_b128 v[236:239], v141 offset:6144
	ds_read_b128 v[240:243], v141 offset:7168
	buffer_load_dwordx4 v136, s[60:63], s13 offen lds
	s_mov_b32 m0, s72
	s_nop 0
	buffer_load_dwordx4 v138, s[60:63], s13 offen lds
	s_waitcnt vmcnt(8)
	s_waitcnt lgkmcnt(0)
	s_setprio 1
	s_barrier
	v_mfma_f32_16x16x32_bf16 v[126:129], v[132:135], v[190:193], v[126:129]
	v_mfma_f32_16x16x32_bf16 v[106:109], v[154:157], v[190:193], v[106:109]
	v_mfma_f32_16x16x32_bf16 v[114:117], v[154:157], v[198:201], v[114:117]
	v_mfma_f32_16x16x32_bf16 v[118:121], v[132:135], v[198:201], v[118:121]
	v_mfma_f32_16x16x32_bf16 v[94:97], v[132:135], v[228:231], v[94:97]
	v_mfma_f32_16x16x32_bf16 v[90:93], v[154:157], v[228:231], v[90:93]
	v_mfma_f32_16x16x32_bf16 v[74:77], v[154:157], v[236:239], v[74:77]
	v_mfma_f32_16x16x32_bf16 v[78:81], v[132:135], v[236:239], v[78:81]
	v_mfma_f32_16x16x32_bf16 v[70:73], v[174:177], v[236:239], v[70:73]
	v_mfma_f32_16x16x32_bf16 v[66:69], v[182:185], v[236:239], v[66:69]
	v_mfma_f32_16x16x32_bf16 v[82:85], v[182:185], v[228:231], v[82:85]
	v_mfma_f32_16x16x32_bf16 v[86:89], v[174:177], v[228:231], v[86:89]
	v_mfma_f32_16x16x32_bf16 v[102:105], v[174:177], v[198:201], v[102:105]
	v_mfma_f32_16x16x32_bf16 v[98:101], v[182:185], v[198:201], v[98:101]
	v_mfma_f32_16x16x32_bf16 v[110:113], v[182:185], v[190:193], v[110:113]
	v_mfma_f32_16x16x32_bf16 v[122:125], v[174:177], v[190:193], v[122:125]
	v_mfma_f32_16x16x32_bf16 v[126:129], v[142:145], v[194:197], v[126:129]
	v_mfma_f32_16x16x32_bf16 v[106:109], v[170:173], v[194:197], v[106:109]
	v_mfma_f32_16x16x32_bf16 v[114:117], v[170:173], v[202:205], v[114:117]
	v_mfma_f32_16x16x32_bf16 v[118:121], v[142:145], v[202:205], v[118:121]
	v_mfma_f32_16x16x32_bf16 v[94:97], v[142:145], v[232:235], v[94:97]
	v_mfma_f32_16x16x32_bf16 v[90:93], v[170:173], v[232:235], v[90:93]
	v_mfma_f32_16x16x32_bf16 v[74:77], v[170:173], v[240:243], v[74:77]
	v_mfma_f32_16x16x32_bf16 v[78:81], v[142:145], v[240:243], v[78:81]
	v_mfma_f32_16x16x32_bf16 v[70:73], v[178:181], v[240:243], v[70:73]
	v_mfma_f32_16x16x32_bf16 v[66:69], v[186:189], v[240:243], v[66:69]
	v_mfma_f32_16x16x32_bf16 v[82:85], v[186:189], v[232:235], v[82:85]
	v_mfma_f32_16x16x32_bf16 v[86:89], v[178:181], v[232:235], v[86:89]
	v_mfma_f32_16x16x32_bf16 v[102:105], v[178:181], v[202:205], v[102:105]
	v_mfma_f32_16x16x32_bf16 v[98:101], v[186:189], v[202:205], v[98:101]
	v_mfma_f32_16x16x32_bf16 v[110:113], v[186:189], v[194:197], v[110:113]
	v_mfma_f32_16x16x32_bf16 v[122:125], v[178:181], v[194:197], v[122:125]
	s_barrier
	s_setprio 0
	s_mov_b32 m0, s15
	s_mov_b32 s46, s62
	s_mov_b32 s47, s63
	ds_read_b128 v[190:193], v141 offset:16384
	ds_read_b128 v[194:197], v141 offset:17408
	ds_read_b128 v[198:201], v141 offset:18432
	ds_read_b128 v[202:205], v141 offset:19456
	ds_read_b128 v[228:231], v141 offset:20480
	ds_read_b128 v[232:235], v141 offset:21504
	ds_read_b128 v[236:239], v141 offset:22528
	ds_read_b128 v[240:243], v141 offset:23552
	buffer_load_dwordx4 v137, s[44:47], s26 offen lds
	s_mov_b32 m0, s16
	s_add_i32 s49, s26, 0x80000
	buffer_load_dwordx4 v139, s[44:47], s26 offen lds
	s_mov_b32 m0, s18
	s_nop 0
	buffer_load_dwordx4 v137, s[44:47], s49 offen lds
	s_mov_b32 m0, s19
	s_nop 0
	buffer_load_dwordx4 v139, s[44:47], s49 offen lds
	s_mov_b32 m0, s14
	s_nop 0
	buffer_load_dwordx4 v136, s[60:63], s27 offen lds
	s_mov_b32 m0, s24
	s_nop 0
	buffer_load_dwordx4 v138, s[60:63], s27 offen lds
	s_waitcnt vmcnt(8)
	s_waitcnt lgkmcnt(0)
	s_setprio 1
	s_barrier
	v_mfma_f32_16x16x32_bf16 v[62:65], v[132:135], v[190:193], v[62:65]
	v_mfma_f32_16x16x32_bf16 v[58:61], v[154:157], v[190:193], v[58:61]
	v_mfma_f32_16x16x32_bf16 v[42:45], v[154:157], v[198:201], v[42:45]
	v_mfma_f32_16x16x32_bf16 v[46:49], v[132:135], v[198:201], v[46:49]
	v_mfma_f32_16x16x32_bf16 v[30:33], v[132:135], v[228:231], v[30:33]
	v_mfma_f32_16x16x32_bf16 v[26:29], v[154:157], v[228:231], v[26:29]
	v_mfma_f32_16x16x32_bf16 v[10:13], v[154:157], v[236:239], v[10:13]
	v_mfma_f32_16x16x32_bf16 v[14:17], v[132:135], v[236:239], v[14:17]
	v_mfma_f32_16x16x32_bf16 v[6:9], v[174:177], v[236:239], v[6:9]
	v_mfma_f32_16x16x32_bf16 v[2:5], v[182:185], v[236:239], v[2:5]
	v_mfma_f32_16x16x32_bf16 v[18:21], v[182:185], v[228:231], v[18:21]
	v_mfma_f32_16x16x32_bf16 v[22:25], v[174:177], v[228:231], v[22:25]
	v_mfma_f32_16x16x32_bf16 v[38:41], v[174:177], v[198:201], v[38:41]
	v_mfma_f32_16x16x32_bf16 v[34:37], v[182:185], v[198:201], v[34:37]
	v_mfma_f32_16x16x32_bf16 v[50:53], v[182:185], v[190:193], v[50:53]
	v_mfma_f32_16x16x32_bf16 v[54:57], v[174:177], v[190:193], v[54:57]
	v_mfma_f32_16x16x32_bf16 v[62:65], v[142:145], v[194:197], v[62:65]
	v_mfma_f32_16x16x32_bf16 v[58:61], v[170:173], v[194:197], v[58:61]
	v_mfma_f32_16x16x32_bf16 v[42:45], v[170:173], v[202:205], v[42:45]
	v_mfma_f32_16x16x32_bf16 v[46:49], v[142:145], v[202:205], v[46:49]
	v_mfma_f32_16x16x32_bf16 v[30:33], v[142:145], v[232:235], v[30:33]
	v_mfma_f32_16x16x32_bf16 v[26:29], v[170:173], v[232:235], v[26:29]
	v_mfma_f32_16x16x32_bf16 v[10:13], v[170:173], v[240:243], v[10:13]
	v_mfma_f32_16x16x32_bf16 v[14:17], v[142:145], v[240:243], v[14:17]
	v_mfma_f32_16x16x32_bf16 v[6:9], v[178:181], v[240:243], v[6:9]
	v_mfma_f32_16x16x32_bf16 v[2:5], v[186:189], v[240:243], v[2:5]
	v_mfma_f32_16x16x32_bf16 v[18:21], v[186:189], v[232:235], v[18:21]
	v_mfma_f32_16x16x32_bf16 v[22:25], v[178:181], v[232:235], v[22:25]
	v_mfma_f32_16x16x32_bf16 v[38:41], v[178:181], v[202:205], v[38:41]
	v_mfma_f32_16x16x32_bf16 v[34:37], v[186:189], v[202:205], v[34:37]
	v_mfma_f32_16x16x32_bf16 v[50:53], v[186:189], v[194:197], v[50:53]
	v_mfma_f32_16x16x32_bf16 v[54:57], v[178:181], v[194:197], v[54:57]
	s_barrier
	s_setprio 0
	v_add_u32_e32 v170, 0x18000, v140
	v_add_u32_e32 v186, 0x1c000, v140
	ds_read_b128 v[132:135], v170
	ds_read_b128 v[142:145], v170 offset:1024
	ds_read_b128 v[154:157], v170 offset:2048
	ds_read_b128 v[170:173], v170 offset:3072
	ds_read_b128 v[174:177], v186
	ds_read_b128 v[178:181], v186 offset:1024
	ds_read_b128 v[182:185], v186 offset:2048
	ds_read_b128 v[186:189], v186 offset:3072
	s_add_i32 s27, s27, 0x80000
	s_mov_b32 m0, s25
	ds_read_b128 v[190:193], v141 offset:32768
	ds_read_b128 v[194:197], v141 offset:33792
	ds_read_b128 v[198:201], v141 offset:34816
	ds_read_b128 v[202:205], v141 offset:35840
	ds_read_b128 v[228:231], v141 offset:36864
	ds_read_b128 v[232:235], v141 offset:37888
	ds_read_b128 v[236:239], v141 offset:38912
	ds_read_b128 v[240:243], v141 offset:39936
	buffer_load_dwordx4 v136, s[60:63], s27 offen lds
	s_mov_b32 m0, s30
	s_nop 0
	buffer_load_dwordx4 v138, s[60:63], s27 offen lds
	s_waitcnt vmcnt(8)
	s_waitcnt lgkmcnt(0)
	s_setprio 1
	s_barrier
	v_mfma_f32_16x16x32_bf16 v[126:129], v[132:135], v[190:193], v[126:129]
	v_mfma_f32_16x16x32_bf16 v[106:109], v[154:157], v[190:193], v[106:109]
	v_mfma_f32_16x16x32_bf16 v[114:117], v[154:157], v[198:201], v[114:117]
	v_mfma_f32_16x16x32_bf16 v[118:121], v[132:135], v[198:201], v[118:121]
	v_mfma_f32_16x16x32_bf16 v[94:97], v[132:135], v[228:231], v[94:97]
	v_mfma_f32_16x16x32_bf16 v[90:93], v[154:157], v[228:231], v[90:93]
	v_mfma_f32_16x16x32_bf16 v[74:77], v[154:157], v[236:239], v[74:77]
	v_mfma_f32_16x16x32_bf16 v[78:81], v[132:135], v[236:239], v[78:81]
	v_mfma_f32_16x16x32_bf16 v[70:73], v[174:177], v[236:239], v[70:73]
	v_mfma_f32_16x16x32_bf16 v[66:69], v[182:185], v[236:239], v[66:69]
	v_mfma_f32_16x16x32_bf16 v[82:85], v[182:185], v[228:231], v[82:85]
	v_mfma_f32_16x16x32_bf16 v[86:89], v[174:177], v[228:231], v[86:89]
	v_mfma_f32_16x16x32_bf16 v[102:105], v[174:177], v[198:201], v[102:105]
	v_mfma_f32_16x16x32_bf16 v[98:101], v[182:185], v[198:201], v[98:101]
	v_mfma_f32_16x16x32_bf16 v[110:113], v[182:185], v[190:193], v[110:113]
	v_mfma_f32_16x16x32_bf16 v[122:125], v[174:177], v[190:193], v[122:125]
	v_mfma_f32_16x16x32_bf16 v[126:129], v[142:145], v[194:197], v[126:129]
	v_mfma_f32_16x16x32_bf16 v[106:109], v[170:173], v[194:197], v[106:109]
	v_mfma_f32_16x16x32_bf16 v[114:117], v[170:173], v[202:205], v[114:117]
	v_mfma_f32_16x16x32_bf16 v[118:121], v[142:145], v[202:205], v[118:121]
	v_mfma_f32_16x16x32_bf16 v[94:97], v[142:145], v[232:235], v[94:97]
	v_mfma_f32_16x16x32_bf16 v[90:93], v[170:173], v[232:235], v[90:93]
	v_mfma_f32_16x16x32_bf16 v[74:77], v[170:173], v[240:243], v[74:77]
	v_mfma_f32_16x16x32_bf16 v[78:81], v[142:145], v[240:243], v[78:81]
	v_mfma_f32_16x16x32_bf16 v[70:73], v[178:181], v[240:243], v[70:73]
	v_mfma_f32_16x16x32_bf16 v[66:69], v[186:189], v[240:243], v[66:69]
	v_mfma_f32_16x16x32_bf16 v[82:85], v[186:189], v[232:235], v[82:85]
	v_mfma_f32_16x16x32_bf16 v[86:89], v[178:181], v[232:235], v[86:89]
	v_mfma_f32_16x16x32_bf16 v[102:105], v[178:181], v[202:205], v[102:105]
	v_mfma_f32_16x16x32_bf16 v[98:101], v[186:189], v[202:205], v[98:101]
	v_mfma_f32_16x16x32_bf16 v[110:113], v[186:189], v[194:197], v[110:113]
	v_mfma_f32_16x16x32_bf16 v[122:125], v[178:181], v[194:197], v[122:125]
	s_barrier
	s_setprio 0
	s_mov_b32 m0, s36
	s_or_b32 s27, s26, 0x80
	ds_read_b128 v[190:193], v141 offset:49152
	ds_read_b128 v[194:197], v141 offset:50176
	ds_read_b128 v[198:201], v141 offset:51200
	ds_read_b128 v[202:205], v141 offset:52224
	ds_read_b128 v[228:231], v141 offset:53248
	ds_read_b128 v[232:235], v141 offset:54272
	ds_read_b128 v[236:239], v141 offset:55296
	ds_read_b128 v[240:243], v141 offset:56320
	buffer_load_dwordx4 v137, s[44:47], s27 offen lds
	s_mov_b32 m0, s37
	s_add_i32 s26, s26, 0x80080
	buffer_load_dwordx4 v139, s[44:47], s27 offen lds
	s_mov_b32 m0, s68
	s_nop 0
	buffer_load_dwordx4 v137, s[44:47], s26 offen lds
	s_mov_b32 m0, s69
	s_nop 0
	buffer_load_dwordx4 v139, s[44:47], s26 offen lds
	s_mov_b32 m0, s66
	s_nop 0
	buffer_load_dwordx4 v136, s[60:63], s23 offen lds
	s_mov_b32 m0, s67
	s_nop 0
	buffer_load_dwordx4 v138, s[60:63], s23 offen lds
	s_waitcnt vmcnt(8)
	s_waitcnt lgkmcnt(0)
	s_setprio 1
	s_barrier
	v_mfma_f32_16x16x32_bf16 v[62:65], v[132:135], v[190:193], v[62:65]
	v_mfma_f32_16x16x32_bf16 v[58:61], v[154:157], v[190:193], v[58:61]
	v_mfma_f32_16x16x32_bf16 v[42:45], v[154:157], v[198:201], v[42:45]
	v_mfma_f32_16x16x32_bf16 v[46:49], v[132:135], v[198:201], v[46:49]
	v_mfma_f32_16x16x32_bf16 v[30:33], v[132:135], v[228:231], v[30:33]
	v_mfma_f32_16x16x32_bf16 v[26:29], v[154:157], v[228:231], v[26:29]
	v_mfma_f32_16x16x32_bf16 v[10:13], v[154:157], v[236:239], v[10:13]
	v_mfma_f32_16x16x32_bf16 v[14:17], v[132:135], v[236:239], v[14:17]
	v_mfma_f32_16x16x32_bf16 v[6:9], v[174:177], v[236:239], v[6:9]
	v_mfma_f32_16x16x32_bf16 v[2:5], v[182:185], v[236:239], v[2:5]
	v_mfma_f32_16x16x32_bf16 v[18:21], v[182:185], v[228:231], v[18:21]
	v_mfma_f32_16x16x32_bf16 v[22:25], v[174:177], v[228:231], v[22:25]
	v_mfma_f32_16x16x32_bf16 v[38:41], v[174:177], v[198:201], v[38:41]
	v_mfma_f32_16x16x32_bf16 v[34:37], v[182:185], v[198:201], v[34:37]
	v_mfma_f32_16x16x32_bf16 v[50:53], v[182:185], v[190:193], v[50:53]
	v_mfma_f32_16x16x32_bf16 v[54:57], v[174:177], v[190:193], v[54:57]
	v_mfma_f32_16x16x32_bf16 v[62:65], v[142:145], v[194:197], v[62:65]
	v_mfma_f32_16x16x32_bf16 v[58:61], v[170:173], v[194:197], v[58:61]
	v_mfma_f32_16x16x32_bf16 v[42:45], v[170:173], v[202:205], v[42:45]
	v_mfma_f32_16x16x32_bf16 v[46:49], v[142:145], v[202:205], v[46:49]
	v_mfma_f32_16x16x32_bf16 v[30:33], v[142:145], v[232:235], v[30:33]
	v_mfma_f32_16x16x32_bf16 v[26:29], v[170:173], v[232:235], v[26:29]
	v_mfma_f32_16x16x32_bf16 v[10:13], v[170:173], v[240:243], v[10:13]
	v_mfma_f32_16x16x32_bf16 v[14:17], v[142:145], v[240:243], v[14:17]
	v_mfma_f32_16x16x32_bf16 v[6:9], v[178:181], v[240:243], v[6:9]
	v_mfma_f32_16x16x32_bf16 v[2:5], v[186:189], v[240:243], v[2:5]
	v_mfma_f32_16x16x32_bf16 v[18:21], v[186:189], v[232:235], v[18:21]
	v_mfma_f32_16x16x32_bf16 v[22:25], v[178:181], v[232:235], v[22:25]
	v_mfma_f32_16x16x32_bf16 v[38:41], v[178:181], v[202:205], v[38:41]
	v_mfma_f32_16x16x32_bf16 v[34:37], v[186:189], v[202:205], v[34:37]
	v_mfma_f32_16x16x32_bf16 v[50:53], v[186:189], v[194:197], v[50:53]
	v_mfma_f32_16x16x32_bf16 v[54:57], v[178:181], v[194:197], v[54:57]
	s_barrier
	s_setprio 0
	s_add_i32 s22, s22, 2
	s_addk_i32 s13, 0x100
	s_addk_i32 s21, 0x100
	s_cmp_gt_u32 s22, 29
	s_cbranch_scc0 .LBB0_1589
	s_and_b64 vcc, exec, s[64:65]
	s_cbranch_vccz .LBB0_1592
	s_barrier

.LBB0_1879:
	s_lshl_b32 s18, s91, 20
	s_and_b64 s[8:9], s[48:49], exec
	s_cselect_b32 s8, s18, s95
	s_lshl_b32 s19, s92, 20
	s_and_b64 s[42:43], s[48:49], exec
	s_cselect_b32 s9, s19, s94
	s_add_i32 vcc_lo, s95, 0x80080
	s_add_i32 vcc_hi, s94, 0x100
	s_mov_b32 s94, -2
	v_add_u32_e32 v139, 0x10000, v136
	ds_read_b128 v[140:143], v139
	ds_read_b128 v[154:157], v139 offset:1024
	ds_read_b128 v[170:173], v139 offset:2048
	ds_read_b128 v[174:177], v139 offset:3072
	v_add_u32_e32 v139, 0x14000, v136
	ds_read_b128 v[178:181], v139
	ds_read_b128 v[182:185], v139 offset:1024
	ds_read_b128 v[186:189], v139 offset:2048
	ds_read_b128 v[190:193], v139 offset:3072
	s_add_i32 s42, vcc_lo, 0xfff80080
	s_cmp_eq_u32 s94, 28
	s_cselect_b32 s52, s8, s42
	s_cselect_b32 s96, s9, vcc_hi
	s_or_b32 s95, s52, 0x80
	s_mov_b32 m0, s72
	ds_read_b128 v[194:197], v137
	ds_read_b128 v[198:201], v137 offset:1024
	ds_read_b128 v[202:205], v137 offset:2048
	ds_read_b128 v[228:231], v137 offset:3072
	ds_read_b128 v[232:235], v137 offset:4096
	ds_read_b128 v[236:239], v137 offset:5120
	ds_read_b128 v[240:243], v137 offset:6144
	ds_read_b128 v[244:247], v137 offset:7168
	buffer_load_dwordx4 v132, s[60:63], vcc_lo offen lds
	s_mov_b32 m0, s47
	s_nop 0
	buffer_load_dwordx4 v134, s[60:63], vcc_lo offen lds
	s_waitcnt vmcnt(8)
	s_waitcnt lgkmcnt(0)
	s_setprio 1
	s_barrier
	v_mfma_f32_16x16x32_bf16 v[114:117], v[140:143], v[194:197], 0
	v_mfma_f32_16x16x32_bf16 v[110:113], v[170:173], v[194:197], 0
	v_mfma_f32_16x16x32_bf16 v[102:105], v[170:173], v[202:205], 0
	v_mfma_f32_16x16x32_bf16 v[106:109], v[140:143], v[202:205], 0
	v_mfma_f32_16x16x32_bf16 v[94:97], v[140:143], v[232:235], 0
	v_mfma_f32_16x16x32_bf16 v[86:89], v[170:173], v[232:235], 0
	v_mfma_f32_16x16x32_bf16 v[70:73], v[170:173], v[240:243], 0
	v_mfma_f32_16x16x32_bf16 v[78:81], v[140:143], v[240:243], 0
	v_mfma_f32_16x16x32_bf16 v[74:77], v[178:181], v[240:243], 0
	v_mfma_f32_16x16x32_bf16 v[66:69], v[186:189], v[240:243], 0
	v_mfma_f32_16x16x32_bf16 v[82:85], v[186:189], v[232:235], 0
	v_mfma_f32_16x16x32_bf16 v[90:93], v[178:181], v[232:235], 0
	v_mfma_f32_16x16x32_bf16 v[118:121], v[178:181], v[202:205], 0
	v_mfma_f32_16x16x32_bf16 v[98:101], v[186:189], v[202:205], 0
	v_mfma_f32_16x16x32_bf16 v[122:125], v[186:189], v[194:197], 0
	v_mfma_f32_16x16x32_bf16 v[126:129], v[178:181], v[194:197], 0
	v_mfma_f32_16x16x32_bf16 v[114:117], v[154:157], v[198:201], v[114:117]
	v_mfma_f32_16x16x32_bf16 v[110:113], v[174:177], v[198:201], v[110:113]
	v_mfma_f32_16x16x32_bf16 v[102:105], v[174:177], v[228:231], v[102:105]
	v_mfma_f32_16x16x32_bf16 v[106:109], v[154:157], v[228:231], v[106:109]
	v_mfma_f32_16x16x32_bf16 v[94:97], v[154:157], v[236:239], v[94:97]
	v_mfma_f32_16x16x32_bf16 v[86:89], v[174:177], v[236:239], v[86:89]
	v_mfma_f32_16x16x32_bf16 v[70:73], v[174:177], v[244:247], v[70:73]
	v_mfma_f32_16x16x32_bf16 v[78:81], v[154:157], v[244:247], v[78:81]
	v_mfma_f32_16x16x32_bf16 v[74:77], v[182:185], v[244:247], v[74:77]
	v_mfma_f32_16x16x32_bf16 v[66:69], v[190:193], v[244:247], v[66:69]
	v_mfma_f32_16x16x32_bf16 v[82:85], v[190:193], v[236:239], v[82:85]
	v_mfma_f32_16x16x32_bf16 v[90:93], v[182:185], v[236:239], v[90:93]
	v_mfma_f32_16x16x32_bf16 v[118:121], v[182:185], v[228:231], v[118:121]
	v_mfma_f32_16x16x32_bf16 v[98:101], v[190:193], v[228:231], v[98:101]
	v_mfma_f32_16x16x32_bf16 v[122:125], v[190:193], v[198:201], v[122:125]
	v_mfma_f32_16x16x32_bf16 v[126:129], v[182:185], v[198:201], v[126:129]
	s_barrier
	s_setprio 0
	s_mov_b32 m0, s13
	s_mov_b32 s42, s62
	s_mov_b32 s43, s63
	ds_read_b128 v[194:197], v137 offset:16384
	ds_read_b128 v[198:201], v137 offset:17408
	ds_read_b128 v[202:205], v137 offset:18432
	ds_read_b128 v[228:231], v137 offset:19456
	ds_read_b128 v[232:235], v137 offset:20480
	ds_read_b128 v[236:239], v137 offset:21504
	ds_read_b128 v[240:243], v137 offset:22528
	ds_read_b128 v[244:247], v137 offset:23552
	buffer_load_dwordx4 v133, s[40:43], s96 offen lds
	s_mov_b32 m0, s14
	s_add_i32 s53, s96, 0x80000
	buffer_load_dwordx4 v135, s[40:43], s96 offen lds
	s_mov_b32 m0, s15
	s_nop 0
	buffer_load_dwordx4 v133, s[40:43], s53 offen lds
	s_mov_b32 m0, s16
	s_nop 0
	buffer_load_dwordx4 v135, s[40:43], s53 offen lds
	s_mov_b32 m0, s2
	s_nop 0
	buffer_load_dwordx4 v132, s[60:63], s52 offen lds
	s_mov_b32 m0, s21
	s_nop 0
	buffer_load_dwordx4 v134, s[60:63], s52 offen lds
	s_waitcnt vmcnt(8)
	s_waitcnt lgkmcnt(0)
	s_setprio 1
	s_barrier
	v_mfma_f32_16x16x32_bf16 v[62:65], v[140:143], v[194:197], 0
	v_mfma_f32_16x16x32_bf16 v[54:57], v[170:173], v[194:197], 0
	v_mfma_f32_16x16x32_bf16 v[38:41], v[170:173], v[202:205], 0
	v_mfma_f32_16x16x32_bf16 v[46:49], v[140:143], v[202:205], 0
	v_mfma_f32_16x16x32_bf16 v[30:33], v[140:143], v[232:235], 0
	v_mfma_f32_16x16x32_bf16 v[22:25], v[170:173], v[232:235], 0
	v_mfma_f32_16x16x32_bf16 v[6:9], v[170:173], v[240:243], 0
	v_mfma_f32_16x16x32_bf16 v[14:17], v[140:143], v[240:243], 0
	v_mfma_f32_16x16x32_bf16 v[10:13], v[178:181], v[240:243], 0
	v_mfma_f32_16x16x32_bf16 v[2:5], v[186:189], v[240:243], 0
	v_mfma_f32_16x16x32_bf16 v[18:21], v[186:189], v[232:235], 0
	v_mfma_f32_16x16x32_bf16 v[26:29], v[178:181], v[232:235], 0
	v_mfma_f32_16x16x32_bf16 v[42:45], v[178:181], v[202:205], 0
	v_mfma_f32_16x16x32_bf16 v[34:37], v[186:189], v[202:205], 0
	v_mfma_f32_16x16x32_bf16 v[50:53], v[186:189], v[194:197], 0
	v_mfma_f32_16x16x32_bf16 v[58:61], v[178:181], v[194:197], 0
	v_mfma_f32_16x16x32_bf16 v[62:65], v[154:157], v[198:201], v[62:65]
	v_mfma_f32_16x16x32_bf16 v[54:57], v[174:177], v[198:201], v[54:57]
	v_mfma_f32_16x16x32_bf16 v[38:41], v[174:177], v[228:231], v[38:41]
	v_mfma_f32_16x16x32_bf16 v[46:49], v[154:157], v[228:231], v[46:49]
	v_mfma_f32_16x16x32_bf16 v[30:33], v[154:157], v[236:239], v[30:33]
	v_mfma_f32_16x16x32_bf16 v[22:25], v[174:177], v[236:239], v[22:25]
	v_mfma_f32_16x16x32_bf16 v[6:9], v[174:177], v[244:247], v[6:9]
	v_mfma_f32_16x16x32_bf16 v[14:17], v[154:157], v[244:247], v[14:17]
	v_mfma_f32_16x16x32_bf16 v[10:13], v[182:185], v[244:247], v[10:13]
	v_mfma_f32_16x16x32_bf16 v[2:5], v[190:193], v[244:247], v[2:5]
	v_mfma_f32_16x16x32_bf16 v[18:21], v[190:193], v[236:239], v[18:21]
	v_mfma_f32_16x16x32_bf16 v[26:29], v[182:185], v[236:239], v[26:29]
	v_mfma_f32_16x16x32_bf16 v[42:45], v[182:185], v[228:231], v[42:45]
	v_mfma_f32_16x16x32_bf16 v[34:37], v[190:193], v[228:231], v[34:37]
	v_mfma_f32_16x16x32_bf16 v[50:53], v[190:193], v[198:201], v[50:53]
	v_mfma_f32_16x16x32_bf16 v[58:61], v[182:185], v[198:201], v[58:61]
	s_barrier
	s_setprio 0
	v_add_u32_e32 v139, 0x18000, v136
	ds_read_b128 v[140:143], v139
	ds_read_b128 v[154:157], v139 offset:1024
	ds_read_b128 v[170:173], v139 offset:2048
	ds_read_b128 v[174:177], v139 offset:3072
	v_add_u32_e32 v139, 0x1c000, v136
	ds_read_b128 v[178:181], v139
	ds_read_b128 v[182:185], v139 offset:1024
	ds_read_b128 v[186:189], v139 offset:2048
	ds_read_b128 v[190:193], v139 offset:3072
	s_add_i32 s52, s52, 0x80000
	s_mov_b32 m0, s23
	ds_read_b128 v[194:197], v137 offset:32768
	ds_read_b128 v[198:201], v137 offset:33792
	ds_read_b128 v[202:205], v137 offset:34816
	ds_read_b128 v[228:231], v137 offset:35840
	ds_read_b128 v[232:235], v137 offset:36864
	ds_read_b128 v[236:239], v137 offset:37888
	ds_read_b128 v[240:243], v137 offset:38912
	ds_read_b128 v[244:247], v137 offset:39936
	buffer_load_dwordx4 v132, s[60:63], s52 offen lds
	s_mov_b32 m0, s24
	s_nop 0
	buffer_load_dwordx4 v134, s[60:63], s52 offen lds
	s_waitcnt vmcnt(8)
	s_waitcnt lgkmcnt(0)
	s_setprio 1
	s_barrier
	v_mfma_f32_16x16x32_bf16 v[114:117], v[140:143], v[194:197], v[114:117]
	v_mfma_f32_16x16x32_bf16 v[110:113], v[170:173], v[194:197], v[110:113]
	v_mfma_f32_16x16x32_bf16 v[102:105], v[170:173], v[202:205], v[102:105]
	v_mfma_f32_16x16x32_bf16 v[106:109], v[140:143], v[202:205], v[106:109]
	v_mfma_f32_16x16x32_bf16 v[94:97], v[140:143], v[232:235], v[94:97]
	v_mfma_f32_16x16x32_bf16 v[86:89], v[170:173], v[232:235], v[86:89]
	v_mfma_f32_16x16x32_bf16 v[70:73], v[170:173], v[240:243], v[70:73]
	v_mfma_f32_16x16x32_bf16 v[78:81], v[140:143], v[240:243], v[78:81]
	v_mfma_f32_16x16x32_bf16 v[74:77], v[178:181], v[240:243], v[74:77]
	v_mfma_f32_16x16x32_bf16 v[66:69], v[186:189], v[240:243], v[66:69]
	v_mfma_f32_16x16x32_bf16 v[82:85], v[186:189], v[232:235], v[82:85]
	v_mfma_f32_16x16x32_bf16 v[90:93], v[178:181], v[232:235], v[90:93]
	v_mfma_f32_16x16x32_bf16 v[118:121], v[178:181], v[202:205], v[118:121]
	v_mfma_f32_16x16x32_bf16 v[98:101], v[186:189], v[202:205], v[98:101]
	v_mfma_f32_16x16x32_bf16 v[122:125], v[186:189], v[194:197], v[122:125]
	v_mfma_f32_16x16x32_bf16 v[126:129], v[178:181], v[194:197], v[126:129]
	v_mfma_f32_16x16x32_bf16 v[114:117], v[154:157], v[198:201], v[114:117]
	v_mfma_f32_16x16x32_bf16 v[110:113], v[174:177], v[198:201], v[110:113]
	v_mfma_f32_16x16x32_bf16 v[102:105], v[174:177], v[228:231], v[102:105]
	v_mfma_f32_16x16x32_bf16 v[106:109], v[154:157], v[228:231], v[106:109]
	v_mfma_f32_16x16x32_bf16 v[94:97], v[154:157], v[236:239], v[94:97]
	v_mfma_f32_16x16x32_bf16 v[86:89], v[174:177], v[236:239], v[86:89]
	v_mfma_f32_16x16x32_bf16 v[70:73], v[174:177], v[244:247], v[70:73]
	v_mfma_f32_16x16x32_bf16 v[78:81], v[154:157], v[244:247], v[78:81]
	v_mfma_f32_16x16x32_bf16 v[74:77], v[182:185], v[244:247], v[74:77]
	v_mfma_f32_16x16x32_bf16 v[66:69], v[190:193], v[244:247], v[66:69]
	v_mfma_f32_16x16x32_bf16 v[82:85], v[190:193], v[236:239], v[82:85]
	v_mfma_f32_16x16x32_bf16 v[90:93], v[182:185], v[236:239], v[90:93]
	v_mfma_f32_16x16x32_bf16 v[118:121], v[182:185], v[228:231], v[118:121]
	v_mfma_f32_16x16x32_bf16 v[98:101], v[190:193], v[228:231], v[98:101]
	v_mfma_f32_16x16x32_bf16 v[122:125], v[190:193], v[198:201], v[122:125]
	v_mfma_f32_16x16x32_bf16 v[126:129], v[182:185], v[198:201], v[126:129]
	s_barrier
	s_setprio 0
	s_mov_b32 m0, s31
	s_or_b32 s52, s96, 0x80
	ds_read_b128 v[194:197], v137 offset:49152
	ds_read_b128 v[198:201], v137 offset:50176
	ds_read_b128 v[202:205], v137 offset:51200
	ds_read_b128 v[228:231], v137 offset:52224
	ds_read_b128 v[232:235], v137 offset:53248
	ds_read_b128 v[236:239], v137 offset:54272
	ds_read_b128 v[240:243], v137 offset:55296
	ds_read_b128 v[244:247], v137 offset:56320
	buffer_load_dwordx4 v133, s[40:43], s52 offen lds
	s_mov_b32 m0, s33
	s_add_i32 s96, s96, 0x80080
	buffer_load_dwordx4 v135, s[40:43], s52 offen lds
	s_mov_b32 m0, s36
	s_nop 0
	buffer_load_dwordx4 v133, s[40:43], s96 offen lds
	s_mov_b32 m0, s37
	s_nop 0
	buffer_load_dwordx4 v135, s[40:43], s96 offen lds
	s_mov_b32 m0, s34
	s_nop 0
	buffer_load_dwordx4 v132, s[60:63], s95 offen lds
	s_mov_b32 m0, s35
	s_nop 0
	buffer_load_dwordx4 v134, s[60:63], s95 offen lds
	s_waitcnt vmcnt(8)
	s_waitcnt lgkmcnt(0)
	s_setprio 1
	s_barrier
	v_mfma_f32_16x16x32_bf16 v[62:65], v[140:143], v[194:197], v[62:65]
	v_mfma_f32_16x16x32_bf16 v[54:57], v[170:173], v[194:197], v[54:57]
	v_mfma_f32_16x16x32_bf16 v[38:41], v[170:173], v[202:205], v[38:41]
	v_mfma_f32_16x16x32_bf16 v[46:49], v[140:143], v[202:205], v[46:49]
	v_mfma_f32_16x16x32_bf16 v[30:33], v[140:143], v[232:235], v[30:33]
	v_mfma_f32_16x16x32_bf16 v[22:25], v[170:173], v[232:235], v[22:25]
	v_mfma_f32_16x16x32_bf16 v[6:9], v[170:173], v[240:243], v[6:9]
	v_mfma_f32_16x16x32_bf16 v[14:17], v[140:143], v[240:243], v[14:17]
	v_mfma_f32_16x16x32_bf16 v[10:13], v[178:181], v[240:243], v[10:13]
	v_mfma_f32_16x16x32_bf16 v[2:5], v[186:189], v[240:243], v[2:5]
	v_mfma_f32_16x16x32_bf16 v[18:21], v[186:189], v[232:235], v[18:21]
	v_mfma_f32_16x16x32_bf16 v[26:29], v[178:181], v[232:235], v[26:29]
	v_mfma_f32_16x16x32_bf16 v[42:45], v[178:181], v[202:205], v[42:45]
	v_mfma_f32_16x16x32_bf16 v[34:37], v[186:189], v[202:205], v[34:37]
	v_mfma_f32_16x16x32_bf16 v[50:53], v[186:189], v[194:197], v[50:53]
	v_mfma_f32_16x16x32_bf16 v[58:61], v[178:181], v[194:197], v[58:61]
	v_mfma_f32_16x16x32_bf16 v[62:65], v[154:157], v[198:201], v[62:65]
	v_mfma_f32_16x16x32_bf16 v[54:57], v[174:177], v[198:201], v[54:57]
	v_mfma_f32_16x16x32_bf16 v[38:41], v[174:177], v[228:231], v[38:41]
	v_mfma_f32_16x16x32_bf16 v[46:49], v[154:157], v[228:231], v[46:49]
	v_mfma_f32_16x16x32_bf16 v[30:33], v[154:157], v[236:239], v[30:33]
	v_mfma_f32_16x16x32_bf16 v[22:25], v[174:177], v[236:239], v[22:25]
	v_mfma_f32_16x16x32_bf16 v[6:9], v[174:177], v[244:247], v[6:9]
	v_mfma_f32_16x16x32_bf16 v[14:17], v[154:157], v[244:247], v[14:17]
	v_mfma_f32_16x16x32_bf16 v[10:13], v[182:185], v[244:247], v[10:13]
	v_mfma_f32_16x16x32_bf16 v[2:5], v[190:193], v[244:247], v[2:5]
	v_mfma_f32_16x16x32_bf16 v[18:21], v[190:193], v[236:239], v[18:21]
	v_mfma_f32_16x16x32_bf16 v[26:29], v[182:185], v[236:239], v[26:29]
	v_mfma_f32_16x16x32_bf16 v[42:45], v[182:185], v[228:231], v[42:45]
	v_mfma_f32_16x16x32_bf16 v[34:37], v[190:193], v[228:231], v[34:37]
	v_mfma_f32_16x16x32_bf16 v[50:53], v[190:193], v[198:201], v[50:53]
	v_mfma_f32_16x16x32_bf16 v[58:61], v[182:185], v[198:201], v[58:61]
	s_barrier
	s_setprio 0
	s_add_i32 s94, s94, 2
	s_addk_i32 vcc_lo, 0x100
	s_addk_i32 vcc_hi, 0x100
	s_cmp_gt_u32 s94, 29
.LBB0_1880:
	v_add_u32_e32 v139, 0x10000, v136
	ds_read_b128 v[140:143], v139
	ds_read_b128 v[154:157], v139 offset:1024
	ds_read_b128 v[170:173], v139 offset:2048
	ds_read_b128 v[174:177], v139 offset:3072
	v_add_u32_e32 v139, 0x14000, v136
	ds_read_b128 v[178:181], v139
	ds_read_b128 v[182:185], v139 offset:1024
	ds_read_b128 v[186:189], v139 offset:2048
	ds_read_b128 v[190:193], v139 offset:3072
	s_add_i32 s42, vcc_lo, 0xfff80080
	s_cmp_eq_u32 s94, 28
	s_cselect_b32 s52, s8, s42
	s_cselect_b32 s96, s9, vcc_hi
	s_or_b32 s95, s52, 0x80
	s_mov_b32 m0, s72
	ds_read_b128 v[194:197], v137
	ds_read_b128 v[198:201], v137 offset:1024
	ds_read_b128 v[202:205], v137 offset:2048
	ds_read_b128 v[228:231], v137 offset:3072
	ds_read_b128 v[232:235], v137 offset:4096
	ds_read_b128 v[236:239], v137 offset:5120
	ds_read_b128 v[240:243], v137 offset:6144
	ds_read_b128 v[244:247], v137 offset:7168
	buffer_load_dwordx4 v132, s[60:63], vcc_lo offen lds
	s_mov_b32 m0, s47
	s_nop 0
	buffer_load_dwordx4 v134, s[60:63], vcc_lo offen lds
	s_waitcnt vmcnt(8)
	s_waitcnt lgkmcnt(0)
	s_setprio 1
	s_barrier
	v_mfma_f32_16x16x32_bf16 v[114:117], v[140:143], v[194:197], v[114:117]
	v_mfma_f32_16x16x32_bf16 v[110:113], v[170:173], v[194:197], v[110:113]
	v_mfma_f32_16x16x32_bf16 v[102:105], v[170:173], v[202:205], v[102:105]
	v_mfma_f32_16x16x32_bf16 v[106:109], v[140:143], v[202:205], v[106:109]
	v_mfma_f32_16x16x32_bf16 v[94:97], v[140:143], v[232:235], v[94:97]
	v_mfma_f32_16x16x32_bf16 v[86:89], v[170:173], v[232:235], v[86:89]
	v_mfma_f32_16x16x32_bf16 v[70:73], v[170:173], v[240:243], v[70:73]
	v_mfma_f32_16x16x32_bf16 v[78:81], v[140:143], v[240:243], v[78:81]
	v_mfma_f32_16x16x32_bf16 v[74:77], v[178:181], v[240:243], v[74:77]
	v_mfma_f32_16x16x32_bf16 v[66:69], v[186:189], v[240:243], v[66:69]
	v_mfma_f32_16x16x32_bf16 v[82:85], v[186:189], v[232:235], v[82:85]
	v_mfma_f32_16x16x32_bf16 v[90:93], v[178:181], v[232:235], v[90:93]
	v_mfma_f32_16x16x32_bf16 v[118:121], v[178:181], v[202:205], v[118:121]
	v_mfma_f32_16x16x32_bf16 v[98:101], v[186:189], v[202:205], v[98:101]
	v_mfma_f32_16x16x32_bf16 v[122:125], v[186:189], v[194:197], v[122:125]
	v_mfma_f32_16x16x32_bf16 v[126:129], v[178:181], v[194:197], v[126:129]
	v_mfma_f32_16x16x32_bf16 v[114:117], v[154:157], v[198:201], v[114:117]
	v_mfma_f32_16x16x32_bf16 v[110:113], v[174:177], v[198:201], v[110:113]
	v_mfma_f32_16x16x32_bf16 v[102:105], v[174:177], v[228:231], v[102:105]
	v_mfma_f32_16x16x32_bf16 v[106:109], v[154:157], v[228:231], v[106:109]
	v_mfma_f32_16x16x32_bf16 v[94:97], v[154:157], v[236:239], v[94:97]
	v_mfma_f32_16x16x32_bf16 v[86:89], v[174:177], v[236:239], v[86:89]
	v_mfma_f32_16x16x32_bf16 v[70:73], v[174:177], v[244:247], v[70:73]
	v_mfma_f32_16x16x32_bf16 v[78:81], v[154:157], v[244:247], v[78:81]
	v_mfma_f32_16x16x32_bf16 v[74:77], v[182:185], v[244:247], v[74:77]
	v_mfma_f32_16x16x32_bf16 v[66:69], v[190:193], v[244:247], v[66:69]
	v_mfma_f32_16x16x32_bf16 v[82:85], v[190:193], v[236:239], v[82:85]
	v_mfma_f32_16x16x32_bf16 v[90:93], v[182:185], v[236:239], v[90:93]
	v_mfma_f32_16x16x32_bf16 v[118:121], v[182:185], v[228:231], v[118:121]
	v_mfma_f32_16x16x32_bf16 v[98:101], v[190:193], v[228:231], v[98:101]
	v_mfma_f32_16x16x32_bf16 v[122:125], v[190:193], v[198:201], v[122:125]
	v_mfma_f32_16x16x32_bf16 v[126:129], v[182:185], v[198:201], v[126:129]
	s_barrier
	s_setprio 0
	s_mov_b32 m0, s13
	s_mov_b32 s42, s62
	s_mov_b32 s43, s63
	ds_read_b128 v[194:197], v137 offset:16384
	ds_read_b128 v[198:201], v137 offset:17408
	ds_read_b128 v[202:205], v137 offset:18432
	ds_read_b128 v[228:231], v137 offset:19456
	ds_read_b128 v[232:235], v137 offset:20480
	ds_read_b128 v[236:239], v137 offset:21504
	ds_read_b128 v[240:243], v137 offset:22528
	ds_read_b128 v[244:247], v137 offset:23552
	buffer_load_dwordx4 v133, s[40:43], s96 offen lds
	s_mov_b32 m0, s14
	s_add_i32 s53, s96, 0x80000
	buffer_load_dwordx4 v135, s[40:43], s96 offen lds
	s_mov_b32 m0, s15
	s_nop 0
	buffer_load_dwordx4 v133, s[40:43], s53 offen lds
	s_mov_b32 m0, s16
	s_nop 0
	buffer_load_dwordx4 v135, s[40:43], s53 offen lds
	s_mov_b32 m0, s2
	s_nop 0
	buffer_load_dwordx4 v132, s[60:63], s52 offen lds
	s_mov_b32 m0, s21
	s_nop 0
	buffer_load_dwordx4 v134, s[60:63], s52 offen lds
	s_waitcnt vmcnt(8)
	s_waitcnt lgkmcnt(0)
	s_setprio 1
	s_barrier
	v_mfma_f32_16x16x32_bf16 v[62:65], v[140:143], v[194:197], v[62:65]
	v_mfma_f32_16x16x32_bf16 v[54:57], v[170:173], v[194:197], v[54:57]
	v_mfma_f32_16x16x32_bf16 v[38:41], v[170:173], v[202:205], v[38:41]
	v_mfma_f32_16x16x32_bf16 v[46:49], v[140:143], v[202:205], v[46:49]
	v_mfma_f32_16x16x32_bf16 v[30:33], v[140:143], v[232:235], v[30:33]
	v_mfma_f32_16x16x32_bf16 v[22:25], v[170:173], v[232:235], v[22:25]
	v_mfma_f32_16x16x32_bf16 v[6:9], v[170:173], v[240:243], v[6:9]
	v_mfma_f32_16x16x32_bf16 v[14:17], v[140:143], v[240:243], v[14:17]
	v_mfma_f32_16x16x32_bf16 v[10:13], v[178:181], v[240:243], v[10:13]
	v_mfma_f32_16x16x32_bf16 v[2:5], v[186:189], v[240:243], v[2:5]
	v_mfma_f32_16x16x32_bf16 v[18:21], v[186:189], v[232:235], v[18:21]
	v_mfma_f32_16x16x32_bf16 v[26:29], v[178:181], v[232:235], v[26:29]
	v_mfma_f32_16x16x32_bf16 v[42:45], v[178:181], v[202:205], v[42:45]
	v_mfma_f32_16x16x32_bf16 v[34:37], v[186:189], v[202:205], v[34:37]
	v_mfma_f32_16x16x32_bf16 v[50:53], v[186:189], v[194:197], v[50:53]
	v_mfma_f32_16x16x32_bf16 v[58:61], v[178:181], v[194:197], v[58:61]
	v_mfma_f32_16x16x32_bf16 v[62:65], v[154:157], v[198:201], v[62:65]
	v_mfma_f32_16x16x32_bf16 v[54:57], v[174:177], v[198:201], v[54:57]
	v_mfma_f32_16x16x32_bf16 v[38:41], v[174:177], v[228:231], v[38:41]
	v_mfma_f32_16x16x32_bf16 v[46:49], v[154:157], v[228:231], v[46:49]
	v_mfma_f32_16x16x32_bf16 v[30:33], v[154:157], v[236:239], v[30:33]
	v_mfma_f32_16x16x32_bf16 v[22:25], v[174:177], v[236:239], v[22:25]
	v_mfma_f32_16x16x32_bf16 v[6:9], v[174:177], v[244:247], v[6:9]
	v_mfma_f32_16x16x32_bf16 v[14:17], v[154:157], v[244:247], v[14:17]
	v_mfma_f32_16x16x32_bf16 v[10:13], v[182:185], v[244:247], v[10:13]
	v_mfma_f32_16x16x32_bf16 v[2:5], v[190:193], v[244:247], v[2:5]
	v_mfma_f32_16x16x32_bf16 v[18:21], v[190:193], v[236:239], v[18:21]
	v_mfma_f32_16x16x32_bf16 v[26:29], v[182:185], v[236:239], v[26:29]
	v_mfma_f32_16x16x32_bf16 v[42:45], v[182:185], v[228:231], v[42:45]
	v_mfma_f32_16x16x32_bf16 v[34:37], v[190:193], v[228:231], v[34:37]
	v_mfma_f32_16x16x32_bf16 v[50:53], v[190:193], v[198:201], v[50:53]
	v_mfma_f32_16x16x32_bf16 v[58:61], v[182:185], v[198:201], v[58:61]
	s_barrier
	s_setprio 0
	v_add_u32_e32 v139, 0x18000, v136
	ds_read_b128 v[140:143], v139
	ds_read_b128 v[154:157], v139 offset:1024
	ds_read_b128 v[170:173], v139 offset:2048
	ds_read_b128 v[174:177], v139 offset:3072
	v_add_u32_e32 v139, 0x1c000, v136
	ds_read_b128 v[178:181], v139
	ds_read_b128 v[182:185], v139 offset:1024
	ds_read_b128 v[186:189], v139 offset:2048
	ds_read_b128 v[190:193], v139 offset:3072
	s_add_i32 s52, s52, 0x80000
	s_mov_b32 m0, s23
	ds_read_b128 v[194:197], v137 offset:32768
	ds_read_b128 v[198:201], v137 offset:33792
	ds_read_b128 v[202:205], v137 offset:34816
	ds_read_b128 v[228:231], v137 offset:35840
	ds_read_b128 v[232:235], v137 offset:36864
	ds_read_b128 v[236:239], v137 offset:37888
	ds_read_b128 v[240:243], v137 offset:38912
	ds_read_b128 v[244:247], v137 offset:39936
	buffer_load_dwordx4 v132, s[60:63], s52 offen lds
	s_mov_b32 m0, s24
	s_nop 0
	buffer_load_dwordx4 v134, s[60:63], s52 offen lds
	s_waitcnt vmcnt(8)
	s_waitcnt lgkmcnt(0)
	s_setprio 1
	s_barrier
	v_mfma_f32_16x16x32_bf16 v[114:117], v[140:143], v[194:197], v[114:117]
	v_mfma_f32_16x16x32_bf16 v[110:113], v[170:173], v[194:197], v[110:113]
	v_mfma_f32_16x16x32_bf16 v[102:105], v[170:173], v[202:205], v[102:105]
	v_mfma_f32_16x16x32_bf16 v[106:109], v[140:143], v[202:205], v[106:109]
	v_mfma_f32_16x16x32_bf16 v[94:97], v[140:143], v[232:235], v[94:97]
	v_mfma_f32_16x16x32_bf16 v[86:89], v[170:173], v[232:235], v[86:89]
	v_mfma_f32_16x16x32_bf16 v[70:73], v[170:173], v[240:243], v[70:73]
	v_mfma_f32_16x16x32_bf16 v[78:81], v[140:143], v[240:243], v[78:81]
	v_mfma_f32_16x16x32_bf16 v[74:77], v[178:181], v[240:243], v[74:77]
	v_mfma_f32_16x16x32_bf16 v[66:69], v[186:189], v[240:243], v[66:69]
	v_mfma_f32_16x16x32_bf16 v[82:85], v[186:189], v[232:235], v[82:85]
	v_mfma_f32_16x16x32_bf16 v[90:93], v[178:181], v[232:235], v[90:93]
	v_mfma_f32_16x16x32_bf16 v[118:121], v[178:181], v[202:205], v[118:121]
	v_mfma_f32_16x16x32_bf16 v[98:101], v[186:189], v[202:205], v[98:101]
	v_mfma_f32_16x16x32_bf16 v[122:125], v[186:189], v[194:197], v[122:125]
	v_mfma_f32_16x16x32_bf16 v[126:129], v[178:181], v[194:197], v[126:129]
	v_mfma_f32_16x16x32_bf16 v[114:117], v[154:157], v[198:201], v[114:117]
	v_mfma_f32_16x16x32_bf16 v[110:113], v[174:177], v[198:201], v[110:113]
	v_mfma_f32_16x16x32_bf16 v[102:105], v[174:177], v[228:231], v[102:105]
	v_mfma_f32_16x16x32_bf16 v[106:109], v[154:157], v[228:231], v[106:109]
	v_mfma_f32_16x16x32_bf16 v[94:97], v[154:157], v[236:239], v[94:97]
	v_mfma_f32_16x16x32_bf16 v[86:89], v[174:177], v[236:239], v[86:89]
	v_mfma_f32_16x16x32_bf16 v[70:73], v[174:177], v[244:247], v[70:73]
	v_mfma_f32_16x16x32_bf16 v[78:81], v[154:157], v[244:247], v[78:81]
	v_mfma_f32_16x16x32_bf16 v[74:77], v[182:185], v[244:247], v[74:77]
	v_mfma_f32_16x16x32_bf16 v[66:69], v[190:193], v[244:247], v[66:69]
	v_mfma_f32_16x16x32_bf16 v[82:85], v[190:193], v[236:239], v[82:85]
	v_mfma_f32_16x16x32_bf16 v[90:93], v[182:185], v[236:239], v[90:93]
	v_mfma_f32_16x16x32_bf16 v[118:121], v[182:185], v[228:231], v[118:121]
	v_mfma_f32_16x16x32_bf16 v[98:101], v[190:193], v[228:231], v[98:101]
	v_mfma_f32_16x16x32_bf16 v[122:125], v[190:193], v[198:201], v[122:125]
	v_mfma_f32_16x16x32_bf16 v[126:129], v[182:185], v[198:201], v[126:129]
	s_barrier
	s_setprio 0
	s_mov_b32 m0, s31
	s_or_b32 s52, s96, 0x80
	ds_read_b128 v[194:197], v137 offset:49152
	ds_read_b128 v[198:201], v137 offset:50176
	ds_read_b128 v[202:205], v137 offset:51200
	ds_read_b128 v[228:231], v137 offset:52224
	ds_read_b128 v[232:235], v137 offset:53248
	ds_read_b128 v[236:239], v137 offset:54272
	ds_read_b128 v[240:243], v137 offset:55296
	ds_read_b128 v[244:247], v137 offset:56320
	buffer_load_dwordx4 v133, s[40:43], s52 offen lds
	s_mov_b32 m0, s33
	s_add_i32 s96, s96, 0x80080
	buffer_load_dwordx4 v135, s[40:43], s52 offen lds
	s_mov_b32 m0, s36
	s_nop 0
	buffer_load_dwordx4 v133, s[40:43], s96 offen lds
	s_mov_b32 m0, s37
	s_nop 0
	buffer_load_dwordx4 v135, s[40:43], s96 offen lds
	s_mov_b32 m0, s34
	s_nop 0
	buffer_load_dwordx4 v132, s[60:63], s95 offen lds
	s_mov_b32 m0, s35
	s_nop 0
	buffer_load_dwordx4 v134, s[60:63], s95 offen lds
	s_waitcnt vmcnt(8)
	s_waitcnt lgkmcnt(0)
	s_setprio 1
	s_barrier
	v_mfma_f32_16x16x32_bf16 v[62:65], v[140:143], v[194:197], v[62:65]
	v_mfma_f32_16x16x32_bf16 v[54:57], v[170:173], v[194:197], v[54:57]
	v_mfma_f32_16x16x32_bf16 v[38:41], v[170:173], v[202:205], v[38:41]
	v_mfma_f32_16x16x32_bf16 v[46:49], v[140:143], v[202:205], v[46:49]
	v_mfma_f32_16x16x32_bf16 v[30:33], v[140:143], v[232:235], v[30:33]
	v_mfma_f32_16x16x32_bf16 v[22:25], v[170:173], v[232:235], v[22:25]
	v_mfma_f32_16x16x32_bf16 v[6:9], v[170:173], v[240:243], v[6:9]
	v_mfma_f32_16x16x32_bf16 v[14:17], v[140:143], v[240:243], v[14:17]
	v_mfma_f32_16x16x32_bf16 v[10:13], v[178:181], v[240:243], v[10:13]
	v_mfma_f32_16x16x32_bf16 v[2:5], v[186:189], v[240:243], v[2:5]
	v_mfma_f32_16x16x32_bf16 v[18:21], v[186:189], v[232:235], v[18:21]
	v_mfma_f32_16x16x32_bf16 v[26:29], v[178:181], v[232:235], v[26:29]
	v_mfma_f32_16x16x32_bf16 v[42:45], v[178:181], v[202:205], v[42:45]
	v_mfma_f32_16x16x32_bf16 v[34:37], v[186:189], v[202:205], v[34:37]
	v_mfma_f32_16x16x32_bf16 v[50:53], v[186:189], v[194:197], v[50:53]
	v_mfma_f32_16x16x32_bf16 v[58:61], v[178:181], v[194:197], v[58:61]
	v_mfma_f32_16x16x32_bf16 v[62:65], v[154:157], v[198:201], v[62:65]
	v_mfma_f32_16x16x32_bf16 v[54:57], v[174:177], v[198:201], v[54:57]
	v_mfma_f32_16x16x32_bf16 v[38:41], v[174:177], v[228:231], v[38:41]
	v_mfma_f32_16x16x32_bf16 v[46:49], v[154:157], v[228:231], v[46:49]
	v_mfma_f32_16x16x32_bf16 v[30:33], v[154:157], v[236:239], v[30:33]
	v_mfma_f32_16x16x32_bf16 v[22:25], v[174:177], v[236:239], v[22:25]
	v_mfma_f32_16x16x32_bf16 v[6:9], v[174:177], v[244:247], v[6:9]
	v_mfma_f32_16x16x32_bf16 v[14:17], v[154:157], v[244:247], v[14:17]
	v_mfma_f32_16x16x32_bf16 v[10:13], v[182:185], v[244:247], v[10:13]
	v_mfma_f32_16x16x32_bf16 v[2:5], v[190:193], v[244:247], v[2:5]
	v_mfma_f32_16x16x32_bf16 v[18:21], v[190:193], v[236:239], v[18:21]
	v_mfma_f32_16x16x32_bf16 v[26:29], v[182:185], v[236:239], v[26:29]
	v_mfma_f32_16x16x32_bf16 v[42:45], v[182:185], v[228:231], v[42:45]
	v_mfma_f32_16x16x32_bf16 v[34:37], v[190:193], v[228:231], v[34:37]
	v_mfma_f32_16x16x32_bf16 v[50:53], v[190:193], v[198:201], v[50:53]
	v_mfma_f32_16x16x32_bf16 v[58:61], v[182:185], v[198:201], v[58:61]
	s_barrier
	s_setprio 0
	s_add_i32 s94, s94, 2
	s_addk_i32 vcc_lo, 0x100
	s_addk_i32 vcc_hi, 0x100
	s_cmp_gt_u32 s94, 29
	s_cbranch_scc0 .LBB0_1880
	s_and_b64 vcc, exec, s[64:65]
	s_cbranch_vccz .LBB0_1883
	s_barrier

.LBB0_2155:
	s_mul_i32 s49, s48, 0x2c0000
	s_and_b64 s[8:9], s[42:43], exec
	s_mul_i32 s23, s15, 0x2c0000
	s_cselect_b32 s8, s49, s21
	s_cselect_b32 s9, s23, s13
	s_addk_i32 s13, 0x100
	s_add_i32 s21, s21, 0xc000
	s_mov_b32 s22, -2
	s_waitcnt lgkmcnt(0)
	v_add_u32_e32 v170, 0x10000, v140
	v_add_u32_e32 v186, 0x14000, v140
	ds_read_b128 v[132:135], v170
	ds_read_b128 v[142:145], v170 offset:1024
	ds_read_b128 v[154:157], v170 offset:2048
	ds_read_b128 v[170:173], v170 offset:3072
	ds_read_b128 v[174:177], v186
	ds_read_b128 v[178:181], v186 offset:1024
	ds_read_b128 v[182:185], v186 offset:2048
	ds_read_b128 v[186:189], v186 offset:3072
	s_add_i32 s26, s21, 0x4000
	s_cmpk_eq_i32 s22, 0x54
	s_cselect_b32 s52, s8, s26
	s_cselect_b32 s27, s9, s13
	s_or_b32 s26, s52, 0x8000
	s_mov_b32 m0, s84
	ds_read_b128 v[190:193], v141
	ds_read_b128 v[194:197], v141 offset:1024
	ds_read_b128 v[198:201], v141 offset:2048
	ds_read_b128 v[202:205], v141 offset:3072
	ds_read_b128 v[228:231], v141 offset:4096
	ds_read_b128 v[232:235], v141 offset:5120
	ds_read_b128 v[236:239], v141 offset:6144
	ds_read_b128 v[240:243], v141 offset:7168
	buffer_load_dwordx4 v136, s[60:63], s21 offen lds
	s_mov_b32 m0, s16
	s_nop 0
	buffer_load_dwordx4 v138, s[60:63], s21 offen lds
	s_waitcnt vmcnt(8)
	s_waitcnt lgkmcnt(0)
	s_setprio 1
	s_barrier
	v_mfma_f32_16x16x32_bf16 v[126:129], v[132:135], v[190:193], 0
	v_mfma_f32_16x16x32_bf16 v[106:109], v[154:157], v[190:193], 0
	v_mfma_f32_16x16x32_bf16 v[114:117], v[154:157], v[198:201], 0
	v_mfma_f32_16x16x32_bf16 v[118:121], v[132:135], v[198:201], 0
	v_mfma_f32_16x16x32_bf16 v[94:97], v[132:135], v[228:231], 0
	v_mfma_f32_16x16x32_bf16 v[90:93], v[154:157], v[228:231], 0
	v_mfma_f32_16x16x32_bf16 v[74:77], v[154:157], v[236:239], 0
	v_mfma_f32_16x16x32_bf16 v[78:81], v[132:135], v[236:239], 0
	v_mfma_f32_16x16x32_bf16 v[70:73], v[174:177], v[236:239], 0
	v_mfma_f32_16x16x32_bf16 v[66:69], v[182:185], v[236:239], 0
	v_mfma_f32_16x16x32_bf16 v[82:85], v[182:185], v[228:231], 0
	v_mfma_f32_16x16x32_bf16 v[86:89], v[174:177], v[228:231], 0
	v_mfma_f32_16x16x32_bf16 v[102:105], v[174:177], v[198:201], 0
	v_mfma_f32_16x16x32_bf16 v[98:101], v[182:185], v[198:201], 0
	v_mfma_f32_16x16x32_bf16 v[110:113], v[182:185], v[190:193], 0
	v_mfma_f32_16x16x32_bf16 v[122:125], v[174:177], v[190:193], 0
	v_mfma_f32_16x16x32_bf16 v[126:129], v[142:145], v[194:197], v[126:129]
	v_mfma_f32_16x16x32_bf16 v[106:109], v[170:173], v[194:197], v[106:109]
	v_mfma_f32_16x16x32_bf16 v[114:117], v[170:173], v[202:205], v[114:117]
	v_mfma_f32_16x16x32_bf16 v[118:121], v[142:145], v[202:205], v[118:121]
	v_mfma_f32_16x16x32_bf16 v[94:97], v[142:145], v[232:235], v[94:97]
	v_mfma_f32_16x16x32_bf16 v[90:93], v[170:173], v[232:235], v[90:93]
	v_mfma_f32_16x16x32_bf16 v[74:77], v[170:173], v[240:243], v[74:77]
	v_mfma_f32_16x16x32_bf16 v[78:81], v[142:145], v[240:243], v[78:81]
	v_mfma_f32_16x16x32_bf16 v[70:73], v[178:181], v[240:243], v[70:73]
	v_mfma_f32_16x16x32_bf16 v[66:69], v[186:189], v[240:243], v[66:69]
	v_mfma_f32_16x16x32_bf16 v[82:85], v[186:189], v[232:235], v[82:85]
	v_mfma_f32_16x16x32_bf16 v[86:89], v[178:181], v[232:235], v[86:89]
	v_mfma_f32_16x16x32_bf16 v[102:105], v[178:181], v[202:205], v[102:105]
	v_mfma_f32_16x16x32_bf16 v[98:101], v[186:189], v[202:205], v[98:101]
	v_mfma_f32_16x16x32_bf16 v[110:113], v[186:189], v[194:197], v[110:113]
	v_mfma_f32_16x16x32_bf16 v[122:125], v[178:181], v[194:197], v[122:125]
	s_barrier
	s_setprio 0
	s_mov_b32 m0, s18
	s_mov_b32 s46, s62
	s_mov_b32 s47, s63
	ds_read_b128 v[190:193], v141 offset:16384
	ds_read_b128 v[194:197], v141 offset:17408
	ds_read_b128 v[198:201], v141 offset:18432
	ds_read_b128 v[202:205], v141 offset:19456
	ds_read_b128 v[228:231], v141 offset:20480
	ds_read_b128 v[232:235], v141 offset:21504
	ds_read_b128 v[236:239], v141 offset:22528
	ds_read_b128 v[240:243], v141 offset:23552
	buffer_load_dwordx4 v137, s[44:47], s27 offen lds
	s_mov_b32 m0, s19
	s_add_i32 s53, s27, 0x160000
	buffer_load_dwordx4 v139, s[44:47], s27 offen lds
	s_mov_b32 m0, s24
	s_nop 0
	buffer_load_dwordx4 v137, s[44:47], s53 offen lds
	s_mov_b32 m0, s25
	s_nop 0
	buffer_load_dwordx4 v139, s[44:47], s53 offen lds
	s_mov_b32 m0, s14
	s_nop 0
	buffer_load_dwordx4 v136, s[60:63], s52 offen lds
	s_mov_b32 m0, s30
	s_nop 0
	buffer_load_dwordx4 v138, s[60:63], s52 offen lds
	s_waitcnt vmcnt(8)
	s_waitcnt lgkmcnt(0)
	s_setprio 1
	s_barrier
	v_mfma_f32_16x16x32_bf16 v[62:65], v[132:135], v[190:193], 0
	v_mfma_f32_16x16x32_bf16 v[58:61], v[154:157], v[190:193], 0
	v_mfma_f32_16x16x32_bf16 v[42:45], v[154:157], v[198:201], 0
	v_mfma_f32_16x16x32_bf16 v[46:49], v[132:135], v[198:201], 0
	v_mfma_f32_16x16x32_bf16 v[30:33], v[132:135], v[228:231], 0
	v_mfma_f32_16x16x32_bf16 v[26:29], v[154:157], v[228:231], 0
	v_mfma_f32_16x16x32_bf16 v[10:13], v[154:157], v[236:239], 0
	v_mfma_f32_16x16x32_bf16 v[14:17], v[132:135], v[236:239], 0
	v_mfma_f32_16x16x32_bf16 v[6:9], v[174:177], v[236:239], 0
	v_mfma_f32_16x16x32_bf16 v[2:5], v[182:185], v[236:239], 0
	v_mfma_f32_16x16x32_bf16 v[18:21], v[182:185], v[228:231], 0
	v_mfma_f32_16x16x32_bf16 v[22:25], v[174:177], v[228:231], 0
	v_mfma_f32_16x16x32_bf16 v[38:41], v[174:177], v[198:201], 0
	v_mfma_f32_16x16x32_bf16 v[34:37], v[182:185], v[198:201], 0
	v_mfma_f32_16x16x32_bf16 v[50:53], v[182:185], v[190:193], 0
	v_mfma_f32_16x16x32_bf16 v[54:57], v[174:177], v[190:193], 0
	v_mfma_f32_16x16x32_bf16 v[62:65], v[142:145], v[194:197], v[62:65]
	v_mfma_f32_16x16x32_bf16 v[58:61], v[170:173], v[194:197], v[58:61]
	v_mfma_f32_16x16x32_bf16 v[42:45], v[170:173], v[202:205], v[42:45]
	v_mfma_f32_16x16x32_bf16 v[46:49], v[142:145], v[202:205], v[46:49]
	v_mfma_f32_16x16x32_bf16 v[30:33], v[142:145], v[232:235], v[30:33]
	v_mfma_f32_16x16x32_bf16 v[26:29], v[170:173], v[232:235], v[26:29]
	v_mfma_f32_16x16x32_bf16 v[10:13], v[170:173], v[240:243], v[10:13]
	v_mfma_f32_16x16x32_bf16 v[14:17], v[142:145], v[240:243], v[14:17]
	v_mfma_f32_16x16x32_bf16 v[6:9], v[178:181], v[240:243], v[6:9]
	v_mfma_f32_16x16x32_bf16 v[2:5], v[186:189], v[240:243], v[2:5]
	v_mfma_f32_16x16x32_bf16 v[18:21], v[186:189], v[232:235], v[18:21]
	v_mfma_f32_16x16x32_bf16 v[22:25], v[178:181], v[232:235], v[22:25]
	v_mfma_f32_16x16x32_bf16 v[38:41], v[178:181], v[202:205], v[38:41]
	v_mfma_f32_16x16x32_bf16 v[34:37], v[186:189], v[202:205], v[34:37]
	v_mfma_f32_16x16x32_bf16 v[50:53], v[186:189], v[194:197], v[50:53]
	v_mfma_f32_16x16x32_bf16 v[54:57], v[178:181], v[194:197], v[54:57]
	s_barrier
	s_setprio 0
	v_add_u32_e32 v170, 0x18000, v140
	v_add_u32_e32 v186, 0x1c000, v140
	ds_read_b128 v[132:135], v170
	ds_read_b128 v[142:145], v170 offset:1024
	ds_read_b128 v[154:157], v170 offset:2048
	ds_read_b128 v[170:173], v170 offset:3072
	ds_read_b128 v[174:177], v186
	ds_read_b128 v[178:181], v186 offset:1024
	ds_read_b128 v[182:185], v186 offset:2048
	ds_read_b128 v[186:189], v186 offset:3072
	s_bitset1_b32 s52, 14
	s_mov_b32 m0, s31
	ds_read_b128 v[190:193], v141 offset:32768
	ds_read_b128 v[194:197], v141 offset:33792
	ds_read_b128 v[198:201], v141 offset:34816
	ds_read_b128 v[202:205], v141 offset:35840
	ds_read_b128 v[228:231], v141 offset:36864
	ds_read_b128 v[232:235], v141 offset:37888
	ds_read_b128 v[236:239], v141 offset:38912
	ds_read_b128 v[240:243], v141 offset:39936
	buffer_load_dwordx4 v136, s[60:63], s52 offen lds
	s_mov_b32 m0, s33
	s_nop 0
	buffer_load_dwordx4 v138, s[60:63], s52 offen lds
	s_waitcnt vmcnt(8)
	s_waitcnt lgkmcnt(0)
	s_setprio 1
	s_barrier
	v_mfma_f32_16x16x32_bf16 v[126:129], v[132:135], v[190:193], v[126:129]
	v_mfma_f32_16x16x32_bf16 v[106:109], v[154:157], v[190:193], v[106:109]
	v_mfma_f32_16x16x32_bf16 v[114:117], v[154:157], v[198:201], v[114:117]
	v_mfma_f32_16x16x32_bf16 v[118:121], v[132:135], v[198:201], v[118:121]
	v_mfma_f32_16x16x32_bf16 v[94:97], v[132:135], v[228:231], v[94:97]
	v_mfma_f32_16x16x32_bf16 v[90:93], v[154:157], v[228:231], v[90:93]
	v_mfma_f32_16x16x32_bf16 v[74:77], v[154:157], v[236:239], v[74:77]
	v_mfma_f32_16x16x32_bf16 v[78:81], v[132:135], v[236:239], v[78:81]
	v_mfma_f32_16x16x32_bf16 v[70:73], v[174:177], v[236:239], v[70:73]
	v_mfma_f32_16x16x32_bf16 v[66:69], v[182:185], v[236:239], v[66:69]
	v_mfma_f32_16x16x32_bf16 v[82:85], v[182:185], v[228:231], v[82:85]
	v_mfma_f32_16x16x32_bf16 v[86:89], v[174:177], v[228:231], v[86:89]
	v_mfma_f32_16x16x32_bf16 v[102:105], v[174:177], v[198:201], v[102:105]
	v_mfma_f32_16x16x32_bf16 v[98:101], v[182:185], v[198:201], v[98:101]
	v_mfma_f32_16x16x32_bf16 v[110:113], v[182:185], v[190:193], v[110:113]
	v_mfma_f32_16x16x32_bf16 v[122:125], v[174:177], v[190:193], v[122:125]
	v_mfma_f32_16x16x32_bf16 v[126:129], v[142:145], v[194:197], v[126:129]
	v_mfma_f32_16x16x32_bf16 v[106:109], v[170:173], v[194:197], v[106:109]
	v_mfma_f32_16x16x32_bf16 v[114:117], v[170:173], v[202:205], v[114:117]
	v_mfma_f32_16x16x32_bf16 v[118:121], v[142:145], v[202:205], v[118:121]
	v_mfma_f32_16x16x32_bf16 v[94:97], v[142:145], v[232:235], v[94:97]
	v_mfma_f32_16x16x32_bf16 v[90:93], v[170:173], v[232:235], v[90:93]
	v_mfma_f32_16x16x32_bf16 v[74:77], v[170:173], v[240:243], v[74:77]
	v_mfma_f32_16x16x32_bf16 v[78:81], v[142:145], v[240:243], v[78:81]
	v_mfma_f32_16x16x32_bf16 v[70:73], v[178:181], v[240:243], v[70:73]
	v_mfma_f32_16x16x32_bf16 v[66:69], v[186:189], v[240:243], v[66:69]
	v_mfma_f32_16x16x32_bf16 v[82:85], v[186:189], v[232:235], v[82:85]
	v_mfma_f32_16x16x32_bf16 v[86:89], v[178:181], v[232:235], v[86:89]
	v_mfma_f32_16x16x32_bf16 v[102:105], v[178:181], v[202:205], v[102:105]
	v_mfma_f32_16x16x32_bf16 v[98:101], v[186:189], v[202:205], v[98:101]
	v_mfma_f32_16x16x32_bf16 v[110:113], v[186:189], v[194:197], v[110:113]
	v_mfma_f32_16x16x32_bf16 v[122:125], v[178:181], v[194:197], v[122:125]
	s_barrier
	s_setprio 0
	s_mov_b32 m0, s68
	s_or_b32 s52, s27, 0x80
	ds_read_b128 v[190:193], v141 offset:49152
	ds_read_b128 v[194:197], v141 offset:50176
	ds_read_b128 v[198:201], v141 offset:51200
	ds_read_b128 v[202:205], v141 offset:52224
	ds_read_b128 v[228:231], v141 offset:53248
	ds_read_b128 v[232:235], v141 offset:54272
	ds_read_b128 v[236:239], v141 offset:55296
	ds_read_b128 v[240:243], v141 offset:56320
	buffer_load_dwordx4 v137, s[44:47], s52 offen lds
	s_mov_b32 m0, s69
	s_add_i32 s27, s27, 0x160080
	buffer_load_dwordx4 v139, s[44:47], s52 offen lds
	s_mov_b32 m0, s72
	s_nop 0
	buffer_load_dwordx4 v137, s[44:47], s27 offen lds
	s_mov_b32 m0, s73
	s_nop 0
	buffer_load_dwordx4 v139, s[44:47], s27 offen lds
	s_mov_b32 m0, s70
	s_nop 0
	buffer_load_dwordx4 v136, s[60:63], s26 offen lds
	s_mov_b32 m0, s71
	s_nop 0
	buffer_load_dwordx4 v138, s[60:63], s26 offen lds
	s_waitcnt vmcnt(8)
	s_waitcnt lgkmcnt(0)
	s_setprio 1
	s_barrier
	v_mfma_f32_16x16x32_bf16 v[62:65], v[132:135], v[190:193], v[62:65]
	v_mfma_f32_16x16x32_bf16 v[58:61], v[154:157], v[190:193], v[58:61]
	v_mfma_f32_16x16x32_bf16 v[42:45], v[154:157], v[198:201], v[42:45]
	v_mfma_f32_16x16x32_bf16 v[46:49], v[132:135], v[198:201], v[46:49]
	v_mfma_f32_16x16x32_bf16 v[30:33], v[132:135], v[228:231], v[30:33]
	v_mfma_f32_16x16x32_bf16 v[26:29], v[154:157], v[228:231], v[26:29]
	v_mfma_f32_16x16x32_bf16 v[10:13], v[154:157], v[236:239], v[10:13]
	v_mfma_f32_16x16x32_bf16 v[14:17], v[132:135], v[236:239], v[14:17]
	v_mfma_f32_16x16x32_bf16 v[6:9], v[174:177], v[236:239], v[6:9]
	v_mfma_f32_16x16x32_bf16 v[2:5], v[182:185], v[236:239], v[2:5]
	v_mfma_f32_16x16x32_bf16 v[18:21], v[182:185], v[228:231], v[18:21]
	v_mfma_f32_16x16x32_bf16 v[22:25], v[174:177], v[228:231], v[22:25]
	v_mfma_f32_16x16x32_bf16 v[38:41], v[174:177], v[198:201], v[38:41]
	v_mfma_f32_16x16x32_bf16 v[34:37], v[182:185], v[198:201], v[34:37]
	v_mfma_f32_16x16x32_bf16 v[50:53], v[182:185], v[190:193], v[50:53]
	v_mfma_f32_16x16x32_bf16 v[54:57], v[174:177], v[190:193], v[54:57]
	v_mfma_f32_16x16x32_bf16 v[62:65], v[142:145], v[194:197], v[62:65]
	v_mfma_f32_16x16x32_bf16 v[58:61], v[170:173], v[194:197], v[58:61]
	v_mfma_f32_16x16x32_bf16 v[42:45], v[170:173], v[202:205], v[42:45]
	v_mfma_f32_16x16x32_bf16 v[46:49], v[142:145], v[202:205], v[46:49]
	v_mfma_f32_16x16x32_bf16 v[30:33], v[142:145], v[232:235], v[30:33]
	v_mfma_f32_16x16x32_bf16 v[26:29], v[170:173], v[232:235], v[26:29]
	v_mfma_f32_16x16x32_bf16 v[10:13], v[170:173], v[240:243], v[10:13]
	v_mfma_f32_16x16x32_bf16 v[14:17], v[142:145], v[240:243], v[14:17]
	v_mfma_f32_16x16x32_bf16 v[6:9], v[178:181], v[240:243], v[6:9]
	v_mfma_f32_16x16x32_bf16 v[2:5], v[186:189], v[240:243], v[2:5]
	v_mfma_f32_16x16x32_bf16 v[18:21], v[186:189], v[232:235], v[18:21]
	v_mfma_f32_16x16x32_bf16 v[22:25], v[178:181], v[232:235], v[22:25]
	v_mfma_f32_16x16x32_bf16 v[38:41], v[178:181], v[202:205], v[38:41]
	v_mfma_f32_16x16x32_bf16 v[34:37], v[186:189], v[202:205], v[34:37]
	v_mfma_f32_16x16x32_bf16 v[50:53], v[186:189], v[194:197], v[50:53]
	v_mfma_f32_16x16x32_bf16 v[54:57], v[178:181], v[194:197], v[54:57]
	s_barrier
	s_setprio 0
	s_addk_i32 s13, 0x100
	s_add_i32 s22, s22, 2
	s_add_i32 s21, s21, 0x10000
	s_cmpk_gt_u32 s22, 0x55
.LBB0_2156:
	v_add_u32_e32 v170, 0x10000, v140
	v_add_u32_e32 v186, 0x14000, v140
	ds_read_b128 v[132:135], v170
	ds_read_b128 v[142:145], v170 offset:1024
	ds_read_b128 v[154:157], v170 offset:2048
	ds_read_b128 v[170:173], v170 offset:3072
	ds_read_b128 v[174:177], v186
	ds_read_b128 v[178:181], v186 offset:1024
	ds_read_b128 v[182:185], v186 offset:2048
	ds_read_b128 v[186:189], v186 offset:3072
	s_add_i32 s26, s21, 0x4000
	s_cmpk_eq_i32 s22, 0x54
	s_cselect_b32 s52, s8, s26
	s_cselect_b32 s27, s9, s13
	s_or_b32 s26, s52, 0x8000
	s_mov_b32 m0, s84
	ds_read_b128 v[190:193], v141
	ds_read_b128 v[194:197], v141 offset:1024
	ds_read_b128 v[198:201], v141 offset:2048
	ds_read_b128 v[202:205], v141 offset:3072
	ds_read_b128 v[228:231], v141 offset:4096
	ds_read_b128 v[232:235], v141 offset:5120
	ds_read_b128 v[236:239], v141 offset:6144
	ds_read_b128 v[240:243], v141 offset:7168
	buffer_load_dwordx4 v136, s[60:63], s21 offen lds
	s_mov_b32 m0, s16
	s_nop 0
	buffer_load_dwordx4 v138, s[60:63], s21 offen lds
	s_waitcnt vmcnt(8)
	s_waitcnt lgkmcnt(0)
	s_setprio 1
	s_barrier
	v_mfma_f32_16x16x32_bf16 v[126:129], v[132:135], v[190:193], v[126:129]
	v_mfma_f32_16x16x32_bf16 v[106:109], v[154:157], v[190:193], v[106:109]
	v_mfma_f32_16x16x32_bf16 v[114:117], v[154:157], v[198:201], v[114:117]
	v_mfma_f32_16x16x32_bf16 v[118:121], v[132:135], v[198:201], v[118:121]
	v_mfma_f32_16x16x32_bf16 v[94:97], v[132:135], v[228:231], v[94:97]
	v_mfma_f32_16x16x32_bf16 v[90:93], v[154:157], v[228:231], v[90:93]
	v_mfma_f32_16x16x32_bf16 v[74:77], v[154:157], v[236:239], v[74:77]
	v_mfma_f32_16x16x32_bf16 v[78:81], v[132:135], v[236:239], v[78:81]
	v_mfma_f32_16x16x32_bf16 v[70:73], v[174:177], v[236:239], v[70:73]
	v_mfma_f32_16x16x32_bf16 v[66:69], v[182:185], v[236:239], v[66:69]
	v_mfma_f32_16x16x32_bf16 v[82:85], v[182:185], v[228:231], v[82:85]
	v_mfma_f32_16x16x32_bf16 v[86:89], v[174:177], v[228:231], v[86:89]
	v_mfma_f32_16x16x32_bf16 v[102:105], v[174:177], v[198:201], v[102:105]
	v_mfma_f32_16x16x32_bf16 v[98:101], v[182:185], v[198:201], v[98:101]
	v_mfma_f32_16x16x32_bf16 v[110:113], v[182:185], v[190:193], v[110:113]
	v_mfma_f32_16x16x32_bf16 v[122:125], v[174:177], v[190:193], v[122:125]
	v_mfma_f32_16x16x32_bf16 v[126:129], v[142:145], v[194:197], v[126:129]
	v_mfma_f32_16x16x32_bf16 v[106:109], v[170:173], v[194:197], v[106:109]
	v_mfma_f32_16x16x32_bf16 v[114:117], v[170:173], v[202:205], v[114:117]
	v_mfma_f32_16x16x32_bf16 v[118:121], v[142:145], v[202:205], v[118:121]
	v_mfma_f32_16x16x32_bf16 v[94:97], v[142:145], v[232:235], v[94:97]
	v_mfma_f32_16x16x32_bf16 v[90:93], v[170:173], v[232:235], v[90:93]
	v_mfma_f32_16x16x32_bf16 v[74:77], v[170:173], v[240:243], v[74:77]
	v_mfma_f32_16x16x32_bf16 v[78:81], v[142:145], v[240:243], v[78:81]
	v_mfma_f32_16x16x32_bf16 v[70:73], v[178:181], v[240:243], v[70:73]
	v_mfma_f32_16x16x32_bf16 v[66:69], v[186:189], v[240:243], v[66:69]
	v_mfma_f32_16x16x32_bf16 v[82:85], v[186:189], v[232:235], v[82:85]
	v_mfma_f32_16x16x32_bf16 v[86:89], v[178:181], v[232:235], v[86:89]
	v_mfma_f32_16x16x32_bf16 v[102:105], v[178:181], v[202:205], v[102:105]
	v_mfma_f32_16x16x32_bf16 v[98:101], v[186:189], v[202:205], v[98:101]
	v_mfma_f32_16x16x32_bf16 v[110:113], v[186:189], v[194:197], v[110:113]
	v_mfma_f32_16x16x32_bf16 v[122:125], v[178:181], v[194:197], v[122:125]
	s_barrier
	s_setprio 0
	s_mov_b32 m0, s18
	s_mov_b32 s46, s62
	s_mov_b32 s47, s63
	ds_read_b128 v[190:193], v141 offset:16384
	ds_read_b128 v[194:197], v141 offset:17408
	ds_read_b128 v[198:201], v141 offset:18432
	ds_read_b128 v[202:205], v141 offset:19456
	ds_read_b128 v[228:231], v141 offset:20480
	ds_read_b128 v[232:235], v141 offset:21504
	ds_read_b128 v[236:239], v141 offset:22528
	ds_read_b128 v[240:243], v141 offset:23552
	buffer_load_dwordx4 v137, s[44:47], s27 offen lds
	s_mov_b32 m0, s19
	s_add_i32 s53, s27, 0x160000
	buffer_load_dwordx4 v139, s[44:47], s27 offen lds
	s_mov_b32 m0, s24
	s_nop 0
	buffer_load_dwordx4 v137, s[44:47], s53 offen lds
	s_mov_b32 m0, s25
	s_nop 0
	buffer_load_dwordx4 v139, s[44:47], s53 offen lds
	s_mov_b32 m0, s14
	s_nop 0
	buffer_load_dwordx4 v136, s[60:63], s52 offen lds
	s_mov_b32 m0, s30
	s_nop 0
	buffer_load_dwordx4 v138, s[60:63], s52 offen lds
	s_waitcnt vmcnt(8)
	s_waitcnt lgkmcnt(0)
	s_setprio 1
	s_barrier
	v_mfma_f32_16x16x32_bf16 v[62:65], v[132:135], v[190:193], v[62:65]
	v_mfma_f32_16x16x32_bf16 v[58:61], v[154:157], v[190:193], v[58:61]
	v_mfma_f32_16x16x32_bf16 v[42:45], v[154:157], v[198:201], v[42:45]
	v_mfma_f32_16x16x32_bf16 v[46:49], v[132:135], v[198:201], v[46:49]
	v_mfma_f32_16x16x32_bf16 v[30:33], v[132:135], v[228:231], v[30:33]
	v_mfma_f32_16x16x32_bf16 v[26:29], v[154:157], v[228:231], v[26:29]
	v_mfma_f32_16x16x32_bf16 v[10:13], v[154:157], v[236:239], v[10:13]
	v_mfma_f32_16x16x32_bf16 v[14:17], v[132:135], v[236:239], v[14:17]
	v_mfma_f32_16x16x32_bf16 v[6:9], v[174:177], v[236:239], v[6:9]
	v_mfma_f32_16x16x32_bf16 v[2:5], v[182:185], v[236:239], v[2:5]
	v_mfma_f32_16x16x32_bf16 v[18:21], v[182:185], v[228:231], v[18:21]
	v_mfma_f32_16x16x32_bf16 v[22:25], v[174:177], v[228:231], v[22:25]
	v_mfma_f32_16x16x32_bf16 v[38:41], v[174:177], v[198:201], v[38:41]
	v_mfma_f32_16x16x32_bf16 v[34:37], v[182:185], v[198:201], v[34:37]
	v_mfma_f32_16x16x32_bf16 v[50:53], v[182:185], v[190:193], v[50:53]
	v_mfma_f32_16x16x32_bf16 v[54:57], v[174:177], v[190:193], v[54:57]
	v_mfma_f32_16x16x32_bf16 v[62:65], v[142:145], v[194:197], v[62:65]
	v_mfma_f32_16x16x32_bf16 v[58:61], v[170:173], v[194:197], v[58:61]
	v_mfma_f32_16x16x32_bf16 v[42:45], v[170:173], v[202:205], v[42:45]
	v_mfma_f32_16x16x32_bf16 v[46:49], v[142:145], v[202:205], v[46:49]
	v_mfma_f32_16x16x32_bf16 v[30:33], v[142:145], v[232:235], v[30:33]
	v_mfma_f32_16x16x32_bf16 v[26:29], v[170:173], v[232:235], v[26:29]
	v_mfma_f32_16x16x32_bf16 v[10:13], v[170:173], v[240:243], v[10:13]
	v_mfma_f32_16x16x32_bf16 v[14:17], v[142:145], v[240:243], v[14:17]
	v_mfma_f32_16x16x32_bf16 v[6:9], v[178:181], v[240:243], v[6:9]
	v_mfma_f32_16x16x32_bf16 v[2:5], v[186:189], v[240:243], v[2:5]
	v_mfma_f32_16x16x32_bf16 v[18:21], v[186:189], v[232:235], v[18:21]
	v_mfma_f32_16x16x32_bf16 v[22:25], v[178:181], v[232:235], v[22:25]
	v_mfma_f32_16x16x32_bf16 v[38:41], v[178:181], v[202:205], v[38:41]
	v_mfma_f32_16x16x32_bf16 v[34:37], v[186:189], v[202:205], v[34:37]
	v_mfma_f32_16x16x32_bf16 v[50:53], v[186:189], v[194:197], v[50:53]
	v_mfma_f32_16x16x32_bf16 v[54:57], v[178:181], v[194:197], v[54:57]
	s_barrier
	s_setprio 0
	v_add_u32_e32 v170, 0x18000, v140
	v_add_u32_e32 v186, 0x1c000, v140
	ds_read_b128 v[132:135], v170
	ds_read_b128 v[142:145], v170 offset:1024
	ds_read_b128 v[154:157], v170 offset:2048
	ds_read_b128 v[170:173], v170 offset:3072
	ds_read_b128 v[174:177], v186
	ds_read_b128 v[178:181], v186 offset:1024
	ds_read_b128 v[182:185], v186 offset:2048
	ds_read_b128 v[186:189], v186 offset:3072
	s_bitset1_b32 s52, 14
	s_mov_b32 m0, s31
	ds_read_b128 v[190:193], v141 offset:32768
	ds_read_b128 v[194:197], v141 offset:33792
	ds_read_b128 v[198:201], v141 offset:34816
	ds_read_b128 v[202:205], v141 offset:35840
	ds_read_b128 v[228:231], v141 offset:36864
	ds_read_b128 v[232:235], v141 offset:37888
	ds_read_b128 v[236:239], v141 offset:38912
	ds_read_b128 v[240:243], v141 offset:39936
	buffer_load_dwordx4 v136, s[60:63], s52 offen lds
	s_mov_b32 m0, s33
	s_nop 0
	buffer_load_dwordx4 v138, s[60:63], s52 offen lds
	s_waitcnt vmcnt(8)
	s_waitcnt lgkmcnt(0)
	s_setprio 1
	s_barrier
	v_mfma_f32_16x16x32_bf16 v[126:129], v[132:135], v[190:193], v[126:129]
	v_mfma_f32_16x16x32_bf16 v[106:109], v[154:157], v[190:193], v[106:109]
	v_mfma_f32_16x16x32_bf16 v[114:117], v[154:157], v[198:201], v[114:117]
	v_mfma_f32_16x16x32_bf16 v[118:121], v[132:135], v[198:201], v[118:121]
	v_mfma_f32_16x16x32_bf16 v[94:97], v[132:135], v[228:231], v[94:97]
	v_mfma_f32_16x16x32_bf16 v[90:93], v[154:157], v[228:231], v[90:93]
	v_mfma_f32_16x16x32_bf16 v[74:77], v[154:157], v[236:239], v[74:77]
	v_mfma_f32_16x16x32_bf16 v[78:81], v[132:135], v[236:239], v[78:81]
	v_mfma_f32_16x16x32_bf16 v[70:73], v[174:177], v[236:239], v[70:73]
	v_mfma_f32_16x16x32_bf16 v[66:69], v[182:185], v[236:239], v[66:69]
	v_mfma_f32_16x16x32_bf16 v[82:85], v[182:185], v[228:231], v[82:85]
	v_mfma_f32_16x16x32_bf16 v[86:89], v[174:177], v[228:231], v[86:89]
	v_mfma_f32_16x16x32_bf16 v[102:105], v[174:177], v[198:201], v[102:105]
	v_mfma_f32_16x16x32_bf16 v[98:101], v[182:185], v[198:201], v[98:101]
	v_mfma_f32_16x16x32_bf16 v[110:113], v[182:185], v[190:193], v[110:113]
	v_mfma_f32_16x16x32_bf16 v[122:125], v[174:177], v[190:193], v[122:125]
	v_mfma_f32_16x16x32_bf16 v[126:129], v[142:145], v[194:197], v[126:129]
	v_mfma_f32_16x16x32_bf16 v[106:109], v[170:173], v[194:197], v[106:109]
	v_mfma_f32_16x16x32_bf16 v[114:117], v[170:173], v[202:205], v[114:117]
	v_mfma_f32_16x16x32_bf16 v[118:121], v[142:145], v[202:205], v[118:121]
	v_mfma_f32_16x16x32_bf16 v[94:97], v[142:145], v[232:235], v[94:97]
	v_mfma_f32_16x16x32_bf16 v[90:93], v[170:173], v[232:235], v[90:93]
	v_mfma_f32_16x16x32_bf16 v[74:77], v[170:173], v[240:243], v[74:77]
	v_mfma_f32_16x16x32_bf16 v[78:81], v[142:145], v[240:243], v[78:81]
	v_mfma_f32_16x16x32_bf16 v[70:73], v[178:181], v[240:243], v[70:73]
	v_mfma_f32_16x16x32_bf16 v[66:69], v[186:189], v[240:243], v[66:69]
	v_mfma_f32_16x16x32_bf16 v[82:85], v[186:189], v[232:235], v[82:85]
	v_mfma_f32_16x16x32_bf16 v[86:89], v[178:181], v[232:235], v[86:89]
	v_mfma_f32_16x16x32_bf16 v[102:105], v[178:181], v[202:205], v[102:105]
	v_mfma_f32_16x16x32_bf16 v[98:101], v[186:189], v[202:205], v[98:101]
	v_mfma_f32_16x16x32_bf16 v[110:113], v[186:189], v[194:197], v[110:113]
	v_mfma_f32_16x16x32_bf16 v[122:125], v[178:181], v[194:197], v[122:125]
	s_barrier
	s_setprio 0
	s_mov_b32 m0, s68
	s_or_b32 s52, s27, 0x80
	ds_read_b128 v[190:193], v141 offset:49152
	ds_read_b128 v[194:197], v141 offset:50176
	ds_read_b128 v[198:201], v141 offset:51200
	ds_read_b128 v[202:205], v141 offset:52224
	ds_read_b128 v[228:231], v141 offset:53248
	ds_read_b128 v[232:235], v141 offset:54272
	ds_read_b128 v[236:239], v141 offset:55296
	ds_read_b128 v[240:243], v141 offset:56320
	buffer_load_dwordx4 v137, s[44:47], s52 offen lds
	s_mov_b32 m0, s69
	s_add_i32 s27, s27, 0x160080
	buffer_load_dwordx4 v139, s[44:47], s52 offen lds
	s_mov_b32 m0, s72
	s_nop 0
	buffer_load_dwordx4 v137, s[44:47], s27 offen lds
	s_mov_b32 m0, s73
	s_nop 0
	buffer_load_dwordx4 v139, s[44:47], s27 offen lds
	s_mov_b32 m0, s70
	s_nop 0
	buffer_load_dwordx4 v136, s[60:63], s26 offen lds
	s_mov_b32 m0, s71
	s_nop 0
	buffer_load_dwordx4 v138, s[60:63], s26 offen lds
	s_waitcnt vmcnt(8)
	s_waitcnt lgkmcnt(0)
	s_setprio 1
	s_barrier
	v_mfma_f32_16x16x32_bf16 v[62:65], v[132:135], v[190:193], v[62:65]
	v_mfma_f32_16x16x32_bf16 v[58:61], v[154:157], v[190:193], v[58:61]
	v_mfma_f32_16x16x32_bf16 v[42:45], v[154:157], v[198:201], v[42:45]
	v_mfma_f32_16x16x32_bf16 v[46:49], v[132:135], v[198:201], v[46:49]
	v_mfma_f32_16x16x32_bf16 v[30:33], v[132:135], v[228:231], v[30:33]
	v_mfma_f32_16x16x32_bf16 v[26:29], v[154:157], v[228:231], v[26:29]
	v_mfma_f32_16x16x32_bf16 v[10:13], v[154:157], v[236:239], v[10:13]
	v_mfma_f32_16x16x32_bf16 v[14:17], v[132:135], v[236:239], v[14:17]
	v_mfma_f32_16x16x32_bf16 v[6:9], v[174:177], v[236:239], v[6:9]
	v_mfma_f32_16x16x32_bf16 v[2:5], v[182:185], v[236:239], v[2:5]
	v_mfma_f32_16x16x32_bf16 v[18:21], v[182:185], v[228:231], v[18:21]
	v_mfma_f32_16x16x32_bf16 v[22:25], v[174:177], v[228:231], v[22:25]
	v_mfma_f32_16x16x32_bf16 v[38:41], v[174:177], v[198:201], v[38:41]
	v_mfma_f32_16x16x32_bf16 v[34:37], v[182:185], v[198:201], v[34:37]
	v_mfma_f32_16x16x32_bf16 v[50:53], v[182:185], v[190:193], v[50:53]
	v_mfma_f32_16x16x32_bf16 v[54:57], v[174:177], v[190:193], v[54:57]
	v_mfma_f32_16x16x32_bf16 v[62:65], v[142:145], v[194:197], v[62:65]
	v_mfma_f32_16x16x32_bf16 v[58:61], v[170:173], v[194:197], v[58:61]
	v_mfma_f32_16x16x32_bf16 v[42:45], v[170:173], v[202:205], v[42:45]
	v_mfma_f32_16x16x32_bf16 v[46:49], v[142:145], v[202:205], v[46:49]
	v_mfma_f32_16x16x32_bf16 v[30:33], v[142:145], v[232:235], v[30:33]
	v_mfma_f32_16x16x32_bf16 v[26:29], v[170:173], v[232:235], v[26:29]
	v_mfma_f32_16x16x32_bf16 v[10:13], v[170:173], v[240:243], v[10:13]
	v_mfma_f32_16x16x32_bf16 v[14:17], v[142:145], v[240:243], v[14:17]
	v_mfma_f32_16x16x32_bf16 v[6:9], v[178:181], v[240:243], v[6:9]
	v_mfma_f32_16x16x32_bf16 v[2:5], v[186:189], v[240:243], v[2:5]
	v_mfma_f32_16x16x32_bf16 v[18:21], v[186:189], v[232:235], v[18:21]
	v_mfma_f32_16x16x32_bf16 v[22:25], v[178:181], v[232:235], v[22:25]
	v_mfma_f32_16x16x32_bf16 v[38:41], v[178:181], v[202:205], v[38:41]
	v_mfma_f32_16x16x32_bf16 v[34:37], v[186:189], v[202:205], v[34:37]
	v_mfma_f32_16x16x32_bf16 v[50:53], v[186:189], v[194:197], v[50:53]
	v_mfma_f32_16x16x32_bf16 v[54:57], v[178:181], v[194:197], v[54:57]
	s_barrier
	s_setprio 0
	s_addk_i32 s13, 0x100
	s_add_i32 s22, s22, 2
	s_add_i32 s21, s21, 0x10000
	s_cmpk_gt_u32 s22, 0x55
	s_cbranch_scc0 .LBB0_2156
	s_and_b64 vcc, exec, s[66:67]
	s_cbranch_vccz .LBB0_2159
	s_barrier

.LBB0_2173:
	v_mov_b32_e32 v125, 0
	s_mul_i32 s69, s68, s12
	s_mul_i32 s70, s67, s12
	s_andn2_b64 vcc, exec, s[34:35]
	v_mov_b32_e32 v124, v125
	v_mov_b32_e32 v123, v125
	v_mov_b32_e32 v122, v125
	v_mov_b32_e32 v129, v125
	v_mov_b32_e32 v128, v125
	v_mov_b32_e32 v127, v125
	v_mov_b32_e32 v126, v125
	v_mov_b32_e32 v113, v125
	v_mov_b32_e32 v112, v125
	v_mov_b32_e32 v111, v125
	v_mov_b32_e32 v110, v125
	v_mov_b32_e32 v109, v125
	v_mov_b32_e32 v108, v125
	v_mov_b32_e32 v107, v125
	v_mov_b32_e32 v106, v125
	v_mov_b32_e32 v97, v125
	v_mov_b32_e32 v96, v125
	v_mov_b32_e32 v95, v125
	v_mov_b32_e32 v94, v125
	v_mov_b32_e32 v93, v125
	v_mov_b32_e32 v92, v125
	v_mov_b32_e32 v91, v125
	v_mov_b32_e32 v90, v125
	v_mov_b32_e32 v81, v125
	v_mov_b32_e32 v80, v125
	v_mov_b32_e32 v79, v125
	v_mov_b32_e32 v78, v125
	v_mov_b32_e32 v77, v125
	v_mov_b32_e32 v76, v125
	v_mov_b32_e32 v75, v125
	v_mov_b32_e32 v74, v125
	v_mov_b32_e32 v121, v125
	v_mov_b32_e32 v120, v125
	v_mov_b32_e32 v119, v125
	v_mov_b32_e32 v118, v125
	v_mov_b32_e32 v117, v125
	v_mov_b32_e32 v116, v125
	v_mov_b32_e32 v115, v125
	v_mov_b32_e32 v114, v125
	v_mov_b32_e32 v105, v125
	v_mov_b32_e32 v104, v125
	v_mov_b32_e32 v103, v125
	v_mov_b32_e32 v102, v125
	v_mov_b32_e32 v101, v125
	v_mov_b32_e32 v100, v125
	v_mov_b32_e32 v99, v125
	v_mov_b32_e32 v98, v125
	v_mov_b32_e32 v89, v125
	v_mov_b32_e32 v88, v125
	v_mov_b32_e32 v87, v125
	v_mov_b32_e32 v86, v125
	v_mov_b32_e32 v85, v125
	v_mov_b32_e32 v84, v125
	v_mov_b32_e32 v83, v125
	v_mov_b32_e32 v82, v125
	v_mov_b32_e32 v73, v125
	v_mov_b32_e32 v72, v125
	v_mov_b32_e32 v71, v125
	v_mov_b32_e32 v70, v125
	v_mov_b32_e32 v69, v125
	v_mov_b32_e32 v68, v125
	v_mov_b32_e32 v67, v125
	v_mov_b32_e32 v66, v125
	v_mov_b32_e32 v65, v125
	v_mov_b32_e32 v64, v125
	v_mov_b32_e32 v63, v125
	v_mov_b32_e32 v62, v125
	v_mov_b32_e32 v61, v125
	v_mov_b32_e32 v60, v125
	v_mov_b32_e32 v59, v125
	v_mov_b32_e32 v58, v125
	v_mov_b32_e32 v49, v125
	v_mov_b32_e32 v48, v125
	v_mov_b32_e32 v47, v125
	v_mov_b32_e32 v46, v125
	v_mov_b32_e32 v45, v125
	v_mov_b32_e32 v44, v125
	v_mov_b32_e32 v43, v125
	v_mov_b32_e32 v42, v125
	v_mov_b32_e32 v33, v125
	v_mov_b32_e32 v32, v125
	v_mov_b32_e32 v31, v125
	v_mov_b32_e32 v30, v125
	v_mov_b32_e32 v29, v125
	v_mov_b32_e32 v28, v125
	v_mov_b32_e32 v27, v125
	v_mov_b32_e32 v26, v125
	v_mov_b32_e32 v17, v125
	v_mov_b32_e32 v16, v125
	v_mov_b32_e32 v15, v125
	v_mov_b32_e32 v14, v125
	v_mov_b32_e32 v13, v125
	v_mov_b32_e32 v12, v125
	v_mov_b32_e32 v11, v125
	v_mov_b32_e32 v10, v125
	v_mov_b32_e32 v57, v125
	v_mov_b32_e32 v56, v125
	v_mov_b32_e32 v55, v125
	v_mov_b32_e32 v54, v125
	v_mov_b32_e32 v53, v125
	v_mov_b32_e32 v52, v125
	v_mov_b32_e32 v51, v125
	v_mov_b32_e32 v50, v125
	v_mov_b32_e32 v41, v125
	v_mov_b32_e32 v40, v125
	v_mov_b32_e32 v39, v125
	v_mov_b32_e32 v38, v125
	v_mov_b32_e32 v37, v125
	v_mov_b32_e32 v36, v125
	v_mov_b32_e32 v35, v125
	v_mov_b32_e32 v34, v125
	v_mov_b32_e32 v25, v125
	v_mov_b32_e32 v24, v125
	v_mov_b32_e32 v23, v125
	v_mov_b32_e32 v22, v125
	v_mov_b32_e32 v21, v125
	v_mov_b32_e32 v20, v125
	v_mov_b32_e32 v19, v125
	v_mov_b32_e32 v18, v125
	v_mov_b32_e32 v9, v125
	v_mov_b32_e32 v8, v125
	v_mov_b32_e32 v7, v125
	v_mov_b32_e32 v6, v125
	v_mov_b32_e32 v5, v125
	v_mov_b32_e32 v4, v125
	v_mov_b32_e32 v3, v125
	v_mov_b32_e32 v2, v125
	s_cbranch_vccnz .LBB0_2177
	s_and_b64 s[8:9], s[40:41], exec
	s_cselect_b32 s8, s69, s73
	s_cselect_b32 s9, s70, s82
	s_addk_i32 s73, 0x80
	s_addk_i32 s82, 0x100
	s_mov_b32 s83, 0
	v_add_u32_e32 v144, 0x10000, v134
	ds_read_b128 v[136:139], v144
	ds_read_b128 v[140:143], v144 offset:1024
	ds_read_b128 v[154:157], v144 offset:2048
	ds_read_b128 v[170:173], v144 offset:3072
	v_add_u32_e32 v144, 0x14000, v134
	ds_read_b128 v[174:177], v144
	ds_read_b128 v[178:181], v144 offset:1024
	ds_read_b128 v[182:185], v144 offset:2048
	ds_read_b128 v[186:189], v144 offset:3072
	s_add_i32 s46, s73, 0x80
	s_cmp_eq_u32 s49, s83
	s_cselect_b32 s52, s8, s46
	s_cselect_b32 s85, s9, s82
	s_add_i32 s84, s52, 0x80
	s_add_i32 s46, s2, s73
	s_mov_b32 m0, s64
	ds_read_b128 v[190:193], v135
	ds_read_b128 v[194:197], v135 offset:1024
	ds_read_b128 v[198:201], v135 offset:2048
	ds_read_b128 v[202:205], v135 offset:3072
	ds_read_b128 v[228:231], v135 offset:4096
	ds_read_b128 v[232:235], v135 offset:5120
	ds_read_b128 v[236:239], v135 offset:6144
	ds_read_b128 v[240:243], v135 offset:7168
	buffer_load_dwordx4 v130, s[60:63], s46 offen lds
	s_mov_b32 m0, s65
	s_nop 0
	buffer_load_dwordx4 v132, s[60:63], s46 offen lds
	s_waitcnt vmcnt(8)
	s_waitcnt lgkmcnt(0)
	s_setprio 1
	s_barrier
	v_mfma_f32_16x16x32_bf16 v[122:125], v[136:139], v[190:193], 0
	v_mfma_f32_16x16x32_bf16 v[126:129], v[154:157], v[190:193], 0
	v_mfma_f32_16x16x32_bf16 v[106:109], v[154:157], v[198:201], 0
	v_mfma_f32_16x16x32_bf16 v[110:113], v[136:139], v[198:201], 0
	v_mfma_f32_16x16x32_bf16 v[94:97], v[136:139], v[228:231], 0
	v_mfma_f32_16x16x32_bf16 v[90:93], v[154:157], v[228:231], 0
	v_mfma_f32_16x16x32_bf16 v[74:77], v[154:157], v[236:239], 0
	v_mfma_f32_16x16x32_bf16 v[78:81], v[136:139], v[236:239], 0
	v_mfma_f32_16x16x32_bf16 v[70:73], v[174:177], v[236:239], 0
	v_mfma_f32_16x16x32_bf16 v[66:69], v[182:185], v[236:239], 0
	v_mfma_f32_16x16x32_bf16 v[82:85], v[182:185], v[228:231], 0
	v_mfma_f32_16x16x32_bf16 v[86:89], v[174:177], v[228:231], 0
	v_mfma_f32_16x16x32_bf16 v[102:105], v[174:177], v[198:201], 0
	v_mfma_f32_16x16x32_bf16 v[98:101], v[182:185], v[198:201], 0
	v_mfma_f32_16x16x32_bf16 v[114:117], v[182:185], v[190:193], 0
	v_mfma_f32_16x16x32_bf16 v[118:121], v[174:177], v[190:193], 0
	v_mfma_f32_16x16x32_bf16 v[122:125], v[140:143], v[194:197], v[122:125]
	v_mfma_f32_16x16x32_bf16 v[126:129], v[170:173], v[194:197], v[126:129]
	v_mfma_f32_16x16x32_bf16 v[106:109], v[170:173], v[202:205], v[106:109]
	v_mfma_f32_16x16x32_bf16 v[110:113], v[140:143], v[202:205], v[110:113]
	v_mfma_f32_16x16x32_bf16 v[94:97], v[140:143], v[232:235], v[94:97]
	v_mfma_f32_16x16x32_bf16 v[90:93], v[170:173], v[232:235], v[90:93]
	v_mfma_f32_16x16x32_bf16 v[74:77], v[170:173], v[240:243], v[74:77]
	v_mfma_f32_16x16x32_bf16 v[78:81], v[140:143], v[240:243], v[78:81]
	v_mfma_f32_16x16x32_bf16 v[70:73], v[178:181], v[240:243], v[70:73]
	v_mfma_f32_16x16x32_bf16 v[66:69], v[186:189], v[240:243], v[66:69]
	v_mfma_f32_16x16x32_bf16 v[82:85], v[186:189], v[232:235], v[82:85]
	v_mfma_f32_16x16x32_bf16 v[86:89], v[178:181], v[232:235], v[86:89]
	v_mfma_f32_16x16x32_bf16 v[102:105], v[178:181], v[202:205], v[102:105]
	v_mfma_f32_16x16x32_bf16 v[98:101], v[186:189], v[202:205], v[98:101]
	v_mfma_f32_16x16x32_bf16 v[114:117], v[186:189], v[194:197], v[114:117]
	v_mfma_f32_16x16x32_bf16 v[118:121], v[178:181], v[194:197], v[118:121]
	s_barrier
	s_setprio 0
	s_mov_b32 m0, s14
	s_mov_b32 s46, s62
	s_mov_b32 s47, s63
	ds_read_b128 v[190:193], v135 offset:16384
	ds_read_b128 v[194:197], v135 offset:17408
	ds_read_b128 v[198:201], v135 offset:18432
	ds_read_b128 v[202:205], v135 offset:19456
	ds_read_b128 v[228:231], v135 offset:20480
	ds_read_b128 v[232:235], v135 offset:21504
	ds_read_b128 v[236:239], v135 offset:22528
	ds_read_b128 v[240:243], v135 offset:23552
	buffer_load_dwordx4 v131, s[44:47], s85 offen lds
	s_mov_b32 m0, s15
	s_add_i32 s53, s85, s2
	buffer_load_dwordx4 v133, s[44:47], s85 offen lds
	s_mov_b32 m0, s16
	s_nop 0
	buffer_load_dwordx4 v131, s[44:47], s53 offen lds
	s_mov_b32 m0, s18
	s_nop 0
	buffer_load_dwordx4 v133, s[44:47], s53 offen lds
	s_mov_b32 m0, s13
	s_nop 0
	buffer_load_dwordx4 v130, s[60:63], s52 offen lds
	s_mov_b32 m0, s19
	s_nop 0
	buffer_load_dwordx4 v132, s[60:63], s52 offen lds
	s_waitcnt vmcnt(8)
	s_waitcnt lgkmcnt(0)
	s_setprio 1
	s_barrier
	v_mfma_f32_16x16x32_bf16 v[62:65], v[136:139], v[190:193], 0
	v_mfma_f32_16x16x32_bf16 v[58:61], v[154:157], v[190:193], 0
	v_mfma_f32_16x16x32_bf16 v[42:45], v[154:157], v[198:201], 0
	v_mfma_f32_16x16x32_bf16 v[46:49], v[136:139], v[198:201], 0
	v_mfma_f32_16x16x32_bf16 v[30:33], v[136:139], v[228:231], 0
	v_mfma_f32_16x16x32_bf16 v[26:29], v[154:157], v[228:231], 0
	v_mfma_f32_16x16x32_bf16 v[10:13], v[154:157], v[236:239], 0
	v_mfma_f32_16x16x32_bf16 v[14:17], v[136:139], v[236:239], 0
	v_mfma_f32_16x16x32_bf16 v[6:9], v[174:177], v[236:239], 0
	v_mfma_f32_16x16x32_bf16 v[2:5], v[182:185], v[236:239], 0
	v_mfma_f32_16x16x32_bf16 v[18:21], v[182:185], v[228:231], 0
	v_mfma_f32_16x16x32_bf16 v[22:25], v[174:177], v[228:231], 0
	v_mfma_f32_16x16x32_bf16 v[38:41], v[174:177], v[198:201], 0
	v_mfma_f32_16x16x32_bf16 v[34:37], v[182:185], v[198:201], 0
	v_mfma_f32_16x16x32_bf16 v[50:53], v[182:185], v[190:193], 0
	v_mfma_f32_16x16x32_bf16 v[54:57], v[174:177], v[190:193], 0
	v_mfma_f32_16x16x32_bf16 v[62:65], v[140:143], v[194:197], v[62:65]
	v_mfma_f32_16x16x32_bf16 v[58:61], v[170:173], v[194:197], v[58:61]
	v_mfma_f32_16x16x32_bf16 v[42:45], v[170:173], v[202:205], v[42:45]
	v_mfma_f32_16x16x32_bf16 v[46:49], v[140:143], v[202:205], v[46:49]
	v_mfma_f32_16x16x32_bf16 v[30:33], v[140:143], v[232:235], v[30:33]
	v_mfma_f32_16x16x32_bf16 v[26:29], v[170:173], v[232:235], v[26:29]
	v_mfma_f32_16x16x32_bf16 v[10:13], v[170:173], v[240:243], v[10:13]
	v_mfma_f32_16x16x32_bf16 v[14:17], v[140:143], v[240:243], v[14:17]
	v_mfma_f32_16x16x32_bf16 v[6:9], v[178:181], v[240:243], v[6:9]
	v_mfma_f32_16x16x32_bf16 v[2:5], v[186:189], v[240:243], v[2:5]
	v_mfma_f32_16x16x32_bf16 v[18:21], v[186:189], v[232:235], v[18:21]
	v_mfma_f32_16x16x32_bf16 v[22:25], v[178:181], v[232:235], v[22:25]
	v_mfma_f32_16x16x32_bf16 v[38:41], v[178:181], v[202:205], v[38:41]
	v_mfma_f32_16x16x32_bf16 v[34:37], v[186:189], v[202:205], v[34:37]
	v_mfma_f32_16x16x32_bf16 v[50:53], v[186:189], v[194:197], v[50:53]
	v_mfma_f32_16x16x32_bf16 v[54:57], v[178:181], v[194:197], v[54:57]
	s_barrier
	s_setprio 0
	v_add_u32_e32 v144, 0x18000, v134
	ds_read_b128 v[136:139], v144
	ds_read_b128 v[140:143], v144 offset:1024
	ds_read_b128 v[154:157], v144 offset:2048
	ds_read_b128 v[170:173], v144 offset:3072
	v_add_u32_e32 v144, 0x1c000, v134
	ds_read_b128 v[174:177], v144
	ds_read_b128 v[178:181], v144 offset:1024
	ds_read_b128 v[182:185], v144 offset:2048
	ds_read_b128 v[186:189], v144 offset:3072
	s_add_i32 s52, s52, s2
	s_mov_b32 m0, s21
	ds_read_b128 v[190:193], v135 offset:32768
	ds_read_b128 v[194:197], v135 offset:33792
	ds_read_b128 v[198:201], v135 offset:34816
	ds_read_b128 v[202:205], v135 offset:35840
	ds_read_b128 v[228:231], v135 offset:36864
	ds_read_b128 v[232:235], v135 offset:37888
	ds_read_b128 v[236:239], v135 offset:38912
	ds_read_b128 v[240:243], v135 offset:39936
	buffer_load_dwordx4 v130, s[60:63], s52 offen lds
	s_mov_b32 m0, s22
	s_nop 0
	buffer_load_dwordx4 v132, s[60:63], s52 offen lds
	s_waitcnt vmcnt(8)
	s_waitcnt lgkmcnt(0)
	s_setprio 1
	s_barrier
	v_mfma_f32_16x16x32_bf16 v[122:125], v[136:139], v[190:193], v[122:125]
	v_mfma_f32_16x16x32_bf16 v[126:129], v[154:157], v[190:193], v[126:129]
	v_mfma_f32_16x16x32_bf16 v[106:109], v[154:157], v[198:201], v[106:109]
	v_mfma_f32_16x16x32_bf16 v[110:113], v[136:139], v[198:201], v[110:113]
	v_mfma_f32_16x16x32_bf16 v[94:97], v[136:139], v[228:231], v[94:97]
	v_mfma_f32_16x16x32_bf16 v[90:93], v[154:157], v[228:231], v[90:93]
	v_mfma_f32_16x16x32_bf16 v[74:77], v[154:157], v[236:239], v[74:77]
	v_mfma_f32_16x16x32_bf16 v[78:81], v[136:139], v[236:239], v[78:81]
	v_mfma_f32_16x16x32_bf16 v[70:73], v[174:177], v[236:239], v[70:73]
	v_mfma_f32_16x16x32_bf16 v[66:69], v[182:185], v[236:239], v[66:69]
	v_mfma_f32_16x16x32_bf16 v[82:85], v[182:185], v[228:231], v[82:85]
	v_mfma_f32_16x16x32_bf16 v[86:89], v[174:177], v[228:231], v[86:89]
	v_mfma_f32_16x16x32_bf16 v[102:105], v[174:177], v[198:201], v[102:105]
	v_mfma_f32_16x16x32_bf16 v[98:101], v[182:185], v[198:201], v[98:101]
	v_mfma_f32_16x16x32_bf16 v[114:117], v[182:185], v[190:193], v[114:117]
	v_mfma_f32_16x16x32_bf16 v[118:121], v[174:177], v[190:193], v[118:121]
	v_mfma_f32_16x16x32_bf16 v[122:125], v[140:143], v[194:197], v[122:125]
	v_mfma_f32_16x16x32_bf16 v[126:129], v[170:173], v[194:197], v[126:129]
	v_mfma_f32_16x16x32_bf16 v[106:109], v[170:173], v[202:205], v[106:109]
	v_mfma_f32_16x16x32_bf16 v[110:113], v[140:143], v[202:205], v[110:113]
	v_mfma_f32_16x16x32_bf16 v[94:97], v[140:143], v[232:235], v[94:97]
	v_mfma_f32_16x16x32_bf16 v[90:93], v[170:173], v[232:235], v[90:93]
	v_mfma_f32_16x16x32_bf16 v[74:77], v[170:173], v[240:243], v[74:77]
	v_mfma_f32_16x16x32_bf16 v[78:81], v[140:143], v[240:243], v[78:81]
	v_mfma_f32_16x16x32_bf16 v[70:73], v[178:181], v[240:243], v[70:73]
	v_mfma_f32_16x16x32_bf16 v[66:69], v[186:189], v[240:243], v[66:69]
	v_mfma_f32_16x16x32_bf16 v[82:85], v[186:189], v[232:235], v[82:85]
	v_mfma_f32_16x16x32_bf16 v[86:89], v[178:181], v[232:235], v[86:89]
	v_mfma_f32_16x16x32_bf16 v[102:105], v[178:181], v[202:205], v[102:105]
	v_mfma_f32_16x16x32_bf16 v[98:101], v[186:189], v[202:205], v[98:101]
	v_mfma_f32_16x16x32_bf16 v[114:117], v[186:189], v[194:197], v[114:117]
	v_mfma_f32_16x16x32_bf16 v[118:121], v[178:181], v[194:197], v[118:121]
	s_barrier
	s_setprio 0
	s_mov_b32 m0, s33
	s_add_i32 s52, s85, 0x80
	ds_read_b128 v[190:193], v135 offset:49152
	ds_read_b128 v[194:197], v135 offset:50176
	ds_read_b128 v[198:201], v135 offset:51200
	ds_read_b128 v[202:205], v135 offset:52224
	ds_read_b128 v[228:231], v135 offset:53248
	ds_read_b128 v[232:235], v135 offset:54272
	ds_read_b128 v[236:239], v135 offset:55296
	ds_read_b128 v[240:243], v135 offset:56320
	buffer_load_dwordx4 v131, s[44:47], s52 offen lds
	s_mov_b32 m0, s36
	s_nop 0
	buffer_load_dwordx4 v133, s[44:47], s52 offen lds
	s_add_i32 s52, s52, s2
	s_mov_b32 m0, s43
	s_nop 0
	buffer_load_dwordx4 v131, s[44:47], s52 offen lds
	s_mov_b32 m0, s48
	s_nop 0
	buffer_load_dwordx4 v133, s[44:47], s52 offen lds
	s_mov_b32 m0, s37
	s_nop 0
	buffer_load_dwordx4 v130, s[60:63], s84 offen lds
	s_mov_b32 m0, s42
	s_nop 0
	buffer_load_dwordx4 v132, s[60:63], s84 offen lds
	s_waitcnt vmcnt(8)
	s_waitcnt lgkmcnt(0)
	s_setprio 1
	s_barrier
	v_mfma_f32_16x16x32_bf16 v[62:65], v[136:139], v[190:193], v[62:65]
	v_mfma_f32_16x16x32_bf16 v[58:61], v[154:157], v[190:193], v[58:61]
	v_mfma_f32_16x16x32_bf16 v[42:45], v[154:157], v[198:201], v[42:45]
	v_mfma_f32_16x16x32_bf16 v[46:49], v[136:139], v[198:201], v[46:49]
	v_mfma_f32_16x16x32_bf16 v[30:33], v[136:139], v[228:231], v[30:33]
	v_mfma_f32_16x16x32_bf16 v[26:29], v[154:157], v[228:231], v[26:29]
	v_mfma_f32_16x16x32_bf16 v[10:13], v[154:157], v[236:239], v[10:13]
	v_mfma_f32_16x16x32_bf16 v[14:17], v[136:139], v[236:239], v[14:17]
	v_mfma_f32_16x16x32_bf16 v[6:9], v[174:177], v[236:239], v[6:9]
	v_mfma_f32_16x16x32_bf16 v[2:5], v[182:185], v[236:239], v[2:5]
	v_mfma_f32_16x16x32_bf16 v[18:21], v[182:185], v[228:231], v[18:21]
	v_mfma_f32_16x16x32_bf16 v[22:25], v[174:177], v[228:231], v[22:25]
	v_mfma_f32_16x16x32_bf16 v[38:41], v[174:177], v[198:201], v[38:41]
	v_mfma_f32_16x16x32_bf16 v[34:37], v[182:185], v[198:201], v[34:37]
	v_mfma_f32_16x16x32_bf16 v[50:53], v[182:185], v[190:193], v[50:53]
	v_mfma_f32_16x16x32_bf16 v[54:57], v[174:177], v[190:193], v[54:57]
	v_mfma_f32_16x16x32_bf16 v[62:65], v[140:143], v[194:197], v[62:65]
	v_mfma_f32_16x16x32_bf16 v[58:61], v[170:173], v[194:197], v[58:61]
	v_mfma_f32_16x16x32_bf16 v[42:45], v[170:173], v[202:205], v[42:45]
	v_mfma_f32_16x16x32_bf16 v[46:49], v[140:143], v[202:205], v[46:49]
	v_mfma_f32_16x16x32_bf16 v[30:33], v[140:143], v[232:235], v[30:33]
	v_mfma_f32_16x16x32_bf16 v[26:29], v[170:173], v[232:235], v[26:29]
	v_mfma_f32_16x16x32_bf16 v[10:13], v[170:173], v[240:243], v[10:13]
	v_mfma_f32_16x16x32_bf16 v[14:17], v[140:143], v[240:243], v[14:17]
	v_mfma_f32_16x16x32_bf16 v[6:9], v[178:181], v[240:243], v[6:9]
	v_mfma_f32_16x16x32_bf16 v[2:5], v[186:189], v[240:243], v[2:5]
	v_mfma_f32_16x16x32_bf16 v[18:21], v[186:189], v[232:235], v[18:21]
	v_mfma_f32_16x16x32_bf16 v[22:25], v[178:181], v[232:235], v[22:25]
	v_mfma_f32_16x16x32_bf16 v[38:41], v[178:181], v[202:205], v[38:41]
	v_mfma_f32_16x16x32_bf16 v[34:37], v[186:189], v[202:205], v[34:37]
	v_mfma_f32_16x16x32_bf16 v[50:53], v[186:189], v[194:197], v[50:53]
	v_mfma_f32_16x16x32_bf16 v[54:57], v[178:181], v[194:197], v[54:57]
	s_barrier
	s_setprio 0
	s_add_i32 s83, s83, 2
	s_addk_i32 s73, 0x100
	s_addk_i32 s82, 0x100
	s_cmp_ge_i32 s83, s23
.LBB0_2175:
	v_add_u32_e32 v144, 0x10000, v134
	ds_read_b128 v[136:139], v144
	ds_read_b128 v[140:143], v144 offset:1024
	ds_read_b128 v[154:157], v144 offset:2048
	ds_read_b128 v[170:173], v144 offset:3072
	v_add_u32_e32 v144, 0x14000, v134
	ds_read_b128 v[174:177], v144
	ds_read_b128 v[178:181], v144 offset:1024
	ds_read_b128 v[182:185], v144 offset:2048
	ds_read_b128 v[186:189], v144 offset:3072
	s_add_i32 s46, s73, 0x80
	s_cmp_eq_u32 s49, s83
	s_cselect_b32 s52, s8, s46
	s_cselect_b32 s85, s9, s82
	s_add_i32 s84, s52, 0x80
	s_add_i32 s46, s2, s73
	s_mov_b32 m0, s64
	ds_read_b128 v[190:193], v135
	ds_read_b128 v[194:197], v135 offset:1024
	ds_read_b128 v[198:201], v135 offset:2048
	ds_read_b128 v[202:205], v135 offset:3072
	ds_read_b128 v[228:231], v135 offset:4096
	ds_read_b128 v[232:235], v135 offset:5120
	ds_read_b128 v[236:239], v135 offset:6144
	ds_read_b128 v[240:243], v135 offset:7168
	buffer_load_dwordx4 v130, s[60:63], s46 offen lds
	s_mov_b32 m0, s65
	s_nop 0
	buffer_load_dwordx4 v132, s[60:63], s46 offen lds
	s_waitcnt vmcnt(8)
	s_waitcnt lgkmcnt(0)
	s_setprio 1
	s_barrier
	v_mfma_f32_16x16x32_bf16 v[122:125], v[136:139], v[190:193], v[122:125]
	v_mfma_f32_16x16x32_bf16 v[126:129], v[154:157], v[190:193], v[126:129]
	v_mfma_f32_16x16x32_bf16 v[106:109], v[154:157], v[198:201], v[106:109]
	v_mfma_f32_16x16x32_bf16 v[110:113], v[136:139], v[198:201], v[110:113]
	v_mfma_f32_16x16x32_bf16 v[94:97], v[136:139], v[228:231], v[94:97]
	v_mfma_f32_16x16x32_bf16 v[90:93], v[154:157], v[228:231], v[90:93]
	v_mfma_f32_16x16x32_bf16 v[74:77], v[154:157], v[236:239], v[74:77]
	v_mfma_f32_16x16x32_bf16 v[78:81], v[136:139], v[236:239], v[78:81]
	v_mfma_f32_16x16x32_bf16 v[70:73], v[174:177], v[236:239], v[70:73]
	v_mfma_f32_16x16x32_bf16 v[66:69], v[182:185], v[236:239], v[66:69]
	v_mfma_f32_16x16x32_bf16 v[82:85], v[182:185], v[228:231], v[82:85]
	v_mfma_f32_16x16x32_bf16 v[86:89], v[174:177], v[228:231], v[86:89]
	v_mfma_f32_16x16x32_bf16 v[102:105], v[174:177], v[198:201], v[102:105]
	v_mfma_f32_16x16x32_bf16 v[98:101], v[182:185], v[198:201], v[98:101]
	v_mfma_f32_16x16x32_bf16 v[114:117], v[182:185], v[190:193], v[114:117]
	v_mfma_f32_16x16x32_bf16 v[118:121], v[174:177], v[190:193], v[118:121]
	v_mfma_f32_16x16x32_bf16 v[122:125], v[140:143], v[194:197], v[122:125]
	v_mfma_f32_16x16x32_bf16 v[126:129], v[170:173], v[194:197], v[126:129]
	v_mfma_f32_16x16x32_bf16 v[106:109], v[170:173], v[202:205], v[106:109]
	v_mfma_f32_16x16x32_bf16 v[110:113], v[140:143], v[202:205], v[110:113]
	v_mfma_f32_16x16x32_bf16 v[94:97], v[140:143], v[232:235], v[94:97]
	v_mfma_f32_16x16x32_bf16 v[90:93], v[170:173], v[232:235], v[90:93]
	v_mfma_f32_16x16x32_bf16 v[74:77], v[170:173], v[240:243], v[74:77]
	v_mfma_f32_16x16x32_bf16 v[78:81], v[140:143], v[240:243], v[78:81]
	v_mfma_f32_16x16x32_bf16 v[70:73], v[178:181], v[240:243], v[70:73]
	v_mfma_f32_16x16x32_bf16 v[66:69], v[186:189], v[240:243], v[66:69]
	v_mfma_f32_16x16x32_bf16 v[82:85], v[186:189], v[232:235], v[82:85]
	v_mfma_f32_16x16x32_bf16 v[86:89], v[178:181], v[232:235], v[86:89]
	v_mfma_f32_16x16x32_bf16 v[102:105], v[178:181], v[202:205], v[102:105]
	v_mfma_f32_16x16x32_bf16 v[98:101], v[186:189], v[202:205], v[98:101]
	v_mfma_f32_16x16x32_bf16 v[114:117], v[186:189], v[194:197], v[114:117]
	v_mfma_f32_16x16x32_bf16 v[118:121], v[178:181], v[194:197], v[118:121]
	s_barrier
	s_setprio 0
	s_mov_b32 m0, s14
	s_mov_b32 s46, s62
	s_mov_b32 s47, s63
	ds_read_b128 v[190:193], v135 offset:16384
	ds_read_b128 v[194:197], v135 offset:17408
	ds_read_b128 v[198:201], v135 offset:18432
	ds_read_b128 v[202:205], v135 offset:19456
	ds_read_b128 v[228:231], v135 offset:20480
	ds_read_b128 v[232:235], v135 offset:21504
	ds_read_b128 v[236:239], v135 offset:22528
	ds_read_b128 v[240:243], v135 offset:23552
	buffer_load_dwordx4 v131, s[44:47], s85 offen lds
	s_mov_b32 m0, s15
	s_add_i32 s53, s85, s2
	buffer_load_dwordx4 v133, s[44:47], s85 offen lds
	s_mov_b32 m0, s16
	s_nop 0
	buffer_load_dwordx4 v131, s[44:47], s53 offen lds
	s_mov_b32 m0, s18
	s_nop 0
	buffer_load_dwordx4 v133, s[44:47], s53 offen lds
	s_mov_b32 m0, s13
	s_nop 0
	buffer_load_dwordx4 v130, s[60:63], s52 offen lds
	s_mov_b32 m0, s19
	s_nop 0
	buffer_load_dwordx4 v132, s[60:63], s52 offen lds
	s_waitcnt vmcnt(8)
	s_waitcnt lgkmcnt(0)
	s_setprio 1
	s_barrier
	v_mfma_f32_16x16x32_bf16 v[62:65], v[136:139], v[190:193], v[62:65]
	v_mfma_f32_16x16x32_bf16 v[58:61], v[154:157], v[190:193], v[58:61]
	v_mfma_f32_16x16x32_bf16 v[42:45], v[154:157], v[198:201], v[42:45]
	v_mfma_f32_16x16x32_bf16 v[46:49], v[136:139], v[198:201], v[46:49]
	v_mfma_f32_16x16x32_bf16 v[30:33], v[136:139], v[228:231], v[30:33]
	v_mfma_f32_16x16x32_bf16 v[26:29], v[154:157], v[228:231], v[26:29]
	v_mfma_f32_16x16x32_bf16 v[10:13], v[154:157], v[236:239], v[10:13]
	v_mfma_f32_16x16x32_bf16 v[14:17], v[136:139], v[236:239], v[14:17]
	v_mfma_f32_16x16x32_bf16 v[6:9], v[174:177], v[236:239], v[6:9]
	v_mfma_f32_16x16x32_bf16 v[2:5], v[182:185], v[236:239], v[2:5]
	v_mfma_f32_16x16x32_bf16 v[18:21], v[182:185], v[228:231], v[18:21]
	v_mfma_f32_16x16x32_bf16 v[22:25], v[174:177], v[228:231], v[22:25]
	v_mfma_f32_16x16x32_bf16 v[38:41], v[174:177], v[198:201], v[38:41]
	v_mfma_f32_16x16x32_bf16 v[34:37], v[182:185], v[198:201], v[34:37]
	v_mfma_f32_16x16x32_bf16 v[50:53], v[182:185], v[190:193], v[50:53]
	v_mfma_f32_16x16x32_bf16 v[54:57], v[174:177], v[190:193], v[54:57]
	v_mfma_f32_16x16x32_bf16 v[62:65], v[140:143], v[194:197], v[62:65]
	v_mfma_f32_16x16x32_bf16 v[58:61], v[170:173], v[194:197], v[58:61]
	v_mfma_f32_16x16x32_bf16 v[42:45], v[170:173], v[202:205], v[42:45]
	v_mfma_f32_16x16x32_bf16 v[46:49], v[140:143], v[202:205], v[46:49]
	v_mfma_f32_16x16x32_bf16 v[30:33], v[140:143], v[232:235], v[30:33]
	v_mfma_f32_16x16x32_bf16 v[26:29], v[170:173], v[232:235], v[26:29]
	v_mfma_f32_16x16x32_bf16 v[10:13], v[170:173], v[240:243], v[10:13]
	v_mfma_f32_16x16x32_bf16 v[14:17], v[140:143], v[240:243], v[14:17]
	v_mfma_f32_16x16x32_bf16 v[6:9], v[178:181], v[240:243], v[6:9]
	v_mfma_f32_16x16x32_bf16 v[2:5], v[186:189], v[240:243], v[2:5]
	v_mfma_f32_16x16x32_bf16 v[18:21], v[186:189], v[232:235], v[18:21]
	v_mfma_f32_16x16x32_bf16 v[22:25], v[178:181], v[232:235], v[22:25]
	v_mfma_f32_16x16x32_bf16 v[38:41], v[178:181], v[202:205], v[38:41]
	v_mfma_f32_16x16x32_bf16 v[34:37], v[186:189], v[202:205], v[34:37]
	v_mfma_f32_16x16x32_bf16 v[50:53], v[186:189], v[194:197], v[50:53]
	v_mfma_f32_16x16x32_bf16 v[54:57], v[178:181], v[194:197], v[54:57]
	s_barrier
	s_setprio 0
	v_add_u32_e32 v144, 0x18000, v134
	ds_read_b128 v[136:139], v144
	ds_read_b128 v[140:143], v144 offset:1024
	ds_read_b128 v[154:157], v144 offset:2048
	ds_read_b128 v[170:173], v144 offset:3072
	v_add_u32_e32 v144, 0x1c000, v134
	ds_read_b128 v[174:177], v144
	ds_read_b128 v[178:181], v144 offset:1024
	ds_read_b128 v[182:185], v144 offset:2048
	ds_read_b128 v[186:189], v144 offset:3072
	s_add_i32 s52, s52, s2
	s_mov_b32 m0, s21
	ds_read_b128 v[190:193], v135 offset:32768
	ds_read_b128 v[194:197], v135 offset:33792
	ds_read_b128 v[198:201], v135 offset:34816
	ds_read_b128 v[202:205], v135 offset:35840
	ds_read_b128 v[228:231], v135 offset:36864
	ds_read_b128 v[232:235], v135 offset:37888
	ds_read_b128 v[236:239], v135 offset:38912
	ds_read_b128 v[240:243], v135 offset:39936
	buffer_load_dwordx4 v130, s[60:63], s52 offen lds
	s_mov_b32 m0, s22
	s_nop 0
	buffer_load_dwordx4 v132, s[60:63], s52 offen lds
	s_waitcnt vmcnt(8)
	s_waitcnt lgkmcnt(0)
	s_setprio 1
	s_barrier
	v_mfma_f32_16x16x32_bf16 v[122:125], v[136:139], v[190:193], v[122:125]
	v_mfma_f32_16x16x32_bf16 v[126:129], v[154:157], v[190:193], v[126:129]
	v_mfma_f32_16x16x32_bf16 v[106:109], v[154:157], v[198:201], v[106:109]
	v_mfma_f32_16x16x32_bf16 v[110:113], v[136:139], v[198:201], v[110:113]
	v_mfma_f32_16x16x32_bf16 v[94:97], v[136:139], v[228:231], v[94:97]
	v_mfma_f32_16x16x32_bf16 v[90:93], v[154:157], v[228:231], v[90:93]
	v_mfma_f32_16x16x32_bf16 v[74:77], v[154:157], v[236:239], v[74:77]
	v_mfma_f32_16x16x32_bf16 v[78:81], v[136:139], v[236:239], v[78:81]
	v_mfma_f32_16x16x32_bf16 v[70:73], v[174:177], v[236:239], v[70:73]
	v_mfma_f32_16x16x32_bf16 v[66:69], v[182:185], v[236:239], v[66:69]
	v_mfma_f32_16x16x32_bf16 v[82:85], v[182:185], v[228:231], v[82:85]
	v_mfma_f32_16x16x32_bf16 v[86:89], v[174:177], v[228:231], v[86:89]
	v_mfma_f32_16x16x32_bf16 v[102:105], v[174:177], v[198:201], v[102:105]
	v_mfma_f32_16x16x32_bf16 v[98:101], v[182:185], v[198:201], v[98:101]
	v_mfma_f32_16x16x32_bf16 v[114:117], v[182:185], v[190:193], v[114:117]
	v_mfma_f32_16x16x32_bf16 v[118:121], v[174:177], v[190:193], v[118:121]
	v_mfma_f32_16x16x32_bf16 v[122:125], v[140:143], v[194:197], v[122:125]
	v_mfma_f32_16x16x32_bf16 v[126:129], v[170:173], v[194:197], v[126:129]
	v_mfma_f32_16x16x32_bf16 v[106:109], v[170:173], v[202:205], v[106:109]
	v_mfma_f32_16x16x32_bf16 v[110:113], v[140:143], v[202:205], v[110:113]
	v_mfma_f32_16x16x32_bf16 v[94:97], v[140:143], v[232:235], v[94:97]
	v_mfma_f32_16x16x32_bf16 v[90:93], v[170:173], v[232:235], v[90:93]
	v_mfma_f32_16x16x32_bf16 v[74:77], v[170:173], v[240:243], v[74:77]
	v_mfma_f32_16x16x32_bf16 v[78:81], v[140:143], v[240:243], v[78:81]
	v_mfma_f32_16x16x32_bf16 v[70:73], v[178:181], v[240:243], v[70:73]
	v_mfma_f32_16x16x32_bf16 v[66:69], v[186:189], v[240:243], v[66:69]
	v_mfma_f32_16x16x32_bf16 v[82:85], v[186:189], v[232:235], v[82:85]
	v_mfma_f32_16x16x32_bf16 v[86:89], v[178:181], v[232:235], v[86:89]
	v_mfma_f32_16x16x32_bf16 v[102:105], v[178:181], v[202:205], v[102:105]
	v_mfma_f32_16x16x32_bf16 v[98:101], v[186:189], v[202:205], v[98:101]
	v_mfma_f32_16x16x32_bf16 v[114:117], v[186:189], v[194:197], v[114:117]
	v_mfma_f32_16x16x32_bf16 v[118:121], v[178:181], v[194:197], v[118:121]
	s_barrier
	s_setprio 0
	s_mov_b32 m0, s33
	s_add_i32 s52, s85, 0x80
	ds_read_b128 v[190:193], v135 offset:49152
	ds_read_b128 v[194:197], v135 offset:50176
	ds_read_b128 v[198:201], v135 offset:51200
	ds_read_b128 v[202:205], v135 offset:52224
	ds_read_b128 v[228:231], v135 offset:53248
	ds_read_b128 v[232:235], v135 offset:54272
	ds_read_b128 v[236:239], v135 offset:55296
	ds_read_b128 v[240:243], v135 offset:56320
	buffer_load_dwordx4 v131, s[44:47], s52 offen lds
	s_mov_b32 m0, s36
	s_nop 0
	buffer_load_dwordx4 v133, s[44:47], s52 offen lds
	s_add_i32 s52, s52, s2
	s_mov_b32 m0, s43
	s_nop 0
	buffer_load_dwordx4 v131, s[44:47], s52 offen lds
	s_mov_b32 m0, s48
	s_nop 0
	buffer_load_dwordx4 v133, s[44:47], s52 offen lds
	s_mov_b32 m0, s37
	s_nop 0
	buffer_load_dwordx4 v130, s[60:63], s84 offen lds
	s_mov_b32 m0, s42
	s_nop 0
	buffer_load_dwordx4 v132, s[60:63], s84 offen lds
	s_waitcnt vmcnt(8)
	s_waitcnt lgkmcnt(0)
	s_setprio 1
	s_barrier
	v_mfma_f32_16x16x32_bf16 v[62:65], v[136:139], v[190:193], v[62:65]
	v_mfma_f32_16x16x32_bf16 v[58:61], v[154:157], v[190:193], v[58:61]
	v_mfma_f32_16x16x32_bf16 v[42:45], v[154:157], v[198:201], v[42:45]
	v_mfma_f32_16x16x32_bf16 v[46:49], v[136:139], v[198:201], v[46:49]
	v_mfma_f32_16x16x32_bf16 v[30:33], v[136:139], v[228:231], v[30:33]
	v_mfma_f32_16x16x32_bf16 v[26:29], v[154:157], v[228:231], v[26:29]
	v_mfma_f32_16x16x32_bf16 v[10:13], v[154:157], v[236:239], v[10:13]
	v_mfma_f32_16x16x32_bf16 v[14:17], v[136:139], v[236:239], v[14:17]
	v_mfma_f32_16x16x32_bf16 v[6:9], v[174:177], v[236:239], v[6:9]
	v_mfma_f32_16x16x32_bf16 v[2:5], v[182:185], v[236:239], v[2:5]
	v_mfma_f32_16x16x32_bf16 v[18:21], v[182:185], v[228:231], v[18:21]
	v_mfma_f32_16x16x32_bf16 v[22:25], v[174:177], v[228:231], v[22:25]
	v_mfma_f32_16x16x32_bf16 v[38:41], v[174:177], v[198:201], v[38:41]
	v_mfma_f32_16x16x32_bf16 v[34:37], v[182:185], v[198:201], v[34:37]
	v_mfma_f32_16x16x32_bf16 v[50:53], v[182:185], v[190:193], v[50:53]
	v_mfma_f32_16x16x32_bf16 v[54:57], v[174:177], v[190:193], v[54:57]
	v_mfma_f32_16x16x32_bf16 v[62:65], v[140:143], v[194:197], v[62:65]
	v_mfma_f32_16x16x32_bf16 v[58:61], v[170:173], v[194:197], v[58:61]
	v_mfma_f32_16x16x32_bf16 v[42:45], v[170:173], v[202:205], v[42:45]
	v_mfma_f32_16x16x32_bf16 v[46:49], v[140:143], v[202:205], v[46:49]
	v_mfma_f32_16x16x32_bf16 v[30:33], v[140:143], v[232:235], v[30:33]
	v_mfma_f32_16x16x32_bf16 v[26:29], v[170:173], v[232:235], v[26:29]
	v_mfma_f32_16x16x32_bf16 v[10:13], v[170:173], v[240:243], v[10:13]
	v_mfma_f32_16x16x32_bf16 v[14:17], v[140:143], v[240:243], v[14:17]
	v_mfma_f32_16x16x32_bf16 v[6:9], v[178:181], v[240:243], v[6:9]
	v_mfma_f32_16x16x32_bf16 v[2:5], v[186:189], v[240:243], v[2:5]
	v_mfma_f32_16x16x32_bf16 v[18:21], v[186:189], v[232:235], v[18:21]
	v_mfma_f32_16x16x32_bf16 v[22:25], v[178:181], v[232:235], v[22:25]
	v_mfma_f32_16x16x32_bf16 v[38:41], v[178:181], v[202:205], v[38:41]
	v_mfma_f32_16x16x32_bf16 v[34:37], v[186:189], v[202:205], v[34:37]
	v_mfma_f32_16x16x32_bf16 v[50:53], v[186:189], v[194:197], v[50:53]
	v_mfma_f32_16x16x32_bf16 v[54:57], v[178:181], v[194:197], v[54:57]
	s_barrier
	s_setprio 0
	s_add_i32 s83, s83, 2
	s_addk_i32 s73, 0x100
	s_addk_i32 s82, 0x100
	s_cmp_ge_i32 s83, s23
	s_cbranch_scc0 .LBB0_2175
	v_readlane_b32 s83, v252, 30

.LBB0_2449:
	s_lshl_b32 s73, s72, 20
	s_and_b64 s[8:9], s[40:41], exec
	s_cselect_b32 s8, s73, s13
	s_lshl_b32 s84, s71, 20
	s_and_b64 s[24:25], s[40:41], exec
	s_cselect_b32 s9, s84, s21
	s_add_i32 s13, s13, 0x80080
	s_addk_i32 s21, 0x100
	s_mov_b32 s22, -2
	s_waitcnt lgkmcnt(0)
	v_add_u32_e32 v142, 0x10000, v188
	v_add_u32_e32 v182, 0x14000, v188
	ds_read_b128 v[130:133], v142
	ds_read_b128 v[134:137], v142 offset:1024
	ds_read_b128 v[138:141], v142 offset:2048
	ds_read_b128 v[142:145], v142 offset:3072
	ds_read_b128 v[154:157], v182
	ds_read_b128 v[174:177], v182 offset:1024
	ds_read_b128 v[178:181], v182 offset:2048
	ds_read_b128 v[190:193], v182 offset:3072
	s_add_i32 s24, s13, 0xfff80080
	s_cmp_eq_u32 s22, 28
	s_cselect_b32 s52, s8, s24
	s_cselect_b32 s25, s9, s21
	s_or_b32 s24, s52, 0x80
	s_mov_b32 m0, s68
	ds_read_b128 v[194:197], v189
	ds_read_b128 v[198:201], v189 offset:1024
	ds_read_b128 v[202:205], v189 offset:2048
	ds_read_b128 v[228:231], v189 offset:3072
	ds_read_b128 v[232:235], v189 offset:4096
	ds_read_b128 v[236:239], v189 offset:5120
	ds_read_b128 v[240:243], v189 offset:6144
	ds_read_b128 v[244:247], v189 offset:7168
	buffer_load_dwordx4 v184, s[60:63], s13 offen lds
	s_mov_b32 m0, s70
	s_nop 0
	buffer_load_dwordx4 v186, s[60:63], s13 offen lds
	s_waitcnt vmcnt(8)
	s_waitcnt lgkmcnt(0)
	s_setprio 1
	s_barrier
	v_mfma_f32_16x16x32_bf16 v[126:129], v[130:133], v[194:197], 0
	v_mfma_f32_16x16x32_bf16 v[122:125], v[138:141], v[194:197], 0
	v_mfma_f32_16x16x32_bf16 v[106:109], v[138:141], v[202:205], 0
	v_mfma_f32_16x16x32_bf16 v[110:113], v[130:133], v[202:205], 0
	v_mfma_f32_16x16x32_bf16 v[94:97], v[130:133], v[232:235], 0
	v_mfma_f32_16x16x32_bf16 v[90:93], v[138:141], v[232:235], 0
	v_mfma_f32_16x16x32_bf16 v[74:77], v[138:141], v[240:243], 0
	v_mfma_f32_16x16x32_bf16 v[78:81], v[130:133], v[240:243], 0
	v_mfma_f32_16x16x32_bf16 v[70:73], v[154:157], v[240:243], 0
	v_mfma_f32_16x16x32_bf16 v[66:69], v[178:181], v[240:243], 0
	v_mfma_f32_16x16x32_bf16 v[82:85], v[178:181], v[232:235], 0
	v_mfma_f32_16x16x32_bf16 v[86:89], v[154:157], v[232:235], 0
	v_mfma_f32_16x16x32_bf16 v[102:105], v[154:157], v[202:205], 0
	v_mfma_f32_16x16x32_bf16 v[98:101], v[178:181], v[202:205], 0
	v_mfma_f32_16x16x32_bf16 v[114:117], v[178:181], v[194:197], 0
	v_mfma_f32_16x16x32_bf16 v[118:121], v[154:157], v[194:197], 0
	v_mfma_f32_16x16x32_bf16 v[126:129], v[134:137], v[198:201], v[126:129]
	v_mfma_f32_16x16x32_bf16 v[122:125], v[142:145], v[198:201], v[122:125]
	v_mfma_f32_16x16x32_bf16 v[106:109], v[142:145], v[228:231], v[106:109]
	v_mfma_f32_16x16x32_bf16 v[110:113], v[134:137], v[228:231], v[110:113]
	v_mfma_f32_16x16x32_bf16 v[94:97], v[134:137], v[236:239], v[94:97]
	v_mfma_f32_16x16x32_bf16 v[90:93], v[142:145], v[236:239], v[90:93]
	v_mfma_f32_16x16x32_bf16 v[74:77], v[142:145], v[244:247], v[74:77]
	v_mfma_f32_16x16x32_bf16 v[78:81], v[134:137], v[244:247], v[78:81]
	v_mfma_f32_16x16x32_bf16 v[70:73], v[174:177], v[244:247], v[70:73]
	v_mfma_f32_16x16x32_bf16 v[66:69], v[190:193], v[244:247], v[66:69]
	v_mfma_f32_16x16x32_bf16 v[82:85], v[190:193], v[236:239], v[82:85]
	v_mfma_f32_16x16x32_bf16 v[86:89], v[174:177], v[236:239], v[86:89]
	v_mfma_f32_16x16x32_bf16 v[102:105], v[174:177], v[228:231], v[102:105]
	v_mfma_f32_16x16x32_bf16 v[98:101], v[190:193], v[228:231], v[98:101]
	v_mfma_f32_16x16x32_bf16 v[114:117], v[190:193], v[198:201], v[114:117]
	v_mfma_f32_16x16x32_bf16 v[118:121], v[174:177], v[198:201], v[118:121]
	s_barrier
	s_setprio 0
	s_mov_b32 m0, s16
	s_mov_b32 s46, s62
	s_mov_b32 s47, s63
	ds_read_b128 v[194:197], v189 offset:16384
	ds_read_b128 v[198:201], v189 offset:17408
	ds_read_b128 v[202:205], v189 offset:18432
	ds_read_b128 v[228:231], v189 offset:19456
	ds_read_b128 v[232:235], v189 offset:20480
	ds_read_b128 v[236:239], v189 offset:21504
	ds_read_b128 v[240:243], v189 offset:22528
	ds_read_b128 v[244:247], v189 offset:23552
	buffer_load_dwordx4 v185, s[44:47], s25 offen lds
	s_mov_b32 m0, s18
	s_add_i32 s53, s25, 0x80000
	buffer_load_dwordx4 v187, s[44:47], s25 offen lds
	s_mov_b32 m0, s19
	s_nop 0
	buffer_load_dwordx4 v185, s[44:47], s53 offen lds
	s_mov_b32 m0, s23
	s_nop 0
	buffer_load_dwordx4 v187, s[44:47], s53 offen lds
	s_mov_b32 m0, s15
	s_nop 0
	buffer_load_dwordx4 v184, s[60:63], s52 offen lds
	s_mov_b32 m0, s26
	s_nop 0
	buffer_load_dwordx4 v186, s[60:63], s52 offen lds
	s_waitcnt vmcnt(8)
	s_waitcnt lgkmcnt(0)
	s_setprio 1
	s_barrier
	v_mfma_f32_16x16x32_bf16 v[62:65], v[130:133], v[194:197], 0
	v_mfma_f32_16x16x32_bf16 v[58:61], v[138:141], v[194:197], 0
	v_mfma_f32_16x16x32_bf16 v[42:45], v[138:141], v[202:205], 0
	v_mfma_f32_16x16x32_bf16 v[46:49], v[130:133], v[202:205], 0
	v_mfma_f32_16x16x32_bf16 v[30:33], v[130:133], v[232:235], 0
	v_mfma_f32_16x16x32_bf16 v[26:29], v[138:141], v[232:235], 0
	v_mfma_f32_16x16x32_bf16 v[10:13], v[138:141], v[240:243], 0
	v_mfma_f32_16x16x32_bf16 v[14:17], v[130:133], v[240:243], 0
	v_mfma_f32_16x16x32_bf16 v[6:9], v[154:157], v[240:243], 0
	v_mfma_f32_16x16x32_bf16 v[2:5], v[178:181], v[240:243], 0
	v_mfma_f32_16x16x32_bf16 v[18:21], v[178:181], v[232:235], 0
	v_mfma_f32_16x16x32_bf16 v[22:25], v[154:157], v[232:235], 0
	v_mfma_f32_16x16x32_bf16 v[38:41], v[154:157], v[202:205], 0
	v_mfma_f32_16x16x32_bf16 v[34:37], v[178:181], v[202:205], 0
	v_mfma_f32_16x16x32_bf16 v[50:53], v[178:181], v[194:197], 0
	v_mfma_f32_16x16x32_bf16 v[54:57], v[154:157], v[194:197], 0
	v_mfma_f32_16x16x32_bf16 v[62:65], v[134:137], v[198:201], v[62:65]
	v_mfma_f32_16x16x32_bf16 v[58:61], v[142:145], v[198:201], v[58:61]
	v_mfma_f32_16x16x32_bf16 v[42:45], v[142:145], v[228:231], v[42:45]
	v_mfma_f32_16x16x32_bf16 v[46:49], v[134:137], v[228:231], v[46:49]
	v_mfma_f32_16x16x32_bf16 v[30:33], v[134:137], v[236:239], v[30:33]
	v_mfma_f32_16x16x32_bf16 v[26:29], v[142:145], v[236:239], v[26:29]
	v_mfma_f32_16x16x32_bf16 v[10:13], v[142:145], v[244:247], v[10:13]
	v_mfma_f32_16x16x32_bf16 v[14:17], v[134:137], v[244:247], v[14:17]
	v_mfma_f32_16x16x32_bf16 v[6:9], v[174:177], v[244:247], v[6:9]
	v_mfma_f32_16x16x32_bf16 v[2:5], v[190:193], v[244:247], v[2:5]
	v_mfma_f32_16x16x32_bf16 v[18:21], v[190:193], v[236:239], v[18:21]
	v_mfma_f32_16x16x32_bf16 v[22:25], v[174:177], v[236:239], v[22:25]
	v_mfma_f32_16x16x32_bf16 v[38:41], v[174:177], v[228:231], v[38:41]
	v_mfma_f32_16x16x32_bf16 v[34:37], v[190:193], v[228:231], v[34:37]
	v_mfma_f32_16x16x32_bf16 v[50:53], v[190:193], v[198:201], v[50:53]
	v_mfma_f32_16x16x32_bf16 v[54:57], v[174:177], v[198:201], v[54:57]
	s_barrier
	s_setprio 0
	v_add_u32_e32 v142, 0x18000, v188
	v_add_u32_e32 v182, 0x1c000, v188
	ds_read_b128 v[130:133], v142
	ds_read_b128 v[134:137], v142 offset:1024
	ds_read_b128 v[138:141], v142 offset:2048
	ds_read_b128 v[142:145], v142 offset:3072
	ds_read_b128 v[154:157], v182
	ds_read_b128 v[174:177], v182 offset:1024
	ds_read_b128 v[178:181], v182 offset:2048
	ds_read_b128 v[190:193], v182 offset:3072
	s_add_i32 s52, s52, 0x80000
	s_mov_b32 m0, s27
	ds_read_b128 v[194:197], v189 offset:32768
	ds_read_b128 v[198:201], v189 offset:33792
	ds_read_b128 v[202:205], v189 offset:34816
	ds_read_b128 v[228:231], v189 offset:35840
	ds_read_b128 v[232:235], v189 offset:36864
	ds_read_b128 v[236:239], v189 offset:37888
	ds_read_b128 v[240:243], v189 offset:38912
	ds_read_b128 v[244:247], v189 offset:39936
	buffer_load_dwordx4 v184, s[60:63], s52 offen lds
	s_mov_b32 m0, s30
	s_nop 0
	buffer_load_dwordx4 v186, s[60:63], s52 offen lds
	s_waitcnt vmcnt(8)
	s_waitcnt lgkmcnt(0)
	s_setprio 1
	s_barrier
	v_mfma_f32_16x16x32_bf16 v[126:129], v[130:133], v[194:197], v[126:129]
	v_mfma_f32_16x16x32_bf16 v[122:125], v[138:141], v[194:197], v[122:125]
	v_mfma_f32_16x16x32_bf16 v[106:109], v[138:141], v[202:205], v[106:109]
	v_mfma_f32_16x16x32_bf16 v[110:113], v[130:133], v[202:205], v[110:113]
	v_mfma_f32_16x16x32_bf16 v[94:97], v[130:133], v[232:235], v[94:97]
	v_mfma_f32_16x16x32_bf16 v[90:93], v[138:141], v[232:235], v[90:93]
	v_mfma_f32_16x16x32_bf16 v[74:77], v[138:141], v[240:243], v[74:77]
	v_mfma_f32_16x16x32_bf16 v[78:81], v[130:133], v[240:243], v[78:81]
	v_mfma_f32_16x16x32_bf16 v[70:73], v[154:157], v[240:243], v[70:73]
	v_mfma_f32_16x16x32_bf16 v[66:69], v[178:181], v[240:243], v[66:69]
	v_mfma_f32_16x16x32_bf16 v[82:85], v[178:181], v[232:235], v[82:85]
	v_mfma_f32_16x16x32_bf16 v[86:89], v[154:157], v[232:235], v[86:89]
	v_mfma_f32_16x16x32_bf16 v[102:105], v[154:157], v[202:205], v[102:105]
	v_mfma_f32_16x16x32_bf16 v[98:101], v[178:181], v[202:205], v[98:101]
	v_mfma_f32_16x16x32_bf16 v[114:117], v[178:181], v[194:197], v[114:117]
	v_mfma_f32_16x16x32_bf16 v[118:121], v[154:157], v[194:197], v[118:121]
	v_mfma_f32_16x16x32_bf16 v[126:129], v[134:137], v[198:201], v[126:129]
	v_mfma_f32_16x16x32_bf16 v[122:125], v[142:145], v[198:201], v[122:125]
	v_mfma_f32_16x16x32_bf16 v[106:109], v[142:145], v[228:231], v[106:109]
	v_mfma_f32_16x16x32_bf16 v[110:113], v[134:137], v[228:231], v[110:113]
	v_mfma_f32_16x16x32_bf16 v[94:97], v[134:137], v[236:239], v[94:97]
	v_mfma_f32_16x16x32_bf16 v[90:93], v[142:145], v[236:239], v[90:93]
	v_mfma_f32_16x16x32_bf16 v[74:77], v[142:145], v[244:247], v[74:77]
	v_mfma_f32_16x16x32_bf16 v[78:81], v[134:137], v[244:247], v[78:81]
	v_mfma_f32_16x16x32_bf16 v[70:73], v[174:177], v[244:247], v[70:73]
	v_mfma_f32_16x16x32_bf16 v[66:69], v[190:193], v[244:247], v[66:69]
	v_mfma_f32_16x16x32_bf16 v[82:85], v[190:193], v[236:239], v[82:85]
	v_mfma_f32_16x16x32_bf16 v[86:89], v[174:177], v[236:239], v[86:89]
	v_mfma_f32_16x16x32_bf16 v[102:105], v[174:177], v[228:231], v[102:105]
	v_mfma_f32_16x16x32_bf16 v[98:101], v[190:193], v[228:231], v[98:101]
	v_mfma_f32_16x16x32_bf16 v[114:117], v[190:193], v[198:201], v[114:117]
	v_mfma_f32_16x16x32_bf16 v[118:121], v[174:177], v[198:201], v[118:121]
	s_barrier
	s_setprio 0
	s_mov_b32 m0, s36
	s_or_b32 s52, s25, 0x80
	ds_read_b128 v[194:197], v189 offset:49152
	ds_read_b128 v[198:201], v189 offset:50176
	ds_read_b128 v[202:205], v189 offset:51200
	ds_read_b128 v[228:231], v189 offset:52224
	ds_read_b128 v[232:235], v189 offset:53248
	ds_read_b128 v[236:239], v189 offset:54272
	ds_read_b128 v[240:243], v189 offset:55296
	ds_read_b128 v[244:247], v189 offset:56320
	buffer_load_dwordx4 v185, s[44:47], s52 offen lds
	s_mov_b32 m0, s37
	s_add_i32 s25, s25, 0x80080
	buffer_load_dwordx4 v187, s[44:47], s52 offen lds
	s_mov_b32 m0, s66
	s_nop 0
	buffer_load_dwordx4 v185, s[44:47], s25 offen lds
	s_mov_b32 m0, s67
	s_nop 0
	buffer_load_dwordx4 v187, s[44:47], s25 offen lds
	s_mov_b32 m0, s48
	s_nop 0
	buffer_load_dwordx4 v184, s[60:63], s24 offen lds
	s_mov_b32 m0, s49
	s_nop 0
	buffer_load_dwordx4 v186, s[60:63], s24 offen lds
	s_waitcnt vmcnt(8)
	s_waitcnt lgkmcnt(0)
	s_setprio 1
	s_barrier
	v_mfma_f32_16x16x32_bf16 v[62:65], v[130:133], v[194:197], v[62:65]
	v_mfma_f32_16x16x32_bf16 v[58:61], v[138:141], v[194:197], v[58:61]
	v_mfma_f32_16x16x32_bf16 v[42:45], v[138:141], v[202:205], v[42:45]
	v_mfma_f32_16x16x32_bf16 v[46:49], v[130:133], v[202:205], v[46:49]
	v_mfma_f32_16x16x32_bf16 v[30:33], v[130:133], v[232:235], v[30:33]
	v_mfma_f32_16x16x32_bf16 v[26:29], v[138:141], v[232:235], v[26:29]
	v_mfma_f32_16x16x32_bf16 v[10:13], v[138:141], v[240:243], v[10:13]
	v_mfma_f32_16x16x32_bf16 v[14:17], v[130:133], v[240:243], v[14:17]
	v_mfma_f32_16x16x32_bf16 v[6:9], v[154:157], v[240:243], v[6:9]
	v_mfma_f32_16x16x32_bf16 v[2:5], v[178:181], v[240:243], v[2:5]
	v_mfma_f32_16x16x32_bf16 v[18:21], v[178:181], v[232:235], v[18:21]
	v_mfma_f32_16x16x32_bf16 v[22:25], v[154:157], v[232:235], v[22:25]
	v_mfma_f32_16x16x32_bf16 v[38:41], v[154:157], v[202:205], v[38:41]
	v_mfma_f32_16x16x32_bf16 v[34:37], v[178:181], v[202:205], v[34:37]
	v_mfma_f32_16x16x32_bf16 v[50:53], v[178:181], v[194:197], v[50:53]
	v_mfma_f32_16x16x32_bf16 v[54:57], v[154:157], v[194:197], v[54:57]
	v_mfma_f32_16x16x32_bf16 v[62:65], v[134:137], v[198:201], v[62:65]
	v_mfma_f32_16x16x32_bf16 v[58:61], v[142:145], v[198:201], v[58:61]
	v_mfma_f32_16x16x32_bf16 v[42:45], v[142:145], v[228:231], v[42:45]
	v_mfma_f32_16x16x32_bf16 v[46:49], v[134:137], v[228:231], v[46:49]
	v_mfma_f32_16x16x32_bf16 v[30:33], v[134:137], v[236:239], v[30:33]
	v_mfma_f32_16x16x32_bf16 v[26:29], v[142:145], v[236:239], v[26:29]
	v_mfma_f32_16x16x32_bf16 v[10:13], v[142:145], v[244:247], v[10:13]
	v_mfma_f32_16x16x32_bf16 v[14:17], v[134:137], v[244:247], v[14:17]
	v_mfma_f32_16x16x32_bf16 v[6:9], v[174:177], v[244:247], v[6:9]
	v_mfma_f32_16x16x32_bf16 v[2:5], v[190:193], v[244:247], v[2:5]
	v_mfma_f32_16x16x32_bf16 v[18:21], v[190:193], v[236:239], v[18:21]
	v_mfma_f32_16x16x32_bf16 v[22:25], v[174:177], v[236:239], v[22:25]
	v_mfma_f32_16x16x32_bf16 v[38:41], v[174:177], v[228:231], v[38:41]
	v_mfma_f32_16x16x32_bf16 v[34:37], v[190:193], v[228:231], v[34:37]
	v_mfma_f32_16x16x32_bf16 v[50:53], v[190:193], v[198:201], v[50:53]
	v_mfma_f32_16x16x32_bf16 v[54:57], v[174:177], v[198:201], v[54:57]
	s_barrier
	s_setprio 0
	s_add_i32 s22, s22, 2
	s_addk_i32 s13, 0x100
	s_addk_i32 s21, 0x100
	s_cmp_gt_u32 s22, 29
.LBB0_2450:
	v_add_u32_e32 v142, 0x10000, v188
	v_add_u32_e32 v182, 0x14000, v188
	ds_read_b128 v[130:133], v142
	ds_read_b128 v[134:137], v142 offset:1024
	ds_read_b128 v[138:141], v142 offset:2048
	ds_read_b128 v[142:145], v142 offset:3072
	ds_read_b128 v[154:157], v182
	ds_read_b128 v[174:177], v182 offset:1024
	ds_read_b128 v[178:181], v182 offset:2048
	ds_read_b128 v[190:193], v182 offset:3072
	s_add_i32 s24, s13, 0xfff80080
	s_cmp_eq_u32 s22, 28
	s_cselect_b32 s52, s8, s24
	s_cselect_b32 s25, s9, s21
	s_or_b32 s24, s52, 0x80
	s_mov_b32 m0, s68
	ds_read_b128 v[194:197], v189
	ds_read_b128 v[198:201], v189 offset:1024
	ds_read_b128 v[202:205], v189 offset:2048
	ds_read_b128 v[228:231], v189 offset:3072
	ds_read_b128 v[232:235], v189 offset:4096
	ds_read_b128 v[236:239], v189 offset:5120
	ds_read_b128 v[240:243], v189 offset:6144
	ds_read_b128 v[244:247], v189 offset:7168
	buffer_load_dwordx4 v184, s[60:63], s13 offen lds
	s_mov_b32 m0, s70
	s_nop 0
	buffer_load_dwordx4 v186, s[60:63], s13 offen lds
	s_waitcnt vmcnt(8)
	s_waitcnt lgkmcnt(0)
	s_setprio 1
	s_barrier
	v_mfma_f32_16x16x32_bf16 v[126:129], v[130:133], v[194:197], v[126:129]
	v_mfma_f32_16x16x32_bf16 v[122:125], v[138:141], v[194:197], v[122:125]
	v_mfma_f32_16x16x32_bf16 v[106:109], v[138:141], v[202:205], v[106:109]
	v_mfma_f32_16x16x32_bf16 v[110:113], v[130:133], v[202:205], v[110:113]
	v_mfma_f32_16x16x32_bf16 v[94:97], v[130:133], v[232:235], v[94:97]
	v_mfma_f32_16x16x32_bf16 v[90:93], v[138:141], v[232:235], v[90:93]
	v_mfma_f32_16x16x32_bf16 v[74:77], v[138:141], v[240:243], v[74:77]
	v_mfma_f32_16x16x32_bf16 v[78:81], v[130:133], v[240:243], v[78:81]
	v_mfma_f32_16x16x32_bf16 v[70:73], v[154:157], v[240:243], v[70:73]
	v_mfma_f32_16x16x32_bf16 v[66:69], v[178:181], v[240:243], v[66:69]
	v_mfma_f32_16x16x32_bf16 v[82:85], v[178:181], v[232:235], v[82:85]
	v_mfma_f32_16x16x32_bf16 v[86:89], v[154:157], v[232:235], v[86:89]
	v_mfma_f32_16x16x32_bf16 v[102:105], v[154:157], v[202:205], v[102:105]
	v_mfma_f32_16x16x32_bf16 v[98:101], v[178:181], v[202:205], v[98:101]
	v_mfma_f32_16x16x32_bf16 v[114:117], v[178:181], v[194:197], v[114:117]
	v_mfma_f32_16x16x32_bf16 v[118:121], v[154:157], v[194:197], v[118:121]
	v_mfma_f32_16x16x32_bf16 v[126:129], v[134:137], v[198:201], v[126:129]
	v_mfma_f32_16x16x32_bf16 v[122:125], v[142:145], v[198:201], v[122:125]
	v_mfma_f32_16x16x32_bf16 v[106:109], v[142:145], v[228:231], v[106:109]
	v_mfma_f32_16x16x32_bf16 v[110:113], v[134:137], v[228:231], v[110:113]
	v_mfma_f32_16x16x32_bf16 v[94:97], v[134:137], v[236:239], v[94:97]
	v_mfma_f32_16x16x32_bf16 v[90:93], v[142:145], v[236:239], v[90:93]
	v_mfma_f32_16x16x32_bf16 v[74:77], v[142:145], v[244:247], v[74:77]
	v_mfma_f32_16x16x32_bf16 v[78:81], v[134:137], v[244:247], v[78:81]
	v_mfma_f32_16x16x32_bf16 v[70:73], v[174:177], v[244:247], v[70:73]
	v_mfma_f32_16x16x32_bf16 v[66:69], v[190:193], v[244:247], v[66:69]
	v_mfma_f32_16x16x32_bf16 v[82:85], v[190:193], v[236:239], v[82:85]
	v_mfma_f32_16x16x32_bf16 v[86:89], v[174:177], v[236:239], v[86:89]
	v_mfma_f32_16x16x32_bf16 v[102:105], v[174:177], v[228:231], v[102:105]
	v_mfma_f32_16x16x32_bf16 v[98:101], v[190:193], v[228:231], v[98:101]
	v_mfma_f32_16x16x32_bf16 v[114:117], v[190:193], v[198:201], v[114:117]
	v_mfma_f32_16x16x32_bf16 v[118:121], v[174:177], v[198:201], v[118:121]
	s_barrier
	s_setprio 0
	s_mov_b32 m0, s16
	s_mov_b32 s46, s62
	s_mov_b32 s47, s63
	ds_read_b128 v[194:197], v189 offset:16384
	ds_read_b128 v[198:201], v189 offset:17408
	ds_read_b128 v[202:205], v189 offset:18432
	ds_read_b128 v[228:231], v189 offset:19456
	ds_read_b128 v[232:235], v189 offset:20480
	ds_read_b128 v[236:239], v189 offset:21504
	ds_read_b128 v[240:243], v189 offset:22528
	ds_read_b128 v[244:247], v189 offset:23552
	buffer_load_dwordx4 v185, s[44:47], s25 offen lds
	s_mov_b32 m0, s18
	s_add_i32 s53, s25, 0x80000
	buffer_load_dwordx4 v187, s[44:47], s25 offen lds
	s_mov_b32 m0, s19
	s_nop 0
	buffer_load_dwordx4 v185, s[44:47], s53 offen lds
	s_mov_b32 m0, s23
	s_nop 0
	buffer_load_dwordx4 v187, s[44:47], s53 offen lds
	s_mov_b32 m0, s15
	s_nop 0
	buffer_load_dwordx4 v184, s[60:63], s52 offen lds
	s_mov_b32 m0, s26
	s_nop 0
	buffer_load_dwordx4 v186, s[60:63], s52 offen lds
	s_waitcnt vmcnt(8)
	s_waitcnt lgkmcnt(0)
	s_setprio 1
	s_barrier
	v_mfma_f32_16x16x32_bf16 v[62:65], v[130:133], v[194:197], v[62:65]
	v_mfma_f32_16x16x32_bf16 v[58:61], v[138:141], v[194:197], v[58:61]
	v_mfma_f32_16x16x32_bf16 v[42:45], v[138:141], v[202:205], v[42:45]
	v_mfma_f32_16x16x32_bf16 v[46:49], v[130:133], v[202:205], v[46:49]
	v_mfma_f32_16x16x32_bf16 v[30:33], v[130:133], v[232:235], v[30:33]
	v_mfma_f32_16x16x32_bf16 v[26:29], v[138:141], v[232:235], v[26:29]
	v_mfma_f32_16x16x32_bf16 v[10:13], v[138:141], v[240:243], v[10:13]
	v_mfma_f32_16x16x32_bf16 v[14:17], v[130:133], v[240:243], v[14:17]
	v_mfma_f32_16x16x32_bf16 v[6:9], v[154:157], v[240:243], v[6:9]
	v_mfma_f32_16x16x32_bf16 v[2:5], v[178:181], v[240:243], v[2:5]
	v_mfma_f32_16x16x32_bf16 v[18:21], v[178:181], v[232:235], v[18:21]
	v_mfma_f32_16x16x32_bf16 v[22:25], v[154:157], v[232:235], v[22:25]
	v_mfma_f32_16x16x32_bf16 v[38:41], v[154:157], v[202:205], v[38:41]
	v_mfma_f32_16x16x32_bf16 v[34:37], v[178:181], v[202:205], v[34:37]
	v_mfma_f32_16x16x32_bf16 v[50:53], v[178:181], v[194:197], v[50:53]
	v_mfma_f32_16x16x32_bf16 v[54:57], v[154:157], v[194:197], v[54:57]
	v_mfma_f32_16x16x32_bf16 v[62:65], v[134:137], v[198:201], v[62:65]
	v_mfma_f32_16x16x32_bf16 v[58:61], v[142:145], v[198:201], v[58:61]
	v_mfma_f32_16x16x32_bf16 v[42:45], v[142:145], v[228:231], v[42:45]
	v_mfma_f32_16x16x32_bf16 v[46:49], v[134:137], v[228:231], v[46:49]
	v_mfma_f32_16x16x32_bf16 v[30:33], v[134:137], v[236:239], v[30:33]
	v_mfma_f32_16x16x32_bf16 v[26:29], v[142:145], v[236:239], v[26:29]
	v_mfma_f32_16x16x32_bf16 v[10:13], v[142:145], v[244:247], v[10:13]
	v_mfma_f32_16x16x32_bf16 v[14:17], v[134:137], v[244:247], v[14:17]
	v_mfma_f32_16x16x32_bf16 v[6:9], v[174:177], v[244:247], v[6:9]
	v_mfma_f32_16x16x32_bf16 v[2:5], v[190:193], v[244:247], v[2:5]
	v_mfma_f32_16x16x32_bf16 v[18:21], v[190:193], v[236:239], v[18:21]
	v_mfma_f32_16x16x32_bf16 v[22:25], v[174:177], v[236:239], v[22:25]
	v_mfma_f32_16x16x32_bf16 v[38:41], v[174:177], v[228:231], v[38:41]
	v_mfma_f32_16x16x32_bf16 v[34:37], v[190:193], v[228:231], v[34:37]
	v_mfma_f32_16x16x32_bf16 v[50:53], v[190:193], v[198:201], v[50:53]
	v_mfma_f32_16x16x32_bf16 v[54:57], v[174:177], v[198:201], v[54:57]
	s_barrier
	s_setprio 0
	v_add_u32_e32 v142, 0x18000, v188
	v_add_u32_e32 v182, 0x1c000, v188
	ds_read_b128 v[130:133], v142
	ds_read_b128 v[134:137], v142 offset:1024
	ds_read_b128 v[138:141], v142 offset:2048
	ds_read_b128 v[142:145], v142 offset:3072
	ds_read_b128 v[154:157], v182
	ds_read_b128 v[174:177], v182 offset:1024
	ds_read_b128 v[178:181], v182 offset:2048
	ds_read_b128 v[190:193], v182 offset:3072
	s_add_i32 s52, s52, 0x80000
	s_mov_b32 m0, s27
	ds_read_b128 v[194:197], v189 offset:32768
	ds_read_b128 v[198:201], v189 offset:33792
	ds_read_b128 v[202:205], v189 offset:34816
	ds_read_b128 v[228:231], v189 offset:35840
	ds_read_b128 v[232:235], v189 offset:36864
	ds_read_b128 v[236:239], v189 offset:37888
	ds_read_b128 v[240:243], v189 offset:38912
	ds_read_b128 v[244:247], v189 offset:39936
	buffer_load_dwordx4 v184, s[60:63], s52 offen lds
	s_mov_b32 m0, s30
	s_nop 0
	buffer_load_dwordx4 v186, s[60:63], s52 offen lds
	s_waitcnt vmcnt(8)
	s_waitcnt lgkmcnt(0)
	s_setprio 1
	s_barrier
	v_mfma_f32_16x16x32_bf16 v[126:129], v[130:133], v[194:197], v[126:129]
	v_mfma_f32_16x16x32_bf16 v[122:125], v[138:141], v[194:197], v[122:125]
	v_mfma_f32_16x16x32_bf16 v[106:109], v[138:141], v[202:205], v[106:109]
	v_mfma_f32_16x16x32_bf16 v[110:113], v[130:133], v[202:205], v[110:113]
	v_mfma_f32_16x16x32_bf16 v[94:97], v[130:133], v[232:235], v[94:97]
	v_mfma_f32_16x16x32_bf16 v[90:93], v[138:141], v[232:235], v[90:93]
	v_mfma_f32_16x16x32_bf16 v[74:77], v[138:141], v[240:243], v[74:77]
	v_mfma_f32_16x16x32_bf16 v[78:81], v[130:133], v[240:243], v[78:81]
	v_mfma_f32_16x16x32_bf16 v[70:73], v[154:157], v[240:243], v[70:73]
	v_mfma_f32_16x16x32_bf16 v[66:69], v[178:181], v[240:243], v[66:69]
	v_mfma_f32_16x16x32_bf16 v[82:85], v[178:181], v[232:235], v[82:85]
	v_mfma_f32_16x16x32_bf16 v[86:89], v[154:157], v[232:235], v[86:89]
	v_mfma_f32_16x16x32_bf16 v[102:105], v[154:157], v[202:205], v[102:105]
	v_mfma_f32_16x16x32_bf16 v[98:101], v[178:181], v[202:205], v[98:101]
	v_mfma_f32_16x16x32_bf16 v[114:117], v[178:181], v[194:197], v[114:117]
	v_mfma_f32_16x16x32_bf16 v[118:121], v[154:157], v[194:197], v[118:121]
	v_mfma_f32_16x16x32_bf16 v[126:129], v[134:137], v[198:201], v[126:129]
	v_mfma_f32_16x16x32_bf16 v[122:125], v[142:145], v[198:201], v[122:125]
	v_mfma_f32_16x16x32_bf16 v[106:109], v[142:145], v[228:231], v[106:109]
	v_mfma_f32_16x16x32_bf16 v[110:113], v[134:137], v[228:231], v[110:113]
	v_mfma_f32_16x16x32_bf16 v[94:97], v[134:137], v[236:239], v[94:97]
	v_mfma_f32_16x16x32_bf16 v[90:93], v[142:145], v[236:239], v[90:93]
	v_mfma_f32_16x16x32_bf16 v[74:77], v[142:145], v[244:247], v[74:77]
	v_mfma_f32_16x16x32_bf16 v[78:81], v[134:137], v[244:247], v[78:81]
	v_mfma_f32_16x16x32_bf16 v[70:73], v[174:177], v[244:247], v[70:73]
	v_mfma_f32_16x16x32_bf16 v[66:69], v[190:193], v[244:247], v[66:69]
	v_mfma_f32_16x16x32_bf16 v[82:85], v[190:193], v[236:239], v[82:85]
	v_mfma_f32_16x16x32_bf16 v[86:89], v[174:177], v[236:239], v[86:89]
	v_mfma_f32_16x16x32_bf16 v[102:105], v[174:177], v[228:231], v[102:105]
	v_mfma_f32_16x16x32_bf16 v[98:101], v[190:193], v[228:231], v[98:101]
	v_mfma_f32_16x16x32_bf16 v[114:117], v[190:193], v[198:201], v[114:117]
	v_mfma_f32_16x16x32_bf16 v[118:121], v[174:177], v[198:201], v[118:121]
	s_barrier
	s_setprio 0
	s_mov_b32 m0, s36
	s_or_b32 s52, s25, 0x80
	ds_read_b128 v[194:197], v189 offset:49152
	ds_read_b128 v[198:201], v189 offset:50176
	ds_read_b128 v[202:205], v189 offset:51200
	ds_read_b128 v[228:231], v189 offset:52224
	ds_read_b128 v[232:235], v189 offset:53248
	ds_read_b128 v[236:239], v189 offset:54272
	ds_read_b128 v[240:243], v189 offset:55296
	ds_read_b128 v[244:247], v189 offset:56320
	buffer_load_dwordx4 v185, s[44:47], s52 offen lds
	s_mov_b32 m0, s37
	s_add_i32 s25, s25, 0x80080
	buffer_load_dwordx4 v187, s[44:47], s52 offen lds
	s_mov_b32 m0, s66
	s_nop 0
	buffer_load_dwordx4 v185, s[44:47], s25 offen lds
	s_mov_b32 m0, s67
	s_nop 0
	buffer_load_dwordx4 v187, s[44:47], s25 offen lds
	s_mov_b32 m0, s48
	s_nop 0
	buffer_load_dwordx4 v184, s[60:63], s24 offen lds
	s_mov_b32 m0, s49
	s_nop 0
	buffer_load_dwordx4 v186, s[60:63], s24 offen lds
	s_waitcnt vmcnt(8)
	s_waitcnt lgkmcnt(0)
	s_setprio 1
	s_barrier
	v_mfma_f32_16x16x32_bf16 v[62:65], v[130:133], v[194:197], v[62:65]
	v_mfma_f32_16x16x32_bf16 v[58:61], v[138:141], v[194:197], v[58:61]
	v_mfma_f32_16x16x32_bf16 v[42:45], v[138:141], v[202:205], v[42:45]
	v_mfma_f32_16x16x32_bf16 v[46:49], v[130:133], v[202:205], v[46:49]
	v_mfma_f32_16x16x32_bf16 v[30:33], v[130:133], v[232:235], v[30:33]
	v_mfma_f32_16x16x32_bf16 v[26:29], v[138:141], v[232:235], v[26:29]
	v_mfma_f32_16x16x32_bf16 v[10:13], v[138:141], v[240:243], v[10:13]
	v_mfma_f32_16x16x32_bf16 v[14:17], v[130:133], v[240:243], v[14:17]
	v_mfma_f32_16x16x32_bf16 v[6:9], v[154:157], v[240:243], v[6:9]
	v_mfma_f32_16x16x32_bf16 v[2:5], v[178:181], v[240:243], v[2:5]
	v_mfma_f32_16x16x32_bf16 v[18:21], v[178:181], v[232:235], v[18:21]
	v_mfma_f32_16x16x32_bf16 v[22:25], v[154:157], v[232:235], v[22:25]
	v_mfma_f32_16x16x32_bf16 v[38:41], v[154:157], v[202:205], v[38:41]
	v_mfma_f32_16x16x32_bf16 v[34:37], v[178:181], v[202:205], v[34:37]
	v_mfma_f32_16x16x32_bf16 v[50:53], v[178:181], v[194:197], v[50:53]
	v_mfma_f32_16x16x32_bf16 v[54:57], v[154:157], v[194:197], v[54:57]
	v_mfma_f32_16x16x32_bf16 v[62:65], v[134:137], v[198:201], v[62:65]
	v_mfma_f32_16x16x32_bf16 v[58:61], v[142:145], v[198:201], v[58:61]
	v_mfma_f32_16x16x32_bf16 v[42:45], v[142:145], v[228:231], v[42:45]
	v_mfma_f32_16x16x32_bf16 v[46:49], v[134:137], v[228:231], v[46:49]
	v_mfma_f32_16x16x32_bf16 v[30:33], v[134:137], v[236:239], v[30:33]
	v_mfma_f32_16x16x32_bf16 v[26:29], v[142:145], v[236:239], v[26:29]
	v_mfma_f32_16x16x32_bf16 v[10:13], v[142:145], v[244:247], v[10:13]
	v_mfma_f32_16x16x32_bf16 v[14:17], v[134:137], v[244:247], v[14:17]
	v_mfma_f32_16x16x32_bf16 v[6:9], v[174:177], v[244:247], v[6:9]
	v_mfma_f32_16x16x32_bf16 v[2:5], v[190:193], v[244:247], v[2:5]
	v_mfma_f32_16x16x32_bf16 v[18:21], v[190:193], v[236:239], v[18:21]
	v_mfma_f32_16x16x32_bf16 v[22:25], v[174:177], v[236:239], v[22:25]
	v_mfma_f32_16x16x32_bf16 v[38:41], v[174:177], v[228:231], v[38:41]
	v_mfma_f32_16x16x32_bf16 v[34:37], v[190:193], v[228:231], v[34:37]
	v_mfma_f32_16x16x32_bf16 v[50:53], v[190:193], v[198:201], v[50:53]
	v_mfma_f32_16x16x32_bf16 v[54:57], v[174:177], v[198:201], v[54:57]
	s_barrier
	s_setprio 0
	s_add_i32 s22, s22, 2
	s_addk_i32 s13, 0x100
	s_addk_i32 s21, 0x100
	s_cmp_gt_u32 s22, 29
	s_cbranch_scc0 .LBB0_2450
	s_and_b64 vcc, exec, s[64:65]
	s_cbranch_vccz .LBB0_2453
	s_barrier
